# all 222 global stores write-through (sc1) so barrier L2 write-backs find clean L2; + no entry grid.sync
# baseline (speedup 1.0000x reference)
; __device__ __forceinline__ float bf_lo(unsigned w) { return __uint_as_float(w << 16); }
; __device__ __forceinline__ float bf_hi(unsigned w) { return __uint_as_float(w & 0xffff0000u); }
; __device__ __forceinline__ unsigned cvt_pk_bf16(float lo, float hi) { f32x2_t v = {lo, hi}; bf16x2_t b = __builtin_convertvector(v, bf16x2_t); return __builtin_bit_cast(unsigned, b); }
; #define EPI_LANE() int t__ = threadIdx.x; asm volatile("" : "+v"(t__)); const int wid__ = __builtin_amdgcn_readfirstlane(t__ >> 6); wr = wid__ >> 2; wc = wid__ & 3; fr = t__ & 15; fq = (t__ & 63) >> 4
;     __device__ __forceinline__ void operator()(const f32x4 (&acc)[2][2][4][2], const Unit& u, int wr, int wc, int fr, int fq) const {
;         EPI_LANE();
;         const char* g_b = gbase(2, u, wid__) + (t__ & 63) * 16; char* mb = (char*)(Mg + (size_t)u.pm * BM * 1024 + u.pn * BM);
;         unsigned rl0 = (unsigned)(wr * 64 + fr), cl0 = (unsigned)(wc * 32 + 8 * fq); asm volatile("" : "+v"(rl0), "+v"(cl0));
; #pragma unroll
;         for (int ai = 0; ai < 2; ++ai) {
;             u32x4 gv[4][2];
; #pragma unroll
;             for (int m = 0; m < 4; ++m)
; #pragma unroll
;                 for (int bj = 0; bj < 2; ++bj) gv[m][bj] = *(const u32x4*)(g_b + ((ai * 4 + m) * 2 + bj) * 1024);
; #pragma unroll
;             for (int m = 0; m < 4; ++m) { const unsigned rl = rl0 + (unsigned)(ai * HALF + m * 16);
; #pragma unroll
;                 for (int bj = 0; bj < 2; ++bj) { const unsigned cl = cl0 + (unsigned)(bj * HALF);
;                     const u32x4 g = gv[m][bj];
;                     const f32x4 v0 = acc[ai][bj][m][0], v1 = acc[ai][bj][m][1];
;                     u32x4 w;
;                     w.x = cvt_pk_bf16(v0[0] * __builtin_amdgcn_rcpf(bf_lo(g.x)), v0[1] * __builtin_amdgcn_rcpf(bf_hi(g.x)));
;                     w.y = cvt_pk_bf16(v0[2] * __builtin_amdgcn_rcpf(bf_lo(g.y)), v0[3] * __builtin_amdgcn_rcpf(bf_hi(g.y)));
;                     w.z = cvt_pk_bf16(v1[0] * __builtin_amdgcn_rcpf(bf_lo(g.z)), v1[1] * __builtin_amdgcn_rcpf(bf_hi(g.z)));
;                     w.w = cvt_pk_bf16(v1[2] * __builtin_amdgcn_rcpf(bf_lo(g.w)), v1[3] * __builtin_amdgcn_rcpf(bf_hi(g.w)));
;                     *(u32x4*)(mb + (rl * 1024u + cl) * 2u) = w; } }
.LBB0_57:
	v_mov_b32_e32 v132, v212
	s_lshl_b32 s61, s6, 10
	v_readfirstlane_b32 s31, v132
	s_lshl_b32 s62, s60, 3
	s_ashr_i32 s36, s31, 6
	s_add_i32 s61, s61, s62
	s_add_i32 s61, s61, s36
	s_add_i32 s62, s61, 0x2000
	s_ashr_i32 s63, s62, 31
	s_lshl_b64 s[62:63], s[62:63], 14
	s_add_u32 s62, s33, s62
	s_addc_u32 s63, s37, s63
	s_ashr_i32 s61, s60, 31
	s_lshl_b64 s[60:61], s[60:61], 19
	s_add_u32 s64, s89, s60
	s_addc_u32 s65, s3, s61
	s_lshl_b32 s60, s6, 8
	s_ashr_i32 s61, s60, 31
	s_lshl_b64 s[60:61], s[60:61], 1
	s_add_u32 s60, s64, s60
	s_addc_u32 s61, s65, s61
	s_ashr_i32 s6, s31, 2
	s_andn2_b32 s6, s6, 63
	v_and_or_b32 v158, v132, 15, s6
	s_lshl_b32 s6, s36, 5
	v_lshlrev_b32_e32 v96, 4, v132
	s_and_b32 s6, s6, 0x60
	v_lshrrev_b32_e32 v132, 1, v132
	v_and_b32_e32 v96, 0x3f0, v96
	v_and_or_b32 v159, v132, 24, s6
	global_load_dwordx4 v[160:163], v96, s[62:63]
	global_load_dwordx4 v[164:167], v96, s[62:63] offset:1024
	global_load_dwordx4 v[152:155], v96, s[62:63] offset:2048
	global_load_dwordx4 v[148:151], v96, s[62:63] offset:3072
	v_lshl_add_u64 v[98:99], s[62:63], 0, v[96:97]
	s_movk_i32 s6, 0x1000
	v_add_co_u32_e32 v132, vcc, s6, v98
	s_movk_i32 s6, 0x2000
	s_nop 0
	v_addc_co_u32_e32 v133, vcc, 0, v99, vcc
	v_add_co_u32_e32 v156, vcc, s6, v98
	v_lshlrev_b32_e32 v96, 1, v159
	s_nop 0
	v_addc_co_u32_e32 v157, vcc, 0, v99, vcc
	global_load_dwordx4 v[144:147], v[156:157], off offset:-4096
	global_load_dwordx4 v[140:143], v[132:133], off offset:1024
	global_load_dwordx4 v[136:139], v[132:133], off offset:2048
	s_nop 0
	global_load_dwordx4 v[132:135], v[132:133], off offset:3072
	v_lshl_add_u32 v96, v158, 11, v96
	s_movk_i32 s6, 0x3000
	s_waitcnt vmcnt(0)
	v_lshlrev_b32_e32 v168, 16, v160
	v_and_b32_e32 v160, 0xffff0000, v160
	v_rcp_f32_e32 v168, v168
	v_rcp_f32_e32 v169, v160
	s_nop 0
	v_pk_mul_f32 v[128:129], v[128:129], v[168:169]
	s_nop 0
	v_cvt_pk_bf16_f32 v128, v128, v129
	v_lshlrev_b32_e32 v129, 16, v161
	v_rcp_f32_e32 v160, v129
	v_and_b32_e32 v129, 0xffff0000, v161
	v_rcp_f32_e32 v161, v129
	s_nop 0
	v_pk_mul_f32 v[130:131], v[130:131], v[160:161]
	s_nop 0
	v_cvt_pk_bf16_f32 v129, v130, v131
	v_lshlrev_b32_e32 v130, 16, v162
	v_and_b32_e32 v131, 0xffff0000, v162
	v_rcp_f32_e32 v130, v130
	v_rcp_f32_e32 v131, v131
	s_nop 0
	v_pk_mul_f32 v[120:121], v[120:121], v[130:131]
	s_nop 0
	v_cvt_pk_bf16_f32 v130, v120, v121
	v_lshlrev_b32_e32 v120, 16, v163
	v_and_b32_e32 v121, 0xffff0000, v163
	v_rcp_f32_e32 v120, v120
	v_rcp_f32_e32 v121, v121
	s_nop 0
	v_pk_mul_f32 v[120:121], v[122:123], v[120:121]
	s_nop 0
	v_cvt_pk_bf16_f32 v131, v120, v121
	v_lshlrev_b32_e32 v120, 16, v164
	v_and_b32_e32 v121, 0xffff0000, v164
	v_rcp_f32_e32 v120, v120
	v_rcp_f32_e32 v121, v121
	global_store_dwordx4 v96, v[128:131], s[60:61] sc1
	v_pk_mul_f32 v[120:121], v[124:125], v[120:121]
	s_nop 0
	v_cvt_pk_bf16_f32 v120, v120, v121
	v_lshlrev_b32_e32 v121, 16, v165
	v_rcp_f32_e32 v122, v121
	v_and_b32_e32 v121, 0xffff0000, v165
	v_rcp_f32_e32 v123, v121
	s_nop 0
	v_pk_mul_f32 v[122:123], v[126:127], v[122:123]
	s_nop 0
	v_cvt_pk_bf16_f32 v121, v122, v123
	v_lshlrev_b32_e32 v122, 16, v166
	v_and_b32_e32 v123, 0xffff0000, v166
	v_rcp_f32_e32 v122, v122
	v_rcp_f32_e32 v123, v123
	s_nop 0
	v_pk_mul_f32 v[116:117], v[116:117], v[122:123]
	s_nop 0
	v_cvt_pk_bf16_f32 v122, v116, v117
	v_lshlrev_b32_e32 v116, 16, v167
	v_and_b32_e32 v117, 0xffff0000, v167
	v_rcp_f32_e32 v116, v116
	v_rcp_f32_e32 v117, v117
	s_nop 0
	v_pk_mul_f32 v[116:117], v[118:119], v[116:117]
	s_nop 0
	v_cvt_pk_bf16_f32 v123, v116, v117
	v_add_u32_e32 v116, 0x100, v96
	global_store_dwordx4 v116, v[120:123], s[60:61] sc1
	v_lshlrev_b32_e32 v116, 16, v152
	v_and_b32_e32 v117, 0xffff0000, v152
	v_rcp_f32_e32 v116, v116
	v_rcp_f32_e32 v117, v117
	v_add_u32_e32 v118, 0x8000, v96
	v_pk_mul_f32 v[112:113], v[112:113], v[116:117]
	s_nop 0
	v_cvt_pk_bf16_f32 v112, v112, v113
	v_lshlrev_b32_e32 v113, 16, v153
	v_rcp_f32_e32 v116, v113
	v_and_b32_e32 v113, 0xffff0000, v153
	v_rcp_f32_e32 v117, v113
	s_nop 0
	v_pk_mul_f32 v[114:115], v[114:115], v[116:117]
	s_nop 0
	v_cvt_pk_bf16_f32 v113, v114, v115
	v_lshlrev_b32_e32 v114, 16, v154
	v_and_b32_e32 v115, 0xffff0000, v154
	v_rcp_f32_e32 v114, v114
	v_rcp_f32_e32 v115, v115
	s_nop 0
	v_pk_mul_f32 v[108:109], v[108:109], v[114:115]
	s_nop 0
	v_cvt_pk_bf16_f32 v114, v108, v109
	v_lshlrev_b32_e32 v108, 16, v155
	v_and_b32_e32 v109, 0xffff0000, v155
	v_rcp_f32_e32 v108, v108
	v_rcp_f32_e32 v109, v109
	s_nop 0
	v_pk_mul_f32 v[108:109], v[110:111], v[108:109]
	s_nop 0
	v_cvt_pk_bf16_f32 v115, v108, v109
	v_lshlrev_b32_e32 v108, 16, v148
	v_and_b32_e32 v109, 0xffff0000, v148
	v_rcp_f32_e32 v108, v108
	v_rcp_f32_e32 v109, v109
	global_store_dwordx4 v118, v[112:115], s[60:61] sc1
	v_pk_mul_f32 v[104:105], v[104:105], v[108:109]
	s_nop 0
	v_cvt_pk_bf16_f32 v104, v104, v105
	v_lshlrev_b32_e32 v105, 16, v149
	v_rcp_f32_e32 v108, v105
	v_and_b32_e32 v105, 0xffff0000, v149
	v_rcp_f32_e32 v109, v105
	s_nop 0
	v_pk_mul_f32 v[106:107], v[106:107], v[108:109]
	s_nop 0
	v_cvt_pk_bf16_f32 v105, v106, v107
	v_lshlrev_b32_e32 v106, 16, v150
	v_and_b32_e32 v107, 0xffff0000, v150
	v_rcp_f32_e32 v106, v106
	v_rcp_f32_e32 v107, v107
	s_nop 0
	v_pk_mul_f32 v[100:101], v[100:101], v[106:107]
	s_nop 0
	v_cvt_pk_bf16_f32 v106, v100, v101
	v_lshlrev_b32_e32 v100, 16, v151
	v_and_b32_e32 v101, 0xffff0000, v151
	v_rcp_f32_e32 v100, v100
	v_rcp_f32_e32 v101, v101
	s_nop 0
	v_pk_mul_f32 v[100:101], v[102:103], v[100:101]
	s_nop 0
	v_cvt_pk_bf16_f32 v107, v100, v101
	v_add_u32_e32 v100, 0x8100, v96
	global_store_dwordx4 v100, v[104:107], s[60:61] sc1
	v_lshlrev_b32_e32 v100, 16, v144
; __device__ __forceinline__ float bf_lo(unsigned w) { return __uint_as_float(w << 16); }
; __device__ __forceinline__ float bf_hi(unsigned w) { return __uint_as_float(w & 0xffff0000u); }
; __device__ __forceinline__ unsigned cvt_pk_bf16(float lo, float hi) { f32x2_t v = {lo, hi}; bf16x2_t b = __builtin_convertvector(v, bf16x2_t); return __builtin_bit_cast(unsigned, b); }
;     __device__ __forceinline__ void operator()(const f32x4 (&acc)[2][2][4][2], const Unit& u, int wr, int wc, int fr, int fq) const {
;     ...
;         for (int ai = 0; ai < 2; ++ai) {
;             u32x4 gv[4][2];
; #pragma unroll
;             for (int m = 0; m < 4; ++m)
; #pragma unroll
;                 for (int bj = 0; bj < 2; ++bj) gv[m][bj] = *(const u32x4*)(g_b + ((ai * 4 + m) * 2 + bj) * 1024);
; #pragma unroll
;             for (int m = 0; m < 4; ++m) { const unsigned rl = rl0 + (unsigned)(ai * HALF + m * 16);
; #pragma unroll
;                 for (int bj = 0; bj < 2; ++bj) { const unsigned cl = cl0 + (unsigned)(bj * HALF);
;                     const u32x4 g = gv[m][bj];
;                     const f32x4 v0 = acc[ai][bj][m][0], v1 = acc[ai][bj][m][1];
;                     u32x4 w;
;                     w.x = cvt_pk_bf16(v0[0] * __builtin_amdgcn_rcpf(bf_lo(g.x)), v0[1] * __builtin_amdgcn_rcpf(bf_hi(g.x)));
;                     w.y = cvt_pk_bf16(v0[2] * __builtin_amdgcn_rcpf(bf_lo(g.y)), v0[3] * __builtin_amdgcn_rcpf(bf_hi(g.y)));
;                     w.z = cvt_pk_bf16(v1[0] * __builtin_amdgcn_rcpf(bf_lo(g.z)), v1[1] * __builtin_amdgcn_rcpf(bf_hi(g.z)));
;                     w.w = cvt_pk_bf16(v1[2] * __builtin_amdgcn_rcpf(bf_lo(g.w)), v1[3] * __builtin_amdgcn_rcpf(bf_hi(g.w)));
;                     *(u32x4*)(mb + (rl * 1024u + cl) * 2u) = w; } }
;             asm volatile("" : "+v"(rl0), "+v"(cl0) :: "memory"); }
	v_and_b32_e32 v101, 0xffff0000, v144
	v_rcp_f32_e32 v100, v100
	v_rcp_f32_e32 v101, v101
	v_add_u32_e32 v102, 0x10000, v96
	v_pk_mul_f32 v[92:93], v[92:93], v[100:101]
	s_nop 0
	v_cvt_pk_bf16_f32 v92, v92, v93
	v_lshlrev_b32_e32 v93, 16, v145
	v_rcp_f32_e32 v100, v93
	v_and_b32_e32 v93, 0xffff0000, v145
	v_rcp_f32_e32 v101, v93
	s_nop 0
	v_pk_mul_f32 v[94:95], v[94:95], v[100:101]
	s_nop 0
	v_cvt_pk_bf16_f32 v93, v94, v95
	v_lshlrev_b32_e32 v94, 16, v146
	v_and_b32_e32 v95, 0xffff0000, v146
	v_rcp_f32_e32 v94, v94
	v_rcp_f32_e32 v95, v95
	s_nop 0
	v_pk_mul_f32 v[88:89], v[88:89], v[94:95]
	s_nop 0
	v_cvt_pk_bf16_f32 v94, v88, v89
	v_lshlrev_b32_e32 v88, 16, v147
	v_and_b32_e32 v89, 0xffff0000, v147
	v_rcp_f32_e32 v88, v88
	v_rcp_f32_e32 v89, v89
	s_nop 0
	v_pk_mul_f32 v[88:89], v[90:91], v[88:89]
	s_nop 0
	v_cvt_pk_bf16_f32 v95, v88, v89
	v_lshlrev_b32_e32 v88, 16, v140
	v_and_b32_e32 v89, 0xffff0000, v140
	v_rcp_f32_e32 v88, v88
	v_rcp_f32_e32 v89, v89
	global_store_dwordx4 v102, v[92:95], s[60:61] sc1
	v_pk_mul_f32 v[84:85], v[84:85], v[88:89]
	s_nop 0
	v_cvt_pk_bf16_f32 v84, v84, v85
	v_lshlrev_b32_e32 v85, 16, v141
	v_rcp_f32_e32 v88, v85
	v_and_b32_e32 v85, 0xffff0000, v141
	v_rcp_f32_e32 v89, v85
	s_nop 0
	v_pk_mul_f32 v[86:87], v[86:87], v[88:89]
	s_nop 0
	v_cvt_pk_bf16_f32 v85, v86, v87
	v_lshlrev_b32_e32 v86, 16, v142
	v_and_b32_e32 v87, 0xffff0000, v142
	v_rcp_f32_e32 v86, v86
	v_rcp_f32_e32 v87, v87
	s_nop 0
	v_pk_mul_f32 v[80:81], v[80:81], v[86:87]
	s_nop 0
	v_cvt_pk_bf16_f32 v86, v80, v81
	v_lshlrev_b32_e32 v80, 16, v143
	v_and_b32_e32 v81, 0xffff0000, v143
	v_rcp_f32_e32 v80, v80
	v_rcp_f32_e32 v81, v81
	s_nop 0
	v_pk_mul_f32 v[80:81], v[82:83], v[80:81]
	s_nop 0
	v_cvt_pk_bf16_f32 v87, v80, v81
	v_add_u32_e32 v80, 0x10100, v96
	global_store_dwordx4 v80, v[84:87], s[60:61] sc1
	v_lshlrev_b32_e32 v80, 16, v136
	v_and_b32_e32 v81, 0xffff0000, v136
	v_rcp_f32_e32 v80, v80
	v_rcp_f32_e32 v81, v81
	v_add_u32_e32 v82, 0x18000, v96
	v_pk_mul_f32 v[76:77], v[76:77], v[80:81]
	s_nop 0
	v_cvt_pk_bf16_f32 v76, v76, v77
	v_lshlrev_b32_e32 v77, 16, v137
	v_rcp_f32_e32 v80, v77
	v_and_b32_e32 v77, 0xffff0000, v137
	v_rcp_f32_e32 v81, v77
	s_nop 0
	v_pk_mul_f32 v[78:79], v[78:79], v[80:81]
	s_nop 0
	v_cvt_pk_bf16_f32 v77, v78, v79
	v_lshlrev_b32_e32 v78, 16, v138
	v_and_b32_e32 v79, 0xffff0000, v138
	v_rcp_f32_e32 v78, v78
	v_rcp_f32_e32 v79, v79
	s_nop 0
	v_pk_mul_f32 v[72:73], v[72:73], v[78:79]
	s_nop 0
	v_cvt_pk_bf16_f32 v78, v72, v73
	v_lshlrev_b32_e32 v72, 16, v139
	v_and_b32_e32 v73, 0xffff0000, v139
	v_rcp_f32_e32 v72, v72
	v_rcp_f32_e32 v73, v73
	s_nop 0
	v_pk_mul_f32 v[72:73], v[74:75], v[72:73]
	s_nop 0
	v_cvt_pk_bf16_f32 v79, v72, v73
	v_lshlrev_b32_e32 v72, 16, v132
	v_and_b32_e32 v73, 0xffff0000, v132
	v_rcp_f32_e32 v72, v72
	v_rcp_f32_e32 v73, v73
	global_store_dwordx4 v82, v[76:79], s[60:61] sc1
	v_pk_mul_f32 v[68:69], v[68:69], v[72:73]
	s_nop 0
	v_cvt_pk_bf16_f32 v68, v68, v69
	v_lshlrev_b32_e32 v69, 16, v133
	v_rcp_f32_e32 v72, v69
	v_and_b32_e32 v69, 0xffff0000, v133
	v_rcp_f32_e32 v73, v69
	s_nop 0
	v_pk_mul_f32 v[70:71], v[70:71], v[72:73]
	s_nop 0
	v_cvt_pk_bf16_f32 v69, v70, v71
	v_lshlrev_b32_e32 v70, 16, v134
	v_and_b32_e32 v71, 0xffff0000, v134
	v_rcp_f32_e32 v70, v70
	v_rcp_f32_e32 v71, v71
	s_nop 0
	v_pk_mul_f32 v[64:65], v[64:65], v[70:71]
	s_nop 0
	v_cvt_pk_bf16_f32 v70, v64, v65
	v_lshlrev_b32_e32 v64, 16, v135
	v_and_b32_e32 v65, 0xffff0000, v135
	v_rcp_f32_e32 v64, v64
	v_rcp_f32_e32 v65, v65
	s_nop 0
	v_pk_mul_f32 v[64:65], v[66:67], v[64:65]
	s_nop 0
	v_cvt_pk_bf16_f32 v71, v64, v65
	v_add_u32_e32 v64, 0x18100, v96
	global_store_dwordx4 v64, v[68:71], s[60:61] sc1
	global_load_dwordx4 v[90:93], v[156:157], off
	global_load_dwordx4 v[100:103], v[156:157], off offset:1024
	global_load_dwordx4 v[84:87], v[156:157], off offset:2048
	global_load_dwordx4 v[80:83], v[156:157], off offset:3072
	v_add_co_u32_e32 v64, vcc, s6, v98
	v_lshlrev_b32_e32 v88, 11, v158
	s_nop 0
	v_addc_co_u32_e32 v65, vcc, 0, v99, vcc
	global_load_dwordx4 v[76:79], v[64:65], off
	global_load_dwordx4 v[72:75], v[64:65], off offset:1024
	global_load_dwordx4 v[68:71], v[64:65], off offset:2048
	s_nop 0
	global_load_dwordx4 v[64:67], v[64:65], off offset:3072
	v_lshl_add_u32 v88, v159, 1, v88
	v_add_u32_e32 v89, 0x40000, v88
	s_and_b64 vcc, exec, s[38:39]
	s_waitcnt vmcnt(0)
; __device__ __forceinline__ float bf_lo(unsigned w) { return __uint_as_float(w << 16); }
; __device__ __forceinline__ float bf_hi(unsigned w) { return __uint_as_float(w & 0xffff0000u); }
; __device__ __forceinline__ unsigned cvt_pk_bf16(float lo, float hi) { f32x2_t v = {lo, hi}; bf16x2_t b = __builtin_convertvector(v, bf16x2_t); return __builtin_bit_cast(unsigned, b); }
;     __device__ __forceinline__ void operator()(const f32x4 (&acc)[2][2][4][2], const Unit& u, int wr, int wc, int fr, int fq) const {
;     ...
;         for (int ai = 0; ai < 2; ++ai) {
;             u32x4 gv[4][2];
; #pragma unroll
;             for (int m = 0; m < 4; ++m)
; #pragma unroll
;                 for (int bj = 0; bj < 2; ++bj) gv[m][bj] = *(const u32x4*)(g_b + ((ai * 4 + m) * 2 + bj) * 1024);
; #pragma unroll
;             for (int m = 0; m < 4; ++m) { const unsigned rl = rl0 + (unsigned)(ai * HALF + m * 16);
; #pragma unroll
;                 for (int bj = 0; bj < 2; ++bj) { const unsigned cl = cl0 + (unsigned)(bj * HALF);
;                     const u32x4 g = gv[m][bj];
;                     const f32x4 v0 = acc[ai][bj][m][0], v1 = acc[ai][bj][m][1];
;                     u32x4 w;
;                     w.x = cvt_pk_bf16(v0[0] * __builtin_amdgcn_rcpf(bf_lo(g.x)), v0[1] * __builtin_amdgcn_rcpf(bf_hi(g.x)));
;                     w.y = cvt_pk_bf16(v0[2] * __builtin_amdgcn_rcpf(bf_lo(g.y)), v0[3] * __builtin_amdgcn_rcpf(bf_hi(g.y)));
;                     w.z = cvt_pk_bf16(v1[0] * __builtin_amdgcn_rcpf(bf_lo(g.z)), v1[1] * __builtin_amdgcn_rcpf(bf_hi(g.z)));
;                     w.w = cvt_pk_bf16(v1[2] * __builtin_amdgcn_rcpf(bf_lo(g.w)), v1[3] * __builtin_amdgcn_rcpf(bf_hi(g.w)));
;                     *(u32x4*)(mb + (rl * 1024u + cl) * 2u) = w; } }
;             asm volatile("" : "+v"(rl0), "+v"(cl0) :: "memory"); }
	v_lshlrev_b32_e32 v94, 16, v90
	v_and_b32_e32 v90, 0xffff0000, v90
	v_rcp_f32_e32 v94, v94
	v_rcp_f32_e32 v95, v90
	s_nop 0
	v_pk_mul_f32 v[60:61], v[60:61], v[94:95]
	s_nop 0
	v_cvt_pk_bf16_f32 v60, v60, v61
	v_lshlrev_b32_e32 v61, 16, v91
	v_rcp_f32_e32 v90, v61
	v_and_b32_e32 v61, 0xffff0000, v91
	v_rcp_f32_e32 v91, v61
	s_nop 0
	v_pk_mul_f32 v[62:63], v[62:63], v[90:91]
	s_nop 0
	v_cvt_pk_bf16_f32 v61, v62, v63
	v_lshlrev_b32_e32 v62, 16, v92
	v_and_b32_e32 v63, 0xffff0000, v92
	v_rcp_f32_e32 v62, v62
	v_rcp_f32_e32 v63, v63
	s_nop 0
	v_pk_mul_f32 v[56:57], v[56:57], v[62:63]
	s_nop 0
	v_cvt_pk_bf16_f32 v62, v56, v57
	v_lshlrev_b32_e32 v56, 16, v93
	v_and_b32_e32 v57, 0xffff0000, v93
	v_rcp_f32_e32 v56, v56
	v_rcp_f32_e32 v57, v57
	s_nop 0
	v_pk_mul_f32 v[56:57], v[58:59], v[56:57]
	s_nop 0
	v_cvt_pk_bf16_f32 v63, v56, v57
	v_lshlrev_b32_e32 v56, 16, v100
	v_and_b32_e32 v57, 0xffff0000, v100
	v_rcp_f32_e32 v56, v56
	v_rcp_f32_e32 v57, v57
	global_store_dwordx4 v89, v[60:63], s[60:61] sc1
	v_pk_mul_f32 v[52:53], v[52:53], v[56:57]
	s_nop 0
	v_cvt_pk_bf16_f32 v52, v52, v53
	v_lshlrev_b32_e32 v53, 16, v101
	v_rcp_f32_e32 v56, v53
	v_and_b32_e32 v53, 0xffff0000, v101
	v_rcp_f32_e32 v57, v53
	s_nop 0
	v_pk_mul_f32 v[54:55], v[54:55], v[56:57]
	s_nop 0
	v_cvt_pk_bf16_f32 v53, v54, v55
	v_lshlrev_b32_e32 v54, 16, v102
	v_and_b32_e32 v55, 0xffff0000, v102
	v_rcp_f32_e32 v54, v54
	v_rcp_f32_e32 v55, v55
	s_nop 0
	v_pk_mul_f32 v[48:49], v[48:49], v[54:55]
	s_nop 0
	v_cvt_pk_bf16_f32 v54, v48, v49
	v_lshlrev_b32_e32 v48, 16, v103
	v_and_b32_e32 v49, 0xffff0000, v103
	v_rcp_f32_e32 v48, v48
	v_rcp_f32_e32 v49, v49
	s_nop 0
	v_pk_mul_f32 v[48:49], v[50:51], v[48:49]
	s_nop 0
	v_cvt_pk_bf16_f32 v55, v48, v49
	v_add_u32_e32 v48, 0x40100, v88
	global_store_dwordx4 v48, v[52:55], s[60:61] sc1
	v_lshlrev_b32_e32 v48, 16, v84
	v_and_b32_e32 v49, 0xffff0000, v84
	v_rcp_f32_e32 v48, v48
	v_rcp_f32_e32 v49, v49
	v_add_u32_e32 v50, 0x48000, v88
	v_pk_mul_f32 v[44:45], v[44:45], v[48:49]
	s_nop 0
	v_cvt_pk_bf16_f32 v44, v44, v45
	v_lshlrev_b32_e32 v45, 16, v85
	v_rcp_f32_e32 v48, v45
	v_and_b32_e32 v45, 0xffff0000, v85
	v_rcp_f32_e32 v49, v45
	s_nop 0
	v_pk_mul_f32 v[46:47], v[46:47], v[48:49]
	s_nop 0
	v_cvt_pk_bf16_f32 v45, v46, v47
	v_lshlrev_b32_e32 v46, 16, v86
	v_and_b32_e32 v47, 0xffff0000, v86
	v_rcp_f32_e32 v46, v46
	v_rcp_f32_e32 v47, v47
	s_nop 0
	v_pk_mul_f32 v[40:41], v[40:41], v[46:47]
	s_nop 0
	v_cvt_pk_bf16_f32 v46, v40, v41
	v_lshlrev_b32_e32 v40, 16, v87
	v_and_b32_e32 v41, 0xffff0000, v87
	v_rcp_f32_e32 v40, v40
	v_rcp_f32_e32 v41, v41
	s_nop 0
	v_pk_mul_f32 v[40:41], v[42:43], v[40:41]
	s_nop 0
	v_cvt_pk_bf16_f32 v47, v40, v41
	v_lshlrev_b32_e32 v40, 16, v80
	v_and_b32_e32 v41, 0xffff0000, v80
	v_rcp_f32_e32 v40, v40
	v_rcp_f32_e32 v41, v41
	global_store_dwordx4 v50, v[44:47], s[60:61] sc1
	v_pk_mul_f32 v[36:37], v[36:37], v[40:41]
	s_nop 0
	v_cvt_pk_bf16_f32 v36, v36, v37
	v_lshlrev_b32_e32 v37, 16, v81
	v_rcp_f32_e32 v40, v37
	v_and_b32_e32 v37, 0xffff0000, v81
	v_rcp_f32_e32 v41, v37
	s_nop 0
	v_pk_mul_f32 v[38:39], v[38:39], v[40:41]
	s_nop 0
	v_cvt_pk_bf16_f32 v37, v38, v39
	v_lshlrev_b32_e32 v38, 16, v82
	v_and_b32_e32 v39, 0xffff0000, v82
	v_rcp_f32_e32 v38, v38
	v_rcp_f32_e32 v39, v39
	s_nop 0
	v_pk_mul_f32 v[32:33], v[32:33], v[38:39]
	s_nop 0
	v_cvt_pk_bf16_f32 v38, v32, v33
	v_lshlrev_b32_e32 v32, 16, v83
	v_and_b32_e32 v33, 0xffff0000, v83
	v_rcp_f32_e32 v32, v32
	v_rcp_f32_e32 v33, v33
	s_nop 0
	v_pk_mul_f32 v[32:33], v[34:35], v[32:33]
	s_nop 0
	v_cvt_pk_bf16_f32 v39, v32, v33
	v_add_u32_e32 v32, 0x48100, v88
	global_store_dwordx4 v32, v[36:39], s[60:61] sc1
	v_lshlrev_b32_e32 v32, 16, v76
; __device__ __forceinline__ float bf_lo(unsigned w) { return __uint_as_float(w << 16); }
;     __device__ __forceinline__ void operator()(const f32x4 (&acc)[2][2][4][2], const Unit& u, int wr, int wc, int fr, int fq) const {
;     ...
;         for (int ai = 0; ai < 2; ++ai) {
;             u32x4 gv[4][2];
; #pragma unroll
;             for (int m = 0; m < 4; ++m)
; #pragma unroll
;                 for (int bj = 0; bj < 2; ++bj) gv[m][bj] = *(const u32x4*)(g_b + ((ai * 4 + m) * 2 + bj) * 1024);
; #pragma unroll
;             for (int m = 0; m < 4; ++m) { const unsigned rl = rl0 + (unsigned)(ai * HALF + m * 16);
; #pragma unroll
;                 for (int bj = 0; bj < 2; ++bj) { const unsigned cl = cl0 + (unsigned)(bj * HALF);
;                     const u32x4 g = gv[m][bj];
;                     const f32x4 v0 = acc[ai][bj][m][0], v1 = acc[ai][bj][m][1];
;                     u32x4 w;
;                     w.x = cvt_pk_bf16(v0[0] * __builtin_amdgcn_rcpf(bf_lo(g.x)), v0[1] * __builtin_amdgcn_rcpf(bf_hi(g.x)));
;                     w.y = cvt_pk_bf16(v0[2] * __builtin_amdgcn_rcpf(bf_lo(g.y)), v0[3] * __builtin_amdgcn_rcpf(bf_hi(g.y)));
;                     w.z = cvt_pk_bf16(v1[0] * __builtin_amdgcn_rcpf(bf_lo(g.z)), v1[1] * __builtin_amdgcn_rcpf(bf_hi(g.z)));
;                     w.w = cvt_pk_bf16(v1[2] * __builtin_amdgcn_rcpf(bf_lo(g.w)), v1[3] * __builtin_amdgcn_rcpf(bf_hi(g.w)));
;                     *(u32x4*)(mb + (rl * 1024u + cl) * 2u) = w; } }
;             asm volatile("" : "+v"(rl0), "+v"(cl0) :: "memory"); }
; template <class Epi, class Sched, bool ALIGN_EPI = false, bool SP2 = false>
; __device__ __forceinline__ void gemm_phase(PG8_LAS unsigned char* lds, const Gemm g, const Sched& S, const Epi& E) {
;     ...
;         if constexpr (ALIGN_EPI) { if (wr == 0) PG8_BAR; }
;         if constexpr (!Epi::AFTER_DRAIN) { E(acc, cur, wr, wc, fr, fq); S.done(cur); }
;         if (!has_next) break;
;         if constexpr (Epi::ACC_INIT) E.acc_init(ini, nxt);
; #pragma unroll
;         for (int a = 0; a < 2; ++a)
; #pragma unroll
;             for (int b = 0; b < 2; ++b)
; #pragma unroll
;                 for (int m = 0; m < 4; ++m)
; #pragma unroll
;                     for (int n = 0; n < 2; ++n) acc[a][b][m][n] = ini[b][n];
;         cur = nxt; cA = nA; cB = nB; ++ui;
;         if constexpr (ALIGN_EPI) { if (wr == 1) PG8_BAR; }
	v_and_b32_e32 v33, 0xffff0000, v76
	v_rcp_f32_e32 v32, v32
	v_rcp_f32_e32 v33, v33
	v_add_u32_e32 v34, 0x50000, v88
	v_pk_mul_f32 v[28:29], v[28:29], v[32:33]
	s_nop 0
	v_cvt_pk_bf16_f32 v28, v28, v29
	v_lshlrev_b32_e32 v29, 16, v77
	v_rcp_f32_e32 v32, v29
	v_and_b32_e32 v29, 0xffff0000, v77
	v_rcp_f32_e32 v33, v29
	s_nop 0
	v_pk_mul_f32 v[30:31], v[30:31], v[32:33]
	s_nop 0
	v_cvt_pk_bf16_f32 v29, v30, v31
	v_lshlrev_b32_e32 v30, 16, v78
	v_and_b32_e32 v31, 0xffff0000, v78
	v_rcp_f32_e32 v30, v30
	v_rcp_f32_e32 v31, v31
	s_nop 0
	v_pk_mul_f32 v[24:25], v[24:25], v[30:31]
	s_nop 0
	v_cvt_pk_bf16_f32 v30, v24, v25
	v_lshlrev_b32_e32 v24, 16, v79
	v_and_b32_e32 v25, 0xffff0000, v79
	v_rcp_f32_e32 v24, v24
	v_rcp_f32_e32 v25, v25
	s_nop 0
	v_pk_mul_f32 v[24:25], v[26:27], v[24:25]
	s_nop 0
	v_cvt_pk_bf16_f32 v31, v24, v25
	v_lshlrev_b32_e32 v24, 16, v72
	v_and_b32_e32 v25, 0xffff0000, v72
	v_rcp_f32_e32 v24, v24
	v_rcp_f32_e32 v25, v25
	global_store_dwordx4 v34, v[28:31], s[60:61] sc1
	v_pk_mul_f32 v[20:21], v[20:21], v[24:25]
	s_nop 0
	v_cvt_pk_bf16_f32 v20, v20, v21
	v_lshlrev_b32_e32 v21, 16, v73
	v_rcp_f32_e32 v24, v21
	v_and_b32_e32 v21, 0xffff0000, v73
	v_rcp_f32_e32 v25, v21
	s_nop 0
	v_pk_mul_f32 v[22:23], v[22:23], v[24:25]
	s_nop 0
	v_cvt_pk_bf16_f32 v21, v22, v23
	v_lshlrev_b32_e32 v22, 16, v74
	v_and_b32_e32 v23, 0xffff0000, v74
	v_rcp_f32_e32 v22, v22
	v_rcp_f32_e32 v23, v23
	s_nop 0
	v_pk_mul_f32 v[12:13], v[12:13], v[22:23]
	s_nop 0
	v_cvt_pk_bf16_f32 v22, v12, v13
	v_lshlrev_b32_e32 v12, 16, v75
	v_and_b32_e32 v13, 0xffff0000, v75
	v_rcp_f32_e32 v12, v12
	v_rcp_f32_e32 v13, v13
	s_nop 0
	v_pk_mul_f32 v[12:13], v[14:15], v[12:13]
	s_nop 0
	v_cvt_pk_bf16_f32 v23, v12, v13
	v_add_u32_e32 v12, 0x50100, v88
	global_store_dwordx4 v12, v[20:23], s[60:61] sc1
	v_lshlrev_b32_e32 v12, 16, v68
	v_and_b32_e32 v13, 0xffff0000, v68
	v_rcp_f32_e32 v12, v12
	v_rcp_f32_e32 v13, v13
	v_add_u32_e32 v20, 0x58000, v88
	v_pk_mul_f32 v[12:13], v[16:17], v[12:13]
	s_nop 0
	v_cvt_pk_bf16_f32 v12, v12, v13
	v_lshlrev_b32_e32 v13, 16, v69
	v_rcp_f32_e32 v14, v13
	v_and_b32_e32 v13, 0xffff0000, v69
	v_rcp_f32_e32 v15, v13
	s_nop 0
	v_pk_mul_f32 v[14:15], v[18:19], v[14:15]
	s_nop 0
	v_cvt_pk_bf16_f32 v13, v14, v15
	v_lshlrev_b32_e32 v14, 16, v70
	v_and_b32_e32 v15, 0xffff0000, v70
	v_rcp_f32_e32 v14, v14
	v_rcp_f32_e32 v15, v15
	s_nop 0
	v_pk_mul_f32 v[8:9], v[8:9], v[14:15]
	s_nop 0
	v_cvt_pk_bf16_f32 v14, v8, v9
	v_lshlrev_b32_e32 v8, 16, v71
	v_and_b32_e32 v9, 0xffff0000, v71
	v_rcp_f32_e32 v8, v8
	v_rcp_f32_e32 v9, v9
	s_nop 0
	v_pk_mul_f32 v[8:9], v[10:11], v[8:9]
	s_nop 0
	v_cvt_pk_bf16_f32 v15, v8, v9
	v_lshlrev_b32_e32 v8, 16, v64
	v_and_b32_e32 v9, 0xffff0000, v64
	v_rcp_f32_e32 v8, v8
	v_rcp_f32_e32 v9, v9
	global_store_dwordx4 v20, v[12:15], s[60:61] sc1
	v_pk_mul_f32 v[4:5], v[4:5], v[8:9]
	s_nop 0
	v_cvt_pk_bf16_f32 v4, v4, v5
	v_lshlrev_b32_e32 v5, 16, v65
	v_rcp_f32_e32 v8, v5
	v_and_b32_e32 v5, 0xffff0000, v65
	v_rcp_f32_e32 v9, v5
	s_nop 0
	v_pk_mul_f32 v[6:7], v[6:7], v[8:9]
	s_nop 0
	v_cvt_pk_bf16_f32 v5, v6, v7
	v_lshlrev_b32_e32 v6, 16, v66
	v_and_b32_e32 v7, 0xffff0000, v66
	v_rcp_f32_e32 v6, v6
	v_rcp_f32_e32 v7, v7
	s_nop 0
	v_pk_mul_f32 v[0:1], v[0:1], v[6:7]
	s_nop 0
	v_cvt_pk_bf16_f32 v6, v0, v1
	v_lshlrev_b32_e32 v0, 16, v67
	v_and_b32_e32 v1, 0xffff0000, v67
	v_rcp_f32_e32 v0, v0
	v_rcp_f32_e32 v1, v1
	s_nop 0
	v_pk_mul_f32 v[0:1], v[2:3], v[0:1]
	s_nop 0
	v_cvt_pk_bf16_f32 v7, v0, v1
	v_add_u32_e32 v0, 0x58100, v88
	global_store_dwordx4 v0, v[4:7], s[60:61] sc1
	s_mov_b64 s[60:61], -1
	s_cbranch_vccnz .LBB0_35
	s_andn2_b64 vcc, exec, s[46:47]
	s_cbranch_vccnz .LBB0_34
	s_barrier
	s_branch .LBB0_34

; __device__ __forceinline__ float sigm(float v) { return __builtin_amdgcn_rcpf(1.0f + __builtin_amdgcn_exp2f(-LOG2E * v)); }
; __device__ __forceinline__ float bf_lo(unsigned w) { return __uint_as_float(w << 16); }
; __device__ __forceinline__ float silu_f(float v) { return v * __builtin_amdgcn_rcpf(1.0f + __builtin_amdgcn_exp2f(-1.4426950408889634f * v)); }
; __device__ __forceinline__ float bf_hi(unsigned w) { return __uint_as_float(w & 0xffff0000u); }
; __device__ __forceinline__ unsigned cvt_pk_bf16(float lo, float hi) { f32x2_t v = {lo, hi}; bf16x2_t b = __builtin_convertvector(v, bf16x2_t); return __builtin_bit_cast(unsigned, b); }
; #define EPI_LANE() int t__ = threadIdx.x; asm volatile("" : "+v"(t__)); const int wid__ = __builtin_amdgcn_readfirstlane(t__ >> 6); wr = wid__ >> 2; wc = wid__ & 3; fr = t__ & 15; fq = (t__ & 63) >> 4
;     __device__ __forceinline__ void operator()(const f32x4 (&acc)[2][2][4][2], const Unit& u, int wr, int wc, int fr, int fq) const {
;         EPI_LANE();
;         const char* ygb = (const char*)(YG + (size_t)u.pm * BM * 256); const char* sgb = (const char*)(ZC + (size_t)u.pm * BM * 512 + 256); char* yb = (char*)(Y + (size_t)u.pm * BM * 1024 + 768);
;         unsigned rl0 = (unsigned)(wr * 64 + fr), col0 = (unsigned)(wc * 32 + 8 * fq); asm volatile("" : "+v"(rl0), "+v"(col0));
; #pragma unroll
;         for (int bj = 0; bj < 2; ++bj) { const unsigned col = col0 + bj * HALF;
; #pragma unroll
;             for (int ai = 0; ai < 2; ++ai) {
;                 u32x4 ygv[4], sgv[4];
; #pragma unroll
;                 for (int m = 0; m < 4; ++m) { const unsigned rl = rl0 + (unsigned)(ai * HALF + m * 16);
;                     ygv[m] = *(const u32x4*)(ygb + (rl * 256u + col) * 2u); sgv[m] = *(const u32x4*)(sgb + (rl * 512u + col) * 2u); }
;     ...
;                     w.x = cvt_pk_bf16(bf_lo(yg.x) * sigm(v0[0]) * silu_f(bf_lo(sg.x)), bf_hi(yg.x) * sigm(v0[1]) * silu_f(bf_hi(sg.x)));
;                     w.y = cvt_pk_bf16(bf_lo(yg.y) * sigm(v0[2]) * silu_f(bf_lo(sg.y)), bf_hi(yg.y) * sigm(v0[3]) * silu_f(bf_hi(sg.y)));
;                     w.z = cvt_pk_bf16(bf_lo(yg.z) * sigm(v1[0]) * silu_f(bf_lo(sg.z)), bf_hi(yg.z) * sigm(v1[1]) * silu_f(bf_hi(sg.z)));
;                     w.w = cvt_pk_bf16(bf_lo(yg.w) * sigm(v1[2]) * silu_f(bf_lo(sg.w)), bf_hi(yg.w) * sigm(v1[3]) * silu_f(bf_hi(sg.w)));
.LBB0_82:
	v_readlane_b32 s20, v253, 0
	v_readlane_b32 s21, v253, 1
	s_load_dwordx4 s[76:79], s[20:21], 0xa8
	s_ashr_i32 s61, s60, 31
	s_lshl_b64 s[16:17], s[60:61], 17
	s_add_u32 s62, s90, s16
	s_addc_u32 s63, s91, s17
	s_lshl_b64 s[16:17], s[60:61], 18
	s_waitcnt lgkmcnt(0)
	s_add_u32 s6, s78, s16
	s_addc_u32 s12, s79, s17
	s_add_u32 s64, s6, 0xc000200
	v_mov_b32_e32 v106, v212
	s_addc_u32 s65, s12, 0
	s_lshl_b64 s[16:17], s[60:61], 19
	s_add_u32 s60, s82, s16
	v_readfirstlane_b32 s0, v106
	s_addc_u32 s61, s83, s17
	s_ashr_i32 s6, s0, 2
	s_andn2_b32 s6, s6, 63
	s_lshr_b32 s0, s0, 1
	v_and_or_b32 v174, v106, 15, s6
	s_and_b32 s0, s0, 0x60
	v_lshrrev_b32_e32 v106, 1, v106
	v_and_or_b32 v175, v106, 24, s0
	v_mul_f32_e32 v158, 0xbfb8aa3b, v158
	v_lshlrev_b32_e32 v176, 1, v175
	v_lshlrev_b32_e32 v106, 9, v174
	v_add_u32_e32 v107, v106, v176
	v_add_u32_e32 v177, v107, v106
	global_load_dwordx4 v[150:153], v107, s[62:63]
	global_load_dwordx4 v[154:157], v177, s[64:65]
	v_add_u32_e32 v107, 0x2000, v106
	v_add_u32_e32 v108, v107, v176
	v_add_u32_e32 v107, v108, v107
	global_load_dwordx4 v[138:141], v108, s[62:63]
	global_load_dwordx4 v[142:145], v107, s[64:65]
	v_mul_f32_e32 v159, 0xbfb8aa3b, v159
	v_exp_f32_e32 v158, v158
	v_exp_f32_e32 v159, v159
	v_mul_f32_e32 v146, 0xbfb8aa3b, v146
	v_mul_f32_e32 v147, 0xbfb8aa3b, v147
	v_add_f32_e32 v158, 1.0, v158
	v_add_f32_e32 v159, 1.0, v159
	v_rcp_f32_e32 v158, v158
	v_rcp_f32_e32 v159, v159
	v_exp_f32_e32 v146, v146
	v_exp_f32_e32 v147, v147
	v_add_u32_e32 v107, 0x4000, v106
	v_add_u32_e32 v108, v107, v176
	v_add_f32_e32 v146, 1.0, v146
	v_add_f32_e32 v147, 1.0, v147
	v_rcp_f32_e32 v146, v146
	v_rcp_f32_e32 v147, v147
	v_add_u32_e32 v107, v108, v107
	global_load_dwordx4 v[122:125], v108, s[62:63]
	global_load_dwordx4 v[126:129], v107, s[64:65]
	v_add_u32_e32 v110, 0x6000, v106
	v_add_u32_e32 v111, v110, v176
	v_add_u32_e32 v110, v111, v110
	global_load_dwordx4 v[106:109], v111, s[62:63]
	v_mul_f32_e32 v134, 0xbfb8aa3b, v134
	global_load_dwordx4 v[110:113], v110, s[64:65]
	v_mul_f32_e32 v135, 0xbfb8aa3b, v135
	v_exp_f32_e32 v134, v134
	v_exp_f32_e32 v135, v135
	v_mul_f32_e32 v130, 0xbfb8aa3b, v130
	v_mul_f32_e32 v131, 0xbfb8aa3b, v131
	v_add_f32_e32 v134, 1.0, v134
	v_add_f32_e32 v135, 1.0, v135
	v_rcp_f32_e32 v134, v134
	v_rcp_f32_e32 v135, v135
	v_exp_f32_e32 v130, v130
	v_exp_f32_e32 v131, v131
	v_mul_f32_e32 v118, 0xbfb8aa3b, v118
	v_mul_f32_e32 v119, 0xbfb8aa3b, v119
	v_add_f32_e32 v130, 1.0, v130
	v_add_f32_e32 v131, 1.0, v131
	v_rcp_f32_e32 v130, v130
	v_rcp_f32_e32 v131, v131
	v_exp_f32_e32 v118, v118
	v_exp_f32_e32 v119, v119
	v_mul_f32_e32 v114, 0xbfb8aa3b, v114
	v_mul_f32_e32 v115, 0xbfb8aa3b, v115
	v_add_f32_e32 v118, 1.0, v118
	v_add_f32_e32 v119, 1.0, v119
	v_rcp_f32_e32 v118, v118
	v_rcp_f32_e32 v119, v119
	v_exp_f32_e32 v114, v114
	v_exp_f32_e32 v115, v115
	v_mul_f32_e32 v102, 0xbfb8aa3b, v102
	v_mul_f32_e32 v103, 0xbfb8aa3b, v103
	v_add_f32_e32 v114, 1.0, v114
	v_add_f32_e32 v115, 1.0, v115
	v_rcp_f32_e32 v114, v114
	v_rcp_f32_e32 v115, v115
	v_exp_f32_e32 v102, v102
	v_exp_f32_e32 v103, v103
	v_mul_f32_e32 v98, 0xbfb8aa3b, v98
	v_mul_f32_e32 v99, 0xbfb8aa3b, v99
	v_add_f32_e32 v102, 1.0, v102
	v_add_f32_e32 v103, 1.0, v103
	v_rcp_f32_e32 v102, v102
	v_rcp_f32_e32 v103, v103
	v_exp_f32_e32 v98, v98
	v_exp_f32_e32 v99, v99
	v_mul_f32_e32 v92, 0xbfb8aa3b, v92
	v_mul_f32_e32 v93, 0xbfb8aa3b, v93
	v_add_f32_e32 v98, 1.0, v98
	v_add_f32_e32 v99, 1.0, v99
	s_waitcnt vmcnt(0)
	v_lshlrev_b32_e32 v182, 16, v150
	v_lshlrev_b32_e32 v178, 16, v154
	v_and_b32_e32 v179, 0xffff0000, v154
	v_mul_f32_e32 v154, 0xbfb8aa3b, v178
	v_and_b32_e32 v183, 0xffff0000, v150
	v_mul_f32_e32 v150, 0xbfb8aa3b, v179
	v_exp_f32_e32 v154, v154
	v_exp_f32_e32 v150, v150
	v_pk_mul_f32 v[158:159], v[158:159], v[182:183]
	v_rcp_f32_e32 v98, v98
	v_add_f32_e32 v154, 1.0, v154
	v_add_f32_e32 v150, 1.0, v150
	v_rcp_f32_e32 v180, v154
	v_rcp_f32_e32 v181, v150
	v_mul_f32_e32 v154, 0xbfb8aa3b, v160
	v_exp_f32_e32 v154, v154
	v_rcp_f32_e32 v99, v99
	v_pk_mul_f32 v[178:179], v[180:181], v[178:179]
	v_exp_f32_e32 v92, v92
	v_pk_mul_f32 v[158:159], v[158:159], v[178:179]
	v_add_f32_e32 v154, 1.0, v154
	v_cvt_pk_bf16_f32 v150, v158, v159
	v_rcp_f32_e32 v158, v154
	v_mul_f32_e32 v154, 0xbfb8aa3b, v161
	v_exp_f32_e32 v154, v154
	v_lshlrev_b32_e32 v178, 16, v151
	v_and_b32_e32 v179, 0xffff0000, v151
	v_exp_f32_e32 v93, v93
	v_add_f32_e32 v154, 1.0, v154
	v_rcp_f32_e32 v159, v154
	v_lshlrev_b32_e32 v154, 16, v155
	v_and_b32_e32 v155, 0xffff0000, v155
	v_mul_f32_e32 v160, 0xbfb8aa3b, v154
	v_mul_f32_e32 v151, 0xbfb8aa3b, v155
	v_exp_f32_e32 v160, v160
	v_exp_f32_e32 v151, v151
	v_pk_mul_f32 v[158:159], v[158:159], v[178:179]
	v_add_f32_e32 v92, 1.0, v92
	v_add_f32_e32 v160, 1.0, v160
	v_add_f32_e32 v151, 1.0, v151
	v_rcp_f32_e32 v160, v160
	v_rcp_f32_e32 v161, v151
	v_add_f32_e32 v93, 1.0, v93
	v_rcp_f32_e32 v92, v92
	v_rcp_f32_e32 v93, v93
	v_pk_mul_f32 v[154:155], v[160:161], v[154:155]
	v_lshlrev_b32_e32 v160, 16, v152
	v_pk_mul_f32 v[154:155], v[158:159], v[154:155]
	v_and_b32_e32 v161, 0xffff0000, v152
	v_cvt_pk_bf16_f32 v151, v154, v155
	v_lshlrev_b32_e32 v154, 16, v156
	v_and_b32_e32 v155, 0xffff0000, v156
	v_mul_f32_e32 v156, 0xbfb8aa3b, v154
	v_mul_f32_e32 v152, 0xbfb8aa3b, v155
	v_exp_f32_e32 v156, v156
	v_exp_f32_e32 v152, v152
	v_pk_mul_f32 v[146:147], v[146:147], v[160:161]
	v_mul_f32_e32 v88, 0xbfb8aa3b, v88
	v_add_f32_e32 v156, 1.0, v156
	v_add_f32_e32 v152, 1.0, v152
	v_rcp_f32_e32 v158, v156
	v_rcp_f32_e32 v159, v152
	v_lshlrev_b32_e32 v156, 16, v153
	v_mul_f32_e32 v89, 0xbfb8aa3b, v89
	v_exp_f32_e32 v88, v88
; __device__ __forceinline__ float sigm(float v) { return __builtin_amdgcn_rcpf(1.0f + __builtin_amdgcn_exp2f(-LOG2E * v)); }
; __device__ __forceinline__ float bf_lo(unsigned w) { return __uint_as_float(w << 16); }
; __device__ __forceinline__ float silu_f(float v) { return v * __builtin_amdgcn_rcpf(1.0f + __builtin_amdgcn_exp2f(-1.4426950408889634f * v)); }
; __device__ __forceinline__ float bf_hi(unsigned w) { return __uint_as_float(w & 0xffff0000u); }
; __device__ __forceinline__ unsigned cvt_pk_bf16(float lo, float hi) { f32x2_t v = {lo, hi}; bf16x2_t b = __builtin_convertvector(v, bf16x2_t); return __builtin_bit_cast(unsigned, b); }
;     __device__ __forceinline__ void operator()(const f32x4 (&acc)[2][2][4][2], const Unit& u, int wr, int wc, int fr, int fq) const {
;     ...
;                 for (int m = 0; m < 4; ++m) { const unsigned rl = rl0 + (unsigned)(ai * HALF + m * 16);
;                     ygv[m] = *(const u32x4*)(ygb + (rl * 256u + col) * 2u); sgv[m] = *(const u32x4*)(sgb + (rl * 512u + col) * 2u); }
; #pragma unroll
;                 for (int m = 0; m < 4; ++m) { const unsigned rl = rl0 + (unsigned)(ai * HALF + m * 16);
;                     const u32x4 yg = ygv[m], sg = sgv[m];
;                     const f32x4 v0 = acc[ai][bj][m][0], v1 = acc[ai][bj][m][1];
;                     u32x4 w;
;                     w.x = cvt_pk_bf16(bf_lo(yg.x) * sigm(v0[0]) * silu_f(bf_lo(sg.x)), bf_hi(yg.x) * sigm(v0[1]) * silu_f(bf_hi(sg.x)));
;                     w.y = cvt_pk_bf16(bf_lo(yg.y) * sigm(v0[2]) * silu_f(bf_lo(sg.y)), bf_hi(yg.y) * sigm(v0[3]) * silu_f(bf_hi(sg.y)));
;                     w.z = cvt_pk_bf16(bf_lo(yg.z) * sigm(v1[0]) * silu_f(bf_lo(sg.z)), bf_hi(yg.z) * sigm(v1[1]) * silu_f(bf_hi(sg.z)));
;                     w.w = cvt_pk_bf16(bf_lo(yg.w) * sigm(v1[2]) * silu_f(bf_lo(sg.w)), bf_hi(yg.w) * sigm(v1[3]) * silu_f(bf_hi(sg.w)));
;                     *(u32x4*)(yb + (rl * 1024u + col) * 2u) = w; }
	v_pk_mul_f32 v[154:155], v[158:159], v[154:155]
	v_exp_f32_e32 v89, v89
	v_pk_mul_f32 v[146:147], v[146:147], v[154:155]
	v_add_f32_e32 v88, 1.0, v88
	v_cvt_pk_bf16_f32 v152, v146, v147
	v_mul_f32_e32 v146, 0xbfb8aa3b, v148
	v_mul_f32_e32 v147, 0xbfb8aa3b, v149
	v_lshlrev_b32_e32 v148, 16, v157
	v_and_b32_e32 v149, 0xffff0000, v157
	v_mul_f32_e32 v154, 0xbfb8aa3b, v148
	v_and_b32_e32 v157, 0xffff0000, v153
	v_mul_f32_e32 v153, 0xbfb8aa3b, v149
	v_exp_f32_e32 v146, v146
	v_exp_f32_e32 v147, v147
	v_exp_f32_e32 v154, v154
	v_exp_f32_e32 v153, v153
	v_add_f32_e32 v146, 1.0, v146
	v_add_f32_e32 v147, 1.0, v147
	v_add_f32_e32 v154, 1.0, v154
	v_add_f32_e32 v153, 1.0, v153
	v_rcp_f32_e32 v146, v146
	v_rcp_f32_e32 v147, v147
	v_rcp_f32_e32 v154, v154
	v_rcp_f32_e32 v155, v153
	v_add_f32_e32 v89, 1.0, v89
	v_pk_mul_f32 v[146:147], v[146:147], v[156:157]
	v_rcp_f32_e32 v88, v88
	v_pk_mul_f32 v[148:149], v[154:155], v[148:149]
	v_rcp_f32_e32 v89, v89
	v_pk_mul_f32 v[146:147], v[146:147], v[148:149]
	v_lshlrev_b32_e32 v148, 16, v142
	v_cvt_pk_bf16_f32 v153, v146, v147
	v_lshl_add_u32 v146, v174, 10, v177
	v_and_b32_e32 v149, 0xffff0000, v142
	global_store_dwordx4 v146, v[150:153], s[60:61] offset:1536 sc1
	v_mul_f32_e32 v142, 0xbfb8aa3b, v148
	v_exp_f32_e32 v142, v142
	v_lshlrev_b32_e32 v152, 16, v138
	v_and_b32_e32 v153, 0xffff0000, v138
	v_mul_f32_e32 v138, 0xbfb8aa3b, v149
	v_exp_f32_e32 v138, v138
	v_add_f32_e32 v142, 1.0, v142
	v_rcp_f32_e32 v150, v142
	v_pk_mul_f32 v[134:135], v[134:135], v[152:153]
	v_add_f32_e32 v138, 1.0, v138
	v_rcp_f32_e32 v151, v138
	v_lshlrev_b32_e32 v142, 16, v143
	v_and_b32_e32 v143, 0xffff0000, v143
	v_mul_f32_e32 v84, 0xbfb8aa3b, v84
	v_pk_mul_f32 v[148:149], v[150:151], v[148:149]
	v_mul_f32_e32 v85, 0xbfb8aa3b, v85
	v_pk_mul_f32 v[134:135], v[134:135], v[148:149]
	v_lshlrev_b32_e32 v148, 16, v139
	v_cvt_pk_bf16_f32 v134, v134, v135
	v_mul_f32_e32 v135, 0xbfb8aa3b, v136
	v_exp_f32_e32 v135, v135
	v_and_b32_e32 v149, 0xffff0000, v139
	v_exp_f32_e32 v84, v84
	v_exp_f32_e32 v85, v85
	v_add_f32_e32 v135, 1.0, v135
	v_rcp_f32_e32 v136, v135
	v_mul_f32_e32 v135, 0xbfb8aa3b, v137
	v_exp_f32_e32 v135, v135
	v_add_f32_e32 v84, 1.0, v84
	v_add_f32_e32 v85, 1.0, v85
	v_rcp_f32_e32 v84, v84
	v_add_f32_e32 v135, 1.0, v135
	v_rcp_f32_e32 v137, v135
	v_mul_f32_e32 v135, 0xbfb8aa3b, v142
	v_exp_f32_e32 v135, v135
	v_rcp_f32_e32 v85, v85
	v_pk_mul_f32 v[136:137], v[136:137], v[148:149]
	v_mul_f32_e32 v80, 0xbfb8aa3b, v80
	v_add_f32_e32 v135, 1.0, v135
	v_rcp_f32_e32 v138, v135
	v_mul_f32_e32 v135, 0xbfb8aa3b, v143
	v_exp_f32_e32 v135, v135
	v_mul_f32_e32 v81, 0xbfb8aa3b, v81
	v_exp_f32_e32 v80, v80
	v_exp_f32_e32 v81, v81
	v_add_f32_e32 v135, 1.0, v135
	v_rcp_f32_e32 v139, v135
	v_add_f32_e32 v80, 1.0, v80
	v_add_f32_e32 v81, 1.0, v81
	v_rcp_f32_e32 v80, v80
	v_pk_mul_f32 v[138:139], v[138:139], v[142:143]
	v_lshlrev_b32_e32 v142, 16, v140
	v_pk_mul_f32 v[136:137], v[136:137], v[138:139]
	v_and_b32_e32 v143, 0xffff0000, v140
	v_cvt_pk_bf16_f32 v135, v136, v137
	v_lshlrev_b32_e32 v136, 16, v144
	v_and_b32_e32 v137, 0xffff0000, v144
	v_mul_f32_e32 v138, 0xbfb8aa3b, v136
	v_mul_f32_e32 v139, 0xbfb8aa3b, v137
	v_exp_f32_e32 v138, v138
	v_exp_f32_e32 v139, v139
	v_pk_mul_f32 v[130:131], v[130:131], v[142:143]
	v_lshlrev_b32_e32 v140, 16, v141
	v_add_f32_e32 v138, 1.0, v138
	v_add_f32_e32 v139, 1.0, v139
	v_rcp_f32_e32 v138, v138
	v_rcp_f32_e32 v139, v139
	v_and_b32_e32 v141, 0xffff0000, v141
	v_rcp_f32_e32 v81, v81
	v_mul_f32_e32 v76, 0xbfb8aa3b, v76
	v_pk_mul_f32 v[136:137], v[138:139], v[136:137]
	v_mul_f32_e32 v77, 0xbfb8aa3b, v77
	v_pk_mul_f32 v[130:131], v[130:131], v[136:137]
	v_exp_f32_e32 v76, v76
	v_cvt_pk_bf16_f32 v136, v130, v131
	v_mul_f32_e32 v130, 0xbfb8aa3b, v132
	v_lshlrev_b32_e32 v132, 16, v145
	v_mul_f32_e32 v137, 0xbfb8aa3b, v132
	v_exp_f32_e32 v137, v137
	v_mul_f32_e32 v131, 0xbfb8aa3b, v133
	v_and_b32_e32 v133, 0xffff0000, v145
	v_exp_f32_e32 v130, v130
	v_add_f32_e32 v137, 1.0, v137
	v_rcp_f32_e32 v138, v137
	v_mul_f32_e32 v137, 0xbfb8aa3b, v133
	v_exp_f32_e32 v131, v131
	v_exp_f32_e32 v137, v137
	v_add_f32_e32 v130, 1.0, v130
	v_rcp_f32_e32 v130, v130
	v_add_f32_e32 v131, 1.0, v131
	v_add_f32_e32 v137, 1.0, v137
	v_rcp_f32_e32 v131, v131
	v_rcp_f32_e32 v139, v137
	v_exp_f32_e32 v77, v77
	v_add_f32_e32 v76, 1.0, v76
	v_pk_mul_f32 v[130:131], v[130:131], v[140:141]
	v_pk_mul_f32 v[132:133], v[138:139], v[132:133]
	v_add_f32_e32 v77, 1.0, v77
	v_pk_mul_f32 v[130:131], v[130:131], v[132:133]
	v_rcp_f32_e32 v76, v76
	v_cvt_pk_bf16_f32 v137, v130, v131
	v_add_u32_e32 v130, 0x8000, v146
	global_store_dwordx4 v130, v[134:137], s[60:61] offset:1536 sc1
	v_lshlrev_b32_e32 v130, 16, v126
	v_and_b32_e32 v131, 0xffff0000, v126
	v_mul_f32_e32 v126, 0xbfb8aa3b, v130
	v_lshlrev_b32_e32 v134, 16, v122
	v_and_b32_e32 v135, 0xffff0000, v122
	v_mul_f32_e32 v122, 0xbfb8aa3b, v131
	v_exp_f32_e32 v126, v126
	v_exp_f32_e32 v122, v122
	v_pk_mul_f32 v[118:119], v[118:119], v[134:135]
	v_rcp_f32_e32 v77, v77
	v_add_f32_e32 v126, 1.0, v126
	v_add_f32_e32 v122, 1.0, v122
	v_rcp_f32_e32 v132, v126
	v_rcp_f32_e32 v133, v122
	v_lshlrev_b32_e32 v126, 16, v127
	v_and_b32_e32 v127, 0xffff0000, v127
	v_mul_f32_e32 v72, 0xbfb8aa3b, v72
	v_pk_mul_f32 v[130:131], v[132:133], v[130:131]
	v_mul_f32_e32 v73, 0xbfb8aa3b, v73
	v_pk_mul_f32 v[118:119], v[118:119], v[130:131]
	v_lshlrev_b32_e32 v130, 16, v123
	v_cvt_pk_bf16_f32 v118, v118, v119
	v_mul_f32_e32 v119, 0xbfb8aa3b, v120
	v_exp_f32_e32 v119, v119
	v_and_b32_e32 v131, 0xffff0000, v123
	v_exp_f32_e32 v72, v72
	v_exp_f32_e32 v73, v73
	v_add_f32_e32 v119, 1.0, v119
	v_rcp_f32_e32 v120, v119
; __device__ __forceinline__ float sigm(float v) { return __builtin_amdgcn_rcpf(1.0f + __builtin_amdgcn_exp2f(-LOG2E * v)); }
; __device__ __forceinline__ float bf_lo(unsigned w) { return __uint_as_float(w << 16); }
; __device__ __forceinline__ float silu_f(float v) { return v * __builtin_amdgcn_rcpf(1.0f + __builtin_amdgcn_exp2f(-1.4426950408889634f * v)); }
; __device__ __forceinline__ float bf_hi(unsigned w) { return __uint_as_float(w & 0xffff0000u); }
; __device__ __forceinline__ unsigned cvt_pk_bf16(float lo, float hi) { f32x2_t v = {lo, hi}; bf16x2_t b = __builtin_convertvector(v, bf16x2_t); return __builtin_bit_cast(unsigned, b); }
;     __device__ __forceinline__ void operator()(const f32x4 (&acc)[2][2][4][2], const Unit& u, int wr, int wc, int fr, int fq) const {
;     ...
;                 for (int m = 0; m < 4; ++m) { const unsigned rl = rl0 + (unsigned)(ai * HALF + m * 16);
;                     ygv[m] = *(const u32x4*)(ygb + (rl * 256u + col) * 2u); sgv[m] = *(const u32x4*)(sgb + (rl * 512u + col) * 2u); }
; #pragma unroll
;                 for (int m = 0; m < 4; ++m) { const unsigned rl = rl0 + (unsigned)(ai * HALF + m * 16);
;                     const u32x4 yg = ygv[m], sg = sgv[m];
;                     const f32x4 v0 = acc[ai][bj][m][0], v1 = acc[ai][bj][m][1];
;                     u32x4 w;
;                     w.x = cvt_pk_bf16(bf_lo(yg.x) * sigm(v0[0]) * silu_f(bf_lo(sg.x)), bf_hi(yg.x) * sigm(v0[1]) * silu_f(bf_hi(sg.x)));
;                     w.y = cvt_pk_bf16(bf_lo(yg.y) * sigm(v0[2]) * silu_f(bf_lo(sg.y)), bf_hi(yg.y) * sigm(v0[3]) * silu_f(bf_hi(sg.y)));
;                     w.z = cvt_pk_bf16(bf_lo(yg.z) * sigm(v1[0]) * silu_f(bf_lo(sg.z)), bf_hi(yg.z) * sigm(v1[1]) * silu_f(bf_hi(sg.z)));
;                     w.w = cvt_pk_bf16(bf_lo(yg.w) * sigm(v1[2]) * silu_f(bf_lo(sg.w)), bf_hi(yg.w) * sigm(v1[3]) * silu_f(bf_hi(sg.w)));
;                     *(u32x4*)(yb + (rl * 1024u + col) * 2u) = w; }
	v_mul_f32_e32 v119, 0xbfb8aa3b, v121
	v_exp_f32_e32 v119, v119
	v_add_f32_e32 v72, 1.0, v72
	v_add_f32_e32 v73, 1.0, v73
	v_rcp_f32_e32 v72, v72
	v_add_f32_e32 v119, 1.0, v119
	v_rcp_f32_e32 v121, v119
	v_mul_f32_e32 v119, 0xbfb8aa3b, v126
	v_exp_f32_e32 v119, v119
	v_rcp_f32_e32 v73, v73
	v_pk_mul_f32 v[120:121], v[120:121], v[130:131]
	v_mul_f32_e32 v68, 0xbfb8aa3b, v68
	v_add_f32_e32 v119, 1.0, v119
	v_rcp_f32_e32 v122, v119
	v_mul_f32_e32 v119, 0xbfb8aa3b, v127
	v_exp_f32_e32 v119, v119
	v_mul_f32_e32 v69, 0xbfb8aa3b, v69
	v_exp_f32_e32 v68, v68
	v_exp_f32_e32 v69, v69
	v_add_f32_e32 v119, 1.0, v119
	v_rcp_f32_e32 v123, v119
	v_add_f32_e32 v68, 1.0, v68
	v_add_f32_e32 v69, 1.0, v69
	v_rcp_f32_e32 v68, v68
	v_pk_mul_f32 v[122:123], v[122:123], v[126:127]
	v_lshlrev_b32_e32 v126, 16, v124
	v_pk_mul_f32 v[120:121], v[120:121], v[122:123]
	v_and_b32_e32 v127, 0xffff0000, v124
	v_cvt_pk_bf16_f32 v119, v120, v121
	v_lshlrev_b32_e32 v120, 16, v128
	v_and_b32_e32 v121, 0xffff0000, v128
	v_mul_f32_e32 v122, 0xbfb8aa3b, v120
	v_mul_f32_e32 v123, 0xbfb8aa3b, v121
	v_exp_f32_e32 v122, v122
	v_exp_f32_e32 v123, v123
	v_pk_mul_f32 v[114:115], v[114:115], v[126:127]
	v_lshlrev_b32_e32 v124, 16, v125
	v_add_f32_e32 v122, 1.0, v122
	v_add_f32_e32 v123, 1.0, v123
	v_rcp_f32_e32 v122, v122
	v_rcp_f32_e32 v123, v123
	v_and_b32_e32 v125, 0xffff0000, v125
	v_rcp_f32_e32 v69, v69
	v_mul_f32_e32 v60, 0xbfb8aa3b, v60
	v_pk_mul_f32 v[120:121], v[122:123], v[120:121]
	v_mul_f32_e32 v61, 0xbfb8aa3b, v61
	v_pk_mul_f32 v[114:115], v[114:115], v[120:121]
	v_exp_f32_e32 v60, v60
	v_cvt_pk_bf16_f32 v120, v114, v115
	v_mul_f32_e32 v114, 0xbfb8aa3b, v116
	v_lshlrev_b32_e32 v116, 16, v129
	v_mul_f32_e32 v121, 0xbfb8aa3b, v116
	v_exp_f32_e32 v121, v121
	v_mul_f32_e32 v115, 0xbfb8aa3b, v117
	v_and_b32_e32 v117, 0xffff0000, v129
	v_exp_f32_e32 v114, v114
	v_add_f32_e32 v121, 1.0, v121
	v_rcp_f32_e32 v122, v121
	v_mul_f32_e32 v121, 0xbfb8aa3b, v117
	v_exp_f32_e32 v115, v115
	v_exp_f32_e32 v121, v121
	v_add_f32_e32 v114, 1.0, v114
	v_rcp_f32_e32 v114, v114
	v_add_f32_e32 v115, 1.0, v115
	v_add_f32_e32 v121, 1.0, v121
	v_rcp_f32_e32 v115, v115
	v_rcp_f32_e32 v123, v121
	v_exp_f32_e32 v61, v61
	v_add_f32_e32 v60, 1.0, v60
	v_pk_mul_f32 v[114:115], v[114:115], v[124:125]
	v_pk_mul_f32 v[116:117], v[122:123], v[116:117]
	v_add_f32_e32 v61, 1.0, v61
	v_pk_mul_f32 v[114:115], v[114:115], v[116:117]
	v_rcp_f32_e32 v60, v60
	v_cvt_pk_bf16_f32 v121, v114, v115
	v_add_u32_e32 v114, 0x10000, v146
	global_store_dwordx4 v114, v[118:121], s[60:61] offset:1536 sc1
	v_lshlrev_b32_e32 v114, 16, v110
	v_and_b32_e32 v115, 0xffff0000, v110
	v_mul_f32_e32 v110, 0xbfb8aa3b, v114
	v_lshlrev_b32_e32 v118, 16, v106
	v_and_b32_e32 v119, 0xffff0000, v106
	v_mul_f32_e32 v106, 0xbfb8aa3b, v115
	v_exp_f32_e32 v110, v110
	v_exp_f32_e32 v106, v106
	v_pk_mul_f32 v[102:103], v[102:103], v[118:119]
	v_rcp_f32_e32 v61, v61
	v_add_f32_e32 v110, 1.0, v110
	v_add_f32_e32 v106, 1.0, v106
	v_rcp_f32_e32 v116, v110
	v_rcp_f32_e32 v117, v106
	v_lshlrev_b32_e32 v110, 16, v111
	v_and_b32_e32 v111, 0xffff0000, v111
	v_mul_f32_e32 v64, 0xbfb8aa3b, v64
	v_pk_mul_f32 v[114:115], v[116:117], v[114:115]
	v_mul_f32_e32 v65, 0xbfb8aa3b, v65
	v_pk_mul_f32 v[102:103], v[102:103], v[114:115]
	v_lshlrev_b32_e32 v114, 16, v107
	v_cvt_pk_bf16_f32 v102, v102, v103
	v_mul_f32_e32 v103, 0xbfb8aa3b, v104
	v_exp_f32_e32 v103, v103
	v_and_b32_e32 v115, 0xffff0000, v107
	v_exp_f32_e32 v64, v64
	v_exp_f32_e32 v65, v65
	v_add_f32_e32 v103, 1.0, v103
	v_rcp_f32_e32 v104, v103
	v_mul_f32_e32 v103, 0xbfb8aa3b, v105
	v_exp_f32_e32 v103, v103
	v_add_f32_e32 v64, 1.0, v64
	v_add_f32_e32 v65, 1.0, v65
	v_rcp_f32_e32 v64, v64
	v_add_f32_e32 v103, 1.0, v103
	v_rcp_f32_e32 v105, v103
	v_mul_f32_e32 v103, 0xbfb8aa3b, v110
	v_exp_f32_e32 v103, v103
	v_rcp_f32_e32 v65, v65
	v_pk_mul_f32 v[104:105], v[104:105], v[114:115]
	v_mul_f32_e32 v56, 0xbfb8aa3b, v56
	v_add_f32_e32 v103, 1.0, v103
	v_rcp_f32_e32 v106, v103
	v_mul_f32_e32 v103, 0xbfb8aa3b, v111
	v_exp_f32_e32 v103, v103
	v_mul_f32_e32 v57, 0xbfb8aa3b, v57
	v_exp_f32_e32 v56, v56
	v_exp_f32_e32 v57, v57
	v_add_f32_e32 v103, 1.0, v103
	v_rcp_f32_e32 v107, v103
	v_add_f32_e32 v56, 1.0, v56
	v_add_f32_e32 v57, 1.0, v57
	v_rcp_f32_e32 v56, v56
	v_pk_mul_f32 v[106:107], v[106:107], v[110:111]
	v_lshlrev_b32_e32 v110, 16, v108
	v_pk_mul_f32 v[104:105], v[104:105], v[106:107]
	v_and_b32_e32 v111, 0xffff0000, v108
	v_cvt_pk_bf16_f32 v103, v104, v105
	v_lshlrev_b32_e32 v104, 16, v112
	v_and_b32_e32 v105, 0xffff0000, v112
	v_mul_f32_e32 v106, 0xbfb8aa3b, v104
	v_mul_f32_e32 v107, 0xbfb8aa3b, v105
	v_exp_f32_e32 v106, v106
	v_exp_f32_e32 v107, v107
	v_pk_mul_f32 v[98:99], v[98:99], v[110:111]
	v_lshlrev_b32_e32 v108, 16, v109
	v_add_f32_e32 v106, 1.0, v106
	v_add_f32_e32 v107, 1.0, v107
	v_rcp_f32_e32 v106, v106
	v_rcp_f32_e32 v107, v107
	v_and_b32_e32 v109, 0xffff0000, v109
	v_rcp_f32_e32 v57, v57
	v_mul_f32_e32 v52, 0xbfb8aa3b, v52
	v_pk_mul_f32 v[104:105], v[106:107], v[104:105]
	v_mul_f32_e32 v53, 0xbfb8aa3b, v53
	v_pk_mul_f32 v[98:99], v[98:99], v[104:105]
	v_exp_f32_e32 v52, v52
	v_cvt_pk_bf16_f32 v104, v98, v99
	v_mul_f32_e32 v98, 0xbfb8aa3b, v100
	v_lshlrev_b32_e32 v100, 16, v113
	v_mul_f32_e32 v105, 0xbfb8aa3b, v100
	v_exp_f32_e32 v105, v105
	v_mul_f32_e32 v99, 0xbfb8aa3b, v101
	v_and_b32_e32 v101, 0xffff0000, v113
	v_exp_f32_e32 v98, v98
	v_add_f32_e32 v105, 1.0, v105
	v_rcp_f32_e32 v106, v105
	v_mul_f32_e32 v105, 0xbfb8aa3b, v101
	v_exp_f32_e32 v99, v99
	v_exp_f32_e32 v105, v105
	v_add_f32_e32 v98, 1.0, v98
	v_rcp_f32_e32 v98, v98
	v_add_f32_e32 v99, 1.0, v99
	v_add_f32_e32 v105, 1.0, v105
; __device__ __forceinline__ float sigm(float v) { return __builtin_amdgcn_rcpf(1.0f + __builtin_amdgcn_exp2f(-LOG2E * v)); }
; __device__ __forceinline__ float bf_lo(unsigned w) { return __uint_as_float(w << 16); }
; __device__ __forceinline__ float silu_f(float v) { return v * __builtin_amdgcn_rcpf(1.0f + __builtin_amdgcn_exp2f(-1.4426950408889634f * v)); }
; __device__ __forceinline__ float bf_hi(unsigned w) { return __uint_as_float(w & 0xffff0000u); }
; __device__ __forceinline__ unsigned cvt_pk_bf16(float lo, float hi) { f32x2_t v = {lo, hi}; bf16x2_t b = __builtin_convertvector(v, bf16x2_t); return __builtin_bit_cast(unsigned, b); }
;     __device__ __forceinline__ void operator()(const f32x4 (&acc)[2][2][4][2], const Unit& u, int wr, int wc, int fr, int fq) const {
;     ...
; #pragma unroll
;         for (int bj = 0; bj < 2; ++bj) { const unsigned col = col0 + bj * HALF;
; #pragma unroll
;             for (int ai = 0; ai < 2; ++ai) {
;                 u32x4 ygv[4], sgv[4];
; #pragma unroll
;                 for (int m = 0; m < 4; ++m) { const unsigned rl = rl0 + (unsigned)(ai * HALF + m * 16);
;                     ygv[m] = *(const u32x4*)(ygb + (rl * 256u + col) * 2u); sgv[m] = *(const u32x4*)(sgb + (rl * 512u + col) * 2u); }
; #pragma unroll
;                 for (int m = 0; m < 4; ++m) { const unsigned rl = rl0 + (unsigned)(ai * HALF + m * 16);
;                     const u32x4 yg = ygv[m], sg = sgv[m];
;                     const f32x4 v0 = acc[ai][bj][m][0], v1 = acc[ai][bj][m][1];
;                     u32x4 w;
;                     w.x = cvt_pk_bf16(bf_lo(yg.x) * sigm(v0[0]) * silu_f(bf_lo(sg.x)), bf_hi(yg.x) * sigm(v0[1]) * silu_f(bf_hi(sg.x)));
;                     w.y = cvt_pk_bf16(bf_lo(yg.y) * sigm(v0[2]) * silu_f(bf_lo(sg.y)), bf_hi(yg.y) * sigm(v0[3]) * silu_f(bf_hi(sg.y)));
;                     w.z = cvt_pk_bf16(bf_lo(yg.z) * sigm(v1[0]) * silu_f(bf_lo(sg.z)), bf_hi(yg.z) * sigm(v1[1]) * silu_f(bf_hi(sg.z)));
;                     w.w = cvt_pk_bf16(bf_lo(yg.w) * sigm(v1[2]) * silu_f(bf_lo(sg.w)), bf_hi(yg.w) * sigm(v1[3]) * silu_f(bf_hi(sg.w)));
;                     *(u32x4*)(yb + (rl * 1024u + col) * 2u) = w; }
	v_rcp_f32_e32 v99, v99
	v_rcp_f32_e32 v107, v105
	v_exp_f32_e32 v53, v53
	v_add_f32_e32 v52, 1.0, v52
	v_pk_mul_f32 v[98:99], v[98:99], v[108:109]
	v_pk_mul_f32 v[100:101], v[106:107], v[100:101]
	v_add_f32_e32 v53, 1.0, v53
	v_pk_mul_f32 v[98:99], v[98:99], v[100:101]
	v_rcp_f32_e32 v52, v52
	v_cvt_pk_bf16_f32 v105, v98, v99
	v_add_u32_e32 v98, 0x18000, v146
	global_store_dwordx4 v98, v[102:105], s[60:61] offset:1536 sc1
	v_rcp_f32_e32 v53, v53
	v_lshlrev_b32_e32 v98, 9, v174
	v_add_u32_e32 v99, 0x10000, v98
	v_add_u32_e32 v100, v99, v176
	v_add_u32_e32 v99, v100, v99
	global_load_dwordx4 v[122:125], v100, s[62:63]
	global_load_dwordx4 v[126:129], v99, s[64:65]
	v_add_u32_e32 v99, 0x12000, v98
	v_add_u32_e32 v100, v99, v176
	v_add_u32_e32 v99, v100, v99
	global_load_dwordx4 v[114:117], v100, s[62:63]
	global_load_dwordx4 v[118:121], v99, s[64:65]
	v_add_u32_e32 v99, 0x14000, v98
	v_add_u32_e32 v102, 0x16000, v98
	v_add_u32_e32 v100, v99, v176
	v_add_u32_e32 v103, v102, v176
	v_add_u32_e32 v99, v100, v99
	v_add_u32_e32 v102, v103, v102
	global_load_dwordx4 v[106:109], v100, s[62:63]
	global_load_dwordx4 v[110:113], v99, s[64:65]
	v_mul_f32_e32 v48, 0xbfb8aa3b, v48
	global_load_dwordx4 v[98:101], v103, s[62:63]
	v_mul_f32_e32 v49, 0xbfb8aa3b, v49
	global_load_dwordx4 v[102:105], v102, s[64:65]
	v_exp_f32_e32 v48, v48
	v_exp_f32_e32 v49, v49
	v_mul_f32_e32 v44, 0xbfb8aa3b, v44
	v_mul_f32_e32 v45, 0xbfb8aa3b, v45
	v_add_f32_e32 v48, 1.0, v48
	v_add_f32_e32 v49, 1.0, v49
	v_rcp_f32_e32 v48, v48
	v_rcp_f32_e32 v49, v49
	v_exp_f32_e32 v44, v44
	v_exp_f32_e32 v45, v45
	v_mul_f32_e32 v40, 0xbfb8aa3b, v40
	v_mul_f32_e32 v41, 0xbfb8aa3b, v41
	v_add_f32_e32 v44, 1.0, v44
	v_add_f32_e32 v45, 1.0, v45
	v_rcp_f32_e32 v44, v44
	v_rcp_f32_e32 v45, v45
	v_exp_f32_e32 v40, v40
	v_exp_f32_e32 v41, v41
	v_mul_f32_e32 v36, 0xbfb8aa3b, v36
	v_mul_f32_e32 v37, 0xbfb8aa3b, v37
	v_add_f32_e32 v40, 1.0, v40
	v_add_f32_e32 v41, 1.0, v41
	v_rcp_f32_e32 v40, v40
	v_rcp_f32_e32 v41, v41
	v_exp_f32_e32 v36, v36
	v_exp_f32_e32 v37, v37
	v_mul_f32_e32 v32, 0xbfb8aa3b, v32
	v_mul_f32_e32 v33, 0xbfb8aa3b, v33
	v_add_f32_e32 v36, 1.0, v36
	v_add_f32_e32 v37, 1.0, v37
	v_rcp_f32_e32 v36, v36
	v_rcp_f32_e32 v37, v37
	v_exp_f32_e32 v32, v32
	v_exp_f32_e32 v33, v33
	v_mul_f32_e32 v28, 0xbfb8aa3b, v28
	v_mul_f32_e32 v29, 0xbfb8aa3b, v29
	v_add_f32_e32 v32, 1.0, v32
	v_add_f32_e32 v33, 1.0, v33
	v_rcp_f32_e32 v32, v32
	v_rcp_f32_e32 v33, v33
	v_exp_f32_e32 v28, v28
	v_exp_f32_e32 v29, v29
	v_mul_f32_e32 v24, 0xbfb8aa3b, v24
	v_mul_f32_e32 v25, 0xbfb8aa3b, v25
	v_add_f32_e32 v28, 1.0, v28
	v_add_f32_e32 v29, 1.0, v29
	v_rcp_f32_e32 v28, v28
	v_rcp_f32_e32 v29, v29
	v_exp_f32_e32 v24, v24
	v_exp_f32_e32 v25, v25
	v_mul_f32_e32 v20, 0xbfb8aa3b, v20
	v_mul_f32_e32 v21, 0xbfb8aa3b, v21
	v_add_f32_e32 v24, 1.0, v24
	v_add_f32_e32 v25, 1.0, v25
	v_rcp_f32_e32 v24, v24
	v_rcp_f32_e32 v25, v25
	v_exp_f32_e32 v20, v20
	v_exp_f32_e32 v21, v21
	v_mul_f32_e32 v16, 0xbfb8aa3b, v16
	v_mul_f32_e32 v17, 0xbfb8aa3b, v17
	v_add_f32_e32 v20, 1.0, v20
	s_waitcnt vmcnt(7)
	v_lshlrev_b32_e32 v134, 16, v122
	s_waitcnt vmcnt(6)
	v_lshlrev_b32_e32 v130, 16, v126
	v_and_b32_e32 v131, 0xffff0000, v126
	v_mul_f32_e32 v126, 0xbfb8aa3b, v130
	v_and_b32_e32 v135, 0xffff0000, v122
	v_mul_f32_e32 v122, 0xbfb8aa3b, v131
	v_exp_f32_e32 v126, v126
	v_exp_f32_e32 v122, v122
	v_pk_mul_f32 v[92:93], v[92:93], v[134:135]
	v_add_f32_e32 v21, 1.0, v21
	v_add_f32_e32 v126, 1.0, v126
	v_add_f32_e32 v122, 1.0, v122
	v_rcp_f32_e32 v132, v126
	v_rcp_f32_e32 v133, v122
	v_lshlrev_b32_e32 v126, 16, v127
	v_and_b32_e32 v127, 0xffff0000, v127
	v_rcp_f32_e32 v20, v20
	v_pk_mul_f32 v[130:131], v[132:133], v[130:131]
	v_rcp_f32_e32 v21, v21
	v_pk_mul_f32 v[92:93], v[92:93], v[130:131]
	v_lshlrev_b32_e32 v130, 16, v123
	v_cvt_pk_bf16_f32 v92, v92, v93
	v_mul_f32_e32 v93, 0xbfb8aa3b, v94
	v_exp_f32_e32 v93, v93
	v_and_b32_e32 v131, 0xffff0000, v123
	v_exp_f32_e32 v16, v16
	v_exp_f32_e32 v17, v17
	v_add_f32_e32 v93, 1.0, v93
	v_rcp_f32_e32 v94, v93
	v_mul_f32_e32 v93, 0xbfb8aa3b, v95
	v_exp_f32_e32 v93, v93
	v_add_f32_e32 v16, 1.0, v16
	v_add_f32_e32 v17, 1.0, v17
	v_rcp_f32_e32 v16, v16
	v_add_f32_e32 v93, 1.0, v93
	v_rcp_f32_e32 v95, v93
	v_mul_f32_e32 v93, 0xbfb8aa3b, v126
	v_exp_f32_e32 v93, v93
	v_rcp_f32_e32 v17, v17
	v_pk_mul_f32 v[94:95], v[94:95], v[130:131]
	v_mul_f32_e32 v12, 0xbfb8aa3b, v12
	v_add_f32_e32 v93, 1.0, v93
	v_rcp_f32_e32 v122, v93
	v_mul_f32_e32 v93, 0xbfb8aa3b, v127
	v_exp_f32_e32 v93, v93
	v_mul_f32_e32 v13, 0xbfb8aa3b, v13
	v_exp_f32_e32 v12, v12
	v_exp_f32_e32 v13, v13
	v_add_f32_e32 v93, 1.0, v93
	v_rcp_f32_e32 v123, v93
	v_add_f32_e32 v12, 1.0, v12
	v_add_f32_e32 v13, 1.0, v13
	v_rcp_f32_e32 v12, v12
	v_pk_mul_f32 v[122:123], v[122:123], v[126:127]
	v_lshlrev_b32_e32 v126, 16, v124
	v_pk_mul_f32 v[94:95], v[94:95], v[122:123]
	v_and_b32_e32 v127, 0xffff0000, v124
	v_cvt_pk_bf16_f32 v93, v94, v95
	v_lshlrev_b32_e32 v94, 16, v128
	v_and_b32_e32 v95, 0xffff0000, v128
	v_mul_f32_e32 v122, 0xbfb8aa3b, v94
	v_mul_f32_e32 v123, 0xbfb8aa3b, v95
	v_exp_f32_e32 v122, v122
	v_exp_f32_e32 v123, v123
	v_pk_mul_f32 v[88:89], v[88:89], v[126:127]
	v_lshlrev_b32_e32 v124, 16, v125
	v_add_f32_e32 v122, 1.0, v122
	v_add_f32_e32 v123, 1.0, v123
	v_rcp_f32_e32 v122, v122
	v_rcp_f32_e32 v123, v123
	v_and_b32_e32 v125, 0xffff0000, v125
	v_rcp_f32_e32 v13, v13
	v_mul_f32_e32 v8, 0xbfb8aa3b, v8
	v_pk_mul_f32 v[94:95], v[122:123], v[94:95]
	v_mul_f32_e32 v9, 0xbfb8aa3b, v9
	v_pk_mul_f32 v[88:89], v[88:89], v[94:95]
	v_exp_f32_e32 v8, v8
	v_cvt_pk_bf16_f32 v94, v88, v89
	v_mul_f32_e32 v88, 0xbfb8aa3b, v90
	v_lshlrev_b32_e32 v90, 16, v129
	v_mul_f32_e32 v95, 0xbfb8aa3b, v90
	v_exp_f32_e32 v95, v95
	v_mul_f32_e32 v89, 0xbfb8aa3b, v91
	v_and_b32_e32 v91, 0xffff0000, v129
	v_exp_f32_e32 v88, v88
	v_add_f32_e32 v95, 1.0, v95
	v_rcp_f32_e32 v122, v95
	v_mul_f32_e32 v95, 0xbfb8aa3b, v91
	v_exp_f32_e32 v89, v89
	v_exp_f32_e32 v95, v95
	v_add_f32_e32 v88, 1.0, v88
	v_rcp_f32_e32 v88, v88
	v_add_f32_e32 v89, 1.0, v89
	v_add_f32_e32 v95, 1.0, v95
	v_rcp_f32_e32 v89, v89
	v_rcp_f32_e32 v123, v95
	v_exp_f32_e32 v9, v9
	v_add_f32_e32 v8, 1.0, v8
	v_pk_mul_f32 v[88:89], v[88:89], v[124:125]
	v_pk_mul_f32 v[90:91], v[122:123], v[90:91]
	v_add_f32_e32 v9, 1.0, v9
	v_pk_mul_f32 v[88:89], v[88:89], v[90:91]
	s_waitcnt vmcnt(4)
; __device__ __forceinline__ float sigm(float v) { return __builtin_amdgcn_rcpf(1.0f + __builtin_amdgcn_exp2f(-LOG2E * v)); }
; __device__ __forceinline__ float bf_lo(unsigned w) { return __uint_as_float(w << 16); }
; __device__ __forceinline__ float silu_f(float v) { return v * __builtin_amdgcn_rcpf(1.0f + __builtin_amdgcn_exp2f(-1.4426950408889634f * v)); }
; __device__ __forceinline__ float bf_hi(unsigned w) { return __uint_as_float(w & 0xffff0000u); }
; __device__ __forceinline__ unsigned cvt_pk_bf16(float lo, float hi) { f32x2_t v = {lo, hi}; bf16x2_t b = __builtin_convertvector(v, bf16x2_t); return __builtin_bit_cast(unsigned, b); }
;     __device__ __forceinline__ void operator()(const f32x4 (&acc)[2][2][4][2], const Unit& u, int wr, int wc, int fr, int fq) const {
;     ...
;                 for (int m = 0; m < 4; ++m) { const unsigned rl = rl0 + (unsigned)(ai * HALF + m * 16);
;                     ygv[m] = *(const u32x4*)(ygb + (rl * 256u + col) * 2u); sgv[m] = *(const u32x4*)(sgb + (rl * 512u + col) * 2u); }
; #pragma unroll
;                 for (int m = 0; m < 4; ++m) { const unsigned rl = rl0 + (unsigned)(ai * HALF + m * 16);
;                     const u32x4 yg = ygv[m], sg = sgv[m];
;                     const f32x4 v0 = acc[ai][bj][m][0], v1 = acc[ai][bj][m][1];
;                     u32x4 w;
;                     w.x = cvt_pk_bf16(bf_lo(yg.x) * sigm(v0[0]) * silu_f(bf_lo(sg.x)), bf_hi(yg.x) * sigm(v0[1]) * silu_f(bf_hi(sg.x)));
;                     w.y = cvt_pk_bf16(bf_lo(yg.y) * sigm(v0[2]) * silu_f(bf_lo(sg.y)), bf_hi(yg.y) * sigm(v0[3]) * silu_f(bf_hi(sg.y)));
;                     w.z = cvt_pk_bf16(bf_lo(yg.z) * sigm(v1[0]) * silu_f(bf_lo(sg.z)), bf_hi(yg.z) * sigm(v1[1]) * silu_f(bf_hi(sg.z)));
;                     w.w = cvt_pk_bf16(bf_lo(yg.w) * sigm(v1[2]) * silu_f(bf_lo(sg.w)), bf_hi(yg.w) * sigm(v1[3]) * silu_f(bf_hi(sg.w)));
;                     *(u32x4*)(yb + (rl * 1024u + col) * 2u) = w; }
	v_lshlrev_b32_e32 v90, 16, v118
	v_cvt_pk_bf16_f32 v95, v88, v89
	v_lshl_add_u32 v88, v174, 11, v176
	v_add_u32_e32 v89, 0x40000, v88
	global_store_dwordx4 v89, v[92:95], s[60:61] offset:1536 sc1
	v_mul_f32_e32 v89, 0xbfb8aa3b, v90
	v_exp_f32_e32 v89, v89
	v_and_b32_e32 v91, 0xffff0000, v118
	v_lshlrev_b32_e32 v94, 16, v114
	v_and_b32_e32 v95, 0xffff0000, v114
	v_add_f32_e32 v89, 1.0, v89
	v_rcp_f32_e32 v92, v89
	v_mul_f32_e32 v89, 0xbfb8aa3b, v91
	v_exp_f32_e32 v89, v89
	v_pk_mul_f32 v[84:85], v[84:85], v[94:95]
	v_lshlrev_b32_e32 v94, 16, v115
	v_and_b32_e32 v95, 0xffff0000, v115
	v_add_f32_e32 v89, 1.0, v89
	v_rcp_f32_e32 v93, v89
	v_rcp_f32_e32 v8, v8
	v_rcp_f32_e32 v9, v9
	v_mul_f32_e32 v4, 0xbfb8aa3b, v4
	v_pk_mul_f32 v[90:91], v[92:93], v[90:91]
	v_mul_f32_e32 v5, 0xbfb8aa3b, v5
	v_pk_mul_f32 v[84:85], v[84:85], v[90:91]
	v_lshlrev_b32_e32 v90, 16, v119
	v_cvt_pk_bf16_f32 v84, v84, v85
	v_mul_f32_e32 v85, 0xbfb8aa3b, v86
	v_exp_f32_e32 v85, v85
	v_and_b32_e32 v91, 0xffff0000, v119
	v_exp_f32_e32 v4, v4
	v_exp_f32_e32 v5, v5
	v_add_f32_e32 v85, 1.0, v85
	v_rcp_f32_e32 v86, v85
	v_mul_f32_e32 v85, 0xbfb8aa3b, v87
	v_exp_f32_e32 v85, v85
	v_add_f32_e32 v4, 1.0, v4
	v_add_f32_e32 v5, 1.0, v5
	v_rcp_f32_e32 v4, v4
	v_add_f32_e32 v85, 1.0, v85
	v_rcp_f32_e32 v87, v85
	v_mul_f32_e32 v85, 0xbfb8aa3b, v90
	v_exp_f32_e32 v85, v85
	v_rcp_f32_e32 v5, v5
	v_pk_mul_f32 v[86:87], v[86:87], v[94:95]
	v_mul_f32_e32 v0, 0xbfb8aa3b, v0
	v_add_f32_e32 v85, 1.0, v85
	v_rcp_f32_e32 v92, v85
	v_mul_f32_e32 v85, 0xbfb8aa3b, v91
	v_exp_f32_e32 v85, v85
	v_mul_f32_e32 v1, 0xbfb8aa3b, v1
	v_exp_f32_e32 v0, v0
	v_exp_f32_e32 v1, v1
	v_add_f32_e32 v85, 1.0, v85
	v_rcp_f32_e32 v93, v85
	v_add_f32_e32 v0, 1.0, v0
	v_add_f32_e32 v1, 1.0, v1
	v_rcp_f32_e32 v0, v0
	v_pk_mul_f32 v[90:91], v[92:93], v[90:91]
	v_lshlrev_b32_e32 v92, 16, v116
	v_pk_mul_f32 v[86:87], v[86:87], v[90:91]
	v_and_b32_e32 v93, 0xffff0000, v116
	v_cvt_pk_bf16_f32 v85, v86, v87
	v_lshlrev_b32_e32 v86, 16, v120
	v_mul_f32_e32 v89, 0xbfb8aa3b, v86
	v_exp_f32_e32 v89, v89
	v_and_b32_e32 v87, 0xffff0000, v120
	v_pk_mul_f32 v[80:81], v[80:81], v[92:93]
	v_lshlrev_b32_e32 v92, 16, v117
	v_add_f32_e32 v89, 1.0, v89
	v_rcp_f32_e32 v90, v89
	v_mul_f32_e32 v89, 0xbfb8aa3b, v87
	v_exp_f32_e32 v89, v89
	v_and_b32_e32 v93, 0xffff0000, v117
	v_rcp_f32_e32 v1, v1
	s_and_b64 vcc, exec, s[38:39]
	v_add_f32_e32 v89, 1.0, v89
	v_rcp_f32_e32 v91, v89
	s_nop 0
	v_pk_mul_f32 v[86:87], v[90:91], v[86:87]
	s_nop 0
	v_pk_mul_f32 v[80:81], v[80:81], v[86:87]
	s_nop 0
	v_cvt_pk_bf16_f32 v86, v80, v81
	v_mul_f32_e32 v80, 0xbfb8aa3b, v82
	v_lshlrev_b32_e32 v82, 16, v121
	v_mul_f32_e32 v87, 0xbfb8aa3b, v82
	v_exp_f32_e32 v87, v87
	v_mul_f32_e32 v81, 0xbfb8aa3b, v83
	v_and_b32_e32 v83, 0xffff0000, v121
	v_exp_f32_e32 v80, v80
	v_add_f32_e32 v87, 1.0, v87
	v_rcp_f32_e32 v90, v87
	v_mul_f32_e32 v87, 0xbfb8aa3b, v83
	v_exp_f32_e32 v81, v81
	v_exp_f32_e32 v87, v87
	v_add_f32_e32 v80, 1.0, v80
	v_rcp_f32_e32 v80, v80
	v_add_f32_e32 v81, 1.0, v81
	v_add_f32_e32 v87, 1.0, v87
	v_rcp_f32_e32 v81, v81
	v_rcp_f32_e32 v91, v87
	v_pk_mul_f32 v[80:81], v[80:81], v[92:93]
	v_pk_mul_f32 v[82:83], v[90:91], v[82:83]
	s_nop 0
	v_pk_mul_f32 v[80:81], v[80:81], v[82:83]
	s_nop 0
	v_cvt_pk_bf16_f32 v87, v80, v81
	v_add_u32_e32 v80, 0x48000, v88
	global_store_dwordx4 v80, v[84:87], s[60:61] offset:1536 sc1
	s_waitcnt vmcnt(4)
	v_lshlrev_b32_e32 v80, 16, v110
	v_and_b32_e32 v81, 0xffff0000, v110
	v_mul_f32_e32 v82, 0xbfb8aa3b, v80
	v_mul_f32_e32 v83, 0xbfb8aa3b, v81
	v_exp_f32_e32 v82, v82
	v_exp_f32_e32 v83, v83
	v_lshlrev_b32_e32 v84, 16, v106
	v_and_b32_e32 v85, 0xffff0000, v106
	v_add_f32_e32 v82, 1.0, v82
	v_add_f32_e32 v83, 1.0, v83
	v_rcp_f32_e32 v82, v82
	v_rcp_f32_e32 v83, v83
	v_pk_mul_f32 v[76:77], v[76:77], v[84:85]
	v_lshlrev_b32_e32 v84, 16, v107
	v_and_b32_e32 v85, 0xffff0000, v107
	v_pk_mul_f32 v[80:81], v[82:83], v[80:81]
	s_nop 0
	v_pk_mul_f32 v[76:77], v[76:77], v[80:81]
	v_lshlrev_b32_e32 v80, 16, v111
	v_cvt_pk_bf16_f32 v76, v76, v77
	v_mul_f32_e32 v77, 0xbfb8aa3b, v78
	v_exp_f32_e32 v77, v77
	v_and_b32_e32 v81, 0xffff0000, v111
	v_add_f32_e32 v77, 1.0, v77
	v_rcp_f32_e32 v78, v77
	v_mul_f32_e32 v77, 0xbfb8aa3b, v79
	v_exp_f32_e32 v77, v77
	s_nop 0
	v_add_f32_e32 v77, 1.0, v77
	v_rcp_f32_e32 v79, v77
	v_mul_f32_e32 v77, 0xbfb8aa3b, v80
	v_exp_f32_e32 v77, v77
	v_pk_mul_f32 v[78:79], v[78:79], v[84:85]
	v_add_f32_e32 v77, 1.0, v77
	v_rcp_f32_e32 v82, v77
	v_mul_f32_e32 v77, 0xbfb8aa3b, v81
	v_exp_f32_e32 v77, v77
	s_nop 0
	v_add_f32_e32 v77, 1.0, v77
	v_rcp_f32_e32 v83, v77
	s_nop 0
	v_pk_mul_f32 v[80:81], v[82:83], v[80:81]
	s_nop 0
	v_pk_mul_f32 v[78:79], v[78:79], v[80:81]
	v_lshlrev_b32_e32 v82, 16, v108
	v_cvt_pk_bf16_f32 v77, v78, v79
	v_lshlrev_b32_e32 v78, 16, v112
	v_and_b32_e32 v79, 0xffff0000, v112
	v_mul_f32_e32 v80, 0xbfb8aa3b, v78
	v_mul_f32_e32 v81, 0xbfb8aa3b, v79
	v_exp_f32_e32 v80, v80
	v_exp_f32_e32 v81, v81
	v_and_b32_e32 v83, 0xffff0000, v108
	v_pk_mul_f32 v[72:73], v[72:73], v[82:83]
	v_add_f32_e32 v80, 1.0, v80
	v_add_f32_e32 v81, 1.0, v81
	v_rcp_f32_e32 v80, v80
	v_rcp_f32_e32 v81, v81
	v_lshlrev_b32_e32 v82, 16, v109
	v_and_b32_e32 v83, 0xffff0000, v109
	v_pk_mul_f32 v[78:79], v[80:81], v[78:79]
	s_nop 0
	v_pk_mul_f32 v[72:73], v[72:73], v[78:79]
	s_nop 0
	v_cvt_pk_bf16_f32 v78, v72, v73
	v_mul_f32_e32 v72, 0xbfb8aa3b, v74
	v_lshlrev_b32_e32 v74, 16, v113
	v_mul_f32_e32 v79, 0xbfb8aa3b, v74
	v_exp_f32_e32 v79, v79
	v_mul_f32_e32 v73, 0xbfb8aa3b, v75
	v_and_b32_e32 v75, 0xffff0000, v113
	v_exp_f32_e32 v72, v72
	v_add_f32_e32 v79, 1.0, v79
	v_rcp_f32_e32 v80, v79
	v_mul_f32_e32 v79, 0xbfb8aa3b, v75
	v_exp_f32_e32 v73, v73
	v_exp_f32_e32 v79, v79
	v_add_f32_e32 v72, 1.0, v72
	v_rcp_f32_e32 v72, v72
	v_add_f32_e32 v73, 1.0, v73
	v_add_f32_e32 v79, 1.0, v79
	v_rcp_f32_e32 v73, v73
	v_rcp_f32_e32 v81, v79
	v_pk_mul_f32 v[72:73], v[72:73], v[82:83]
	v_pk_mul_f32 v[74:75], v[80:81], v[74:75]
	s_nop 0
	v_pk_mul_f32 v[72:73], v[72:73], v[74:75]
	s_nop 0
	v_cvt_pk_bf16_f32 v79, v72, v73
	v_add_u32_e32 v72, 0x50000, v88
	global_store_dwordx4 v72, v[76:79], s[60:61] offset:1536 sc1
	s_waitcnt vmcnt(3)
; __device__ __forceinline__ float sigm(float v) { return __builtin_amdgcn_rcpf(1.0f + __builtin_amdgcn_exp2f(-LOG2E * v)); }
; __device__ __forceinline__ float bf_lo(unsigned w) { return __uint_as_float(w << 16); }
; __device__ __forceinline__ float silu_f(float v) { return v * __builtin_amdgcn_rcpf(1.0f + __builtin_amdgcn_exp2f(-1.4426950408889634f * v)); }
; __device__ __forceinline__ float bf_hi(unsigned w) { return __uint_as_float(w & 0xffff0000u); }
; __device__ __forceinline__ unsigned cvt_pk_bf16(float lo, float hi) { f32x2_t v = {lo, hi}; bf16x2_t b = __builtin_convertvector(v, bf16x2_t); return __builtin_bit_cast(unsigned, b); }
;     __device__ __forceinline__ void operator()(const f32x4 (&acc)[2][2][4][2], const Unit& u, int wr, int wc, int fr, int fq) const {
;     ...
; #pragma unroll
;         for (int bj = 0; bj < 2; ++bj) { const unsigned col = col0 + bj * HALF;
; #pragma unroll
;             for (int ai = 0; ai < 2; ++ai) {
;                 u32x4 ygv[4], sgv[4];
; #pragma unroll
;                 for (int m = 0; m < 4; ++m) { const unsigned rl = rl0 + (unsigned)(ai * HALF + m * 16);
;                     ygv[m] = *(const u32x4*)(ygb + (rl * 256u + col) * 2u); sgv[m] = *(const u32x4*)(sgb + (rl * 512u + col) * 2u); }
; #pragma unroll
;                 for (int m = 0; m < 4; ++m) { const unsigned rl = rl0 + (unsigned)(ai * HALF + m * 16);
;                     const u32x4 yg = ygv[m], sg = sgv[m];
;                     const f32x4 v0 = acc[ai][bj][m][0], v1 = acc[ai][bj][m][1];
;                     u32x4 w;
;                     w.x = cvt_pk_bf16(bf_lo(yg.x) * sigm(v0[0]) * silu_f(bf_lo(sg.x)), bf_hi(yg.x) * sigm(v0[1]) * silu_f(bf_hi(sg.x)));
;                     w.y = cvt_pk_bf16(bf_lo(yg.y) * sigm(v0[2]) * silu_f(bf_lo(sg.y)), bf_hi(yg.y) * sigm(v0[3]) * silu_f(bf_hi(sg.y)));
;                     w.z = cvt_pk_bf16(bf_lo(yg.z) * sigm(v1[0]) * silu_f(bf_lo(sg.z)), bf_hi(yg.z) * sigm(v1[1]) * silu_f(bf_hi(sg.z)));
;                     w.w = cvt_pk_bf16(bf_lo(yg.w) * sigm(v1[2]) * silu_f(bf_lo(sg.w)), bf_hi(yg.w) * sigm(v1[3]) * silu_f(bf_hi(sg.w)));
;                     *(u32x4*)(yb + (rl * 1024u + col) * 2u) = w; }
	v_lshlrev_b32_e32 v72, 16, v102
	v_and_b32_e32 v73, 0xffff0000, v102
	v_mul_f32_e32 v74, 0xbfb8aa3b, v72
	v_mul_f32_e32 v75, 0xbfb8aa3b, v73
	v_exp_f32_e32 v74, v74
	v_exp_f32_e32 v75, v75
	v_lshlrev_b32_e32 v76, 16, v98
	v_and_b32_e32 v77, 0xffff0000, v98
	v_add_f32_e32 v74, 1.0, v74
	v_add_f32_e32 v75, 1.0, v75
	v_rcp_f32_e32 v74, v74
	v_rcp_f32_e32 v75, v75
	v_pk_mul_f32 v[68:69], v[68:69], v[76:77]
	v_lshlrev_b32_e32 v76, 16, v99
	v_and_b32_e32 v77, 0xffff0000, v99
	v_pk_mul_f32 v[72:73], v[74:75], v[72:73]
	s_nop 0
	v_pk_mul_f32 v[68:69], v[68:69], v[72:73]
	v_lshlrev_b32_e32 v72, 16, v103
	v_cvt_pk_bf16_f32 v68, v68, v69
	v_mul_f32_e32 v69, 0xbfb8aa3b, v70
	v_exp_f32_e32 v69, v69
	v_and_b32_e32 v73, 0xffff0000, v103
	v_add_f32_e32 v69, 1.0, v69
	v_rcp_f32_e32 v70, v69
	v_mul_f32_e32 v69, 0xbfb8aa3b, v71
	v_exp_f32_e32 v69, v69
	s_nop 0
	v_add_f32_e32 v69, 1.0, v69
	v_rcp_f32_e32 v71, v69
	v_mul_f32_e32 v69, 0xbfb8aa3b, v72
	v_exp_f32_e32 v69, v69
	v_pk_mul_f32 v[70:71], v[70:71], v[76:77]
	v_add_f32_e32 v69, 1.0, v69
	v_rcp_f32_e32 v74, v69
	v_mul_f32_e32 v69, 0xbfb8aa3b, v73
	v_exp_f32_e32 v69, v69
	s_nop 0
	v_add_f32_e32 v69, 1.0, v69
	v_rcp_f32_e32 v75, v69
	s_nop 0
	v_pk_mul_f32 v[72:73], v[74:75], v[72:73]
	s_nop 0
	v_pk_mul_f32 v[70:71], v[70:71], v[72:73]
	v_lshlrev_b32_e32 v74, 16, v100
	v_cvt_pk_bf16_f32 v69, v70, v71
	v_lshlrev_b32_e32 v70, 16, v104
	v_and_b32_e32 v71, 0xffff0000, v104
	v_mul_f32_e32 v72, 0xbfb8aa3b, v70
	v_mul_f32_e32 v73, 0xbfb8aa3b, v71
	v_exp_f32_e32 v72, v72
	v_exp_f32_e32 v73, v73
	v_and_b32_e32 v75, 0xffff0000, v100
	v_pk_mul_f32 v[60:61], v[60:61], v[74:75]
	v_add_f32_e32 v72, 1.0, v72
	v_add_f32_e32 v73, 1.0, v73
	v_rcp_f32_e32 v72, v72
	v_rcp_f32_e32 v73, v73
	v_lshlrev_b32_e32 v74, 16, v101
	v_and_b32_e32 v75, 0xffff0000, v101
	v_pk_mul_f32 v[70:71], v[72:73], v[70:71]
	s_nop 0
	v_pk_mul_f32 v[60:61], v[60:61], v[70:71]
	s_nop 0
	v_cvt_pk_bf16_f32 v70, v60, v61
	v_mul_f32_e32 v60, 0xbfb8aa3b, v62
	v_lshlrev_b32_e32 v62, 16, v105
	v_mul_f32_e32 v71, 0xbfb8aa3b, v62
	v_exp_f32_e32 v71, v71
	v_mul_f32_e32 v61, 0xbfb8aa3b, v63
	v_and_b32_e32 v63, 0xffff0000, v105
	v_exp_f32_e32 v60, v60
	v_add_f32_e32 v71, 1.0, v71
	v_rcp_f32_e32 v72, v71
	v_mul_f32_e32 v71, 0xbfb8aa3b, v63
	v_exp_f32_e32 v61, v61
	v_exp_f32_e32 v71, v71
	v_add_f32_e32 v60, 1.0, v60
	v_rcp_f32_e32 v60, v60
	v_add_f32_e32 v61, 1.0, v61
	v_add_f32_e32 v71, 1.0, v71
	v_rcp_f32_e32 v61, v61
	v_rcp_f32_e32 v73, v71
	v_pk_mul_f32 v[60:61], v[60:61], v[74:75]
	v_pk_mul_f32 v[62:63], v[72:73], v[62:63]
	s_nop 0
	v_pk_mul_f32 v[60:61], v[60:61], v[62:63]
	s_nop 0
	v_cvt_pk_bf16_f32 v71, v60, v61
	v_add_u32_e32 v60, 0x58000, v88
	global_store_dwordx4 v60, v[68:71], s[60:61] offset:1536 sc1
	v_mov_b32_e32 v60, 0x100
	s_nop 0
	v_lshl_add_u32 v98, v175, 1, v60
	v_lshlrev_b32_e32 v60, 9, v174
	v_add_u32_e32 v61, v98, v60
	v_add_u32_e32 v99, v61, v60
	global_load_dwordx4 v[88:91], v61, s[62:63]
	global_load_dwordx4 v[92:95], v99, s[64:65]
	v_add_u32_e32 v61, 0x2000, v60
	v_add_u32_e32 v62, v61, v98
	v_add_u32_e32 v61, v62, v61
	global_load_dwordx4 v[80:83], v62, s[62:63]
	global_load_dwordx4 v[84:87], v61, s[64:65]
	v_add_u32_e32 v61, 0x4000, v60
	v_add_u32_e32 v68, 0x6000, v60
	v_add_u32_e32 v62, v61, v98
	v_add_u32_e32 v69, v68, v98
	v_add_u32_e32 v61, v62, v61
	v_add_u32_e32 v68, v69, v68
	global_load_dwordx4 v[72:75], v62, s[62:63]
	global_load_dwordx4 v[76:79], v61, s[64:65]
	s_waitcnt vmcnt(5)
	v_lshlrev_b32_e32 v104, 16, v88
	s_waitcnt vmcnt(4)
	v_lshlrev_b32_e32 v100, 16, v92
	v_and_b32_e32 v101, 0xffff0000, v92
	v_mul_f32_e32 v92, 0xbfb8aa3b, v100
	v_and_b32_e32 v105, 0xffff0000, v88
	v_mul_f32_e32 v88, 0xbfb8aa3b, v101
	v_exp_f32_e32 v92, v92
	v_exp_f32_e32 v88, v88
	v_pk_mul_f32 v[64:65], v[64:65], v[104:105]
	global_load_dwordx4 v[60:63], v69, s[62:63]
	v_add_f32_e32 v92, 1.0, v92
	v_add_f32_e32 v88, 1.0, v88
	v_rcp_f32_e32 v102, v92
	v_rcp_f32_e32 v103, v88
	v_lshlrev_b32_e32 v92, 16, v93
	v_and_b32_e32 v93, 0xffff0000, v93
	global_load_dwordx4 v[68:71], v68, s[64:65]
	v_pk_mul_f32 v[100:101], v[102:103], v[100:101]
	s_nop 0
	v_pk_mul_f32 v[64:65], v[64:65], v[100:101]
	v_lshlrev_b32_e32 v100, 16, v89
	v_cvt_pk_bf16_f32 v64, v64, v65
	v_mul_f32_e32 v65, 0xbfb8aa3b, v66
	v_exp_f32_e32 v65, v65
	v_and_b32_e32 v101, 0xffff0000, v89
	v_add_f32_e32 v65, 1.0, v65
	v_rcp_f32_e32 v66, v65
	v_mul_f32_e32 v65, 0xbfb8aa3b, v67
	v_exp_f32_e32 v65, v65
	s_nop 0
	v_add_f32_e32 v65, 1.0, v65
	v_rcp_f32_e32 v67, v65
	v_mul_f32_e32 v65, 0xbfb8aa3b, v92
	v_exp_f32_e32 v65, v65
	v_pk_mul_f32 v[66:67], v[66:67], v[100:101]
	v_add_f32_e32 v65, 1.0, v65
	v_rcp_f32_e32 v88, v65
	v_mul_f32_e32 v65, 0xbfb8aa3b, v93
	v_exp_f32_e32 v65, v65
	s_nop 0
	v_add_f32_e32 v65, 1.0, v65
	v_rcp_f32_e32 v89, v65
	s_nop 0
	v_pk_mul_f32 v[88:89], v[88:89], v[92:93]
	s_nop 0
	v_pk_mul_f32 v[66:67], v[66:67], v[88:89]
	v_lshlrev_b32_e32 v92, 16, v90
	v_cvt_pk_bf16_f32 v65, v66, v67
	v_lshlrev_b32_e32 v66, 16, v94
	v_and_b32_e32 v67, 0xffff0000, v94
	v_mul_f32_e32 v88, 0xbfb8aa3b, v66
	v_mul_f32_e32 v89, 0xbfb8aa3b, v67
	v_exp_f32_e32 v88, v88
	v_exp_f32_e32 v89, v89
	v_and_b32_e32 v93, 0xffff0000, v90
	v_pk_mul_f32 v[56:57], v[56:57], v[92:93]
	v_add_f32_e32 v88, 1.0, v88
	v_add_f32_e32 v89, 1.0, v89
	v_rcp_f32_e32 v88, v88
	v_rcp_f32_e32 v89, v89
	v_lshlrev_b32_e32 v90, 16, v91
	v_and_b32_e32 v91, 0xffff0000, v91
	v_pk_mul_f32 v[66:67], v[88:89], v[66:67]
	s_nop 0
	v_pk_mul_f32 v[56:57], v[56:57], v[66:67]
	s_nop 0
	v_cvt_pk_bf16_f32 v66, v56, v57
	v_mul_f32_e32 v56, 0xbfb8aa3b, v58
	v_lshlrev_b32_e32 v58, 16, v95
	v_mul_f32_e32 v67, 0xbfb8aa3b, v58
	v_exp_f32_e32 v67, v67
	v_mul_f32_e32 v57, 0xbfb8aa3b, v59
	v_and_b32_e32 v59, 0xffff0000, v95
	v_exp_f32_e32 v56, v56
	v_add_f32_e32 v67, 1.0, v67
	v_rcp_f32_e32 v88, v67
	v_mul_f32_e32 v67, 0xbfb8aa3b, v59
	v_exp_f32_e32 v57, v57
	v_exp_f32_e32 v67, v67
	v_add_f32_e32 v56, 1.0, v56
	v_rcp_f32_e32 v56, v56
	v_add_f32_e32 v57, 1.0, v57
	v_add_f32_e32 v67, 1.0, v67
	v_rcp_f32_e32 v57, v57
	v_rcp_f32_e32 v89, v67
	v_pk_mul_f32 v[56:57], v[56:57], v[90:91]
	v_pk_mul_f32 v[58:59], v[88:89], v[58:59]
	s_nop 0
	v_pk_mul_f32 v[56:57], v[56:57], v[58:59]
	s_waitcnt vmcnt(4)
; __device__ __forceinline__ float sigm(float v) { return __builtin_amdgcn_rcpf(1.0f + __builtin_amdgcn_exp2f(-LOG2E * v)); }
; __device__ __forceinline__ float bf_lo(unsigned w) { return __uint_as_float(w << 16); }
; __device__ __forceinline__ float silu_f(float v) { return v * __builtin_amdgcn_rcpf(1.0f + __builtin_amdgcn_exp2f(-1.4426950408889634f * v)); }
; __device__ __forceinline__ float bf_hi(unsigned w) { return __uint_as_float(w & 0xffff0000u); }
; __device__ __forceinline__ unsigned cvt_pk_bf16(float lo, float hi) { f32x2_t v = {lo, hi}; bf16x2_t b = __builtin_convertvector(v, bf16x2_t); return __builtin_bit_cast(unsigned, b); }
;     __device__ __forceinline__ void operator()(const f32x4 (&acc)[2][2][4][2], const Unit& u, int wr, int wc, int fr, int fq) const {
;     ...
;                 for (int m = 0; m < 4; ++m) { const unsigned rl = rl0 + (unsigned)(ai * HALF + m * 16);
;                     ygv[m] = *(const u32x4*)(ygb + (rl * 256u + col) * 2u); sgv[m] = *(const u32x4*)(sgb + (rl * 512u + col) * 2u); }
; #pragma unroll
;                 for (int m = 0; m < 4; ++m) { const unsigned rl = rl0 + (unsigned)(ai * HALF + m * 16);
;                     const u32x4 yg = ygv[m], sg = sgv[m];
;                     const f32x4 v0 = acc[ai][bj][m][0], v1 = acc[ai][bj][m][1];
;                     u32x4 w;
;                     w.x = cvt_pk_bf16(bf_lo(yg.x) * sigm(v0[0]) * silu_f(bf_lo(sg.x)), bf_hi(yg.x) * sigm(v0[1]) * silu_f(bf_hi(sg.x)));
;                     w.y = cvt_pk_bf16(bf_lo(yg.y) * sigm(v0[2]) * silu_f(bf_lo(sg.y)), bf_hi(yg.y) * sigm(v0[3]) * silu_f(bf_hi(sg.y)));
;                     w.z = cvt_pk_bf16(bf_lo(yg.z) * sigm(v1[0]) * silu_f(bf_lo(sg.z)), bf_hi(yg.z) * sigm(v1[1]) * silu_f(bf_hi(sg.z)));
;                     w.w = cvt_pk_bf16(bf_lo(yg.w) * sigm(v1[2]) * silu_f(bf_lo(sg.w)), bf_hi(yg.w) * sigm(v1[3]) * silu_f(bf_hi(sg.w)));
;                     *(u32x4*)(yb + (rl * 1024u + col) * 2u) = w; }
	v_lshlrev_b32_e32 v58, 16, v84
	v_cvt_pk_bf16_f32 v67, v56, v57
	v_mul_f32_e32 v57, 0xbfb8aa3b, v58
	v_exp_f32_e32 v57, v57
	v_lshl_add_u32 v56, v174, 10, v99
	v_and_b32_e32 v59, 0xffff0000, v84
	global_store_dwordx4 v56, v[64:67], s[60:61] offset:1536 sc1
	v_add_f32_e32 v57, 1.0, v57
	s_nop 0
	v_rcp_f32_e32 v64, v57
	v_mul_f32_e32 v57, 0xbfb8aa3b, v59
	v_exp_f32_e32 v57, v57
	v_lshlrev_b32_e32 v66, 16, v80
	v_and_b32_e32 v67, 0xffff0000, v80
	v_pk_mul_f32 v[52:53], v[52:53], v[66:67]
	v_add_f32_e32 v57, 1.0, v57
	v_rcp_f32_e32 v65, v57
	v_lshlrev_b32_e32 v66, 16, v81
	v_and_b32_e32 v67, 0xffff0000, v81
	v_pk_mul_f32 v[58:59], v[64:65], v[58:59]
	s_nop 0
	v_pk_mul_f32 v[52:53], v[52:53], v[58:59]
	v_lshlrev_b32_e32 v58, 16, v85
	v_cvt_pk_bf16_f32 v52, v52, v53
	v_mul_f32_e32 v53, 0xbfb8aa3b, v54
	v_exp_f32_e32 v53, v53
	v_and_b32_e32 v59, 0xffff0000, v85
	v_add_f32_e32 v53, 1.0, v53
	v_rcp_f32_e32 v54, v53
	v_mul_f32_e32 v53, 0xbfb8aa3b, v55
	v_exp_f32_e32 v53, v53
	s_nop 0
	v_add_f32_e32 v53, 1.0, v53
	v_rcp_f32_e32 v55, v53
	v_mul_f32_e32 v53, 0xbfb8aa3b, v58
	v_exp_f32_e32 v53, v53
	v_pk_mul_f32 v[54:55], v[54:55], v[66:67]
	v_add_f32_e32 v53, 1.0, v53
	v_rcp_f32_e32 v64, v53
	v_mul_f32_e32 v53, 0xbfb8aa3b, v59
	v_exp_f32_e32 v53, v53
	s_nop 0
	v_add_f32_e32 v53, 1.0, v53
	v_rcp_f32_e32 v65, v53
	s_nop 0
	v_pk_mul_f32 v[58:59], v[64:65], v[58:59]
	s_nop 0
	v_pk_mul_f32 v[54:55], v[54:55], v[58:59]
	v_lshlrev_b32_e32 v64, 16, v82
	v_cvt_pk_bf16_f32 v53, v54, v55
	v_lshlrev_b32_e32 v54, 16, v86
	v_mul_f32_e32 v57, 0xbfb8aa3b, v54
	v_exp_f32_e32 v57, v57
	v_and_b32_e32 v55, 0xffff0000, v86
	v_and_b32_e32 v65, 0xffff0000, v82
	v_pk_mul_f32 v[48:49], v[48:49], v[64:65]
	v_add_f32_e32 v57, 1.0, v57
	v_rcp_f32_e32 v58, v57
	v_mul_f32_e32 v57, 0xbfb8aa3b, v55
	v_exp_f32_e32 v57, v57
	v_lshlrev_b32_e32 v64, 16, v83
	v_and_b32_e32 v65, 0xffff0000, v83
	v_add_f32_e32 v57, 1.0, v57
	v_rcp_f32_e32 v59, v57
	s_nop 0
	v_pk_mul_f32 v[54:55], v[58:59], v[54:55]
	s_nop 0
	v_pk_mul_f32 v[48:49], v[48:49], v[54:55]
	s_nop 0
	v_cvt_pk_bf16_f32 v54, v48, v49
	v_mul_f32_e32 v48, 0xbfb8aa3b, v50
	v_lshlrev_b32_e32 v50, 16, v87
	v_mul_f32_e32 v55, 0xbfb8aa3b, v50
	v_exp_f32_e32 v55, v55
	v_mul_f32_e32 v49, 0xbfb8aa3b, v51
	v_and_b32_e32 v51, 0xffff0000, v87
	v_exp_f32_e32 v48, v48
	v_add_f32_e32 v55, 1.0, v55
	v_rcp_f32_e32 v58, v55
	v_mul_f32_e32 v55, 0xbfb8aa3b, v51
	v_exp_f32_e32 v49, v49
	v_exp_f32_e32 v55, v55
	v_add_f32_e32 v48, 1.0, v48
	v_rcp_f32_e32 v48, v48
	v_add_f32_e32 v49, 1.0, v49
	v_add_f32_e32 v55, 1.0, v55
	v_rcp_f32_e32 v49, v49
	v_rcp_f32_e32 v59, v55
	v_pk_mul_f32 v[48:49], v[48:49], v[64:65]
	v_pk_mul_f32 v[50:51], v[58:59], v[50:51]
	s_nop 0
	v_pk_mul_f32 v[48:49], v[48:49], v[50:51]
	s_nop 0
	v_cvt_pk_bf16_f32 v55, v48, v49
	v_add_u32_e32 v48, 0x8000, v56
	global_store_dwordx4 v48, v[52:55], s[60:61] offset:1536 sc1
	s_waitcnt vmcnt(4)
	v_lshlrev_b32_e32 v48, 16, v76
	v_and_b32_e32 v49, 0xffff0000, v76
	v_mul_f32_e32 v50, 0xbfb8aa3b, v48
	v_mul_f32_e32 v51, 0xbfb8aa3b, v49
	v_exp_f32_e32 v50, v50
	v_exp_f32_e32 v51, v51
	v_lshlrev_b32_e32 v52, 16, v72
	v_and_b32_e32 v53, 0xffff0000, v72
	v_add_f32_e32 v50, 1.0, v50
	v_add_f32_e32 v51, 1.0, v51
	v_rcp_f32_e32 v50, v50
	v_rcp_f32_e32 v51, v51
	v_pk_mul_f32 v[44:45], v[44:45], v[52:53]
	v_lshlrev_b32_e32 v52, 16, v73
	v_and_b32_e32 v53, 0xffff0000, v73
	v_pk_mul_f32 v[48:49], v[50:51], v[48:49]
	s_nop 0
	v_pk_mul_f32 v[44:45], v[44:45], v[48:49]
	v_lshlrev_b32_e32 v48, 16, v77
	v_cvt_pk_bf16_f32 v44, v44, v45
	v_mul_f32_e32 v45, 0xbfb8aa3b, v46
	v_exp_f32_e32 v45, v45
	v_and_b32_e32 v49, 0xffff0000, v77
	v_add_f32_e32 v45, 1.0, v45
	v_rcp_f32_e32 v46, v45
	v_mul_f32_e32 v45, 0xbfb8aa3b, v47
	v_exp_f32_e32 v45, v45
	s_nop 0
	v_add_f32_e32 v45, 1.0, v45
	v_rcp_f32_e32 v47, v45
	v_mul_f32_e32 v45, 0xbfb8aa3b, v48
	v_exp_f32_e32 v45, v45
	v_pk_mul_f32 v[46:47], v[46:47], v[52:53]
	v_add_f32_e32 v45, 1.0, v45
	v_rcp_f32_e32 v50, v45
	v_mul_f32_e32 v45, 0xbfb8aa3b, v49
	v_exp_f32_e32 v45, v45
	s_nop 0
	v_add_f32_e32 v45, 1.0, v45
	v_rcp_f32_e32 v51, v45
	s_nop 0
	v_pk_mul_f32 v[48:49], v[50:51], v[48:49]
	s_nop 0
	v_pk_mul_f32 v[46:47], v[46:47], v[48:49]
	v_lshlrev_b32_e32 v50, 16, v74
	v_cvt_pk_bf16_f32 v45, v46, v47
	v_lshlrev_b32_e32 v46, 16, v78
	v_and_b32_e32 v47, 0xffff0000, v78
	v_mul_f32_e32 v48, 0xbfb8aa3b, v46
	v_mul_f32_e32 v49, 0xbfb8aa3b, v47
	v_exp_f32_e32 v48, v48
	v_exp_f32_e32 v49, v49
	v_and_b32_e32 v51, 0xffff0000, v74
	v_pk_mul_f32 v[40:41], v[40:41], v[50:51]
	v_add_f32_e32 v48, 1.0, v48
	v_add_f32_e32 v49, 1.0, v49
	v_rcp_f32_e32 v48, v48
	v_rcp_f32_e32 v49, v49
	v_lshlrev_b32_e32 v50, 16, v75
	v_and_b32_e32 v51, 0xffff0000, v75
	v_pk_mul_f32 v[46:47], v[48:49], v[46:47]
	s_nop 0
	v_pk_mul_f32 v[40:41], v[40:41], v[46:47]
	s_nop 0
	v_cvt_pk_bf16_f32 v46, v40, v41
	v_mul_f32_e32 v40, 0xbfb8aa3b, v42
	v_lshlrev_b32_e32 v42, 16, v79
	v_mul_f32_e32 v47, 0xbfb8aa3b, v42
	v_exp_f32_e32 v47, v47
	v_mul_f32_e32 v41, 0xbfb8aa3b, v43
	v_and_b32_e32 v43, 0xffff0000, v79
	v_exp_f32_e32 v40, v40
	v_add_f32_e32 v47, 1.0, v47
	v_rcp_f32_e32 v48, v47
	v_mul_f32_e32 v47, 0xbfb8aa3b, v43
	v_exp_f32_e32 v41, v41
	v_exp_f32_e32 v47, v47
	v_add_f32_e32 v40, 1.0, v40
	v_rcp_f32_e32 v40, v40
	v_add_f32_e32 v41, 1.0, v41
	v_add_f32_e32 v47, 1.0, v47
	v_rcp_f32_e32 v41, v41
	v_rcp_f32_e32 v49, v47
	v_pk_mul_f32 v[40:41], v[40:41], v[50:51]
	v_pk_mul_f32 v[42:43], v[48:49], v[42:43]
	s_nop 0
	v_pk_mul_f32 v[40:41], v[40:41], v[42:43]
	s_nop 0
	v_cvt_pk_bf16_f32 v47, v40, v41
	v_add_u32_e32 v40, 0x10000, v56
	global_store_dwordx4 v40, v[44:47], s[60:61] offset:1536 sc1
	s_waitcnt vmcnt(3)
; __device__ __forceinline__ float sigm(float v) { return __builtin_amdgcn_rcpf(1.0f + __builtin_amdgcn_exp2f(-LOG2E * v)); }
; __device__ __forceinline__ float bf_lo(unsigned w) { return __uint_as_float(w << 16); }
; __device__ __forceinline__ float silu_f(float v) { return v * __builtin_amdgcn_rcpf(1.0f + __builtin_amdgcn_exp2f(-1.4426950408889634f * v)); }
; __device__ __forceinline__ float bf_hi(unsigned w) { return __uint_as_float(w & 0xffff0000u); }
; __device__ __forceinline__ unsigned cvt_pk_bf16(float lo, float hi) { f32x2_t v = {lo, hi}; bf16x2_t b = __builtin_convertvector(v, bf16x2_t); return __builtin_bit_cast(unsigned, b); }
;     __device__ __forceinline__ void operator()(const f32x4 (&acc)[2][2][4][2], const Unit& u, int wr, int wc, int fr, int fq) const {
;     ...
; #pragma unroll
;         for (int bj = 0; bj < 2; ++bj) { const unsigned col = col0 + bj * HALF;
; #pragma unroll
;             for (int ai = 0; ai < 2; ++ai) {
;                 u32x4 ygv[4], sgv[4];
; #pragma unroll
;                 for (int m = 0; m < 4; ++m) { const unsigned rl = rl0 + (unsigned)(ai * HALF + m * 16);
;                     ygv[m] = *(const u32x4*)(ygb + (rl * 256u + col) * 2u); sgv[m] = *(const u32x4*)(sgb + (rl * 512u + col) * 2u); }
; #pragma unroll
;                 for (int m = 0; m < 4; ++m) { const unsigned rl = rl0 + (unsigned)(ai * HALF + m * 16);
;                     const u32x4 yg = ygv[m], sg = sgv[m];
;                     const f32x4 v0 = acc[ai][bj][m][0], v1 = acc[ai][bj][m][1];
;                     u32x4 w;
;                     w.x = cvt_pk_bf16(bf_lo(yg.x) * sigm(v0[0]) * silu_f(bf_lo(sg.x)), bf_hi(yg.x) * sigm(v0[1]) * silu_f(bf_hi(sg.x)));
;                     w.y = cvt_pk_bf16(bf_lo(yg.y) * sigm(v0[2]) * silu_f(bf_lo(sg.y)), bf_hi(yg.y) * sigm(v0[3]) * silu_f(bf_hi(sg.y)));
;                     w.z = cvt_pk_bf16(bf_lo(yg.z) * sigm(v1[0]) * silu_f(bf_lo(sg.z)), bf_hi(yg.z) * sigm(v1[1]) * silu_f(bf_hi(sg.z)));
;                     w.w = cvt_pk_bf16(bf_lo(yg.w) * sigm(v1[2]) * silu_f(bf_lo(sg.w)), bf_hi(yg.w) * sigm(v1[3]) * silu_f(bf_hi(sg.w)));
;                     *(u32x4*)(yb + (rl * 1024u + col) * 2u) = w; }
	v_lshlrev_b32_e32 v40, 16, v68
	v_and_b32_e32 v41, 0xffff0000, v68
	v_mul_f32_e32 v42, 0xbfb8aa3b, v40
	v_mul_f32_e32 v43, 0xbfb8aa3b, v41
	v_exp_f32_e32 v42, v42
	v_exp_f32_e32 v43, v43
	v_lshlrev_b32_e32 v44, 16, v60
	v_and_b32_e32 v45, 0xffff0000, v60
	v_add_f32_e32 v42, 1.0, v42
	v_add_f32_e32 v43, 1.0, v43
	v_rcp_f32_e32 v42, v42
	v_rcp_f32_e32 v43, v43
	v_pk_mul_f32 v[36:37], v[36:37], v[44:45]
	v_lshlrev_b32_e32 v44, 16, v61
	v_and_b32_e32 v45, 0xffff0000, v61
	v_pk_mul_f32 v[40:41], v[42:43], v[40:41]
	s_nop 0
	v_pk_mul_f32 v[36:37], v[36:37], v[40:41]
	v_lshlrev_b32_e32 v40, 16, v69
	v_cvt_pk_bf16_f32 v36, v36, v37
	v_mul_f32_e32 v37, 0xbfb8aa3b, v38
	v_exp_f32_e32 v37, v37
	v_and_b32_e32 v41, 0xffff0000, v69
	v_add_f32_e32 v37, 1.0, v37
	v_rcp_f32_e32 v38, v37
	v_mul_f32_e32 v37, 0xbfb8aa3b, v39
	v_exp_f32_e32 v37, v37
	s_nop 0
	v_add_f32_e32 v37, 1.0, v37
	v_rcp_f32_e32 v39, v37
	v_mul_f32_e32 v37, 0xbfb8aa3b, v40
	v_exp_f32_e32 v37, v37
	v_pk_mul_f32 v[38:39], v[38:39], v[44:45]
	v_add_f32_e32 v37, 1.0, v37
	v_rcp_f32_e32 v42, v37
	v_mul_f32_e32 v37, 0xbfb8aa3b, v41
	v_exp_f32_e32 v37, v37
	s_nop 0
	v_add_f32_e32 v37, 1.0, v37
	v_rcp_f32_e32 v43, v37
	s_nop 0
	v_pk_mul_f32 v[40:41], v[42:43], v[40:41]
	s_nop 0
	v_pk_mul_f32 v[38:39], v[38:39], v[40:41]
	v_lshlrev_b32_e32 v42, 16, v62
	v_cvt_pk_bf16_f32 v37, v38, v39
	v_lshlrev_b32_e32 v38, 16, v70
	v_and_b32_e32 v39, 0xffff0000, v70
	v_mul_f32_e32 v40, 0xbfb8aa3b, v38
	v_mul_f32_e32 v41, 0xbfb8aa3b, v39
	v_exp_f32_e32 v40, v40
	v_exp_f32_e32 v41, v41
	v_and_b32_e32 v43, 0xffff0000, v62
	v_pk_mul_f32 v[32:33], v[32:33], v[42:43]
	v_add_f32_e32 v40, 1.0, v40
	v_add_f32_e32 v41, 1.0, v41
	v_rcp_f32_e32 v40, v40
	v_rcp_f32_e32 v41, v41
	v_lshlrev_b32_e32 v42, 16, v63
	v_and_b32_e32 v43, 0xffff0000, v63
	v_pk_mul_f32 v[38:39], v[40:41], v[38:39]
	s_nop 0
	v_pk_mul_f32 v[32:33], v[32:33], v[38:39]
	s_nop 0
	v_cvt_pk_bf16_f32 v38, v32, v33
	v_mul_f32_e32 v32, 0xbfb8aa3b, v34
	v_lshlrev_b32_e32 v34, 16, v71
	v_mul_f32_e32 v39, 0xbfb8aa3b, v34
	v_exp_f32_e32 v39, v39
	v_mul_f32_e32 v33, 0xbfb8aa3b, v35
	v_and_b32_e32 v35, 0xffff0000, v71
	v_exp_f32_e32 v32, v32
	v_add_f32_e32 v39, 1.0, v39
	v_rcp_f32_e32 v40, v39
	v_mul_f32_e32 v39, 0xbfb8aa3b, v35
	v_exp_f32_e32 v33, v33
	v_exp_f32_e32 v39, v39
	v_add_f32_e32 v32, 1.0, v32
	v_rcp_f32_e32 v32, v32
	v_add_f32_e32 v33, 1.0, v33
	v_add_f32_e32 v39, 1.0, v39
	v_rcp_f32_e32 v33, v33
	v_rcp_f32_e32 v41, v39
	v_pk_mul_f32 v[32:33], v[32:33], v[42:43]
	v_pk_mul_f32 v[34:35], v[40:41], v[34:35]
	s_nop 0
	v_pk_mul_f32 v[32:33], v[32:33], v[34:35]
	s_nop 0
	v_cvt_pk_bf16_f32 v39, v32, v33
	v_add_u32_e32 v32, 0x18000, v56
	global_store_dwordx4 v32, v[36:39], s[60:61] offset:1536 sc1
	s_nop 0
	v_lshlrev_b32_e32 v32, 9, v174
	v_add_u32_e32 v33, 0x10000, v32
	v_add_u32_e32 v34, v33, v98
	v_add_u32_e32 v33, v34, v33
	global_load_dwordx4 v[56:59], v34, s[62:63]
	global_load_dwordx4 v[60:63], v33, s[64:65]
	v_add_u32_e32 v33, 0x12000, v32
	v_add_u32_e32 v34, v33, v98
	v_add_u32_e32 v33, v34, v33
	global_load_dwordx4 v[48:51], v34, s[62:63]
	global_load_dwordx4 v[52:55], v33, s[64:65]
	v_add_u32_e32 v33, 0x14000, v32
	v_add_u32_e32 v36, 0x16000, v32
	v_add_u32_e32 v34, v33, v98
	v_add_u32_e32 v37, v36, v98
	v_add_u32_e32 v33, v34, v33
	v_add_u32_e32 v36, v37, v36
	global_load_dwordx4 v[40:43], v34, s[62:63]
	global_load_dwordx4 v[44:47], v33, s[64:65]
	s_waitcnt vmcnt(5)
	v_lshlrev_b32_e32 v68, 16, v56
	s_waitcnt vmcnt(4)
	v_lshlrev_b32_e32 v64, 16, v60
	v_and_b32_e32 v65, 0xffff0000, v60
	v_mul_f32_e32 v60, 0xbfb8aa3b, v64
	v_and_b32_e32 v69, 0xffff0000, v56
	v_mul_f32_e32 v56, 0xbfb8aa3b, v65
	v_exp_f32_e32 v60, v60
	v_exp_f32_e32 v56, v56
	v_pk_mul_f32 v[28:29], v[28:29], v[68:69]
	global_load_dwordx4 v[32:35], v37, s[62:63]
	v_add_f32_e32 v60, 1.0, v60
	v_add_f32_e32 v56, 1.0, v56
	v_rcp_f32_e32 v66, v60
	v_rcp_f32_e32 v67, v56
	v_lshlrev_b32_e32 v60, 16, v61
	v_and_b32_e32 v61, 0xffff0000, v61
	global_load_dwordx4 v[36:39], v36, s[64:65]
	v_pk_mul_f32 v[64:65], v[66:67], v[64:65]
	s_nop 0
	v_pk_mul_f32 v[28:29], v[28:29], v[64:65]
	v_lshlrev_b32_e32 v64, 16, v57
	v_cvt_pk_bf16_f32 v28, v28, v29
	v_mul_f32_e32 v29, 0xbfb8aa3b, v30
	v_exp_f32_e32 v29, v29
	v_and_b32_e32 v65, 0xffff0000, v57
	v_add_f32_e32 v29, 1.0, v29
	v_rcp_f32_e32 v30, v29
	v_mul_f32_e32 v29, 0xbfb8aa3b, v31
	v_exp_f32_e32 v29, v29
	s_nop 0
	v_add_f32_e32 v29, 1.0, v29
	v_rcp_f32_e32 v31, v29
	v_mul_f32_e32 v29, 0xbfb8aa3b, v60
	v_exp_f32_e32 v29, v29
	v_pk_mul_f32 v[30:31], v[30:31], v[64:65]
	v_add_f32_e32 v29, 1.0, v29
	v_rcp_f32_e32 v56, v29
	v_mul_f32_e32 v29, 0xbfb8aa3b, v61
	v_exp_f32_e32 v29, v29
	s_nop 0
	v_add_f32_e32 v29, 1.0, v29
	v_rcp_f32_e32 v57, v29
	s_nop 0
	v_pk_mul_f32 v[56:57], v[56:57], v[60:61]
	s_nop 0
	v_pk_mul_f32 v[30:31], v[30:31], v[56:57]
	v_lshlrev_b32_e32 v60, 16, v58
	v_cvt_pk_bf16_f32 v29, v30, v31
	v_lshlrev_b32_e32 v30, 16, v62
	v_and_b32_e32 v31, 0xffff0000, v62
	v_mul_f32_e32 v56, 0xbfb8aa3b, v30
	v_mul_f32_e32 v57, 0xbfb8aa3b, v31
	v_exp_f32_e32 v56, v56
	v_exp_f32_e32 v57, v57
	v_and_b32_e32 v61, 0xffff0000, v58
	v_pk_mul_f32 v[24:25], v[24:25], v[60:61]
	v_add_f32_e32 v56, 1.0, v56
	v_add_f32_e32 v57, 1.0, v57
	v_rcp_f32_e32 v56, v56
	v_rcp_f32_e32 v57, v57
	v_lshlrev_b32_e32 v58, 16, v59
	v_and_b32_e32 v59, 0xffff0000, v59
	v_pk_mul_f32 v[30:31], v[56:57], v[30:31]
	s_nop 0
	v_pk_mul_f32 v[24:25], v[24:25], v[30:31]
	s_nop 0
	v_cvt_pk_bf16_f32 v30, v24, v25
	v_mul_f32_e32 v24, 0xbfb8aa3b, v26
	v_lshlrev_b32_e32 v26, 16, v63
	v_mul_f32_e32 v31, 0xbfb8aa3b, v26
	v_exp_f32_e32 v31, v31
	v_mul_f32_e32 v25, 0xbfb8aa3b, v27
	v_and_b32_e32 v27, 0xffff0000, v63
	v_exp_f32_e32 v24, v24
	v_add_f32_e32 v31, 1.0, v31
	v_rcp_f32_e32 v56, v31
	v_mul_f32_e32 v31, 0xbfb8aa3b, v27
	v_exp_f32_e32 v25, v25
	v_exp_f32_e32 v31, v31
	v_add_f32_e32 v24, 1.0, v24
	v_rcp_f32_e32 v24, v24
	v_add_f32_e32 v25, 1.0, v25
	v_add_f32_e32 v31, 1.0, v31
	v_rcp_f32_e32 v25, v25
	v_rcp_f32_e32 v57, v31
	v_pk_mul_f32 v[24:25], v[24:25], v[58:59]
	v_pk_mul_f32 v[26:27], v[56:57], v[26:27]
	s_nop 0
	v_pk_mul_f32 v[24:25], v[24:25], v[26:27]
	s_waitcnt vmcnt(4)
; __device__ __forceinline__ float sigm(float v) { return __builtin_amdgcn_rcpf(1.0f + __builtin_amdgcn_exp2f(-LOG2E * v)); }
; __device__ __forceinline__ float bf_lo(unsigned w) { return __uint_as_float(w << 16); }
; __device__ __forceinline__ float silu_f(float v) { return v * __builtin_amdgcn_rcpf(1.0f + __builtin_amdgcn_exp2f(-1.4426950408889634f * v)); }
; __device__ __forceinline__ float bf_hi(unsigned w) { return __uint_as_float(w & 0xffff0000u); }
; __device__ __forceinline__ unsigned cvt_pk_bf16(float lo, float hi) { f32x2_t v = {lo, hi}; bf16x2_t b = __builtin_convertvector(v, bf16x2_t); return __builtin_bit_cast(unsigned, b); }
;     __device__ __forceinline__ void operator()(const f32x4 (&acc)[2][2][4][2], const Unit& u, int wr, int wc, int fr, int fq) const {
;     ...
;                 for (int m = 0; m < 4; ++m) { const unsigned rl = rl0 + (unsigned)(ai * HALF + m * 16);
;                     ygv[m] = *(const u32x4*)(ygb + (rl * 256u + col) * 2u); sgv[m] = *(const u32x4*)(sgb + (rl * 512u + col) * 2u); }
; #pragma unroll
;                 for (int m = 0; m < 4; ++m) { const unsigned rl = rl0 + (unsigned)(ai * HALF + m * 16);
;                     const u32x4 yg = ygv[m], sg = sgv[m];
;                     const f32x4 v0 = acc[ai][bj][m][0], v1 = acc[ai][bj][m][1];
;                     u32x4 w;
;                     w.x = cvt_pk_bf16(bf_lo(yg.x) * sigm(v0[0]) * silu_f(bf_lo(sg.x)), bf_hi(yg.x) * sigm(v0[1]) * silu_f(bf_hi(sg.x)));
;                     w.y = cvt_pk_bf16(bf_lo(yg.y) * sigm(v0[2]) * silu_f(bf_lo(sg.y)), bf_hi(yg.y) * sigm(v0[3]) * silu_f(bf_hi(sg.y)));
;                     w.z = cvt_pk_bf16(bf_lo(yg.z) * sigm(v1[0]) * silu_f(bf_lo(sg.z)), bf_hi(yg.z) * sigm(v1[1]) * silu_f(bf_hi(sg.z)));
;                     w.w = cvt_pk_bf16(bf_lo(yg.w) * sigm(v1[2]) * silu_f(bf_lo(sg.w)), bf_hi(yg.w) * sigm(v1[3]) * silu_f(bf_hi(sg.w)));
;                     *(u32x4*)(yb + (rl * 1024u + col) * 2u) = w; }
	v_lshlrev_b32_e32 v26, 16, v52
	v_cvt_pk_bf16_f32 v31, v24, v25
	v_lshl_add_u32 v24, v174, 11, v98
	v_add_u32_e32 v25, 0x40000, v24
	global_store_dwordx4 v25, v[28:31], s[60:61] offset:1536 sc1
	v_mul_f32_e32 v25, 0xbfb8aa3b, v26
	v_exp_f32_e32 v25, v25
	v_and_b32_e32 v27, 0xffff0000, v52
	v_lshlrev_b32_e32 v30, 16, v48
	v_and_b32_e32 v31, 0xffff0000, v48
	v_add_f32_e32 v25, 1.0, v25
	v_rcp_f32_e32 v28, v25
	v_mul_f32_e32 v25, 0xbfb8aa3b, v27
	v_exp_f32_e32 v25, v25
	v_pk_mul_f32 v[20:21], v[20:21], v[30:31]
	v_lshlrev_b32_e32 v30, 16, v49
	v_and_b32_e32 v31, 0xffff0000, v49
	v_add_f32_e32 v25, 1.0, v25
	v_rcp_f32_e32 v29, v25
	s_nop 0
	v_pk_mul_f32 v[26:27], v[28:29], v[26:27]
	s_nop 0
	v_pk_mul_f32 v[20:21], v[20:21], v[26:27]
	v_lshlrev_b32_e32 v26, 16, v53
	v_cvt_pk_bf16_f32 v20, v20, v21
	v_mul_f32_e32 v21, 0xbfb8aa3b, v22
	v_exp_f32_e32 v21, v21
	v_and_b32_e32 v27, 0xffff0000, v53
	v_add_f32_e32 v21, 1.0, v21
	v_rcp_f32_e32 v22, v21
	v_mul_f32_e32 v21, 0xbfb8aa3b, v23
	v_exp_f32_e32 v21, v21
	s_nop 0
	v_add_f32_e32 v21, 1.0, v21
	v_rcp_f32_e32 v23, v21
	v_mul_f32_e32 v21, 0xbfb8aa3b, v26
	v_exp_f32_e32 v21, v21
	v_pk_mul_f32 v[22:23], v[22:23], v[30:31]
	v_add_f32_e32 v21, 1.0, v21
	v_rcp_f32_e32 v28, v21
	v_mul_f32_e32 v21, 0xbfb8aa3b, v27
	v_exp_f32_e32 v21, v21
	s_nop 0
	v_add_f32_e32 v21, 1.0, v21
	v_rcp_f32_e32 v29, v21
	s_nop 0
	v_pk_mul_f32 v[26:27], v[28:29], v[26:27]
	s_nop 0
	v_pk_mul_f32 v[22:23], v[22:23], v[26:27]
	v_lshlrev_b32_e32 v28, 16, v50
	v_cvt_pk_bf16_f32 v21, v22, v23
	v_lshlrev_b32_e32 v22, 16, v54
	v_mul_f32_e32 v25, 0xbfb8aa3b, v22
	v_exp_f32_e32 v25, v25
	v_and_b32_e32 v23, 0xffff0000, v54
	v_and_b32_e32 v29, 0xffff0000, v50
	v_pk_mul_f32 v[16:17], v[16:17], v[28:29]
	v_add_f32_e32 v25, 1.0, v25
	v_rcp_f32_e32 v26, v25
	v_mul_f32_e32 v25, 0xbfb8aa3b, v23
	v_exp_f32_e32 v25, v25
	v_lshlrev_b32_e32 v28, 16, v51
	v_and_b32_e32 v29, 0xffff0000, v51
	v_add_f32_e32 v25, 1.0, v25
	v_rcp_f32_e32 v27, v25
	s_nop 0
	v_pk_mul_f32 v[22:23], v[26:27], v[22:23]
	s_nop 0
	v_pk_mul_f32 v[16:17], v[16:17], v[22:23]
	s_nop 0
	v_cvt_pk_bf16_f32 v22, v16, v17
	v_mul_f32_e32 v16, 0xbfb8aa3b, v18
	v_lshlrev_b32_e32 v18, 16, v55
	v_mul_f32_e32 v23, 0xbfb8aa3b, v18
	v_exp_f32_e32 v23, v23
	v_mul_f32_e32 v17, 0xbfb8aa3b, v19
	v_and_b32_e32 v19, 0xffff0000, v55
	v_exp_f32_e32 v16, v16
	v_add_f32_e32 v23, 1.0, v23
	v_rcp_f32_e32 v26, v23
	v_mul_f32_e32 v23, 0xbfb8aa3b, v19
	v_exp_f32_e32 v17, v17
	v_exp_f32_e32 v23, v23
	v_add_f32_e32 v16, 1.0, v16
	v_rcp_f32_e32 v16, v16
	v_add_f32_e32 v17, 1.0, v17
	v_add_f32_e32 v23, 1.0, v23
	v_rcp_f32_e32 v17, v17
	v_rcp_f32_e32 v27, v23
	v_pk_mul_f32 v[16:17], v[16:17], v[28:29]
	v_pk_mul_f32 v[18:19], v[26:27], v[18:19]
	s_nop 0
	v_pk_mul_f32 v[16:17], v[16:17], v[18:19]
	s_nop 0
	v_cvt_pk_bf16_f32 v23, v16, v17
	v_add_u32_e32 v16, 0x48000, v24
	global_store_dwordx4 v16, v[20:23], s[60:61] offset:1536 sc1
	s_waitcnt vmcnt(4)
	v_lshlrev_b32_e32 v16, 16, v44
	v_and_b32_e32 v17, 0xffff0000, v44
	v_mul_f32_e32 v18, 0xbfb8aa3b, v16
	v_mul_f32_e32 v19, 0xbfb8aa3b, v17
	v_exp_f32_e32 v18, v18
	v_exp_f32_e32 v19, v19
	v_lshlrev_b32_e32 v20, 16, v40
	v_and_b32_e32 v21, 0xffff0000, v40
	v_add_f32_e32 v18, 1.0, v18
	v_add_f32_e32 v19, 1.0, v19
	v_rcp_f32_e32 v18, v18
	v_rcp_f32_e32 v19, v19
	v_pk_mul_f32 v[12:13], v[12:13], v[20:21]
	v_lshlrev_b32_e32 v20, 16, v41
	v_and_b32_e32 v21, 0xffff0000, v41
	v_pk_mul_f32 v[16:17], v[18:19], v[16:17]
	s_nop 0
	v_pk_mul_f32 v[12:13], v[12:13], v[16:17]
	v_lshlrev_b32_e32 v16, 16, v45
	v_cvt_pk_bf16_f32 v12, v12, v13
	v_mul_f32_e32 v13, 0xbfb8aa3b, v14
	v_exp_f32_e32 v13, v13
	v_and_b32_e32 v17, 0xffff0000, v45
	v_add_f32_e32 v13, 1.0, v13
	v_rcp_f32_e32 v14, v13
	v_mul_f32_e32 v13, 0xbfb8aa3b, v15
	v_exp_f32_e32 v13, v13
	s_nop 0
	v_add_f32_e32 v13, 1.0, v13
	v_rcp_f32_e32 v15, v13
	v_mul_f32_e32 v13, 0xbfb8aa3b, v16
	v_exp_f32_e32 v13, v13
	v_pk_mul_f32 v[14:15], v[14:15], v[20:21]
	v_add_f32_e32 v13, 1.0, v13
	v_rcp_f32_e32 v18, v13
	v_mul_f32_e32 v13, 0xbfb8aa3b, v17
	v_exp_f32_e32 v13, v13
	s_nop 0
	v_add_f32_e32 v13, 1.0, v13
	v_rcp_f32_e32 v19, v13
	s_nop 0
	v_pk_mul_f32 v[16:17], v[18:19], v[16:17]
	s_nop 0
	v_pk_mul_f32 v[14:15], v[14:15], v[16:17]
	v_lshlrev_b32_e32 v18, 16, v42
	v_cvt_pk_bf16_f32 v13, v14, v15
	v_lshlrev_b32_e32 v14, 16, v46
	v_and_b32_e32 v15, 0xffff0000, v46
	v_mul_f32_e32 v16, 0xbfb8aa3b, v14
	v_mul_f32_e32 v17, 0xbfb8aa3b, v15
	v_exp_f32_e32 v16, v16
	v_exp_f32_e32 v17, v17
	v_and_b32_e32 v19, 0xffff0000, v42
	v_pk_mul_f32 v[8:9], v[8:9], v[18:19]
	v_add_f32_e32 v16, 1.0, v16
	v_add_f32_e32 v17, 1.0, v17
	v_rcp_f32_e32 v16, v16
	v_rcp_f32_e32 v17, v17
	v_lshlrev_b32_e32 v18, 16, v43
	v_and_b32_e32 v19, 0xffff0000, v43
	v_pk_mul_f32 v[14:15], v[16:17], v[14:15]
	s_nop 0
	v_pk_mul_f32 v[8:9], v[8:9], v[14:15]
	s_nop 0
	v_cvt_pk_bf16_f32 v14, v8, v9
	v_mul_f32_e32 v8, 0xbfb8aa3b, v10
	v_lshlrev_b32_e32 v10, 16, v47
	v_mul_f32_e32 v15, 0xbfb8aa3b, v10
	v_exp_f32_e32 v15, v15
	v_mul_f32_e32 v9, 0xbfb8aa3b, v11
	v_and_b32_e32 v11, 0xffff0000, v47
	v_exp_f32_e32 v8, v8
	v_add_f32_e32 v15, 1.0, v15
	v_rcp_f32_e32 v16, v15
	v_mul_f32_e32 v15, 0xbfb8aa3b, v11
	v_exp_f32_e32 v9, v9
	v_exp_f32_e32 v15, v15
	v_add_f32_e32 v8, 1.0, v8
	v_rcp_f32_e32 v8, v8
	v_add_f32_e32 v9, 1.0, v9
	v_add_f32_e32 v15, 1.0, v15
	v_rcp_f32_e32 v9, v9
	v_rcp_f32_e32 v17, v15
	v_pk_mul_f32 v[8:9], v[8:9], v[18:19]
	v_pk_mul_f32 v[10:11], v[16:17], v[10:11]
	s_nop 0
	v_pk_mul_f32 v[8:9], v[8:9], v[10:11]
	s_nop 0
	v_cvt_pk_bf16_f32 v15, v8, v9
	v_add_u32_e32 v8, 0x50000, v24
	global_store_dwordx4 v8, v[12:15], s[60:61] offset:1536 sc1
	s_waitcnt vmcnt(3)
; __device__ __forceinline__ float sigm(float v) { return __builtin_amdgcn_rcpf(1.0f + __builtin_amdgcn_exp2f(-LOG2E * v)); }
; __device__ __forceinline__ float bf_lo(unsigned w) { return __uint_as_float(w << 16); }
; __device__ __forceinline__ float silu_f(float v) { return v * __builtin_amdgcn_rcpf(1.0f + __builtin_amdgcn_exp2f(-1.4426950408889634f * v)); }
; __device__ __forceinline__ float bf_hi(unsigned w) { return __uint_as_float(w & 0xffff0000u); }
;     __device__ __forceinline__ void acc_init(f32x4 (&ini)[2][2], const Unit& u) const {
;         int t__ = threadIdx.x; asm volatile("" : "+v"(t__)); const int wid__ = __builtin_amdgcn_readfirstlane(t__ >> 6), wc = wid__ & 3, fq = (t__ & 63) >> 4;
;         const float* bp = bias + wc * 32 + 8 * fq; (void)u;
; #pragma unroll
;         for (int bj = 0; bj < 2; ++bj)
; #pragma unroll
;             for (int n = 0; n < 2; ++n) ini[bj][n] = *(const f32x4*)(bp + bj * HALF + 4 * n);
;     __device__ __forceinline__ void operator()(const f32x4 (&acc)[2][2][4][2], const Unit& u, int wr, int wc, int fr, int fq) const {
;     ...
;                 for (int m = 0; m < 4; ++m) { const unsigned rl = rl0 + (unsigned)(ai * HALF + m * 16);
;                     ygv[m] = *(const u32x4*)(ygb + (rl * 256u + col) * 2u); sgv[m] = *(const u32x4*)(sgb + (rl * 512u + col) * 2u); }
; #pragma unroll
;                 for (int m = 0; m < 4; ++m) { const unsigned rl = rl0 + (unsigned)(ai * HALF + m * 16);
;                     const u32x4 yg = ygv[m], sg = sgv[m];
;                     const f32x4 v0 = acc[ai][bj][m][0], v1 = acc[ai][bj][m][1];
;                     u32x4 w;
;                     w.x = cvt_pk_bf16(bf_lo(yg.x) * sigm(v0[0]) * silu_f(bf_lo(sg.x)), bf_hi(yg.x) * sigm(v0[1]) * silu_f(bf_hi(sg.x)));
;                     w.y = cvt_pk_bf16(bf_lo(yg.y) * sigm(v0[2]) * silu_f(bf_lo(sg.y)), bf_hi(yg.y) * sigm(v0[3]) * silu_f(bf_hi(sg.y)));
;                     w.z = cvt_pk_bf16(bf_lo(yg.z) * sigm(v1[0]) * silu_f(bf_lo(sg.z)), bf_hi(yg.z) * sigm(v1[1]) * silu_f(bf_hi(sg.z)));
;                     w.w = cvt_pk_bf16(bf_lo(yg.w) * sigm(v1[2]) * silu_f(bf_lo(sg.w)), bf_hi(yg.w) * sigm(v1[3]) * silu_f(bf_hi(sg.w)));
;                     *(u32x4*)(yb + (rl * 1024u + col) * 2u) = w; }
	v_lshlrev_b32_e32 v8, 16, v36
	v_and_b32_e32 v9, 0xffff0000, v36
	v_mul_f32_e32 v10, 0xbfb8aa3b, v8
	v_mul_f32_e32 v11, 0xbfb8aa3b, v9
	v_exp_f32_e32 v10, v10
	v_exp_f32_e32 v11, v11
	v_lshlrev_b32_e32 v12, 16, v32
	v_and_b32_e32 v13, 0xffff0000, v32
	v_add_f32_e32 v10, 1.0, v10
	v_add_f32_e32 v11, 1.0, v11
	v_rcp_f32_e32 v10, v10
	v_rcp_f32_e32 v11, v11
	v_pk_mul_f32 v[4:5], v[4:5], v[12:13]
	v_lshlrev_b32_e32 v12, 16, v33
	v_and_b32_e32 v13, 0xffff0000, v33
	v_pk_mul_f32 v[8:9], v[10:11], v[8:9]
	s_nop 0
	v_pk_mul_f32 v[4:5], v[4:5], v[8:9]
	v_lshlrev_b32_e32 v8, 16, v37
	v_cvt_pk_bf16_f32 v4, v4, v5
	v_mul_f32_e32 v5, 0xbfb8aa3b, v6
	v_exp_f32_e32 v5, v5
	v_and_b32_e32 v9, 0xffff0000, v37
	v_add_f32_e32 v5, 1.0, v5
	v_rcp_f32_e32 v6, v5
	v_mul_f32_e32 v5, 0xbfb8aa3b, v7
	v_exp_f32_e32 v5, v5
	s_nop 0
	v_add_f32_e32 v5, 1.0, v5
	v_rcp_f32_e32 v7, v5
	v_mul_f32_e32 v5, 0xbfb8aa3b, v8
	v_exp_f32_e32 v5, v5
	v_pk_mul_f32 v[6:7], v[6:7], v[12:13]
	v_add_f32_e32 v5, 1.0, v5
	v_rcp_f32_e32 v10, v5
	v_mul_f32_e32 v5, 0xbfb8aa3b, v9
	v_exp_f32_e32 v5, v5
	s_nop 0
	v_add_f32_e32 v5, 1.0, v5
	v_rcp_f32_e32 v11, v5
	s_nop 0
	v_pk_mul_f32 v[8:9], v[10:11], v[8:9]
	s_nop 0
	v_pk_mul_f32 v[6:7], v[6:7], v[8:9]
	v_lshlrev_b32_e32 v10, 16, v34
	v_cvt_pk_bf16_f32 v5, v6, v7
	v_lshlrev_b32_e32 v6, 16, v38
	v_and_b32_e32 v7, 0xffff0000, v38
	v_mul_f32_e32 v8, 0xbfb8aa3b, v6
	v_mul_f32_e32 v9, 0xbfb8aa3b, v7
	v_exp_f32_e32 v8, v8
	v_exp_f32_e32 v9, v9
	v_and_b32_e32 v11, 0xffff0000, v34
	v_pk_mul_f32 v[0:1], v[0:1], v[10:11]
	v_add_f32_e32 v8, 1.0, v8
	v_add_f32_e32 v9, 1.0, v9
	v_rcp_f32_e32 v8, v8
	v_rcp_f32_e32 v9, v9
	v_lshlrev_b32_e32 v10, 16, v35
	v_and_b32_e32 v11, 0xffff0000, v35
	v_pk_mul_f32 v[6:7], v[8:9], v[6:7]
	s_nop 0
	v_pk_mul_f32 v[0:1], v[0:1], v[6:7]
	s_nop 0
	v_cvt_pk_bf16_f32 v6, v0, v1
	v_mul_f32_e32 v0, 0xbfb8aa3b, v2
	v_lshlrev_b32_e32 v2, 16, v39
	v_mul_f32_e32 v7, 0xbfb8aa3b, v2
	v_exp_f32_e32 v7, v7
	v_mul_f32_e32 v1, 0xbfb8aa3b, v3
	v_and_b32_e32 v3, 0xffff0000, v39
	v_exp_f32_e32 v0, v0
	v_add_f32_e32 v7, 1.0, v7
	v_rcp_f32_e32 v8, v7
	v_mul_f32_e32 v7, 0xbfb8aa3b, v3
	v_exp_f32_e32 v1, v1
	v_exp_f32_e32 v7, v7
	v_add_f32_e32 v0, 1.0, v0
	v_rcp_f32_e32 v0, v0
	v_add_f32_e32 v1, 1.0, v1
	v_add_f32_e32 v7, 1.0, v7
	v_rcp_f32_e32 v1, v1
	v_rcp_f32_e32 v9, v7
	v_pk_mul_f32 v[0:1], v[0:1], v[10:11]
	v_pk_mul_f32 v[2:3], v[8:9], v[2:3]
	s_nop 0
	v_pk_mul_f32 v[0:1], v[0:1], v[2:3]
	s_nop 0
	v_cvt_pk_bf16_f32 v7, v0, v1
	v_add_u32_e32 v0, 0x58000, v24
	global_store_dwordx4 v0, v[4:7], s[60:61] offset:1536 sc1
	s_mov_b64 s[60:61], -1
	s_cbranch_vccnz .LBB0_68
	v_mov_b32_e32 v0, v212
	s_nop 0
	v_readfirstlane_b32 s0, v0
	s_lshl_b32 s0, s0, 1
	s_and_b32 s0, s0, 0x180
	s_add_u32 s16, s25, s0
	v_lshlrev_b32_e32 v0, 1, v0
	s_addc_u32 s17, s31, 0
	v_and_b32_e32 v4, 0x60, v0
	global_load_dwordx4 v[60:63], v4, s[16:17] offset:16
	global_load_dwordx4 v[68:71], v4, s[16:17]
	global_load_dwordx4 v[0:3], v4, s[16:17] offset:528
	s_nop 0
	global_load_dwordx4 v[4:7], v4, s[16:17] offset:512
	v_readlane_b32 s16, v252, 52
	v_readlane_b32 s17, v252, 53
	s_andn2_b64 vcc, exec, s[16:17]
	s_cbranch_vccnz .LBB0_67
	s_barrier
	s_branch .LBB0_67

; __device__ __forceinline__ float sigm(float v) { return __builtin_amdgcn_rcpf(1.0f + __builtin_amdgcn_exp2f(-LOG2E * v)); }
; __device__ __forceinline__ unsigned pk_bf16(float lo, float hi) { return pg8::cvt_pk_bf16(lo, hi); }
; #define LDS_FENCE() asm volatile("s_waitcnt lgkmcnt(0)" ::: "memory")
; template <bool PASS2> __device__ __forceinline__ void ssm2_pass(const Ctx& c, int l) {
;     ...
;                     xAr = half_bcast(xAr, ps); xAi = half_bcast(xAi, ps); xBr = half_bcast(xBr, ps); xBi = half_bcast(xBi, ps);
;                 }
;                 if (PASS2 && (gq & 1)) {
;                     LDS_FENCE();
;                     f32x4 a0 = {0.f, 0.f, 0.f, 0.f}, a1 = {0.f, 0.f, 0.f, 0.f};
;                     const unsigned* xp = XP + (lane & 15) * 132 + 4 * (lane >> 4);
; #pragma unroll
;                     for (int s_ = 0; s_ < 8; s_ += 2) {
;                         a0 = __builtin_amdgcn_mfma_f32_16x16x32_bf16(*(const bf16x8*)(xp + 16 * s_), Cb[s_], a0, 0, 0, 0);
;                         a1 = __builtin_amdgcn_mfma_f32_16x16x32_bf16(*(const bf16x8*)(xp + 16 * s_ + 16), Cb[s_ + 1], a1, 0, 0, 0);
;                     }
;                     const int h = lane & 15, t16 = (gq >> 1) * 16;
; #pragma unroll
;                     for (int i = 0; i < 4; ++i) { const int tt = 4 * (lane >> 4) + i;
;                         float y = a0[i] + a1[i] + dsk * Ul[(t16 + tt) * 16 + h];
;                         const float z = 0.7978845608028654f * (y + 0.044715f * y * y * y);
;                         y = y * sigm(2.0f * z);
;                         YG[(row0 + blk * 32 + t16 + tt) * 256 + g * 16 + h] = (bf16_t)(pk_bf16(y, 0.f) & 0xffffu); }
;                     LDS_FENCE();
.LBB0_124:
	s_or_b64 exec, exec, s[44:45]
	v_mov_b32_e32 v166, v4
	v_mov_b32_e32 v168, v6
	v_mov_b32_e32 v167, v5
	v_mov_b32_e32 v169, v7
	v_permlane32_swap_b32_e32 v4, v166
	v_permlane32_swap_b32_e32 v6, v168
	v_permlane32_swap_b32_e32 v5, v167
	v_permlane32_swap_b32_e32 v7, v169
	s_waitcnt lgkmcnt(0)
	ds_read_b128 v[4:7], v171
	ds_read_b128 v[8:11], v171 offset:64
	ds_read_b128 v[12:15], v171 offset:128
	s_waitcnt lgkmcnt(2)
	v_mfma_f32_16x16x32_bf16 v[4:7], v[4:7], v[80:83], 0
	v_add_co_u32_e32 v0, vcc, s1, v0
	s_add_u32 s42, s42, 0x4000
	s_waitcnt lgkmcnt(0)
	v_mfma_f32_16x16x32_bf16 v[4:7], v[12:15], v[88:91], v[4:7]
	ds_read_b128 v[12:15], v171 offset:192
	v_addc_co_u32_e32 v1, vcc, 0, v1, vcc
	v_mfma_f32_16x16x32_bf16 v[8:11], v[8:11], v[84:87], 0
	s_addc_u32 s43, s43, 0
	s_mov_b64 s[44:45], 0x8000
	s_waitcnt vmcnt(4)
	v_mov_b64_e32 v[136:137], v[132:133]
	s_waitcnt lgkmcnt(0)
	v_mfma_f32_16x16x32_bf16 v[8:11], v[12:15], v[92:95], v[8:11]
	ds_read_b128 v[12:15], v171 offset:256
	v_lshl_add_u64 v[162:163], v[162:163], 0, s[44:45]
	s_cmp_eq_u32 s42, 0x20000
	s_waitcnt lgkmcnt(0)
	v_mfma_f32_16x16x32_bf16 v[4:7], v[12:15], v[98:101], v[4:7]
	ds_read_b128 v[12:15], v171 offset:320
	v_mov_b64_e32 v[134:135], v[130:131]
	s_waitcnt lgkmcnt(0)
	v_mfma_f32_16x16x32_bf16 v[8:11], v[12:15], v[102:105], v[8:11]
	ds_read_b128 v[12:15], v171 offset:384
	s_waitcnt lgkmcnt(0)
	v_mfma_f32_16x16x32_bf16 v[4:7], v[12:15], v[106:109], v[4:7]
	ds_read_b128 v[12:15], v171 offset:448
	s_waitcnt lgkmcnt(0)
	v_mfma_f32_16x16x32_bf16 v[8:11], v[12:15], v[110:113], v[8:11]
	s_nop 7
	v_add_f32_e32 v4, v4, v8
	v_add_u32_e32 v8, 0x400, v174
	ds_read2_b32 v[12:13], v8 offset1:16
	s_waitcnt lgkmcnt(0)
	v_fmac_f32_e32 v4, v178, v12
	v_mul_f32_e32 v8, 0x3d372713, v4
	v_mul_f32_e32 v8, v4, v8
	v_fma_f32 v8, v4, v8, v4
	v_mul_f32_e32 v8, 0x3f4c422a, v8
	v_add_f32_e32 v8, v8, v8
	v_mul_f32_e32 v8, 0xbfb8aa3b, v8
	v_exp_f32_e32 v8, v8
	s_nop 0
	v_add_f32_e32 v8, 1.0, v8
	v_rcp_f32_e32 v8, v8
	s_nop 0
	v_mul_f32_e32 v4, v4, v8
	v_cvt_pk_bf16_f32 v4, v4, s0
	global_store_short v[0:1], v4, off sc1
	v_add_f32_e32 v4, v5, v9
	v_fmac_f32_e32 v4, v178, v13
	v_mul_f32_e32 v5, 0x3d372713, v4
	v_mul_f32_e32 v5, v4, v5
	v_fma_f32 v5, v4, v5, v4
	v_mul_f32_e32 v5, 0x3f4c422a, v5
	v_add_f32_e32 v5, v5, v5
	v_mul_f32_e32 v5, 0xbfb8aa3b, v5
	v_exp_f32_e32 v5, v5
	s_nop 0
	v_add_f32_e32 v5, 1.0, v5
	v_rcp_f32_e32 v5, v5
	s_nop 0
	v_mul_f32_e32 v4, v4, v5
	ds_read_b32 v5, v174 offset:1152
	v_cvt_pk_bf16_f32 v4, v4, s0
	global_store_short v[0:1], v4, off offset:512 sc1
	v_add_f32_e32 v4, v6, v10
	s_waitcnt lgkmcnt(0)
	v_fmac_f32_e32 v4, v178, v5
	v_mul_f32_e32 v5, 0x3d372713, v4
	v_mul_f32_e32 v5, v4, v5
	v_fma_f32 v5, v4, v5, v4
	v_mul_f32_e32 v5, 0x3f4c422a, v5
	v_add_f32_e32 v5, v5, v5
	v_mul_f32_e32 v5, 0xbfb8aa3b, v5
	v_exp_f32_e32 v5, v5
	s_nop 0
	v_add_f32_e32 v5, 1.0, v5
	v_rcp_f32_e32 v5, v5
	s_nop 0
	v_mul_f32_e32 v4, v4, v5
	v_cvt_pk_bf16_f32 v4, v4, s0
	global_store_short v[0:1], v4, off offset:1024 sc1
	ds_read_b32 v1, v177 offset:1024
	v_add_f32_e32 v0, v7, v11
	s_waitcnt lgkmcnt(0)
	v_fmac_f32_e32 v0, v178, v1
	v_mul_f32_e32 v1, 0x3d372713, v0
	v_mul_f32_e32 v1, v0, v1
	v_fma_f32 v1, v0, v1, v0
	v_mul_f32_e32 v1, 0x3f4c422a, v1
	v_add_f32_e32 v1, v1, v1
	v_mul_f32_e32 v1, 0xbfb8aa3b, v1
	v_exp_f32_e32 v1, v1
	s_nop 0
	v_add_f32_e32 v1, 1.0, v1
	v_rcp_f32_e32 v1, v1
	s_nop 0
	v_mul_f32_e32 v0, v0, v1
	v_cvt_pk_bf16_f32 v4, v0, s0
	v_add_co_u32_e32 v0, vcc, s1, v2
	s_nop 1
	v_addc_co_u32_e32 v1, vcc, 0, v3, vcc
	global_store_short v[0:1], v4, off sc1
	s_waitcnt lgkmcnt(0)
	s_cbranch_scc1 .LBB0_101

; __device__ __forceinline__ float sigm(float v) { return __builtin_amdgcn_rcpf(1.0f + __builtin_amdgcn_exp2f(-LOG2E * v)); }
; __device__ __forceinline__ float bf_lo(unsigned w) { return __uint_as_float(w << 16); }
; #define LDS_FENCE() asm volatile("s_waitcnt lgkmcnt(0)" ::: "memory")
; template <bool PASS2> __device__ __forceinline__ void ssm2_pass(const Ctx& c, int l) {
;     ...
;                         float nr = arA * xAr - aiA * xAi + D0[r], ni = arA * xAi + aiA * xAr + D2[r]; xAr = nr; xAi = ni;
;                         nr = arB * xBr - aiB * xBi + D1[r]; ni = arB * xBi + aiB * xBr + D3[r]; xBr = nr; xBi = ni;
;                         if (PASS2) { if (hi == ps) { const int row = (8 * gq + 4 * ps + i) & 15;
;                             const unsigned hr = pk_bf16(xAr, xBr), hm = pk_bf16(xAi, xBi);
;                             const unsigned lr = pk_bf16(xAr - bf_lo(hr), xBr - bf_hi(hr)), lm = pk_bf16(xAi - bf_lo(hm), xBi - bf_hi(hm));
;                             XP[row * 132 + q] = (hr & 0xffffu) | (lr << 16); XP[row * 132 + 32 + q] = (hr >> 16) | (lr & 0xffff0000u);
;                             XP[row * 132 + 64 + q] = (hm & 0xffffu) | (lm << 16); XP[row * 132 + 96 + q] = (hm >> 16) | (lm & 0xffff0000u); } } }
;     ...
;                 if (PASS2 && (gq & 1)) {
;                     LDS_FENCE();
;                     f32x4 a0 = {0.f, 0.f, 0.f, 0.f}, a1 = {0.f, 0.f, 0.f, 0.f};
;                     const unsigned* xp = XP + (lane & 15) * 132 + 4 * (lane >> 4);
; #pragma unroll
;                     for (int s_ = 0; s_ < 8; s_ += 2) {
;                         a0 = __builtin_amdgcn_mfma_f32_16x16x32_bf16(*(const bf16x8*)(xp + 16 * s_), Cb[s_], a0, 0, 0, 0);
;                         a1 = __builtin_amdgcn_mfma_f32_16x16x32_bf16(*(const bf16x8*)(xp + 16 * s_ + 16), Cb[s_ + 1], a1, 0, 0, 0);
;                     }
;                     const int h = lane & 15, t16 = (gq >> 1) * 16;
; #pragma unroll
;                     for (int i = 0; i < 4; ++i) { const int tt = 4 * (lane >> 4) + i;
;                         float y = a0[i] + a1[i] + dsk * Ul[(t16 + tt) * 16 + h];
;                         const float z = 0.7978845608028654f * (y + 0.044715f * y * y * y);
;                         y = y * sigm(2.0f * z);
;                         YG[(row0 + blk * 32 + t16 + tt) * 256 + g * 16 + h] = (bf16_t)(pk_bf16(y, 0.f) & 0xffffu); }
;                     LDS_FENCE();
.LBB0_159:
	s_or_b64 exec, exec, s[44:45]
	v_mov_b32_e32 v4, v0
	v_mov_b32_e32 v6, v2
	v_mov_b32_e32 v5, v1
	v_mov_b32_e32 v7, v3
	v_permlane32_swap_b32_e32 v0, v4
	v_permlane32_swap_b32_e32 v2, v6
	v_permlane32_swap_b32_e32 v1, v5
	v_permlane32_swap_b32_e32 v3, v7
	s_waitcnt lgkmcnt(0)
	ds_read_b128 v[0:3], v171
	ds_read_b128 v[16:19], v171 offset:64
	ds_read_b128 v[20:23], v171 offset:128
	s_waitcnt lgkmcnt(2)
	v_mfma_f32_16x16x32_bf16 v[0:3], v[0:3], v[80:83], 0
	s_waitcnt lgkmcnt(0)
	v_mfma_f32_16x16x32_bf16 v[0:3], v[20:23], v[88:91], v[0:3]
	ds_read_b128 v[20:23], v171 offset:192
	v_mfma_f32_16x16x32_bf16 v[16:19], v[16:19], v[84:87], 0
	s_waitcnt lgkmcnt(0)
	v_mfma_f32_16x16x32_bf16 v[16:19], v[20:23], v[92:95], v[16:19]
	ds_read_b128 v[20:23], v171 offset:256
	s_waitcnt lgkmcnt(0)
	v_mfma_f32_16x16x32_bf16 v[0:3], v[20:23], v[98:101], v[0:3]
	ds_read_b128 v[20:23], v171 offset:320
	s_waitcnt lgkmcnt(0)
	v_mfma_f32_16x16x32_bf16 v[16:19], v[20:23], v[102:105], v[16:19]
	ds_read_b128 v[20:23], v171 offset:384
	s_waitcnt lgkmcnt(0)
	v_mfma_f32_16x16x32_bf16 v[20:23], v[20:23], v[106:109], v[0:3]
	s_nop 2
	ds_read_b128 v[0:3], v171 offset:448
	s_waitcnt lgkmcnt(0)
	v_mfma_f32_16x16x32_bf16 v[16:19], v[0:3], v[110:113], v[16:19]
	ds_read_b32 v1, v174
	s_nop 6
	v_add_f32_e32 v0, v20, v16
	s_waitcnt lgkmcnt(0)
	v_fmac_f32_e32 v0, v178, v1
	v_mul_f32_e32 v1, 0x3d372713, v0
	v_mul_f32_e32 v1, v0, v1
	v_fma_f32 v1, v0, v1, v0
	v_mul_f32_e32 v1, 0x3f4c422a, v1
	v_add_f32_e32 v1, v1, v1
	v_mul_f32_e32 v1, 0xbfb8aa3b, v1
	v_exp_f32_e32 v1, v1
	s_nop 0
	v_add_f32_e32 v1, 1.0, v1
	v_rcp_f32_e32 v1, v1
	s_nop 0
	v_mul_f32_e32 v0, v0, v1
	v_cvt_pk_bf16_f32 v16, v0, s0
	v_lshl_add_u64 v[0:1], v[164:165], 0, s[42:43]
	v_add_co_u32_e32 v2, vcc, s7, v0
	s_nop 1
	v_addc_co_u32_e32 v3, vcc, 0, v1, vcc
	global_store_short v[2:3], v16, off sc1
	v_add_f32_e32 v16, v21, v17
	ds_read_b32 v17, v175
	s_waitcnt lgkmcnt(0)
	v_fmac_f32_e32 v16, v178, v17
	v_mul_f32_e32 v17, 0x3d372713, v16
	v_mul_f32_e32 v17, v16, v17
	v_fma_f32 v17, v16, v17, v16
	v_mul_f32_e32 v17, 0x3f4c422a, v17
	v_add_f32_e32 v17, v17, v17
	v_mul_f32_e32 v17, 0xbfb8aa3b, v17
	v_exp_f32_e32 v17, v17
	s_nop 0
	v_add_f32_e32 v17, 1.0, v17
	v_rcp_f32_e32 v17, v17
	s_nop 0
	v_mul_f32_e32 v16, v16, v17
	ds_read_b32 v17, v176
	v_cvt_pk_bf16_f32 v16, v16, s0
	global_store_short v[2:3], v16, off offset:512 sc1
	v_add_f32_e32 v16, v22, v18
	s_waitcnt lgkmcnt(0)
	v_fmac_f32_e32 v16, v178, v17
	v_mul_f32_e32 v17, 0x3d372713, v16
	v_mul_f32_e32 v17, v16, v17
	v_fma_f32 v17, v16, v17, v16
	v_mul_f32_e32 v17, 0x3f4c422a, v17
	v_add_f32_e32 v17, v17, v17
	v_mul_f32_e32 v17, 0xbfb8aa3b, v17
	v_exp_f32_e32 v17, v17
	s_nop 0
	v_add_f32_e32 v17, 1.0, v17
	v_rcp_f32_e32 v17, v17
	s_nop 0
	v_mul_f32_e32 v16, v16, v17
	v_cvt_pk_bf16_f32 v16, v16, s0
	global_store_short v[2:3], v16, off offset:1024 sc1
	ds_read_b32 v3, v177
	v_add_f32_e32 v2, v23, v19
	s_waitcnt lgkmcnt(0)
	v_fmac_f32_e32 v2, v178, v3
	v_mul_f32_e32 v3, 0x3d372713, v2
	v_mul_f32_e32 v3, v2, v3
	v_fma_f32 v3, v2, v3, v2
	v_mul_f32_e32 v3, 0x3f4c422a, v3
	v_add_f32_e32 v3, v3, v3
	v_mul_f32_e32 v3, 0xbfb8aa3b, v3
	v_exp_f32_e32 v3, v3
	s_nop 0
	v_add_f32_e32 v3, 1.0, v3
	v_rcp_f32_e32 v3, v3
	s_nop 0
	v_mul_f32_e32 v2, v2, v3
	v_cvt_pk_bf16_f32 v18, v2, s0
	v_lshl_add_u64 v[2:3], v[160:161], 0, s[42:43]
	v_add_co_u32_e32 v16, vcc, s7, v2
	s_nop 1
	v_addc_co_u32_e32 v17, vcc, 0, v3, vcc
	global_store_short v[16:17], v18, off sc1
	s_waitcnt lgkmcnt(0)
	v_pk_mul_f32 v[18:19], v[158:159], v[6:7]
	v_pk_mul_f32 v[6:7], v[156:157], v[6:7]
	v_mov_b32_e32 v16, v56
	v_mov_b32_e32 v17, v8
	v_pk_fma_f32 v[18:19], v[156:157], v[4:5], v[18:19] neg_lo:[0,0,1] neg_hi:[0,0,1]
	v_pk_fma_f32 v[6:7], v[158:159], v[4:5], v[6:7]
	v_mov_b32_e32 v4, v40
	v_mov_b32_e32 v5, v24
	v_pk_add_f32 v[18:19], v[16:17], v[18:19]
	v_pk_add_f32 v[6:7], v[4:5], v[6:7]
	s_and_saveexec_b64 s[44:45], s[38:39]
	s_cbranch_execz .LBB0_161
	v_cvt_pk_bf16_f32 v8, v18, v19
	v_lshlrev_b32_e32 v20, 16, v8
	v_and_b32_e32 v21, 0xffff0000, v8
	v_cvt_pk_bf16_f32 v22, v6, v7
	v_pk_add_f32 v[20:21], v[18:19], v[20:21] neg_lo:[0,1] neg_hi:[0,1]
	s_nop 0
	v_cvt_pk_bf16_f32 v23, v20, v21
	v_lshlrev_b32_e32 v20, 16, v22
	v_and_b32_e32 v21, 0xffff0000, v22
	v_pk_add_f32 v[20:21], v[6:7], v[20:21] neg_lo:[0,1] neg_hi:[0,1]
	s_nop 0
	v_cvt_pk_bf16_f32 v20, v20, v21
	v_and_b32_e32 v21, 0xffff, v8
	v_lshrrev_b32_e32 v8, 16, v8
	v_lshl_or_b32 v21, v23, 16, v21
	v_and_or_b32 v8, v23, s59, v8
	ds_write2_b32 v172, v21, v8 offset1:32
	v_and_b32_e32 v8, 0xffff, v22
	v_lshrrev_b32_e32 v21, 16, v22
	v_lshl_or_b32 v8, v20, 16, v8
	v_and_or_b32 v20, v20, s59, v21
	ds_write2_b32 v172, v8, v20 offset0:64 offset1:96

; __device__ __forceinline__ float bf_lo(unsigned w) { return __uint_as_float(w << 16); }
; __device__ __forceinline__ float silu_f(float v) { return v * __builtin_amdgcn_rcpf(1.0f + __builtin_amdgcn_exp2f(-1.4426950408889634f * v)); }
; __device__ __forceinline__ float bf_hi(unsigned w) { return __uint_as_float(w & 0xffff0000u); }
; __device__ __forceinline__ int crow(int r, int hi) { return (r & 3) + 8 * (r >> 2) + 4 * hi; }
; __device__ __forceinline__ int crow(int r,int hi){return (r&3)+8*(r>>2)+4*hi;}
; __device__ __forceinline__ unsigned cvtpk_s(float lo,float hi){f32x2_t v={lo,hi};bf16x2_t b=__builtin_convertvector(v,bf16x2_t);return __builtin_bit_cast(unsigned,b);}
; template<int THRL> __device__ __forceinline__ void attn_unit(int b,int h,int qb,const bf16*Q,const bf16*__restrict__ K,const bf16*__restrict__ V,const unsigned short*GB,unsigned short*Y,const float*Fcum,int ts,char*shm){
;     ...
;   {auto rr=__builtin_amdgcn_permlane32_swap(__float_as_uint(l_reg),__float_as_uint(l_reg),false,false);l_reg=__uint_as_float(rr[0])+__uint_as_float(rr[1]);}
;   if(hi==0)wsf[32+r32]=l_reg;asm volatile("s_waitcnt lgkmcnt(0)":::"memory");
;   float rli[16];
;   #pragma unroll
;   for(int r=0;r<16;++r)rli[r]=__builtin_amdgcn_rcpf(wsf[32+crow(r,hi)]);
;   { bf16*stg=(bf16*)(shm+LDS_OST)+wid*2048;
;     #pragma unroll
;     for(int r=0;r<16;++r){const int orow=crow(r,hi);
;       #pragma unroll
;       for(int d0=0;d0<2;++d0)stg[orow*64+d0*32+r32]=__float2bfloat16(o[d0][r]*rli[r]);}
;     asm volatile("s_waitcnt lgkmcnt(0)":::"memory");
;     const long grow0=rowbase+q0+wid*QBLK;
;     #pragma unroll
;     for(int i=0;i<4;++i){const int row=i*8+(lane>>3),ch=lane&7; const u32x4 v=*(const u32x4*)(stg+row*64+ch*8);
;       const u32x4 g=*(const u32x4*)(shm+LDS_G+wid*4096+i*1024+lane*16); u32x4 w;
;       w.x=cvtpk_s(bf_lo(v.x)*silu_f(bf_lo(g.x)),bf_hi(v.x)*silu_f(bf_hi(g.x))); w.y=cvtpk_s(bf_lo(v.y)*silu_f(bf_lo(g.y)),bf_hi(v.y)*silu_f(bf_hi(g.y)));
;       w.z=cvtpk_s(bf_lo(v.z)*silu_f(bf_lo(g.z)),bf_hi(v.z)*silu_f(bf_hi(g.z))); w.w=cvtpk_s(bf_lo(v.w)*silu_f(bf_lo(g.w)),bf_hi(v.w)*silu_f(bf_hi(g.w)));
;       *(u32x4*)(Y+(grow0+row)*1024+256+h*D+ch*8)=w;} }
.LBB0_197:
	s_or_b64 exec, exec, s[38:39]
	s_waitcnt lgkmcnt(0)
	ds_read_b128 v[32:35], v236 offset:49280
	ds_read_b128 v[36:39], v236 offset:49312
	v_lshlrev_b32_e32 v49, 9, v231
	v_lshlrev_b32_e32 v50, 1, v230
	v_add3_u32 v49, s68, v49, v50
	s_waitcnt lgkmcnt(1)
	v_rcp_f32_e32 v40, v32
	v_rcp_f32_e32 v41, v33
	v_rcp_f32_e32 v42, v34
	v_rcp_f32_e32 v43, v35
	v_mul_f32_e32 v0, v0, v40
	v_mul_f32_e32 v16, v16, v40
	v_cvt_pk_bf16_f32 v0, v0, s0
	s_waitcnt lgkmcnt(0)
	v_rcp_f32_e32 v44, v36
	ds_read_b128 v[32:35], v236 offset:49344
	v_rcp_f32_e32 v45, v37
	v_rcp_f32_e32 v46, v38
	v_rcp_f32_e32 v47, v39
	ds_read_b128 v[36:39], v236 offset:49376
	v_lshlrev_b32_e32 v48, 7, v232
	v_cvt_pk_bf16_f32 v16, v16, s0
	ds_write_b16 v49, v0 offset:51264
	v_mul_f32_e32 v0, v17, v41
	ds_write_b16 v49, v16 offset:51200
	v_cvt_pk_bf16_f32 v0, v0, s0
	v_add3_u32 v16, s68, v48, v50
	ds_write_b16 v16, v0 offset:51328
	v_mul_f32_e32 v0, v1, v41
	v_cvt_pk_bf16_f32 v0, v0, s0
	ds_write_b16 v16, v0 offset:51392
	v_mul_f32_e32 v0, v18, v42
	v_cvt_pk_bf16_f32 v0, v0, s0
	ds_write_b16 v16, v0 offset:51456
	v_mul_f32_e32 v0, v2, v42
	v_cvt_pk_bf16_f32 v0, v0, s0
	ds_write_b16 v16, v0 offset:51520
	v_mul_f32_e32 v0, v19, v43
	v_cvt_pk_bf16_f32 v0, v0, s0
	ds_write_b16 v16, v0 offset:51584
	v_mul_f32_e32 v0, v3, v43
	v_cvt_pk_bf16_f32 v0, v0, s0
	ds_write_b16 v16, v0 offset:51648
	v_mul_f32_e32 v0, v20, v44
	v_cvt_pk_bf16_f32 v0, v0, s0
	ds_write_b16 v16, v0 offset:52224
	v_mul_f32_e32 v0, v4, v44
	v_cvt_pk_bf16_f32 v0, v0, s0
	ds_write_b16 v16, v0 offset:52288
	v_mul_f32_e32 v0, v21, v45
	v_cvt_pk_bf16_f32 v0, v0, s0
	ds_write_b16 v16, v0 offset:52352
	v_mul_f32_e32 v0, v5, v45
	v_cvt_pk_bf16_f32 v0, v0, s0
	ds_write_b16 v16, v0 offset:52416
	v_mul_f32_e32 v0, v22, v46
	v_cvt_pk_bf16_f32 v0, v0, s0
	ds_write_b16 v16, v0 offset:52480
	v_mul_f32_e32 v0, v6, v46
	v_cvt_pk_bf16_f32 v0, v0, s0
	s_waitcnt lgkmcnt(14)
	v_rcp_f32_e32 v32, v32
	ds_write_b16 v16, v0 offset:52544
	v_mul_f32_e32 v0, v23, v47
	v_cvt_pk_bf16_f32 v0, v0, s0
	ds_write_b16 v16, v0 offset:52608
	v_mul_f32_e32 v0, v7, v47
	v_cvt_pk_bf16_f32 v0, v0, s0
	v_rcp_f32_e32 v33, v33
	ds_write_b16 v16, v0 offset:52672
	v_mul_f32_e32 v0, v24, v32
	v_cvt_pk_bf16_f32 v0, v0, s0
	ds_write_b16 v16, v0 offset:53248
	v_mul_f32_e32 v0, v8, v32
	v_cvt_pk_bf16_f32 v0, v0, s0
	v_rcp_f32_e32 v34, v34
	ds_write_b16 v16, v0 offset:53312
	v_mul_f32_e32 v0, v25, v33
	v_cvt_pk_bf16_f32 v0, v0, s0
	ds_write_b16 v16, v0 offset:53376
	v_mul_f32_e32 v0, v9, v33
	v_cvt_pk_bf16_f32 v0, v0, s0
	v_rcp_f32_e32 v35, v35
	ds_write_b16 v16, v0 offset:53440
	v_mul_f32_e32 v0, v26, v34
	v_cvt_pk_bf16_f32 v0, v0, s0
	ds_write_b16 v16, v0 offset:53504
	v_mul_f32_e32 v0, v10, v34
	v_cvt_pk_bf16_f32 v0, v0, s0
	s_waitcnt lgkmcnt(14)
	v_rcp_f32_e32 v36, v36
	ds_write_b16 v16, v0 offset:53568
	v_mul_f32_e32 v0, v27, v35
	v_cvt_pk_bf16_f32 v0, v0, s0
	ds_write_b16 v16, v0 offset:53632
	v_mul_f32_e32 v0, v11, v35
	v_cvt_pk_bf16_f32 v0, v0, s0
	v_rcp_f32_e32 v37, v37
	ds_write_b16 v16, v0 offset:53696
	v_mul_f32_e32 v0, v28, v36
	v_cvt_pk_bf16_f32 v0, v0, s0
	ds_write_b16 v16, v0 offset:54272
	v_mul_f32_e32 v0, v12, v36
	v_cvt_pk_bf16_f32 v0, v0, s0
	v_rcp_f32_e32 v38, v38
	ds_write_b16 v16, v0 offset:54336
	v_mul_f32_e32 v0, v29, v37
	v_cvt_pk_bf16_f32 v0, v0, s0
	ds_write_b16 v16, v0 offset:54400
	v_mul_f32_e32 v0, v13, v37
	v_cvt_pk_bf16_f32 v0, v0, s0
	v_rcp_f32_e32 v39, v39
	ds_write_b16 v16, v0 offset:54464
	v_mul_f32_e32 v0, v30, v38
	v_cvt_pk_bf16_f32 v0, v0, s0
	ds_write_b16 v16, v0 offset:54528
	v_mul_f32_e32 v0, v14, v38
	v_cvt_pk_bf16_f32 v0, v0, s0
	ds_write_b16 v16, v0 offset:54592
	v_mul_f32_e32 v0, v31, v39
	v_cvt_pk_bf16_f32 v0, v0, s0
	ds_write_b16 v16, v0 offset:54656
	v_mul_f32_e32 v0, v15, v39
	v_cvt_pk_bf16_f32 v0, v0, s0
	ds_write_b16 v16, v0 offset:54720
	v_lshl_add_u32 v0, v229, 4, s68
	s_waitcnt lgkmcnt(0)
	v_add_u32_e32 v22, 0x18800, v0
	ds_read_b128 v[0:3], v22
	ds_read_b128 v[4:7], v22 offset:1024
	v_add_u32_e32 v23, s68, v96
	v_lshl_add_u32 v8, v211, 7, v23
	v_or_b32_e32 v24, 8, v211
	s_waitcnt lgkmcnt(1)
	v_lshlrev_b32_e32 v16, 16, v0
	v_and_b32_e32 v17, 0xffff0000, v0
	v_mul_f32_e32 v0, 0xbfb8aa3b, v16
	v_exp_f32_e32 v0, v0
	v_mul_f32_e32 v9, 0xbfb8aa3b, v17
	v_exp_f32_e32 v12, v9
	ds_read_b128 v[8:11], v8 offset:51200
	v_add_f32_e32 v0, 1.0, v0
	v_rcp_f32_e32 v18, v0
	v_add_f32_e32 v0, 1.0, v12
	v_rcp_f32_e32 v19, v0
	v_lshl_add_u32 v0, v24, 7, v23
	ds_read_b128 v[12:15], v0 offset:51200
	s_waitcnt lgkmcnt(1)
; __device__ __forceinline__ float bf_lo(unsigned w) { return __uint_as_float(w << 16); }
; __device__ __forceinline__ float silu_f(float v) { return v * __builtin_amdgcn_rcpf(1.0f + __builtin_amdgcn_exp2f(-1.4426950408889634f * v)); }
; __device__ __forceinline__ float bf_hi(unsigned w) { return __uint_as_float(w & 0xffff0000u); }
; __device__ __forceinline__ unsigned cvtpk_s(float lo,float hi){f32x2_t v={lo,hi};bf16x2_t b=__builtin_convertvector(v,bf16x2_t);return __builtin_bit_cast(unsigned,b);}
; template<int THRL> __device__ __forceinline__ void attn_unit(int b,int h,int qb,const bf16*Q,const bf16*__restrict__ K,const bf16*__restrict__ V,const unsigned short*GB,unsigned short*Y,const float*Fcum,int ts,char*shm){
;     ...
;     for(int i=0;i<4;++i){const int row=i*8+(lane>>3),ch=lane&7; const u32x4 v=*(const u32x4*)(stg+row*64+ch*8);
;       const u32x4 g=*(const u32x4*)(shm+LDS_G+wid*4096+i*1024+lane*16); u32x4 w;
;       w.x=cvtpk_s(bf_lo(v.x)*silu_f(bf_lo(g.x)),bf_hi(v.x)*silu_f(bf_hi(g.x))); w.y=cvtpk_s(bf_lo(v.y)*silu_f(bf_lo(g.y)),bf_hi(v.y)*silu_f(bf_hi(g.y)));
;       w.z=cvtpk_s(bf_lo(v.z)*silu_f(bf_lo(g.z)),bf_hi(v.z)*silu_f(bf_hi(g.z))); w.w=cvtpk_s(bf_lo(v.w)*silu_f(bf_lo(g.w)),bf_hi(v.w)*silu_f(bf_hi(g.w)));
;       *(u32x4*)(Y+(grow0+row)*1024+256+h*D+ch*8)=w;} }
	v_lshlrev_b32_e32 v20, 16, v8
	v_pk_mul_f32 v[16:17], v[18:19], v[16:17]
	v_lshlrev_b32_e32 v18, 16, v1
	v_and_b32_e32 v19, 0xffff0000, v1
	v_mul_f32_e32 v0, 0xbfb8aa3b, v18
	v_and_b32_e32 v21, 0xffff0000, v8
	v_exp_f32_e32 v8, v0
	v_mul_f32_e32 v0, 0xbfb8aa3b, v19
	v_exp_f32_e32 v25, v0
	v_pk_mul_f32 v[0:1], v[16:17], v[20:21]
	v_add_f32_e32 v8, 1.0, v8
	v_rcp_f32_e32 v16, v8
	v_add_f32_e32 v8, 1.0, v25
	v_rcp_f32_e32 v17, v8
	v_cvt_pk_bf16_f32 v0, v0, v1
	v_lshlrev_b32_e32 v8, 16, v9
	v_and_b32_e32 v9, 0xffff0000, v9
	v_pk_mul_f32 v[16:17], v[16:17], v[18:19]
	v_lshlrev_b32_e32 v18, 16, v2
	v_and_b32_e32 v19, 0xffff0000, v2
	v_mul_f32_e32 v1, 0xbfb8aa3b, v18
	v_exp_f32_e32 v1, v1
	v_mul_f32_e32 v2, 0xbfb8aa3b, v19
	v_exp_f32_e32 v2, v2
	v_pk_mul_f32 v[8:9], v[16:17], v[8:9]
	v_add_f32_e32 v1, 1.0, v1
	v_rcp_f32_e32 v16, v1
	v_add_f32_e32 v1, 1.0, v2
	v_rcp_f32_e32 v17, v1
	v_cvt_pk_bf16_f32 v1, v8, v9
	v_lshlrev_b32_e32 v8, 16, v10
	v_and_b32_e32 v9, 0xffff0000, v10
	v_pk_mul_f32 v[16:17], v[16:17], v[18:19]
	v_lshlrev_b32_e32 v18, 16, v3
	v_and_b32_e32 v19, 0xffff0000, v3
	v_mul_f32_e32 v2, 0xbfb8aa3b, v18
	v_exp_f32_e32 v10, v2
	v_mul_f32_e32 v2, 0xbfb8aa3b, v19
	v_exp_f32_e32 v20, v2
	v_pk_mul_f32 v[2:3], v[16:17], v[8:9]
	v_add_f32_e32 v8, 1.0, v10
	v_rcp_f32_e32 v8, v8
	v_add_f32_e32 v9, 1.0, v20
	v_rcp_f32_e32 v9, v9
	v_lshlrev_b32_e32 v10, 16, v11
	v_and_b32_e32 v11, 0xffff0000, v11
	v_cvt_pk_bf16_f32 v2, v2, v3
	v_pk_mul_f32 v[8:9], v[8:9], v[18:19]
	s_lshl_b32 s34, s17, 1
	v_pk_mul_f32 v[8:9], v[8:9], v[10:11]
	v_lshlrev_b32_e32 v10, 16, v4
	v_and_b32_e32 v11, 0xffff0000, v4
	v_mul_f32_e32 v4, 0xbfb8aa3b, v10
	v_exp_f32_e32 v4, v4
	v_mul_f32_e32 v16, 0xbfb8aa3b, v11
	v_exp_f32_e32 v17, v16
	v_cvt_pk_bf16_f32 v3, v8, v9
	v_lshlrev_b64 v[8:9], 11, v[202:203]
	v_lshl_add_u64 v[8:9], s[82:83], 0, v[8:9]
	v_add_f32_e32 v4, 1.0, v4
	v_lshl_add_u64 v[8:9], v[8:9], 0, s[34:35]
	v_rcp_f32_e32 v16, v4
	v_add_f32_e32 v4, 1.0, v17
	v_lshl_add_u64 v[8:9], v[8:9], 0, v[96:97]
	v_rcp_f32_e32 v17, v4
	v_lshlrev_b32_e32 v4, 16, v5
	global_store_dwordx4 v[8:9], v[0:3], off offset:512 sc1
	v_and_b32_e32 v5, 0xffff0000, v5
	v_mul_f32_e32 v8, 0xbfb8aa3b, v4
	v_exp_f32_e32 v8, v8
	v_mul_f32_e32 v9, 0xbfb8aa3b, v5
	v_exp_f32_e32 v9, v9
	s_waitcnt lgkmcnt(0)
	v_lshlrev_b32_e32 v0, 16, v12
	v_and_b32_e32 v1, 0xffff0000, v12
	v_pk_mul_f32 v[2:3], v[16:17], v[10:11]
	s_add_i32 s67, s67, 1
	v_pk_mul_f32 v[0:1], v[2:3], v[0:1]
	v_add_f32_e32 v2, 1.0, v8
	v_rcp_f32_e32 v8, v2
	v_add_f32_e32 v2, 1.0, v9
	v_rcp_f32_e32 v9, v2
	v_cvt_pk_bf16_f32 v2, v0, v1
	v_lshlrev_b32_e32 v0, 16, v13
	v_and_b32_e32 v1, 0xffff0000, v13
	v_pk_mul_f32 v[4:5], v[8:9], v[4:5]
	v_lshlrev_b32_e32 v8, 16, v6
	v_and_b32_e32 v9, 0xffff0000, v6
	v_mul_f32_e32 v3, 0xbfb8aa3b, v8
	v_exp_f32_e32 v3, v3
	v_mul_f32_e32 v6, 0xbfb8aa3b, v9
	v_exp_f32_e32 v6, v6
	v_pk_mul_f32 v[0:1], v[4:5], v[0:1]
	v_add_f32_e32 v3, 1.0, v3
	v_rcp_f32_e32 v4, v3
	v_add_f32_e32 v3, 1.0, v6
	v_rcp_f32_e32 v5, v3
	v_lshlrev_b32_e32 v6, 16, v7
	v_and_b32_e32 v7, 0xffff0000, v7
	v_cvt_pk_bf16_f32 v3, v0, v1
	v_pk_mul_f32 v[4:5], v[4:5], v[8:9]
	v_mul_f32_e32 v8, 0xbfb8aa3b, v6
	v_exp_f32_e32 v8, v8
	v_mul_f32_e32 v9, 0xbfb8aa3b, v7
	v_exp_f32_e32 v9, v9
	v_lshlrev_b32_e32 v0, 16, v14
	v_and_b32_e32 v1, 0xffff0000, v14
	v_pk_mul_f32 v[0:1], v[4:5], v[0:1]
	v_add_f32_e32 v4, 1.0, v8
	v_rcp_f32_e32 v8, v4
	v_add_f32_e32 v4, 1.0, v9
	v_rcp_f32_e32 v9, v4
	v_cvt_pk_bf16_f32 v4, v0, v1
	v_lshlrev_b32_e32 v0, 16, v15
	v_and_b32_e32 v1, 0xffff0000, v15
	v_pk_mul_f32 v[6:7], v[8:9], v[6:7]
	s_cmp_eq_u32 s67, 4
	v_pk_mul_f32 v[0:1], v[6:7], v[0:1]
	s_nop 0
	v_cvt_pk_bf16_f32 v5, v0, v1
	v_or_b32_e32 v0, s50, v24
	v_mov_b32_e32 v1, s51
	v_lshlrev_b64 v[6:7], 11, v[0:1]
	v_lshl_add_u64 v[6:7], s[82:83], 0, v[6:7]
	v_lshl_add_u64 v[6:7], v[6:7], 0, s[34:35]
	v_lshl_add_u64 v[10:11], v[6:7], 0, v[96:97]
	ds_read_b128 v[6:9], v22 offset:2048
	global_store_dwordx4 v[10:11], v[2:5], off offset:512 sc1
	ds_read_b128 v[2:5], v22 offset:3072
	v_or_b32_e32 v0, 16, v211
	v_lshl_add_u32 v10, v0, 7, v23
	s_waitcnt lgkmcnt(1)
; __device__ __forceinline__ float bf_lo(unsigned w) { return __uint_as_float(w << 16); }
; __device__ __forceinline__ float silu_f(float v) { return v * __builtin_amdgcn_rcpf(1.0f + __builtin_amdgcn_exp2f(-1.4426950408889634f * v)); }
; __device__ __forceinline__ float bf_hi(unsigned w) { return __uint_as_float(w & 0xffff0000u); }
; __device__ __forceinline__ unsigned cvtpk_s(float lo,float hi){f32x2_t v={lo,hi};bf16x2_t b=__builtin_convertvector(v,bf16x2_t);return __builtin_bit_cast(unsigned,b);}
; template<int THRL> __device__ __forceinline__ void attn_unit(int b,int h,int qb,const bf16*Q,const bf16*__restrict__ K,const bf16*__restrict__ V,const unsigned short*GB,unsigned short*Y,const float*Fcum,int ts,char*shm){
;     ...
;     const long grow0=rowbase+q0+wid*QBLK;
;     #pragma unroll
;     for(int i=0;i<4;++i){const int row=i*8+(lane>>3),ch=lane&7; const u32x4 v=*(const u32x4*)(stg+row*64+ch*8);
;       const u32x4 g=*(const u32x4*)(shm+LDS_G+wid*4096+i*1024+lane*16); u32x4 w;
;       w.x=cvtpk_s(bf_lo(v.x)*silu_f(bf_lo(g.x)),bf_hi(v.x)*silu_f(bf_hi(g.x))); w.y=cvtpk_s(bf_lo(v.y)*silu_f(bf_lo(g.y)),bf_hi(v.y)*silu_f(bf_hi(g.y)));
;       w.z=cvtpk_s(bf_lo(v.z)*silu_f(bf_lo(g.z)),bf_hi(v.z)*silu_f(bf_hi(g.z))); w.w=cvtpk_s(bf_lo(v.w)*silu_f(bf_lo(g.w)),bf_hi(v.w)*silu_f(bf_hi(g.w)));
;       *(u32x4*)(Y+(grow0+row)*1024+256+h*D+ch*8)=w;} }
;   asm volatile("s_waitcnt lgkmcnt(0)\n\ts_barrier":::"memory");
	v_lshlrev_b32_e32 v18, 16, v6
	v_and_b32_e32 v19, 0xffff0000, v6
	v_mul_f32_e32 v6, 0xbfb8aa3b, v18
	v_exp_f32_e32 v6, v6
	v_mul_f32_e32 v11, 0xbfb8aa3b, v19
	v_exp_f32_e32 v14, v11
	ds_read_b128 v[10:13], v10 offset:51200
	v_add_f32_e32 v6, 1.0, v6
	v_rcp_f32_e32 v20, v6
	v_add_f32_e32 v6, 1.0, v14
	v_rcp_f32_e32 v21, v6
	v_or_b32_e32 v24, 24, v211
	v_lshl_add_u32 v6, v24, 7, v23
	ds_read_b128 v[14:17], v6 offset:51200
	v_pk_mul_f32 v[18:19], v[20:21], v[18:19]
	v_lshlrev_b32_e32 v20, 16, v7
	v_and_b32_e32 v21, 0xffff0000, v7
	v_mul_f32_e32 v6, 0xbfb8aa3b, v20
	s_waitcnt lgkmcnt(1)
	v_lshlrev_b32_e32 v22, 16, v10
	v_and_b32_e32 v23, 0xffff0000, v10
	v_exp_f32_e32 v10, v6
	v_mul_f32_e32 v6, 0xbfb8aa3b, v21
	v_exp_f32_e32 v25, v6
	v_pk_mul_f32 v[6:7], v[18:19], v[22:23]
	v_add_f32_e32 v10, 1.0, v10
	v_rcp_f32_e32 v18, v10
	v_add_f32_e32 v10, 1.0, v25
	v_rcp_f32_e32 v19, v10
	v_cvt_pk_bf16_f32 v6, v6, v7
	v_lshlrev_b32_e32 v10, 16, v11
	v_and_b32_e32 v11, 0xffff0000, v11
	v_pk_mul_f32 v[18:19], v[18:19], v[20:21]
	v_lshlrev_b32_e32 v20, 16, v8
	v_and_b32_e32 v21, 0xffff0000, v8
	v_mul_f32_e32 v7, 0xbfb8aa3b, v20
	v_exp_f32_e32 v7, v7
	v_mul_f32_e32 v8, 0xbfb8aa3b, v21
	v_exp_f32_e32 v8, v8
	v_pk_mul_f32 v[10:11], v[18:19], v[10:11]
	v_add_f32_e32 v7, 1.0, v7
	v_rcp_f32_e32 v18, v7
	v_add_f32_e32 v7, 1.0, v8
	v_rcp_f32_e32 v19, v7
	v_cvt_pk_bf16_f32 v7, v10, v11
	v_lshlrev_b32_e32 v10, 16, v12
	v_and_b32_e32 v11, 0xffff0000, v12
	v_pk_mul_f32 v[18:19], v[18:19], v[20:21]
	v_lshlrev_b32_e32 v20, 16, v9
	v_and_b32_e32 v21, 0xffff0000, v9
	v_mul_f32_e32 v8, 0xbfb8aa3b, v20
	v_exp_f32_e32 v12, v8
	v_mul_f32_e32 v8, 0xbfb8aa3b, v21
	v_exp_f32_e32 v22, v8
	v_pk_mul_f32 v[8:9], v[18:19], v[10:11]
	v_add_f32_e32 v10, 1.0, v12
	v_rcp_f32_e32 v10, v10
	v_add_f32_e32 v11, 1.0, v22
	v_rcp_f32_e32 v11, v11
	v_lshlrev_b32_e32 v12, 16, v13
	v_and_b32_e32 v13, 0xffff0000, v13
	v_or_b32_e32 v0, s50, v0
	v_pk_mul_f32 v[10:11], v[10:11], v[20:21]
	v_cvt_pk_bf16_f32 v8, v8, v9
	v_pk_mul_f32 v[10:11], v[10:11], v[12:13]
	v_lshlrev_b32_e32 v12, 16, v2
	v_cvt_pk_bf16_f32 v9, v10, v11
	v_lshlrev_b64 v[10:11], 11, v[0:1]
	v_and_b32_e32 v13, 0xffff0000, v2
	v_mul_f32_e32 v0, 0xbfb8aa3b, v12
	v_exp_f32_e32 v0, v0
	v_mul_f32_e32 v2, 0xbfb8aa3b, v13
	v_exp_f32_e32 v2, v2
	v_lshl_add_u64 v[10:11], s[82:83], 0, v[10:11]
	v_add_f32_e32 v0, 1.0, v0
	v_lshl_add_u64 v[10:11], v[10:11], 0, s[34:35]
	v_rcp_f32_e32 v18, v0
	v_add_f32_e32 v0, 1.0, v2
	v_lshl_add_u64 v[10:11], v[10:11], 0, v[96:97]
	v_rcp_f32_e32 v19, v0
	global_store_dwordx4 v[10:11], v[6:9], off offset:512 sc1
	v_lshlrev_b32_e32 v10, 16, v3
	v_and_b32_e32 v11, 0xffff0000, v3
	v_mul_f32_e32 v0, 0xbfb8aa3b, v10
	v_exp_f32_e32 v0, v0
	v_mul_f32_e32 v2, 0xbfb8aa3b, v11
	v_pk_mul_f32 v[8:9], v[18:19], v[12:13]
	v_exp_f32_e32 v12, v2
	s_waitcnt lgkmcnt(0)
	v_lshlrev_b32_e32 v6, 16, v14
	v_and_b32_e32 v7, 0xffff0000, v14
	v_add_f32_e32 v0, 1.0, v0
	v_pk_mul_f32 v[2:3], v[8:9], v[6:7]
	v_rcp_f32_e32 v6, v0
	v_add_f32_e32 v0, 1.0, v12
	v_rcp_f32_e32 v7, v0
	v_cvt_pk_bf16_f32 v2, v2, v3
	v_lshlrev_b32_e32 v8, 16, v15
	v_and_b32_e32 v9, 0xffff0000, v15
	v_pk_mul_f32 v[6:7], v[6:7], v[10:11]
	v_lshlrev_b32_e32 v10, 16, v4
	v_and_b32_e32 v11, 0xffff0000, v4
	v_mul_f32_e32 v0, 0xbfb8aa3b, v10
	v_exp_f32_e32 v0, v0
	v_mul_f32_e32 v3, 0xbfb8aa3b, v11
	v_exp_f32_e32 v3, v3
	v_pk_mul_f32 v[6:7], v[6:7], v[8:9]
	v_add_f32_e32 v0, 1.0, v0
	v_rcp_f32_e32 v8, v0
	v_add_f32_e32 v0, 1.0, v3
	v_rcp_f32_e32 v9, v0
	v_cvt_pk_bf16_f32 v3, v6, v7
	v_lshlrev_b32_e32 v6, 16, v16
	v_and_b32_e32 v7, 0xffff0000, v16
	v_pk_mul_f32 v[8:9], v[8:9], v[10:11]
	v_lshlrev_b32_e32 v10, 16, v5
	v_and_b32_e32 v11, 0xffff0000, v5
	v_mul_f32_e32 v0, 0xbfb8aa3b, v10
	v_exp_f32_e32 v0, v0
	v_mul_f32_e32 v4, 0xbfb8aa3b, v11
	v_exp_f32_e32 v12, v4
	v_pk_mul_f32 v[4:5], v[8:9], v[6:7]
	v_add_f32_e32 v0, 1.0, v0
	v_rcp_f32_e32 v6, v0
	v_add_f32_e32 v0, 1.0, v12
	v_rcp_f32_e32 v7, v0
	v_or_b32_e32 v0, s50, v24
	v_lshlrev_b64 v[0:1], 11, v[0:1]
	v_lshlrev_b32_e32 v8, 16, v17
	v_and_b32_e32 v9, 0xffff0000, v17
	v_pk_mul_f32 v[6:7], v[6:7], v[10:11]
	v_lshl_add_u64 v[0:1], s[82:83], 0, v[0:1]
	v_pk_mul_f32 v[6:7], v[6:7], v[8:9]
	v_lshl_add_u64 v[0:1], v[0:1], 0, s[34:35]
	v_cvt_pk_bf16_f32 v4, v4, v5
	v_cvt_pk_bf16_f32 v5, v6, v7
	v_lshl_add_u64 v[0:1], v[0:1], 0, v[96:97]
	global_store_dwordx4 v[0:1], v[2:5], off offset:512 sc1
	s_waitcnt lgkmcnt(0)
	s_barrier
	s_cbranch_scc1 .LBB0_195

; __device__ __forceinline__ void fcum_unit(const Ctx& c, int bh) {
;     ...
;     double base = incl - run;
;     for (int w = 0; w < c.wave; ++w) base += wtot[w];
; #pragma unroll
;     for (int i = 0; i < 8; ++i) fcum[(size_t)bh * SEQ + 8 * tid + i] = (float)((base + loc[i]) * 1.4426950408889634);
;     __syncthreads();
.LBB0_318:
	s_ashr_i32 s61, s60, 31
	s_lshl_b64 s[12:13], s[60:61], 14
	v_lshl_add_u64 v[24:25], v[4:5], 0, s[12:13]
	s_mov_b32 s12, 0x652b82fe
	v_add_f64 v[8:9], v[8:9], v[22:23]
	v_add_f64 v[6:7], v[6:7], v[22:23]
	s_mov_b32 s13, 0x3ff71547
	v_mul_f64 v[34:35], v[6:7], s[12:13]
	v_mul_f64 v[6:7], v[8:9], s[12:13]
	v_add_f64 v[8:9], v[12:13], v[22:23]
	v_add_f64 v[10:11], v[10:11], v[22:23]
	v_mul_f64 v[10:11], v[10:11], s[12:13]
	v_mul_f64 v[8:9], v[8:9], s[12:13]
	v_cvt_f32_f64_e32 v7, v[6:7]
	v_cvt_f32_f64_e32 v6, v[34:35]
	v_cvt_f32_f64_e32 v9, v[8:9]
	v_cvt_f32_f64_e32 v8, v[10:11]
	global_store_dwordx4 v[24:25], v[6:9], off sc1
	v_add_f64 v[10:11], v[18:19], v[22:23]
	v_mul_f64 v[10:11], v[10:11], s[12:13]
	v_add_f64 v[6:7], v[16:17], v[22:23]
	v_add_f64 v[8:9], v[14:15], v[22:23]
	v_mul_f64 v[8:9], v[8:9], s[12:13]
	v_mul_f64 v[6:7], v[6:7], s[12:13]
	v_cvt_f32_f64_e32 v7, v[6:7]
	v_cvt_f32_f64_e32 v6, v[8:9]
	v_add_f64 v[8:9], v[20:21], v[22:23]
	v_mul_f64 v[8:9], v[8:9], s[12:13]
	s_add_i32 s60, s60, s58
	v_cvt_f32_f64_e32 v9, v[8:9]
	v_cvt_f32_f64_e32 v8, v[10:11]
	s_cmp_gt_i32 s60, 63
	global_store_dwordx4 v[24:25], v[6:9], off offset:16 sc1
	s_barrier
	s_cbranch_scc1 .LBB0_324

; __device__ __forceinline__ void pool_tile(const Ctx& c, int l, int tile) {
;     ...
;             for (int s = 0; s < 32; ++s) {
;                 const float a = Pm[(32 * rt + li) * 65 + 2 * s + lh];
;                 const float b = pw[(size_t)(2 * s + lh) * 64];
;                 acc = __builtin_amdgcn_mfma_f32_32x32x2f32(a, b, acc, 0, 0, 0);
;             }
.LBB0_353:
	v_lshl_add_u64 v[144:145], v[110:111], 0, s[68:69]
	global_load_dword v113, v[144:145], off
	global_load_dword v148, v[144:145], off offset:512
	global_load_dword v149, v[144:145], off offset:1024
	global_load_dword v150, v[144:145], off offset:1536
	global_load_dword v151, v[144:145], off offset:2048
	ds_read2_b32 v[146:147], v112 offset1:2
	global_load_dword v152, v[144:145], off offset:2560
	global_load_dword v153, v[144:145], off offset:3072
	global_load_dword v154, v[144:145], off offset:3584
	ds_read2_b32 v[144:145], v112 offset0:4 offset1:6
	s_add_u32 s68, s68, 0x1000
	s_addc_u32 s69, s69, 0
	s_cmpk_eq_i32 s68, 0x4000
	s_waitcnt vmcnt(7) lgkmcnt(1)
	v_mfma_f32_32x32x2_f32 v[0:15], v146, v113, v[0:15]
	s_waitcnt vmcnt(6)
	v_mfma_f32_32x32x2_f32 v[0:15], v147, v148, v[0:15]
	s_waitcnt vmcnt(5) lgkmcnt(0)
	v_mfma_f32_32x32x2_f32 v[0:15], v144, v149, v[0:15]
	s_waitcnt vmcnt(4)
	v_mfma_f32_32x32x2_f32 v[0:15], v145, v150, v[0:15]
	ds_read2_b32 v[144:145], v112 offset0:8 offset1:10
	s_waitcnt vmcnt(3) lgkmcnt(0)
	v_mfma_f32_32x32x2_f32 v[0:15], v144, v151, v[0:15]
	s_waitcnt vmcnt(2)
	v_mfma_f32_32x32x2_f32 v[0:15], v145, v152, v[0:15]
	ds_read2_b32 v[144:145], v112 offset0:12 offset1:14
	v_add_u32_e32 v112, 64, v112
	s_waitcnt vmcnt(1) lgkmcnt(0)
	v_mfma_f32_32x32x2_f32 v[0:15], v144, v153, v[0:15]
	s_waitcnt vmcnt(0)
	v_mfma_f32_32x32x2_f32 v[0:15], v145, v154, v[0:15]
	s_cbranch_scc0 .LBB0_353
; __device__ __forceinline__ float silu_f(float v) { return v * __builtin_amdgcn_rcpf(1.0f + __builtin_amdgcn_exp2f(-1.4426950408889634f * v)); }
; __device__ __forceinline__ unsigned pk_bf16(float lo, float hi) { return pg8::cvt_pk_bf16(lo, hi); }
; __device__ __forceinline__ void pool_tile(const Ctx& c, int l, int tile) {
;     ...
; #pragma unroll
;             for (int r = 0; r < 16; ++r) {
;                 const int i = (r & 3) + 8 * (r >> 2) + 4 * lh; const size_t tok = (size_t)(t0 + 32 * rt + i);
;                 const float v = acc[r] * sc * silu_f(__uint_as_float((unsigned)gv[r] << 16));
;                 Y[tok * 1024 + gi * 64 + j] = (bf16_t)(pk_bf16(v, 0.f) & 0xffffu);
;             }
;         }
;         __syncthreads();
	v_lshlrev_b32_e32 v143, 16, v143
	v_mul_f32_e32 v144, 0xbfb8aa3b, v143
	v_exp_f32_e32 v144, v144
	s_lshl_b32 s34, s16, 1
	s_nop 12
	v_mul_f32_e32 v0, v129, v0
	v_lshl_add_u64 v[112:113], v[34:35], 0, s[34:35]
	v_add_f32_e32 v144, 1.0, v144
	v_rcp_f32_e32 v144, v144
	s_add_i32 s13, s13, 1
	v_lshl_add_u64 v[110:111], v[110:111], 0, s[96:97]
	s_cmp_eq_u32 s13, 4
	v_mul_f32_e32 v143, v144, v143
	v_mul_f32_e32 v0, v143, v0
	v_cvt_pk_bf16_f32 v0, v0, s0
	v_lshl_add_u64 v[144:145], v[112:113], 0, v[76:77]
	global_store_short v[144:145], v0, off sc1
	v_mul_f32_e32 v0, v129, v1
	v_lshlrev_b32_e32 v1, 16, v142
	v_mul_f32_e32 v142, 0xbfb8aa3b, v1
	v_exp_f32_e32 v142, v142
	s_nop 0
	v_add_f32_e32 v142, 1.0, v142
	v_rcp_f32_e32 v142, v142
	s_nop 0
	v_mul_f32_e32 v1, v142, v1
	v_mul_f32_e32 v0, v1, v0
	v_cvt_pk_bf16_f32 v142, v0, s0
	v_lshl_add_u64 v[0:1], v[112:113], 0, v[78:79]
	global_store_short v[0:1], v142, off sc1
	v_lshlrev_b32_e32 v1, 16, v141
	v_mul_f32_e32 v0, v129, v2
	v_mul_f32_e32 v2, 0xbfb8aa3b, v1
	v_exp_f32_e32 v2, v2
	s_nop 0
	v_add_f32_e32 v2, 1.0, v2
	v_rcp_f32_e32 v2, v2
	s_nop 0
	v_mul_f32_e32 v1, v2, v1
	v_mul_f32_e32 v0, v1, v0
	v_cvt_pk_bf16_f32 v2, v0, s0
	v_lshl_add_u64 v[0:1], v[112:113], 0, v[80:81]
	global_store_short v[0:1], v2, off sc1
	v_lshlrev_b32_e32 v1, 16, v140
	v_mul_f32_e32 v2, 0xbfb8aa3b, v1
	v_exp_f32_e32 v2, v2
	v_mul_f32_e32 v0, v129, v3
	v_add_f32_e32 v2, 1.0, v2
	v_rcp_f32_e32 v2, v2
	s_nop 0
	v_mul_f32_e32 v1, v2, v1
	v_mul_f32_e32 v0, v1, v0
	v_cvt_pk_bf16_f32 v2, v0, s0
	v_lshl_add_u64 v[0:1], v[112:113], 0, v[82:83]
	global_store_short v[0:1], v2, off sc1
	v_lshlrev_b32_e32 v1, 16, v139
	v_mul_f32_e32 v2, 0xbfb8aa3b, v1
	v_exp_f32_e32 v2, v2
	v_mul_f32_e32 v0, v129, v4
	v_add_f32_e32 v2, 1.0, v2
	v_rcp_f32_e32 v2, v2
	s_nop 0
	v_mul_f32_e32 v1, v2, v1
	v_mul_f32_e32 v0, v1, v0
	v_cvt_pk_bf16_f32 v2, v0, s0
	v_lshl_add_u64 v[0:1], v[112:113], 0, v[84:85]
	global_store_short v[0:1], v2, off sc1
	v_lshlrev_b32_e32 v1, 16, v138
	v_mul_f32_e32 v2, 0xbfb8aa3b, v1
	v_exp_f32_e32 v2, v2
	v_mul_f32_e32 v0, v129, v5
	v_add_f32_e32 v2, 1.0, v2
	v_rcp_f32_e32 v2, v2
	s_nop 0
	v_mul_f32_e32 v1, v2, v1
	v_mul_f32_e32 v0, v1, v0
	v_cvt_pk_bf16_f32 v2, v0, s0
	v_lshl_add_u64 v[0:1], v[112:113], 0, v[86:87]
	global_store_short v[0:1], v2, off sc1
	v_lshlrev_b32_e32 v1, 16, v137
	v_mul_f32_e32 v2, 0xbfb8aa3b, v1
	v_exp_f32_e32 v2, v2
	v_mul_f32_e32 v0, v129, v6
	v_add_f32_e32 v2, 1.0, v2
	v_rcp_f32_e32 v2, v2
	s_nop 0
	v_mul_f32_e32 v1, v2, v1
	v_mul_f32_e32 v0, v1, v0
	v_cvt_pk_bf16_f32 v2, v0, s0
	v_lshl_add_u64 v[0:1], v[112:113], 0, v[88:89]
	global_store_short v[0:1], v2, off sc1
	v_lshlrev_b32_e32 v1, 16, v136
	v_mul_f32_e32 v2, 0xbfb8aa3b, v1
	v_exp_f32_e32 v2, v2
	v_mul_f32_e32 v0, v129, v7
	v_add_f32_e32 v2, 1.0, v2
	v_rcp_f32_e32 v2, v2
	s_nop 0
	v_mul_f32_e32 v1, v2, v1
	v_mul_f32_e32 v0, v1, v0
	v_cvt_pk_bf16_f32 v2, v0, s0
	v_lshl_add_u64 v[0:1], v[112:113], 0, v[90:91]
	global_store_short v[0:1], v2, off sc1
	v_lshlrev_b32_e32 v1, 16, v135
	v_mul_f32_e32 v2, 0xbfb8aa3b, v1
	v_exp_f32_e32 v2, v2
	v_mul_f32_e32 v0, v129, v8
	v_add_f32_e32 v2, 1.0, v2
	v_rcp_f32_e32 v2, v2
	s_nop 0
	v_mul_f32_e32 v1, v2, v1
	v_mul_f32_e32 v0, v1, v0
	v_cvt_pk_bf16_f32 v2, v0, s0
	v_lshl_add_u64 v[0:1], v[112:113], 0, v[92:93]
	global_store_short v[0:1], v2, off sc1
	v_lshlrev_b32_e32 v1, 16, v134
	v_mul_f32_e32 v2, 0xbfb8aa3b, v1
	v_exp_f32_e32 v2, v2
	v_mul_f32_e32 v0, v129, v9
	v_add_f32_e32 v2, 1.0, v2
	v_rcp_f32_e32 v2, v2
	s_nop 0
	v_mul_f32_e32 v1, v2, v1
	v_mul_f32_e32 v0, v1, v0
	v_cvt_pk_bf16_f32 v2, v0, s0
	v_lshl_add_u64 v[0:1], v[112:113], 0, v[94:95]
	global_store_short v[0:1], v2, off sc1
	v_lshlrev_b32_e32 v1, 16, v133
	v_mul_f32_e32 v2, 0xbfb8aa3b, v1
	v_exp_f32_e32 v2, v2
	v_mul_f32_e32 v0, v129, v10
	v_add_f32_e32 v2, 1.0, v2
	v_rcp_f32_e32 v2, v2
	s_nop 0
	v_mul_f32_e32 v1, v2, v1
	v_mul_f32_e32 v0, v1, v0
	v_cvt_pk_bf16_f32 v2, v0, s0
	v_lshl_add_u64 v[0:1], v[112:113], 0, v[98:99]
	global_store_short v[0:1], v2, off sc1
	v_lshlrev_b32_e32 v1, 16, v132
	v_mul_f32_e32 v2, 0xbfb8aa3b, v1
	v_exp_f32_e32 v2, v2
	v_mul_f32_e32 v0, v129, v11
	v_add_f32_e32 v2, 1.0, v2
	v_rcp_f32_e32 v2, v2
	s_nop 0
	v_mul_f32_e32 v1, v2, v1
	v_mul_f32_e32 v0, v1, v0
	v_cvt_pk_bf16_f32 v2, v0, s0
	v_lshl_add_u64 v[0:1], v[112:113], 0, v[100:101]
	global_store_short v[0:1], v2, off sc1
	v_lshlrev_b32_e32 v1, 16, v131
	v_mul_f32_e32 v2, 0xbfb8aa3b, v1
	v_exp_f32_e32 v2, v2
	v_mul_f32_e32 v0, v129, v12
	v_add_f32_e32 v2, 1.0, v2
	v_rcp_f32_e32 v2, v2
	s_nop 0
	v_mul_f32_e32 v1, v2, v1
	v_mul_f32_e32 v0, v1, v0
	v_cvt_pk_bf16_f32 v2, v0, s0
	v_lshl_add_u64 v[0:1], v[112:113], 0, v[102:103]
	global_store_short v[0:1], v2, off sc1
	v_lshlrev_b32_e32 v1, 16, v130
	v_mul_f32_e32 v2, 0xbfb8aa3b, v1
	v_exp_f32_e32 v2, v2
	v_mul_f32_e32 v0, v129, v13
	v_add_f32_e32 v2, 1.0, v2
	v_rcp_f32_e32 v2, v2
	s_nop 0
	v_mul_f32_e32 v1, v2, v1
	v_mul_f32_e32 v0, v1, v0
	v_cvt_pk_bf16_f32 v2, v0, s0
	v_lshl_add_u64 v[0:1], v[112:113], 0, v[104:105]
	global_store_short v[0:1], v2, off sc1
	v_lshlrev_b32_e32 v1, 16, v128
	v_mul_f32_e32 v2, 0xbfb8aa3b, v1
	v_exp_f32_e32 v2, v2
	v_mul_f32_e32 v0, v129, v14
	v_add_f32_e32 v2, 1.0, v2
	v_rcp_f32_e32 v2, v2
	s_nop 0
	v_mul_f32_e32 v1, v2, v1
	v_mul_f32_e32 v0, v1, v0
	v_cvt_pk_bf16_f32 v2, v0, s0
	v_lshl_add_u64 v[0:1], v[112:113], 0, v[106:107]
	global_store_short v[0:1], v2, off sc1
	v_lshlrev_b32_e32 v1, 16, v96
	v_mul_f32_e32 v2, 0xbfb8aa3b, v1
	v_exp_f32_e32 v2, v2
	v_mul_f32_e32 v0, v129, v15
	v_add_f32_e32 v2, 1.0, v2
	v_rcp_f32_e32 v2, v2
	s_nop 0
	v_mul_f32_e32 v1, v2, v1
	v_mul_f32_e32 v0, v1, v0
	v_cvt_pk_bf16_f32 v2, v0, s0
	v_lshl_add_u64 v[0:1], v[112:113], 0, v[108:109]
	global_store_short v[0:1], v2, off sc1
	s_barrier
	s_cbranch_scc0 .LBB0_336
	s_branch .LBB0_328

; __device__ __forceinline__ float bf_lo(unsigned w) { return __uint_as_float(w << 16); }
; template <bool PASS2> __device__ __forceinline__ void ssm2_pass(const Ctx& c, int l) {
;     ...
;         for (int blk = 0; blk < 8; ++blk) {
;             const bf16x8 a = an;
;             if (blk + 1 < 8) an = *(const bf16x8*)(up + (size_t)(blk + 1) * 32 * 512);
;             if (PASS2) { const u32x4 w = __builtin_bit_cast(u32x4, a); float* d = Ul + q * 16 + 8 * hi;
;                 *(f32x4*)d = (f32x4){bf_lo(w.x), bf_hi(w.x), bf_lo(w.y), bf_hi(w.y)}; *(f32x4*)(d + 4) = (f32x4){bf_lo(w.z), bf_hi(w.z), bf_lo(w.w), bf_hi(w.w)}; }
;             f32x16 D0 = {}, D1 = {}, D2 = {}, D3 = {};
;             D0 = __builtin_amdgcn_mfma_f32_32x32x16_bf16(a, Bh[0], D0, 0, 0, 0); D1 = __builtin_amdgcn_mfma_f32_32x32x16_bf16(a, Bh[1], D1, 0, 0, 0);
;             D2 = __builtin_amdgcn_mfma_f32_32x32x16_bf16(a, Bh[2], D2, 0, 0, 0); D3 = __builtin_amdgcn_mfma_f32_32x32x16_bf16(a, Bh[3], D3, 0, 0, 0);
;             D0 = __builtin_amdgcn_mfma_f32_32x32x16_bf16(a, Bl[0], D0, 0, 0, 0); D1 = __builtin_amdgcn_mfma_f32_32x32x16_bf16(a, Bl[1], D1, 0, 0, 0);
;             D2 = __builtin_amdgcn_mfma_f32_32x32x16_bf16(a, Bl[2], D2, 0, 0, 0); D3 = __builtin_amdgcn_mfma_f32_32x32x16_bf16(a, Bl[3], D3, 0, 0, 0);
; #pragma unroll
;             for (int gq = 0; gq < 4; ++gq) {
; #pragma unroll
;                 for (int ps = 0; ps < 2; ++ps) {
; #pragma unroll
;                     for (int i = 0; i < 4; ++i) { const int r = 4 * gq + i;
;                         float nr = arA * xAr - aiA * xAi + D0[r], ni = arA * xAi + aiA * xAr + D2[r]; xAr = nr; xAi = ni;
;                         nr = arB * xBr - aiB * xBi + D1[r]; ni = arB * xBi + aiB * xBr + D3[r]; xBr = nr; xBi = ni;
;                         if (PASS2) { if (hi == ps) { const int row = (8 * gq + 4 * ps + i) & 15;
;                             const unsigned hr = pk_bf16(xAr, xBr), hm = pk_bf16(xAi, xBi);
;                             const unsigned lr = pk_bf16(xAr - bf_lo(hr), xBr - bf_hi(hr)), lm = pk_bf16(xAi - bf_lo(hm), xBi - bf_hi(hm));
;                             XP[row * 132 + q] = (hr & 0xffffu) | (lr << 16); XP[row * 132 + 32 + q] = (hr >> 16) | (lr & 0xffff0000u);
;                             XP[row * 132 + 64 + q] = (hm & 0xffffu) | (lm << 16); XP[row * 132 + 96 + q] = (hm >> 16) | (lm & 0xffff0000u); } } }
.LBB0_382:
	v_mfma_f32_32x32x16_bf16 v[32:47], v[102:105], v[72:75], 0
	v_mul_f32_e32 v96, v114, v117
	v_fma_f32 v96, v124, v116, -v96
	s_add_u32 s40, s40, 0x8000
	s_addc_u32 s41, s41, 0
	s_cmp_eq_u32 s40, 0x40000
	v_mfma_f32_32x32x16_bf16 v[48:63], v[102:105], v[64:67], 0
	v_mfma_f32_32x32x16_bf16 v[0:15], v[102:105], v[88:91], 0
	v_mfma_f32_32x32x16_bf16 v[16:31], v[102:105], v[80:83], 0
	v_mfma_f32_32x32x16_bf16 v[32:47], v[102:105], v[76:79], v[32:47]
	v_mfma_f32_32x32x16_bf16 v[48:63], v[102:105], v[68:71], v[48:63]
	v_mfma_f32_32x32x16_bf16 v[0:15], v[102:105], v[92:95], v[0:15]
	s_nop 10
	v_add_f32_e32 v96, v96, v48
	v_mfma_f32_32x32x16_bf16 v[16:31], v[102:105], v[84:87], v[16:31]
	v_mul_f32_e32 v102, v124, v117
	v_fmac_f32_e32 v102, v114, v116
	v_add_f32_e32 v102, v102, v32
	v_mul_f32_e32 v104, v109, v123
	v_mul_f32_e32 v103, v118, v123
	v_fmac_f32_e32 v104, v118, v122
	v_mul_f32_e32 v105, v114, v102
	v_mul_f32_e32 v102, v124, v102
	v_fma_f32 v103, v109, v122, -v103
	v_add_f32_e32 v104, v104, v0
	v_fmac_f32_e32 v102, v114, v96
	s_nop 0
	v_add_f32_e32 v103, v103, v16
	v_fma_f32 v105, v124, v96, -v105
	v_add_f32_e32 v96, v33, v102
	v_mul_f32_e32 v102, v118, v104
	v_mul_f32_e32 v104, v109, v104
	v_fmac_f32_e32 v104, v118, v103
	v_add_f32_e32 v105, v49, v105
	v_fma_f32 v102, v109, v103, -v102
	v_add_f32_e32 v103, v1, v104
	v_mul_f32_e32 v104, v114, v96
	v_fma_f32 v104, v124, v105, -v104
	v_mul_f32_e32 v105, v114, v105
	v_fmac_f32_e32 v105, v124, v96
	v_add_f32_e32 v102, v17, v102
	v_add_f32_e32 v96, v34, v105
	v_mul_f32_e32 v105, v118, v103
	v_fma_f32 v105, v109, v102, -v105
	v_mul_f32_e32 v102, v118, v102
	v_add_f32_e32 v104, v50, v104
	v_fmac_f32_e32 v102, v109, v103
	v_mul_f32_e32 v103, v114, v96
	v_fma_f32 v103, v124, v104, -v103
	v_mul_f32_e32 v104, v114, v104
	v_add_f32_e32 v102, v2, v102
	v_fmac_f32_e32 v104, v124, v96
	v_add_f32_e32 v105, v18, v105
	v_add_f32_e32 v96, v35, v104
	v_mul_f32_e32 v104, v118, v102
	v_fma_f32 v104, v109, v105, -v104
	v_mul_f32_e32 v105, v118, v105
	v_add_f32_e32 v103, v51, v103
	v_fmac_f32_e32 v105, v109, v102
	v_add_f32_e32 v102, v3, v105
	v_mov_b32_e32 v105, v103
	s_nop 1
	v_permlane32_swap_b32_e32 v103, v105
	v_mov_b32_e32 v105, v96
	v_add_f32_e32 v104, v19, v104
	s_nop 0
	v_permlane32_swap_b32_e32 v96, v105
	v_mov_b32_e32 v105, v104
	s_nop 1
	v_permlane32_swap_b32_e32 v104, v105
	v_mov_b32_e32 v105, v102
	s_nop 1
	v_permlane32_swap_b32_e32 v102, v105
	v_mul_f32_e32 v105, v114, v96
	v_mul_f32_e32 v96, v124, v96
	v_fmac_f32_e32 v96, v114, v103
	v_add_f32_e32 v32, v32, v96
	v_mul_f32_e32 v96, v118, v102
	v_fma_f32 v96, v109, v104, -v96
	v_add_f32_e32 v16, v16, v96
	v_mul_f32_e32 v96, v109, v102
	v_fma_f32 v105, v124, v103, -v105
	v_fmac_f32_e32 v96, v118, v104
	v_add_f32_e32 v48, v48, v105
	v_add_f32_e32 v0, v0, v96
	v_mul_f32_e32 v96, v114, v32
	v_fma_f32 v96, v124, v48, -v96
	v_mul_f32_e32 v48, v114, v48
	v_fmac_f32_e32 v48, v124, v32
	v_add_f32_e32 v32, v33, v48
	v_mul_f32_e32 v33, v118, v0
	v_fma_f32 v33, v109, v16, -v33
	v_mul_f32_e32 v16, v118, v16
	v_add_f32_e32 v49, v49, v96
	v_fmac_f32_e32 v16, v109, v0
	v_add_f32_e32 v0, v1, v16
	v_mul_f32_e32 v16, v114, v49
	v_add_f32_e32 v17, v17, v33
	v_mul_f32_e32 v1, v114, v32
	v_fmac_f32_e32 v16, v124, v32
	v_mul_f32_e32 v32, v118, v0
	v_fma_f32 v32, v109, v17, -v32
	v_mul_f32_e32 v17, v118, v17
	v_fma_f32 v1, v124, v49, -v1
	v_add_f32_e32 v16, v34, v16
	v_fmac_f32_e32 v17, v109, v0
	v_add_f32_e32 v1, v50, v1
	v_add_f32_e32 v18, v18, v32
	v_add_f32_e32 v0, v2, v17
	v_mul_f32_e32 v2, v114, v16
	v_fma_f32 v2, v124, v1, -v2
	v_mul_f32_e32 v17, v118, v18
	v_add_f32_e32 v2, v51, v2
	v_mul_f32_e32 v1, v114, v1
	v_fmac_f32_e32 v17, v109, v0
	v_fmac_f32_e32 v1, v124, v16
	v_mul_f32_e32 v16, v118, v0
	v_add_f32_e32 v0, v3, v17
	v_mov_b32_e32 v3, v2
	v_add_f32_e32 v1, v35, v1
	s_nop 0
	v_permlane32_swap_b32_e32 v2, v3
	v_fma_f32 v16, v109, v18, -v16
	v_mov_b32_e32 v2, v1
	v_add_f32_e32 v16, v19, v16
	s_nop 0
	v_permlane32_swap_b32_e32 v1, v2
	v_mov_b32_e32 v1, v16
	s_nop 1
	v_permlane32_swap_b32_e32 v16, v1
	v_mov_b32_e32 v16, v0
	s_nop 1
	v_permlane32_swap_b32_e32 v0, v16
	v_mul_f32_e32 v0, v114, v2
	v_mul_f32_e32 v2, v124, v2
	v_fma_f32 v0, v124, v3, -v0
	v_fmac_f32_e32 v2, v114, v3
	v_mul_f32_e32 v3, v118, v16
	v_mul_f32_e32 v16, v109, v16
	v_add_f32_e32 v2, v36, v2
	v_fmac_f32_e32 v16, v118, v1
	v_add_f32_e32 v0, v52, v0
	v_fma_f32 v3, v109, v1, -v3
	v_add_f32_e32 v1, v4, v16
	v_mul_f32_e32 v16, v114, v2
	v_fma_f32 v16, v124, v0, -v16
	v_mul_f32_e32 v0, v114, v0
	v_add_f32_e32 v3, v20, v3
	v_fmac_f32_e32 v0, v124, v2
	v_mul_f32_e32 v2, v118, v1
	v_fma_f32 v2, v109, v3, -v2
	v_mul_f32_e32 v3, v118, v3
	v_add_f32_e32 v0, v37, v0
	v_fmac_f32_e32 v3, v109, v1
	v_add_f32_e32 v16, v53, v16
	v_add_f32_e32 v1, v5, v3
	v_mul_f32_e32 v3, v114, v0
	v_fma_f32 v3, v124, v16, -v3
	v_mul_f32_e32 v16, v114, v16
	v_fmac_f32_e32 v16, v124, v0
	v_add_f32_e32 v2, v21, v2
	v_add_f32_e32 v0, v38, v16
	v_mul_f32_e32 v16, v118, v1
	v_fma_f32 v16, v109, v2, -v16
	v_mul_f32_e32 v2, v118, v2
	v_fmac_f32_e32 v2, v109, v1
	v_add_f32_e32 v3, v54, v3
	v_add_f32_e32 v1, v6, v2
	v_mul_f32_e32 v2, v114, v0
	v_fma_f32 v2, v124, v3, -v2
	v_mul_f32_e32 v3, v114, v3
	v_fmac_f32_e32 v3, v124, v0
	v_add_f32_e32 v16, v22, v16
	v_add_f32_e32 v0, v39, v3
	v_mul_f32_e32 v3, v118, v1
	v_fma_f32 v3, v109, v16, -v3
	v_mul_f32_e32 v16, v118, v16
	v_add_f32_e32 v2, v55, v2
	v_fmac_f32_e32 v16, v109, v1
	v_add_f32_e32 v1, v7, v16
	v_mov_b32_e32 v16, v2
	s_nop 1
	v_permlane32_swap_b32_e32 v2, v16
	v_mov_b32_e32 v16, v0
	v_add_f32_e32 v3, v23, v3
	s_nop 0
	v_permlane32_swap_b32_e32 v0, v16
; __device__ __forceinline__ float bf_lo(unsigned w) { return __uint_as_float(w << 16); }
; __device__ __forceinline__ float bf_hi(unsigned w) { return __uint_as_float(w & 0xffff0000u); }
; __device__ __forceinline__ unsigned pk_bf16(float lo, float hi) { return pg8::cvt_pk_bf16(lo, hi); }
; template <bool PASS2> __device__ __forceinline__ void ssm2_pass(const Ctx& c, int l) {
;     ...
;             for (int gq = 0; gq < 4; ++gq) {
; #pragma unroll
;                 for (int ps = 0; ps < 2; ++ps) {
; #pragma unroll
;                     for (int i = 0; i < 4; ++i) { const int r = 4 * gq + i;
;                         float nr = arA * xAr - aiA * xAi + D0[r], ni = arA * xAi + aiA * xAr + D2[r]; xAr = nr; xAi = ni;
;                         nr = arB * xBr - aiB * xBi + D1[r]; ni = arB * xBi + aiB * xBr + D3[r]; xBr = nr; xBi = ni;
;                         if (PASS2) { if (hi == ps) { const int row = (8 * gq + 4 * ps + i) & 15;
;                             const unsigned hr = pk_bf16(xAr, xBr), hm = pk_bf16(xAi, xBi);
;                             const unsigned lr = pk_bf16(xAr - bf_lo(hr), xBr - bf_hi(hr)), lm = pk_bf16(xAi - bf_lo(hm), xBi - bf_hi(hm));
;                             XP[row * 132 + q] = (hr & 0xffffu) | (lr << 16); XP[row * 132 + 32 + q] = (hr >> 16) | (lr & 0xffff0000u);
;                             XP[row * 132 + 64 + q] = (hm & 0xffffu) | (lm << 16); XP[row * 132 + 96 + q] = (hm >> 16) | (lm & 0xffff0000u); } } }
;                     xAr = half_bcast(xAr, ps); xAi = half_bcast(xAi, ps); xBr = half_bcast(xBr, ps); xBi = half_bcast(xBi, ps);
	v_mov_b32_e32 v16, v3
	s_nop 1
	v_permlane32_swap_b32_e32 v3, v16
	v_mov_b32_e32 v16, v1
	s_nop 1
	v_permlane32_swap_b32_e32 v1, v16
	v_mul_f32_e32 v16, v114, v0
	v_mul_f32_e32 v0, v124, v0
	v_fma_f32 v16, v124, v2, -v16
	v_fmac_f32_e32 v0, v114, v2
	v_mul_f32_e32 v2, v118, v1
	v_mul_f32_e32 v1, v109, v1
	v_add_f32_e32 v16, v52, v16
	v_fmac_f32_e32 v1, v118, v3
	v_add_f32_e32 v0, v36, v0
	v_add_f32_e32 v1, v4, v1
	v_mul_f32_e32 v4, v114, v16
	v_fma_f32 v2, v109, v3, -v2
	v_fmac_f32_e32 v4, v124, v0
	v_add_f32_e32 v2, v20, v2
	v_mul_f32_e32 v3, v114, v0
	v_add_f32_e32 v0, v37, v4
	v_mul_f32_e32 v4, v118, v1
	v_fma_f32 v4, v109, v2, -v4
	v_mul_f32_e32 v2, v118, v2
	v_fma_f32 v3, v124, v16, -v3
	v_fmac_f32_e32 v2, v109, v1
	v_add_f32_e32 v3, v53, v3
	v_add_f32_e32 v1, v5, v2
	v_mul_f32_e32 v2, v114, v0
	v_fma_f32 v2, v124, v3, -v2
	v_mul_f32_e32 v3, v114, v3
	v_fmac_f32_e32 v3, v124, v0
	v_add_f32_e32 v4, v21, v4
	v_add_f32_e32 v0, v38, v3
	v_mul_f32_e32 v3, v118, v1
	v_fma_f32 v3, v109, v4, -v3
	v_mul_f32_e32 v4, v118, v4
	v_fmac_f32_e32 v4, v109, v1
	v_add_f32_e32 v2, v54, v2
	v_add_f32_e32 v1, v6, v4
	v_mul_f32_e32 v4, v114, v0
	v_fma_f32 v4, v124, v2, -v4
	v_mul_f32_e32 v2, v114, v2
	v_fmac_f32_e32 v2, v124, v0
	v_add_f32_e32 v3, v22, v3
	v_add_f32_e32 v0, v39, v2
	v_mul_f32_e32 v2, v118, v1
	v_fma_f32 v2, v109, v3, -v2
	v_mul_f32_e32 v3, v118, v3
	v_add_f32_e32 v4, v55, v4
	v_fmac_f32_e32 v3, v109, v1
	v_add_f32_e32 v1, v7, v3
	v_mov_b32_e32 v3, v4
	s_nop 1
	v_permlane32_swap_b32_e32 v4, v3
	v_mov_b32_e32 v4, v0
	v_add_f32_e32 v2, v23, v2
	s_nop 0
	v_permlane32_swap_b32_e32 v0, v4
	v_mov_b32_e32 v0, v2
	s_nop 1
	v_permlane32_swap_b32_e32 v2, v0
	v_mov_b32_e32 v2, v1
	s_nop 1
	v_permlane32_swap_b32_e32 v1, v2
	v_mul_f32_e32 v1, v114, v4
	v_mul_f32_e32 v4, v124, v4
	v_fmac_f32_e32 v4, v114, v3
	v_fma_f32 v1, v124, v3, -v1
	v_add_f32_e32 v3, v40, v4
	v_mul_f32_e32 v4, v118, v2
	v_mul_f32_e32 v2, v109, v2
	v_fmac_f32_e32 v2, v118, v0
	v_add_f32_e32 v1, v56, v1
	v_fma_f32 v4, v109, v0, -v4
	v_add_f32_e32 v0, v8, v2
	v_mul_f32_e32 v2, v114, v3
	v_fma_f32 v2, v124, v1, -v2
	v_mul_f32_e32 v1, v114, v1
	v_add_f32_e32 v4, v24, v4
	v_fmac_f32_e32 v1, v124, v3
	v_mul_f32_e32 v3, v118, v0
	v_fma_f32 v3, v109, v4, -v3
	v_mul_f32_e32 v4, v118, v4
	v_add_f32_e32 v1, v41, v1
	v_fmac_f32_e32 v4, v109, v0
	v_add_f32_e32 v2, v57, v2
	v_add_f32_e32 v0, v9, v4
	v_mul_f32_e32 v4, v114, v1
	v_fma_f32 v4, v124, v2, -v4
	v_mul_f32_e32 v2, v114, v2
	v_fmac_f32_e32 v2, v124, v1
	v_add_f32_e32 v3, v25, v3
	v_add_f32_e32 v1, v42, v2
	v_mul_f32_e32 v2, v118, v0
	v_fma_f32 v2, v109, v3, -v2
	v_mul_f32_e32 v3, v118, v3
	v_fmac_f32_e32 v3, v109, v0
	v_add_f32_e32 v4, v58, v4
	v_add_f32_e32 v0, v10, v3
	v_mul_f32_e32 v3, v114, v1
	v_fma_f32 v3, v124, v4, -v3
	v_mul_f32_e32 v4, v114, v4
	v_fmac_f32_e32 v4, v124, v1
	v_add_f32_e32 v2, v26, v2
	v_add_f32_e32 v1, v43, v4
	v_mul_f32_e32 v4, v118, v0
	v_fma_f32 v4, v109, v2, -v4
	v_mul_f32_e32 v2, v118, v2
	v_add_f32_e32 v3, v59, v3
	v_fmac_f32_e32 v2, v109, v0
	v_add_f32_e32 v0, v11, v2
	v_mov_b32_e32 v2, v3
	s_nop 1
	v_permlane32_swap_b32_e32 v3, v2
	v_mov_b32_e32 v2, v1
	v_add_f32_e32 v4, v27, v4
	s_nop 0
	v_permlane32_swap_b32_e32 v1, v2
	v_mov_b32_e32 v2, v4
	s_nop 1
	v_permlane32_swap_b32_e32 v4, v2
	v_mov_b32_e32 v2, v0
	s_nop 1
	v_permlane32_swap_b32_e32 v0, v2
	v_mul_f32_e32 v2, v114, v1
	v_mul_f32_e32 v1, v124, v1
	v_fmac_f32_e32 v1, v114, v3
	v_fma_f32 v2, v124, v3, -v2
	v_add_f32_e32 v1, v40, v1
	v_mul_f32_e32 v3, v118, v0
	v_mul_f32_e32 v0, v109, v0
	v_add_f32_e32 v2, v56, v2
	v_fma_f32 v3, v109, v4, -v3
	v_fmac_f32_e32 v0, v118, v4
	v_mul_f32_e32 v4, v114, v1
	v_fma_f32 v4, v124, v2, -v4
	v_mul_f32_e32 v2, v114, v2
	v_add_f32_e32 v0, v8, v0
	v_fmac_f32_e32 v2, v124, v1
	v_add_f32_e32 v3, v24, v3
	v_add_f32_e32 v1, v41, v2
	v_mul_f32_e32 v2, v118, v0
	v_fma_f32 v2, v109, v3, -v2
	v_mul_f32_e32 v3, v118, v3
	v_fmac_f32_e32 v3, v109, v0
	v_add_f32_e32 v4, v57, v4
	v_add_f32_e32 v0, v9, v3
	v_mul_f32_e32 v3, v114, v1
	v_fma_f32 v3, v124, v4, -v3
	v_mul_f32_e32 v4, v114, v4
	v_fmac_f32_e32 v4, v124, v1
	v_add_f32_e32 v2, v25, v2
	v_add_f32_e32 v1, v42, v4
	v_mul_f32_e32 v4, v118, v0
	v_fma_f32 v4, v109, v2, -v4
	v_mul_f32_e32 v2, v118, v2
; __device__ __forceinline__ float bf_lo(unsigned w) { return __uint_as_float(w << 16); }
; __device__ __forceinline__ float bf_hi(unsigned w) { return __uint_as_float(w & 0xffff0000u); }
; __device__ __forceinline__ unsigned pk_bf16(float lo, float hi) { return pg8::cvt_pk_bf16(lo, hi); }
; template <bool PASS2> __device__ __forceinline__ void ssm2_pass(const Ctx& c, int l) {
;     ...
;             for (int gq = 0; gq < 4; ++gq) {
; #pragma unroll
;                 for (int ps = 0; ps < 2; ++ps) {
; #pragma unroll
;                     for (int i = 0; i < 4; ++i) { const int r = 4 * gq + i;
;                         float nr = arA * xAr - aiA * xAi + D0[r], ni = arA * xAi + aiA * xAr + D2[r]; xAr = nr; xAi = ni;
;                         nr = arB * xBr - aiB * xBi + D1[r]; ni = arB * xBi + aiB * xBr + D3[r]; xBr = nr; xBi = ni;
;                         if (PASS2) { if (hi == ps) { const int row = (8 * gq + 4 * ps + i) & 15;
;                             const unsigned hr = pk_bf16(xAr, xBr), hm = pk_bf16(xAi, xBi);
;                             const unsigned lr = pk_bf16(xAr - bf_lo(hr), xBr - bf_hi(hr)), lm = pk_bf16(xAi - bf_lo(hm), xBi - bf_hi(hm));
;                             XP[row * 132 + q] = (hr & 0xffffu) | (lr << 16); XP[row * 132 + 32 + q] = (hr >> 16) | (lr & 0xffff0000u);
;                             XP[row * 132 + 64 + q] = (hm & 0xffffu) | (lm << 16); XP[row * 132 + 96 + q] = (hm >> 16) | (lm & 0xffff0000u); } } }
;                     xAr = half_bcast(xAr, ps); xAi = half_bcast(xAi, ps); xBr = half_bcast(xBr, ps); xBi = half_bcast(xBi, ps);
;                 }
;     ...
;         if (!PASS2) { if (hi == 0) { *(float2*)(send + ((size_t)(bg * 16 + tk) * 64 + q) * 2) = make_float2(xAr, xAi); *(float2*)(send + ((size_t)(bg * 16 + tk) * 64 + 32 + q) * 2) = make_float2(xBr, xBi); } }
	v_fmac_f32_e32 v2, v109, v0
	v_add_f32_e32 v3, v58, v3
	v_add_f32_e32 v0, v10, v2
	v_mul_f32_e32 v2, v114, v1
	v_fma_f32 v2, v124, v3, -v2
	v_mul_f32_e32 v3, v114, v3
	v_fmac_f32_e32 v3, v124, v1
	v_add_f32_e32 v4, v26, v4
	v_add_f32_e32 v1, v43, v3
	v_mul_f32_e32 v3, v118, v0
	v_fma_f32 v3, v109, v4, -v3
	v_mul_f32_e32 v4, v118, v4
	v_add_f32_e32 v2, v59, v2
	v_fmac_f32_e32 v4, v109, v0
	v_add_f32_e32 v0, v11, v4
	v_mov_b32_e32 v4, v2
	s_nop 1
	v_permlane32_swap_b32_e32 v2, v4
	v_mov_b32_e32 v2, v1
	v_add_f32_e32 v3, v27, v3
	s_nop 0
	v_permlane32_swap_b32_e32 v1, v2
	v_mov_b32_e32 v1, v3
	s_nop 1
	v_permlane32_swap_b32_e32 v3, v1
	v_mov_b32_e32 v3, v0
	s_nop 1
	v_permlane32_swap_b32_e32 v0, v3
	v_mul_f32_e32 v0, v114, v2
	v_mul_f32_e32 v2, v124, v2
	v_fma_f32 v0, v124, v4, -v0
	v_fmac_f32_e32 v2, v114, v4
	v_mul_f32_e32 v4, v118, v3
	v_mul_f32_e32 v3, v109, v3
	v_add_f32_e32 v2, v44, v2
	v_fmac_f32_e32 v3, v118, v1
	v_add_f32_e32 v0, v60, v0
	v_fma_f32 v4, v109, v1, -v4
	v_add_f32_e32 v1, v12, v3
	v_mul_f32_e32 v3, v114, v2
	v_fma_f32 v3, v124, v0, -v3
	v_mul_f32_e32 v0, v114, v0
	v_add_f32_e32 v4, v28, v4
	v_fmac_f32_e32 v0, v124, v2
	v_mul_f32_e32 v2, v118, v1
	v_fma_f32 v2, v109, v4, -v2
	v_mul_f32_e32 v4, v118, v4
	v_add_f32_e32 v0, v45, v0
	v_fmac_f32_e32 v4, v109, v1
	v_add_f32_e32 v3, v61, v3
	v_add_f32_e32 v1, v13, v4
	v_mul_f32_e32 v4, v114, v0
	v_fma_f32 v4, v124, v3, -v4
	v_mul_f32_e32 v3, v114, v3
	v_fmac_f32_e32 v3, v124, v0
	v_add_f32_e32 v2, v29, v2
	v_add_f32_e32 v0, v46, v3
	v_mul_f32_e32 v3, v118, v1
	v_fma_f32 v3, v109, v2, -v3
	v_mul_f32_e32 v2, v118, v2
	v_fmac_f32_e32 v2, v109, v1
	v_add_f32_e32 v4, v62, v4
	v_add_f32_e32 v1, v14, v2
	v_mul_f32_e32 v2, v114, v0
	v_fma_f32 v2, v124, v4, -v2
	v_mul_f32_e32 v4, v114, v4
	v_fmac_f32_e32 v4, v124, v0
	v_add_f32_e32 v3, v30, v3
	v_add_f32_e32 v0, v47, v4
	v_mul_f32_e32 v4, v118, v1
	v_fma_f32 v4, v109, v3, -v4
	v_mul_f32_e32 v3, v118, v3
	v_add_f32_e32 v2, v63, v2
	v_fmac_f32_e32 v3, v109, v1
	v_add_f32_e32 v1, v15, v3
	v_mov_b32_e32 v3, v2
	s_nop 1
	v_permlane32_swap_b32_e32 v2, v3
	v_mov_b32_e32 v3, v0
	v_add_f32_e32 v4, v31, v4
	s_nop 0
	v_permlane32_swap_b32_e32 v0, v3
	v_mov_b32_e32 v3, v4
	s_nop 1
	v_permlane32_swap_b32_e32 v4, v3
	v_mov_b32_e32 v3, v1
	s_nop 1
	v_permlane32_swap_b32_e32 v1, v3
	v_mul_f32_e32 v3, v114, v0
	v_mul_f32_e32 v0, v124, v0
	v_fmac_f32_e32 v0, v114, v2
	v_fma_f32 v3, v124, v2, -v3
	v_add_f32_e32 v0, v44, v0
	v_mul_f32_e32 v2, v118, v1
	v_mul_f32_e32 v1, v109, v1
	v_add_f32_e32 v3, v60, v3
	v_fma_f32 v2, v109, v4, -v2
	v_fmac_f32_e32 v1, v118, v4
	v_mul_f32_e32 v4, v114, v0
	v_fma_f32 v4, v124, v3, -v4
	v_mul_f32_e32 v3, v114, v3
	v_add_f32_e32 v1, v12, v1
	v_fmac_f32_e32 v3, v124, v0
	v_add_f32_e32 v2, v28, v2
	v_add_f32_e32 v0, v45, v3
	v_mul_f32_e32 v3, v118, v1
	v_fma_f32 v3, v109, v2, -v3
	v_mul_f32_e32 v2, v118, v2
	v_fmac_f32_e32 v2, v109, v1
	v_add_f32_e32 v4, v61, v4
	v_add_f32_e32 v1, v13, v2
	v_mul_f32_e32 v2, v114, v0
	v_fma_f32 v2, v124, v4, -v2
	v_mul_f32_e32 v4, v114, v4
	v_fmac_f32_e32 v4, v124, v0
	v_add_f32_e32 v3, v29, v3
	v_add_f32_e32 v0, v46, v4
	v_mul_f32_e32 v4, v118, v1
	v_fma_f32 v4, v109, v3, -v4
	v_mul_f32_e32 v3, v118, v3
	v_fmac_f32_e32 v3, v109, v1
	v_add_f32_e32 v2, v62, v2
	v_add_f32_e32 v1, v14, v3
	v_mul_f32_e32 v3, v114, v0
	v_fma_f32 v3, v124, v2, -v3
	v_mul_f32_e32 v2, v114, v2
	v_fmac_f32_e32 v2, v124, v0
	v_add_f32_e32 v4, v30, v4
	v_add_f32_e32 v0, v47, v2
	v_mul_f32_e32 v2, v118, v1
	v_fma_f32 v2, v109, v4, -v2
	v_mul_f32_e32 v4, v118, v4
	v_fmac_f32_e32 v4, v109, v1
	v_add_f32_e32 v3, v63, v3
	v_add_f32_e32 v2, v31, v2
	v_add_f32_e32 v1, v15, v4
	v_mov_b32_e32 v116, v3
	v_mov_b32_e32 v117, v0
	v_mov_b32_e32 v122, v2
	v_mov_b32_e32 v123, v1
	v_permlane32_swap_b32_e32 v3, v116
	v_permlane32_swap_b32_e32 v0, v117
	v_permlane32_swap_b32_e32 v2, v122
	v_permlane32_swap_b32_e32 v1, v123
	s_cbranch_scc0 .LBB0_380
	s_and_saveexec_b64 s[40:41], s[38:39]
	s_cbranch_execz .LBB0_360
	s_ashr_i32 s47, s46, 31
	s_lshl_b64 s[12:13], s[46:47], 9
	v_lshl_add_u64 v[0:1], v[110:111], 0, s[12:13]
	global_store_dwordx2 v[0:1], v[116:117], off sc1
	global_store_dwordx2 v[0:1], v[122:123], off offset:256 sc1
	s_branch .LBB0_360

;     __device__ __forceinline__ void operator()(const f32x4 (&acc)[2][2][4][2], const Unit& u, int wr, int wc, int fr, int fq) const {
;     ...
;             const char* sp = (const char*)(stats + (size_t)u.pm * BM * 2);
;             unsigned soff0 = (unsigned)(wr * 64 + fr) * 8u, coff0 = (unsigned)(u.pn * BM + wc * 32 + 4 * fq) * 4u; asm volatile("" : "+v"(soff0), "+v"(coff0));
;             f32x4 gv[2][2], bv[2][2];
; #pragma unroll
;             for (int bj = 0; bj < 2; ++bj)
; #pragma unroll
;                 for (int n = 0; n < 2; ++n) { gv[bj][n] = *(const f32x4*)((const char*)lng + coff0 + (unsigned)(bj * HALF + n * 16) * 4u); bv[bj][n] = *(const f32x4*)((const char*)lnb + coff0 + (unsigned)(bj * HALF + n * 16) * 4u); }
; #pragma unroll
;             for (int ai = 0; ai < 2; ++ai)
; #pragma unroll
;                 for (int mh = 0; mh < 2; ++mh) {
;                     f32x4 bs[2][2][2]; f32x2_t st[2];
; #pragma unroll
;                     for (int mm = 0; mm < 2; ++mm) { st[mm] = *(const f32x2_t*)(sp + soff0 + (unsigned)(ai * HALF + (2 * mh + mm) * 16) * 8u);
; #pragma unroll
;                         for (int bj = 0; bj < 2; ++bj)
; #pragma unroll
;                             for (int n = 0; n < 2; ++n) bs[mm][bj][n] = *(const f32x4*)(bb + off0 + (unsigned)((ai * HALF + (2 * mh + mm) * 16) * 1024 + bj * HALF + n * 16) * 4u); }
; #pragma unroll
;                     for (int mm = 0; mm < 2; ++mm)
; #pragma unroll
;                         for (int bj = 0; bj < 2; ++bj)
; #pragma unroll
;                             for (int n = 0; n < 2; ++n) { const f32x4 hv = ((bs[mm][bj][n] - st[mm][0]) * st[mm][1]) * gv[bj][n] + bv[bj][n];
;                                 *(f32x4*)(ob + off0 + (unsigned)((ai * HALF + (2 * mh + mm) * 16) * 1024 + bj * HALF + n * 16) * 4u) = hv * DN_ALPHA + acc[ai][bj][2 * mh + mm][n]; }
.LBB0_443:
	s_ashr_i32 s71, s70, 31
	s_lshl_b32 s86, s72, 8
	v_readlane_b32 s24, v253, 0
	s_lshl_b64 s[66:67], s[70:71], 18
	s_ashr_i32 s68, s86, 31
	v_readlane_b32 s25, v253, 1
	s_add_u32 s66, s66, s86
	s_load_dwordx4 s[76:79], s[24:25], 0xa8
	s_addc_u32 s67, s67, s68
	s_lshl_b64 s[66:67], s[66:67], 2
	s_add_u32 s68, s46, s66
	v_mov_b32_e32 v96, v212
	s_addc_u32 s69, s47, s67
	s_waitcnt lgkmcnt(0)
	s_add_u32 s66, s76, s66
	v_readfirstlane_b32 s73, v96
	s_addc_u32 s67, s77, s67
	s_ashr_i32 s72, s73, 2
	s_andn2_b32 s72, s72, 63
	v_and_or_b32 v130, v96, 15, s72
	s_lshr_b32 s72, s73, 1
	v_lshrrev_b32_e32 v96, 2, v96
	v_lshlrev_b32_e32 v132, 10, v130
	s_and_b32 s87, s72, 0x60
	v_and_b32_e32 v131, 12, v96
	v_or3_b32 v96, v132, s87, v131
	v_lshlrev_b32_e32 v96, 2, v96
	s_mov_b64 s[72:73], -1
	s_and_b64 vcc, exec, s[44:45]
	s_cbranch_vccz .LBB0_445
	s_or_b32 s72, s86, s87
	s_lshl_b64 s[70:71], s[70:71], 11
	v_lshlrev_b32_e32 v190, 3, v130
	v_or_b32_e32 v130, s72, v131
	v_readlane_b32 s24, v253, 37
	v_lshlrev_b32_e32 v134, 2, v130
	s_add_u32 s70, s24, s70
	v_readlane_b32 s24, v253, 38
	s_addc_u32 s71, s24, s71
	global_load_dwordx4 v[154:157], v134, s[54:55]
	global_load_dwordx4 v[158:161], v134, s[42:43]
	global_load_dwordx4 v[146:149], v134, s[54:55] offset:64
	global_load_dwordx4 v[150:153], v134, s[42:43] offset:64
	global_load_dwordx4 v[138:141], v134, s[54:55] offset:512
	global_load_dwordx4 v[142:145], v134, s[42:43] offset:512
	global_load_dwordx4 v[130:133], v134, s[54:55] offset:576
	s_nop 0
	global_load_dwordx4 v[134:137], v134, s[42:43] offset:576
	s_nop 0
	global_load_dwordx2 v[186:187], v190, s[70:71]
	global_load_dwordx4 v[202:205], v96, s[68:69]
	global_load_dwordx4 v[206:209], v96, s[68:69] offset:64
	global_load_dwordx4 v[230:233], v96, s[68:69] offset:512
	global_load_dwordx4 v[234:237], v96, s[68:69] offset:576
	global_load_dwordx2 v[182:183], v190, s[70:71] offset:128
	v_lshl_add_u64 v[162:163], s[68:69], 0, v[96:97]
	s_mov_b32 s24, 0x10000
	v_add_co_u32_e32 v162, vcc, s24, v162
	v_lshl_add_u64 v[184:185], s[66:67], 0, v[96:97]
	s_nop 0
	v_addc_co_u32_e32 v163, vcc, 0, v163, vcc
	global_load_dwordx4 v[238:241], v[162:163], off
	global_load_dwordx4 v[170:173], v[162:163], off offset:64
	global_load_dwordx4 v[166:169], v[162:163], off offset:512
	s_nop 0
	global_load_dwordx4 v[162:165], v[162:163], off offset:576
	v_add_co_u32_e32 v184, vcc, s24, v184
	s_mov_b32 s24, 0x20000
	s_nop 0
	v_addc_co_u32_e32 v185, vcc, 0, v185, vcc
	s_mov_b32 s25, 0x30000
	s_mov_b64 s[72:73], 0
	s_waitcnt vmcnt(0)
	v_sub_f32_e32 v193, v205, v186
	v_sub_f32_e32 v192, v204, v186
	v_sub_f32_e32 v203, v203, v186
	v_sub_f32_e32 v202, v202, v186
	v_pk_mul_f32 v[202:203], v[186:187], v[202:203] op_sel:[1,0]
	v_pk_mul_f32 v[192:193], v[186:187], v[192:193] op_sel:[1,0]
	v_pk_fma_f32 v[202:203], v[154:155], v[202:203], v[158:159]
	v_pk_fma_f32 v[192:193], v[156:157], v[192:193], v[160:161]
	v_pk_fma_f32 v[202:203], v[202:203], s[88:89], v[126:127] op_sel_hi:[1,0,1]
	v_pk_fma_f32 v[204:205], v[192:193], s[88:89], v[128:129] op_sel_hi:[1,0,1]
	global_store_dwordx4 v96, v[202:205], s[66:67] sc1
	v_sub_f32_e32 v193, v209, v186
	v_sub_f32_e32 v192, v208, v186
	v_sub_f32_e32 v203, v207, v186
	v_sub_f32_e32 v202, v206, v186
	v_pk_mul_f32 v[202:203], v[186:187], v[202:203] op_sel:[1,0]
	v_pk_mul_f32 v[192:193], v[186:187], v[192:193] op_sel:[1,0]
	v_pk_fma_f32 v[202:203], v[146:147], v[202:203], v[150:151]
	v_pk_fma_f32 v[192:193], v[148:149], v[192:193], v[152:153]
	v_pk_fma_f32 v[202:203], v[202:203], s[88:89], v[122:123] op_sel_hi:[1,0,1]
	v_pk_fma_f32 v[204:205], v[192:193], s[88:89], v[124:125] op_sel_hi:[1,0,1]
	global_store_dwordx4 v96, v[202:205], s[66:67] offset:64 sc1
	v_sub_f32_e32 v193, v233, v186
	v_sub_f32_e32 v192, v232, v186
	v_sub_f32_e32 v203, v231, v186
	v_sub_f32_e32 v202, v230, v186
	v_pk_mul_f32 v[202:203], v[186:187], v[202:203] op_sel:[1,0]
	v_pk_mul_f32 v[192:193], v[186:187], v[192:193] op_sel:[1,0]
	v_pk_fma_f32 v[202:203], v[138:139], v[202:203], v[142:143]
	v_pk_fma_f32 v[192:193], v[140:141], v[192:193], v[144:145]
	v_pk_fma_f32 v[202:203], v[202:203], s[88:89], v[118:119] op_sel_hi:[1,0,1]
	v_pk_fma_f32 v[204:205], v[192:193], s[88:89], v[120:121] op_sel_hi:[1,0,1]
	global_store_dwordx4 v96, v[202:205], s[66:67] offset:512 sc1
	v_sub_f32_e32 v193, v237, v186
	v_sub_f32_e32 v192, v236, v186
	v_sub_f32_e32 v203, v235, v186
	v_sub_f32_e32 v202, v234, v186
	v_pk_mul_f32 v[202:203], v[186:187], v[202:203] op_sel:[1,0]
	v_pk_mul_f32 v[186:187], v[186:187], v[192:193] op_sel:[1,0]
	v_pk_fma_f32 v[192:193], v[130:131], v[202:203], v[134:135]
	v_pk_fma_f32 v[186:187], v[132:133], v[186:187], v[136:137]
	v_pk_fma_f32 v[202:203], v[192:193], s[88:89], v[114:115] op_sel_hi:[1,0,1]
	v_pk_fma_f32 v[204:205], v[186:187], s[88:89], v[116:117] op_sel_hi:[1,0,1]
	v_sub_f32_e32 v187, v239, v182
	v_sub_f32_e32 v186, v238, v182
	v_sub_f32_e32 v193, v241, v182
	v_sub_f32_e32 v192, v240, v182
	v_sub_f32_e32 v171, v171, v182
	v_sub_f32_e32 v170, v170, v182
	v_sub_f32_e32 v173, v173, v182
	v_sub_f32_e32 v172, v172, v182
	v_sub_f32_e32 v167, v167, v182
	v_sub_f32_e32 v166, v166, v182
	v_sub_f32_e32 v169, v169, v182
	v_sub_f32_e32 v168, v168, v182
	v_sub_f32_e32 v163, v163, v182
	v_sub_f32_e32 v162, v162, v182
	v_sub_f32_e32 v165, v165, v182
	v_sub_f32_e32 v164, v164, v182
	v_pk_mul_f32 v[192:193], v[182:183], v[192:193] op_sel:[1,0]
	v_pk_mul_f32 v[186:187], v[182:183], v[186:187] op_sel:[1,0]
	v_pk_mul_f32 v[172:173], v[182:183], v[172:173] op_sel:[1,0]
	v_pk_mul_f32 v[170:171], v[182:183], v[170:171] op_sel:[1,0]
	v_pk_mul_f32 v[168:169], v[182:183], v[168:169] op_sel:[1,0]
;     __device__ __forceinline__ void operator()(const f32x4 (&acc)[2][2][4][2], const Unit& u, int wr, int wc, int fr, int fq) const {
;     ...
;                 for (int mh = 0; mh < 2; ++mh) {
;                     f32x4 bs[2][2][2]; f32x2_t st[2];
; #pragma unroll
;                     for (int mm = 0; mm < 2; ++mm) { st[mm] = *(const f32x2_t*)(sp + soff0 + (unsigned)(ai * HALF + (2 * mh + mm) * 16) * 8u);
; #pragma unroll
;                         for (int bj = 0; bj < 2; ++bj)
; #pragma unroll
;                             for (int n = 0; n < 2; ++n) bs[mm][bj][n] = *(const f32x4*)(bb + off0 + (unsigned)((ai * HALF + (2 * mh + mm) * 16) * 1024 + bj * HALF + n * 16) * 4u); }
; #pragma unroll
;                     for (int mm = 0; mm < 2; ++mm)
; #pragma unroll
;                         for (int bj = 0; bj < 2; ++bj)
; #pragma unroll
;                             for (int n = 0; n < 2; ++n) { const f32x4 hv = ((bs[mm][bj][n] - st[mm][0]) * st[mm][1]) * gv[bj][n] + bv[bj][n];
;                                 *(f32x4*)(ob + off0 + (unsigned)((ai * HALF + (2 * mh + mm) * 16) * 1024 + bj * HALF + n * 16) * 4u) = hv * DN_ALPHA + acc[ai][bj][2 * mh + mm][n]; }
;                     asm volatile("" : "+v"(off0), "+v"(soff0) :: "memory"); }
	v_pk_mul_f32 v[166:167], v[182:183], v[166:167] op_sel:[1,0]
	v_pk_mul_f32 v[164:165], v[182:183], v[164:165] op_sel:[1,0]
	v_pk_mul_f32 v[162:163], v[182:183], v[162:163] op_sel:[1,0]
	v_pk_fma_f32 v[186:187], v[154:155], v[186:187], v[158:159]
	v_pk_fma_f32 v[192:193], v[156:157], v[192:193], v[160:161]
	v_pk_fma_f32 v[170:171], v[146:147], v[170:171], v[150:151]
	v_pk_fma_f32 v[172:173], v[148:149], v[172:173], v[152:153]
	v_pk_fma_f32 v[166:167], v[138:139], v[166:167], v[142:143]
	v_pk_fma_f32 v[168:169], v[140:141], v[168:169], v[144:145]
	v_pk_fma_f32 v[162:163], v[130:131], v[162:163], v[134:135]
	v_pk_fma_f32 v[164:165], v[132:133], v[164:165], v[136:137]
	global_store_dwordx4 v96, v[202:205], s[66:67] offset:576 sc1
	v_pk_fma_f32 v[172:173], v[172:173], s[88:89], v[108:109] op_sel_hi:[1,0,1]
	v_pk_fma_f32 v[170:171], v[170:171], s[88:89], v[106:107] op_sel_hi:[1,0,1]
	v_pk_fma_f32 v[204:205], v[192:193], s[88:89], v[112:113] op_sel_hi:[1,0,1]
	v_pk_fma_f32 v[202:203], v[186:187], s[88:89], v[110:111] op_sel_hi:[1,0,1]
	v_pk_fma_f32 v[168:169], v[168:169], s[88:89], v[104:105] op_sel_hi:[1,0,1]
	v_pk_fma_f32 v[166:167], v[166:167], s[88:89], v[102:103] op_sel_hi:[1,0,1]
	v_pk_fma_f32 v[164:165], v[164:165], s[88:89], v[100:101] op_sel_hi:[1,0,1]
	v_pk_fma_f32 v[162:163], v[162:163], s[88:89], v[98:99] op_sel_hi:[1,0,1]
	global_store_dwordx4 v[184:185], v[202:205], off sc1
	global_store_dwordx4 v[184:185], v[170:173], off offset:64 sc1
	global_store_dwordx4 v[184:185], v[166:169], off offset:512 sc1
	global_store_dwordx4 v[184:185], v[162:165], off offset:576 sc1
	v_mov_b32_e32 v182, v96
	v_mov_b32_e32 v183, v97
	global_load_dwordx2 v[192:193], v190, s[70:71] offset:256
	v_lshl_add_u64 v[162:163], s[68:69], 0, v[182:183]
	v_add_co_u32_e32 v164, vcc, s24, v162
	v_lshl_add_u64 v[186:187], s[66:67], 0, v[182:183]
	s_nop 0
	v_addc_co_u32_e32 v165, vcc, 0, v163, vcc
	global_load_dwordx4 v[202:205], v[164:165], off
	global_load_dwordx4 v[206:209], v[164:165], off offset:64
	global_load_dwordx4 v[230:233], v[164:165], off offset:512
	global_load_dwordx4 v[234:237], v[164:165], off offset:576
	global_load_dwordx2 v[184:185], v190, s[70:71] offset:384
	v_add_co_u32_e32 v162, vcc, s25, v162
	s_waitcnt vmcnt(4)
	v_sub_f32_e32 v203, v203, v192
	v_addc_co_u32_e32 v163, vcc, 0, v163, vcc
	global_load_dwordx4 v[238:241], v[162:163], off
	global_load_dwordx4 v[170:173], v[162:163], off offset:64
	global_load_dwordx4 v[166:169], v[162:163], off offset:512
	s_nop 0
	global_load_dwordx4 v[162:165], v[162:163], off offset:576
	v_sub_f32_e32 v202, v202, v192
	v_sub_f32_e32 v205, v205, v192
	v_sub_f32_e32 v204, v204, v192
	v_pk_mul_f32 v[204:205], v[192:193], v[204:205] op_sel:[1,0]
	v_pk_mul_f32 v[202:203], v[192:193], v[202:203] op_sel:[1,0]
	v_pk_fma_f32 v[204:205], v[156:157], v[204:205], v[160:161]
	v_pk_fma_f32 v[202:203], v[154:155], v[202:203], v[158:159]
	v_add_co_u32_e32 v210, vcc, s24, v186
	v_pk_fma_f32 v[204:205], v[204:205], s[88:89], v[94:95] op_sel_hi:[1,0,1]
	v_pk_fma_f32 v[202:203], v[202:203], s[88:89], v[92:93] op_sel_hi:[1,0,1]
	v_addc_co_u32_e32 v211, vcc, 0, v187, vcc
	global_store_dwordx4 v[210:211], v[202:205], off sc1
	v_add_co_u32_e32 v186, vcc, s25, v186
	s_waitcnt vmcnt(8)
	v_sub_f32_e32 v203, v207, v192
	v_sub_f32_e32 v202, v206, v192
	v_sub_f32_e32 v205, v209, v192
	v_sub_f32_e32 v204, v208, v192
	v_pk_mul_f32 v[204:205], v[192:193], v[204:205] op_sel:[1,0]
	v_pk_mul_f32 v[202:203], v[192:193], v[202:203] op_sel:[1,0]
	v_pk_fma_f32 v[204:205], v[148:149], v[204:205], v[152:153]
	v_pk_fma_f32 v[202:203], v[146:147], v[202:203], v[150:151]
	v_pk_fma_f32 v[204:205], v[204:205], s[88:89], v[90:91] op_sel_hi:[1,0,1]
	v_pk_fma_f32 v[202:203], v[202:203], s[88:89], v[88:89] op_sel_hi:[1,0,1]
	global_store_dwordx4 v[210:211], v[202:205], off offset:64 sc1
	v_addc_co_u32_e32 v187, vcc, 0, v187, vcc
	s_waitcnt vmcnt(8)
	v_sub_f32_e32 v203, v231, v192
	v_sub_f32_e32 v202, v230, v192
	v_sub_f32_e32 v205, v233, v192
	v_sub_f32_e32 v204, v232, v192
	v_pk_mul_f32 v[204:205], v[192:193], v[204:205] op_sel:[1,0]
	v_pk_mul_f32 v[202:203], v[192:193], v[202:203] op_sel:[1,0]
	v_pk_fma_f32 v[204:205], v[140:141], v[204:205], v[144:145]
	v_pk_fma_f32 v[202:203], v[138:139], v[202:203], v[142:143]
	v_pk_fma_f32 v[204:205], v[204:205], s[88:89], v[86:87] op_sel_hi:[1,0,1]
	v_pk_fma_f32 v[202:203], v[202:203], s[88:89], v[84:85] op_sel_hi:[1,0,1]
	global_store_dwordx4 v[210:211], v[202:205], off offset:512 sc1
	s_mov_b32 s24, 0x80000
	s_mov_b32 s25, 0x90000
	s_waitcnt vmcnt(8)
	v_sub_f32_e32 v203, v235, v192
	v_sub_f32_e32 v202, v234, v192
	v_sub_f32_e32 v205, v237, v192
	v_sub_f32_e32 v204, v236, v192
	v_pk_mul_f32 v[204:205], v[192:193], v[204:205] op_sel:[1,0]
	v_pk_mul_f32 v[192:193], v[192:193], v[202:203] op_sel:[1,0]
	v_pk_fma_f32 v[202:203], v[132:133], v[204:205], v[136:137]
	v_pk_fma_f32 v[192:193], v[130:131], v[192:193], v[134:135]
	v_pk_fma_f32 v[204:205], v[202:203], s[88:89], v[82:83] op_sel_hi:[1,0,1]
	v_pk_fma_f32 v[202:203], v[192:193], s[88:89], v[80:81] op_sel_hi:[1,0,1]
	global_store_dwordx4 v[210:211], v[202:205], off offset:576 sc1
	s_waitcnt vmcnt(7)
	v_sub_f32_e32 v193, v239, v184
	v_sub_f32_e32 v192, v238, v184
	v_sub_f32_e32 v203, v241, v184
	v_sub_f32_e32 v202, v240, v184
	s_waitcnt vmcnt(6)
	v_sub_f32_e32 v171, v171, v184
	v_sub_f32_e32 v170, v170, v184
	v_sub_f32_e32 v173, v173, v184
	v_sub_f32_e32 v172, v172, v184
	s_waitcnt vmcnt(5)
	v_sub_f32_e32 v167, v167, v184
	v_sub_f32_e32 v166, v166, v184
	v_sub_f32_e32 v169, v169, v184
	v_sub_f32_e32 v168, v168, v184
	s_waitcnt vmcnt(4)
;     __device__ __forceinline__ void operator()(const f32x4 (&acc)[2][2][4][2], const Unit& u, int wr, int wc, int fr, int fq) const {
;     ...
;                 for (int mh = 0; mh < 2; ++mh) {
;                     f32x4 bs[2][2][2]; f32x2_t st[2];
; #pragma unroll
;                     for (int mm = 0; mm < 2; ++mm) { st[mm] = *(const f32x2_t*)(sp + soff0 + (unsigned)(ai * HALF + (2 * mh + mm) * 16) * 8u);
; #pragma unroll
;                         for (int bj = 0; bj < 2; ++bj)
; #pragma unroll
;                             for (int n = 0; n < 2; ++n) bs[mm][bj][n] = *(const f32x4*)(bb + off0 + (unsigned)((ai * HALF + (2 * mh + mm) * 16) * 1024 + bj * HALF + n * 16) * 4u); }
; #pragma unroll
;                     for (int mm = 0; mm < 2; ++mm)
; #pragma unroll
;                         for (int bj = 0; bj < 2; ++bj)
; #pragma unroll
;                             for (int n = 0; n < 2; ++n) { const f32x4 hv = ((bs[mm][bj][n] - st[mm][0]) * st[mm][1]) * gv[bj][n] + bv[bj][n];
;                                 *(f32x4*)(ob + off0 + (unsigned)((ai * HALF + (2 * mh + mm) * 16) * 1024 + bj * HALF + n * 16) * 4u) = hv * DN_ALPHA + acc[ai][bj][2 * mh + mm][n]; }
;                     asm volatile("" : "+v"(off0), "+v"(soff0) :: "memory"); }
	v_sub_f32_e32 v163, v163, v184
	v_sub_f32_e32 v162, v162, v184
	v_sub_f32_e32 v165, v165, v184
	v_sub_f32_e32 v164, v164, v184
	v_pk_mul_f32 v[202:203], v[184:185], v[202:203] op_sel:[1,0]
	v_pk_mul_f32 v[192:193], v[184:185], v[192:193] op_sel:[1,0]
	v_pk_mul_f32 v[172:173], v[184:185], v[172:173] op_sel:[1,0]
	v_pk_mul_f32 v[170:171], v[184:185], v[170:171] op_sel:[1,0]
	v_pk_mul_f32 v[168:169], v[184:185], v[168:169] op_sel:[1,0]
	v_pk_mul_f32 v[166:167], v[184:185], v[166:167] op_sel:[1,0]
	v_pk_mul_f32 v[164:165], v[184:185], v[164:165] op_sel:[1,0]
	v_pk_mul_f32 v[162:163], v[184:185], v[162:163] op_sel:[1,0]
	v_pk_fma_f32 v[192:193], v[154:155], v[192:193], v[158:159]
	v_pk_fma_f32 v[202:203], v[156:157], v[202:203], v[160:161]
	v_pk_fma_f32 v[170:171], v[146:147], v[170:171], v[150:151]
	v_pk_fma_f32 v[172:173], v[148:149], v[172:173], v[152:153]
	v_pk_fma_f32 v[166:167], v[138:139], v[166:167], v[142:143]
	v_pk_fma_f32 v[168:169], v[140:141], v[168:169], v[144:145]
	v_pk_fma_f32 v[162:163], v[130:131], v[162:163], v[134:135]
	v_pk_fma_f32 v[164:165], v[132:133], v[164:165], v[136:137]
	v_pk_fma_f32 v[204:205], v[202:203], s[88:89], v[78:79] op_sel_hi:[1,0,1]
	v_pk_fma_f32 v[202:203], v[192:193], s[88:89], v[76:77] op_sel_hi:[1,0,1]
	v_pk_fma_f32 v[172:173], v[172:173], s[88:89], v[74:75] op_sel_hi:[1,0,1]
	v_pk_fma_f32 v[170:171], v[170:171], s[88:89], v[72:73] op_sel_hi:[1,0,1]
	v_pk_fma_f32 v[168:169], v[168:169], s[88:89], v[70:71] op_sel_hi:[1,0,1]
	v_pk_fma_f32 v[166:167], v[166:167], s[88:89], v[68:69] op_sel_hi:[1,0,1]
	v_pk_fma_f32 v[164:165], v[164:165], s[88:89], v[66:67] op_sel_hi:[1,0,1]
	v_pk_fma_f32 v[162:163], v[162:163], s[88:89], v[64:65] op_sel_hi:[1,0,1]
	global_store_dwordx4 v[186:187], v[202:205], off sc1
	global_store_dwordx4 v[186:187], v[170:173], off offset:64 sc1
	global_store_dwordx4 v[186:187], v[166:169], off offset:512 sc1
	global_store_dwordx4 v[186:187], v[162:165], off offset:576 sc1
	global_load_dwordx2 v[210:211], v190, s[70:71] offset:1024
	v_lshl_add_u64 v[192:193], s[68:69], 0, v[182:183]
	v_add_co_u32_e32 v184, vcc, s24, v192
	s_nop 1
	v_addc_co_u32_e32 v185, vcc, 0, v193, vcc
	global_load_dwordx4 v[162:165], v[184:185], off
	global_load_dwordx4 v[166:169], v[184:185], off offset:64
	global_load_dwordx4 v[170:173], v[184:185], off offset:512
	s_nop 0
	global_load_dwordx4 v[184:187], v[184:185], off offset:576
	s_nop 0
	global_load_dwordx2 v[238:239], v190, s[70:71] offset:1152
	v_add_co_u32_e32 v192, vcc, s25, v192
	s_waitcnt vmcnt(4)
	v_sub_f32_e32 v163, v163, v210
	v_addc_co_u32_e32 v193, vcc, 0, v193, vcc
	global_load_dwordx4 v[202:205], v[192:193], off
	global_load_dwordx4 v[206:209], v[192:193], off offset:64
	global_load_dwordx4 v[230:233], v[192:193], off offset:512
	global_load_dwordx4 v[234:237], v[192:193], off offset:576
	v_sub_f32_e32 v162, v162, v210
	v_sub_f32_e32 v165, v165, v210
	v_sub_f32_e32 v164, v164, v210
	v_lshl_add_u64 v[192:193], s[66:67], 0, v[182:183]
	v_pk_mul_f32 v[164:165], v[210:211], v[164:165] op_sel:[1,0]
	v_pk_mul_f32 v[162:163], v[210:211], v[162:163] op_sel:[1,0]
	v_pk_fma_f32 v[164:165], v[156:157], v[164:165], v[160:161]
	v_pk_fma_f32 v[162:163], v[154:155], v[162:163], v[158:159]
	v_add_co_u32_e32 v240, vcc, s24, v192
	v_pk_fma_f32 v[164:165], v[164:165], s[88:89], v[62:63] op_sel_hi:[1,0,1]
	v_pk_fma_f32 v[162:163], v[162:163], s[88:89], v[60:61] op_sel_hi:[1,0,1]
	v_addc_co_u32_e32 v241, vcc, 0, v193, vcc
	global_store_dwordx4 v[240:241], v[162:165], off sc1
	s_mov_b32 s24, 0xa0000
	s_waitcnt vmcnt(8)
	v_sub_f32_e32 v163, v167, v210
	v_sub_f32_e32 v162, v166, v210
	v_sub_f32_e32 v165, v169, v210
	v_sub_f32_e32 v164, v168, v210
	v_pk_mul_f32 v[164:165], v[210:211], v[164:165] op_sel:[1,0]
	v_pk_mul_f32 v[162:163], v[210:211], v[162:163] op_sel:[1,0]
	v_pk_fma_f32 v[164:165], v[148:149], v[164:165], v[152:153]
	v_pk_fma_f32 v[162:163], v[146:147], v[162:163], v[150:151]
	v_pk_fma_f32 v[164:165], v[164:165], s[88:89], v[58:59] op_sel_hi:[1,0,1]
	v_pk_fma_f32 v[162:163], v[162:163], s[88:89], v[56:57] op_sel_hi:[1,0,1]
	global_store_dwordx4 v[240:241], v[162:165], off offset:64 sc1
	v_add_co_u32_e32 v166, vcc, s25, v192
	s_waitcnt vmcnt(8)
	v_sub_f32_e32 v163, v171, v210
	v_sub_f32_e32 v162, v170, v210
	v_sub_f32_e32 v165, v173, v210
	v_sub_f32_e32 v164, v172, v210
	v_pk_mul_f32 v[164:165], v[210:211], v[164:165] op_sel:[1,0]
	v_pk_mul_f32 v[162:163], v[210:211], v[162:163] op_sel:[1,0]
	v_pk_fma_f32 v[164:165], v[140:141], v[164:165], v[144:145]
	v_pk_fma_f32 v[162:163], v[138:139], v[162:163], v[142:143]
	v_pk_fma_f32 v[164:165], v[164:165], s[88:89], v[54:55] op_sel_hi:[1,0,1]
	v_pk_fma_f32 v[162:163], v[162:163], s[88:89], v[52:53] op_sel_hi:[1,0,1]
	global_store_dwordx4 v[240:241], v[162:165], off offset:512 sc1
	v_addc_co_u32_e32 v167, vcc, 0, v193, vcc
	s_waitcnt vmcnt(8)
	v_sub_f32_e32 v163, v185, v210
	v_sub_f32_e32 v162, v184, v210
	v_sub_f32_e32 v165, v187, v210
	v_sub_f32_e32 v164, v186, v210
	v_pk_mul_f32 v[164:165], v[210:211], v[164:165] op_sel:[1,0]
	v_pk_mul_f32 v[162:163], v[210:211], v[162:163] op_sel:[1,0]
	v_pk_fma_f32 v[164:165], v[132:133], v[164:165], v[136:137]
	v_pk_fma_f32 v[162:163], v[130:131], v[162:163], v[134:135]
	v_pk_fma_f32 v[164:165], v[164:165], s[88:89], v[50:51] op_sel_hi:[1,0,1]
	v_pk_fma_f32 v[162:163], v[162:163], s[88:89], v[48:49] op_sel_hi:[1,0,1]
	global_store_dwordx4 v[240:241], v[162:165], off offset:576 sc1
	s_mov_b32 s25, 0xb0000
	s_waitcnt vmcnt(7)
;     __device__ __forceinline__ void operator()(const f32x4 (&acc)[2][2][4][2], const Unit& u, int wr, int wc, int fr, int fq) const {
;     ...
;                 for (int mh = 0; mh < 2; ++mh) {
;                     f32x4 bs[2][2][2]; f32x2_t st[2];
; #pragma unroll
;                     for (int mm = 0; mm < 2; ++mm) { st[mm] = *(const f32x2_t*)(sp + soff0 + (unsigned)(ai * HALF + (2 * mh + mm) * 16) * 8u);
; #pragma unroll
;                         for (int bj = 0; bj < 2; ++bj)
; #pragma unroll
;                             for (int n = 0; n < 2; ++n) bs[mm][bj][n] = *(const f32x4*)(bb + off0 + (unsigned)((ai * HALF + (2 * mh + mm) * 16) * 1024 + bj * HALF + n * 16) * 4u); }
; #pragma unroll
;                     for (int mm = 0; mm < 2; ++mm)
; #pragma unroll
;                         for (int bj = 0; bj < 2; ++bj)
; #pragma unroll
;                             for (int n = 0; n < 2; ++n) { const f32x4 hv = ((bs[mm][bj][n] - st[mm][0]) * st[mm][1]) * gv[bj][n] + bv[bj][n];
;                                 *(f32x4*)(ob + off0 + (unsigned)((ai * HALF + (2 * mh + mm) * 16) * 1024 + bj * HALF + n * 16) * 4u) = hv * DN_ALPHA + acc[ai][bj][2 * mh + mm][n]; }
;                     asm volatile("" : "+v"(off0), "+v"(soff0) :: "memory"); }
	v_sub_f32_e32 v163, v203, v238
	v_sub_f32_e32 v162, v202, v238
	v_sub_f32_e32 v165, v205, v238
	v_sub_f32_e32 v164, v204, v238
	v_pk_mul_f32 v[164:165], v[238:239], v[164:165] op_sel:[1,0]
	v_pk_mul_f32 v[162:163], v[238:239], v[162:163] op_sel:[1,0]
	v_pk_fma_f32 v[164:165], v[156:157], v[164:165], v[160:161]
	v_pk_fma_f32 v[162:163], v[154:155], v[162:163], v[158:159]
	v_pk_fma_f32 v[164:165], v[164:165], s[88:89], v[46:47] op_sel_hi:[1,0,1]
	v_pk_fma_f32 v[162:163], v[162:163], s[88:89], v[44:45] op_sel_hi:[1,0,1]
	global_store_dwordx4 v[166:167], v[162:165], off sc1
	s_waitcnt vmcnt(7)
	s_nop 0
	v_sub_f32_e32 v163, v207, v238
	v_sub_f32_e32 v162, v206, v238
	v_sub_f32_e32 v165, v209, v238
	v_sub_f32_e32 v164, v208, v238
	v_pk_mul_f32 v[164:165], v[238:239], v[164:165] op_sel:[1,0]
	v_pk_mul_f32 v[162:163], v[238:239], v[162:163] op_sel:[1,0]
	v_pk_fma_f32 v[164:165], v[148:149], v[164:165], v[152:153]
	v_pk_fma_f32 v[162:163], v[146:147], v[162:163], v[150:151]
	v_pk_fma_f32 v[164:165], v[164:165], s[88:89], v[42:43] op_sel_hi:[1,0,1]
	v_pk_fma_f32 v[162:163], v[162:163], s[88:89], v[40:41] op_sel_hi:[1,0,1]
	global_store_dwordx4 v[166:167], v[162:165], off offset:64 sc1
	s_waitcnt vmcnt(7)
	s_nop 0
	v_sub_f32_e32 v163, v231, v238
	v_sub_f32_e32 v162, v230, v238
	v_sub_f32_e32 v165, v233, v238
	v_sub_f32_e32 v164, v232, v238
	v_pk_mul_f32 v[164:165], v[238:239], v[164:165] op_sel:[1,0]
	v_pk_mul_f32 v[162:163], v[238:239], v[162:163] op_sel:[1,0]
	v_pk_fma_f32 v[164:165], v[140:141], v[164:165], v[144:145]
	v_pk_fma_f32 v[162:163], v[138:139], v[162:163], v[142:143]
	v_pk_fma_f32 v[164:165], v[164:165], s[88:89], v[38:39] op_sel_hi:[1,0,1]
	v_pk_fma_f32 v[162:163], v[162:163], s[88:89], v[36:37] op_sel_hi:[1,0,1]
	global_store_dwordx4 v[166:167], v[162:165], off offset:512 sc1
	s_waitcnt vmcnt(7)
	s_nop 0
	v_sub_f32_e32 v163, v235, v238
	v_sub_f32_e32 v162, v234, v238
	v_sub_f32_e32 v165, v237, v238
	v_sub_f32_e32 v164, v236, v238
	v_pk_mul_f32 v[164:165], v[238:239], v[164:165] op_sel:[1,0]
	v_pk_mul_f32 v[162:163], v[238:239], v[162:163] op_sel:[1,0]
	v_pk_fma_f32 v[164:165], v[132:133], v[164:165], v[136:137]
	v_pk_fma_f32 v[162:163], v[130:131], v[162:163], v[134:135]
	v_pk_fma_f32 v[164:165], v[164:165], s[88:89], v[30:31] op_sel_hi:[1,0,1]
	v_pk_fma_f32 v[162:163], v[162:163], s[88:89], v[28:29] op_sel_hi:[1,0,1]
	global_store_dwordx4 v[166:167], v[162:165], off offset:576 sc1
	global_load_dwordx2 v[210:211], v190, s[70:71] offset:1280
	v_lshl_add_u64 v[192:193], s[68:69], 0, v[182:183]
	v_add_co_u32_e32 v184, vcc, s24, v192
	s_nop 1
	v_addc_co_u32_e32 v185, vcc, 0, v193, vcc
	global_load_dwordx4 v[162:165], v[184:185], off
	global_load_dwordx4 v[166:169], v[184:185], off offset:64
	global_load_dwordx4 v[170:173], v[184:185], off offset:512
	s_nop 0
	global_load_dwordx4 v[184:187], v[184:185], off offset:576
	s_nop 0
	global_load_dwordx2 v[238:239], v190, s[70:71] offset:1408
	v_add_co_u32_e32 v192, vcc, s25, v192
	s_waitcnt vmcnt(4)
	v_sub_f32_e32 v163, v163, v210
	v_addc_co_u32_e32 v193, vcc, 0, v193, vcc
	global_load_dwordx4 v[202:205], v[192:193], off
	global_load_dwordx4 v[206:209], v[192:193], off offset:64
	global_load_dwordx4 v[230:233], v[192:193], off offset:512
	global_load_dwordx4 v[234:237], v[192:193], off offset:576
	v_sub_f32_e32 v162, v162, v210
	v_sub_f32_e32 v165, v165, v210
	v_sub_f32_e32 v164, v164, v210
	v_lshl_add_u64 v[192:193], s[66:67], 0, v[182:183]
	v_pk_mul_f32 v[164:165], v[210:211], v[164:165] op_sel:[1,0]
	v_pk_mul_f32 v[162:163], v[210:211], v[162:163] op_sel:[1,0]
	v_pk_fma_f32 v[164:165], v[156:157], v[164:165], v[160:161]
	v_pk_fma_f32 v[162:163], v[154:155], v[162:163], v[158:159]
	v_add_co_u32_e32 v240, vcc, s24, v192
	v_pk_fma_f32 v[164:165], v[164:165], s[88:89], v[34:35] op_sel_hi:[1,0,1]
	v_pk_fma_f32 v[162:163], v[162:163], s[88:89], v[32:33] op_sel_hi:[1,0,1]
	v_addc_co_u32_e32 v241, vcc, 0, v193, vcc
	global_store_dwordx4 v[240:241], v[162:165], off sc1
	s_waitcnt vmcnt(8)
	s_nop 0
	v_sub_f32_e32 v163, v167, v210
	v_sub_f32_e32 v162, v166, v210
	v_sub_f32_e32 v165, v169, v210
	v_sub_f32_e32 v164, v168, v210
	v_pk_mul_f32 v[164:165], v[210:211], v[164:165] op_sel:[1,0]
	v_pk_mul_f32 v[162:163], v[210:211], v[162:163] op_sel:[1,0]
	v_pk_fma_f32 v[164:165], v[148:149], v[164:165], v[152:153]
	v_pk_fma_f32 v[162:163], v[146:147], v[162:163], v[150:151]
	v_pk_fma_f32 v[164:165], v[164:165], s[88:89], v[26:27] op_sel_hi:[1,0,1]
	v_pk_fma_f32 v[162:163], v[162:163], s[88:89], v[24:25] op_sel_hi:[1,0,1]
	global_store_dwordx4 v[240:241], v[162:165], off offset:64 sc1
	s_waitcnt vmcnt(8)
	s_nop 0
	v_sub_f32_e32 v163, v171, v210
	v_sub_f32_e32 v162, v170, v210
	v_sub_f32_e32 v165, v173, v210
	v_sub_f32_e32 v164, v172, v210
	v_pk_mul_f32 v[164:165], v[210:211], v[164:165] op_sel:[1,0]
	v_pk_mul_f32 v[162:163], v[210:211], v[162:163] op_sel:[1,0]
	v_pk_fma_f32 v[164:165], v[140:141], v[164:165], v[144:145]
	v_pk_fma_f32 v[162:163], v[138:139], v[162:163], v[142:143]
	v_pk_fma_f32 v[164:165], v[164:165], s[88:89], v[22:23] op_sel_hi:[1,0,1]
	v_pk_fma_f32 v[162:163], v[162:163], s[88:89], v[20:21] op_sel_hi:[1,0,1]
	global_store_dwordx4 v[240:241], v[162:165], off offset:512 sc1
	s_waitcnt vmcnt(8)
	s_nop 0
	v_sub_f32_e32 v163, v185, v210
	v_sub_f32_e32 v162, v184, v210
	v_sub_f32_e32 v165, v187, v210
	v_sub_f32_e32 v164, v186, v210
	v_pk_mul_f32 v[164:165], v[210:211], v[164:165] op_sel:[1,0]
	v_pk_mul_f32 v[162:163], v[210:211], v[162:163] op_sel:[1,0]
	v_pk_fma_f32 v[164:165], v[132:133], v[164:165], v[136:137]
	v_pk_fma_f32 v[162:163], v[130:131], v[162:163], v[134:135]
	v_pk_fma_f32 v[164:165], v[164:165], s[88:89], v[18:19] op_sel_hi:[1,0,1]
	v_pk_fma_f32 v[162:163], v[162:163], s[88:89], v[16:17] op_sel_hi:[1,0,1]
	global_store_dwordx4 v[240:241], v[162:165], off offset:576 sc1
	s_waitcnt vmcnt(7)
;     __device__ __forceinline__ void operator()(const f32x4 (&acc)[2][2][4][2], const Unit& u, int wr, int wc, int fr, int fq) const {
;     ...
;         if (stats == nullptr) {
; #pragma unroll
;             for (int ai = 0; ai < 2; ++ai) {
;                 f32x4 bs[4][2][2];
; #pragma unroll
;                 for (int m = 0; m < 4; ++m)
; #pragma unroll
;                     for (int bj = 0; bj < 2; ++bj)
; #pragma unroll
;                         for (int n = 0; n < 2; ++n) bs[m][bj][n] = *(const f32x4*)(bb + off0 + (unsigned)((ai * HALF + m * 16) * 1024 + bj * HALF + n * 16) * 4u);
; #pragma unroll
;                 for (int m = 0; m < 4; ++m)
; #pragma unroll
;                     for (int bj = 0; bj < 2; ++bj)
; #pragma unroll
;                         for (int n = 0; n < 2; ++n) *(f32x4*)(ob + off0 + (unsigned)((ai * HALF + m * 16) * 1024 + bj * HALF + n * 16) * 4u) = bs[m][bj][n] * DN_ALPHA + acc[ai][bj][m][n];
;                 asm volatile("" : "+v"(off0) :: "memory"); }
;     ...
;                 for (int mh = 0; mh < 2; ++mh) {
;                     f32x4 bs[2][2][2]; f32x2_t st[2];
; #pragma unroll
;                     for (int mm = 0; mm < 2; ++mm) { st[mm] = *(const f32x2_t*)(sp + soff0 + (unsigned)(ai * HALF + (2 * mh + mm) * 16) * 8u);
; #pragma unroll
;                         for (int bj = 0; bj < 2; ++bj)
; #pragma unroll
;                             for (int n = 0; n < 2; ++n) bs[mm][bj][n] = *(const f32x4*)(bb + off0 + (unsigned)((ai * HALF + (2 * mh + mm) * 16) * 1024 + bj * HALF + n * 16) * 4u); }
; #pragma unroll
;                     for (int mm = 0; mm < 2; ++mm)
; #pragma unroll
;                         for (int bj = 0; bj < 2; ++bj)
; #pragma unroll
;                             for (int n = 0; n < 2; ++n) { const f32x4 hv = ((bs[mm][bj][n] - st[mm][0]) * st[mm][1]) * gv[bj][n] + bv[bj][n];
;                                 *(f32x4*)(ob + off0 + (unsigned)((ai * HALF + (2 * mh + mm) * 16) * 1024 + bj * HALF + n * 16) * 4u) = hv * DN_ALPHA + acc[ai][bj][2 * mh + mm][n]; }
;                     asm volatile("" : "+v"(off0), "+v"(soff0) :: "memory"); }
	s_nop 0
	v_sub_f32_e32 v163, v203, v238
	v_sub_f32_e32 v162, v202, v238
	v_sub_f32_e32 v165, v205, v238
	v_sub_f32_e32 v164, v204, v238
	v_pk_mul_f32 v[164:165], v[238:239], v[164:165] op_sel:[1,0]
	v_pk_mul_f32 v[162:163], v[238:239], v[162:163] op_sel:[1,0]
	v_pk_fma_f32 v[156:157], v[156:157], v[164:165], v[160:161]
	v_pk_fma_f32 v[154:155], v[154:155], v[162:163], v[158:159]
	v_add_co_u32_e32 v158, vcc, s25, v192
	v_pk_fma_f32 v[156:157], v[156:157], s[88:89], v[14:15] op_sel_hi:[1,0,1]
	v_pk_fma_f32 v[154:155], v[154:155], s[88:89], v[12:13] op_sel_hi:[1,0,1]
	v_addc_co_u32_e32 v159, vcc, 0, v193, vcc
	global_store_dwordx4 v[158:159], v[154:157], off sc1
	s_waitcnt vmcnt(7)
	s_nop 0
	v_sub_f32_e32 v155, v207, v238
	v_sub_f32_e32 v154, v206, v238
	v_sub_f32_e32 v157, v209, v238
	v_sub_f32_e32 v156, v208, v238
	v_pk_mul_f32 v[156:157], v[238:239], v[156:157] op_sel:[1,0]
	v_pk_mul_f32 v[154:155], v[238:239], v[154:155] op_sel:[1,0]
	v_pk_fma_f32 v[148:149], v[148:149], v[156:157], v[152:153]
	v_pk_fma_f32 v[146:147], v[146:147], v[154:155], v[150:151]
	v_pk_fma_f32 v[148:149], v[148:149], s[88:89], v[10:11] op_sel_hi:[1,0,1]
	v_pk_fma_f32 v[146:147], v[146:147], s[88:89], v[8:9] op_sel_hi:[1,0,1]
	global_store_dwordx4 v[158:159], v[146:149], off offset:64 sc1
	s_waitcnt vmcnt(7)
	s_nop 0
	v_sub_f32_e32 v147, v231, v238
	v_sub_f32_e32 v146, v230, v238
	v_sub_f32_e32 v149, v233, v238
	v_sub_f32_e32 v148, v232, v238
	v_pk_mul_f32 v[148:149], v[238:239], v[148:149] op_sel:[1,0]
	v_pk_mul_f32 v[146:147], v[238:239], v[146:147] op_sel:[1,0]
	v_pk_fma_f32 v[140:141], v[140:141], v[148:149], v[144:145]
	v_pk_fma_f32 v[138:139], v[138:139], v[146:147], v[142:143]
	v_pk_fma_f32 v[140:141], v[140:141], s[88:89], v[6:7] op_sel_hi:[1,0,1]
	v_pk_fma_f32 v[138:139], v[138:139], s[88:89], v[4:5] op_sel_hi:[1,0,1]
	global_store_dwordx4 v[158:159], v[138:141], off offset:512 sc1
	s_waitcnt vmcnt(7)
	s_nop 0
	v_sub_f32_e32 v139, v235, v238
	v_sub_f32_e32 v138, v234, v238
	v_sub_f32_e32 v141, v237, v238
	v_sub_f32_e32 v140, v236, v238
	v_pk_mul_f32 v[140:141], v[238:239], v[140:141] op_sel:[1,0]
	v_pk_mul_f32 v[138:139], v[238:239], v[138:139] op_sel:[1,0]
	v_pk_fma_f32 v[132:133], v[132:133], v[140:141], v[136:137]
	v_pk_fma_f32 v[130:131], v[130:131], v[138:139], v[134:135]
	v_pk_fma_f32 v[132:133], v[132:133], s[88:89], v[2:3] op_sel_hi:[1,0,1]
	v_pk_fma_f32 v[130:131], v[130:131], s[88:89], v[0:1] op_sel_hi:[1,0,1]
	global_store_dwordx4 v[158:159], v[130:133], off offset:576 sc1
.LBB0_445:
	s_andn2_b64 vcc, exec, s[72:73]
	v_readlane_b32 s78, v252, 44
	v_readlane_b32 s79, v252, 45
	s_cbranch_vccnz .LBB0_447
	v_lshl_add_u64 v[130:131], s[68:69], 0, v[96:97]
	global_load_dwordx4 v[144:147], v96, s[68:69]
	global_load_dwordx4 v[148:151], v96, s[68:69] offset:64
	global_load_dwordx4 v[152:155], v96, s[68:69] offset:512
	global_load_dwordx4 v[156:159], v96, s[68:69] offset:576
	v_add_co_u32_e32 v132, vcc, 0x10000, v130
	v_lshl_add_u64 v[142:143], s[66:67], 0, v[96:97]
	s_nop 0
	v_addc_co_u32_e32 v133, vcc, 0, v131, vcc
	global_load_dwordx4 v[160:163], v[132:133], off
	global_load_dwordx4 v[164:167], v[132:133], off offset:64
	global_load_dwordx4 v[168:171], v[132:133], off offset:512
	global_load_dwordx4 v[182:185], v[132:133], off offset:576
	v_add_co_u32_e32 v132, vcc, 0x20000, v130
	s_mov_b32 s24, 0x10000
	s_nop 0
	v_addc_co_u32_e32 v133, vcc, 0, v131, vcc
	global_load_dwordx4 v[190:193], v[132:133], off
	global_load_dwordx4 v[202:205], v[132:133], off offset:64
	global_load_dwordx4 v[206:209], v[132:133], off offset:512
	global_load_dwordx4 v[230:233], v[132:133], off offset:576
	v_add_co_u32_e32 v130, vcc, 0x30000, v130
	s_mov_b32 s25, 0x90000
	s_nop 0
	v_addc_co_u32_e32 v131, vcc, 0, v131, vcc
	global_load_dwordx4 v[234:237], v[130:131], off
	global_load_dwordx4 v[138:141], v[130:131], off offset:64
	global_load_dwordx4 v[134:137], v[130:131], off offset:512
	s_nop 0
	global_load_dwordx4 v[130:133], v[130:131], off offset:576
	s_waitcnt vmcnt(0)
	v_pk_fma_f32 v[126:127], v[144:145], s[88:89], v[126:127] op_sel_hi:[1,0,1]
	v_pk_fma_f32 v[128:129], v[146:147], s[88:89], v[128:129] op_sel_hi:[1,0,1]
	v_pk_fma_f32 v[122:123], v[148:149], s[88:89], v[122:123] op_sel_hi:[1,0,1]
	v_pk_fma_f32 v[114:115], v[156:157], s[88:89], v[114:115] op_sel_hi:[1,0,1]
	v_pk_fma_f32 v[116:117], v[158:159], s[88:89], v[116:117] op_sel_hi:[1,0,1]
	global_store_dwordx4 v96, v[114:117], s[66:67] offset:576 sc1
	v_pk_fma_f32 v[124:125], v[150:151], s[88:89], v[124:125] op_sel_hi:[1,0,1]
	v_pk_fma_f32 v[118:119], v[152:153], s[88:89], v[118:119] op_sel_hi:[1,0,1]
	v_add_co_u32_e32 v114, vcc, s24, v142
	v_pk_fma_f32 v[100:101], v[184:185], s[88:89], v[100:101] op_sel_hi:[1,0,1]
	s_nop 0
	v_addc_co_u32_e32 v115, vcc, 0, v143, vcc
	v_pk_fma_f32 v[98:99], v[182:183], s[88:89], v[98:99] op_sel_hi:[1,0,1]
	s_mov_b32 s24, 0x20000
	global_store_dwordx4 v[114:115], v[98:101], off offset:576 sc1
	v_pk_fma_f32 v[82:83], v[232:233], s[88:89], v[82:83] op_sel_hi:[1,0,1]
	v_pk_fma_f32 v[80:81], v[230:231], s[88:89], v[80:81] op_sel_hi:[1,0,1]
	v_add_co_u32_e32 v98, vcc, s24, v142
	s_mov_b32 s24, 0x30000
	s_nop 0
	v_addc_co_u32_e32 v99, vcc, 0, v143, vcc
	global_store_dwordx4 v[98:99], v[80:83], off offset:576 sc1
	v_pk_fma_f32 v[120:121], v[154:155], s[88:89], v[120:121] op_sel_hi:[1,0,1]
	v_pk_fma_f32 v[112:113], v[162:163], s[88:89], v[112:113] op_sel_hi:[1,0,1]
	v_add_co_u32_e32 v80, vcc, s24, v142
	v_pk_fma_f32 v[110:111], v[160:161], s[88:89], v[110:111] op_sel_hi:[1,0,1]
	v_pk_fma_f32 v[108:109], v[166:167], s[88:89], v[108:109] op_sel_hi:[1,0,1]
;     __device__ __forceinline__ void operator()(const f32x4 (&acc)[2][2][4][2], const Unit& u, int wr, int wc, int fr, int fq) const {
;     ...
;         if (stats == nullptr) {
; #pragma unroll
;             for (int ai = 0; ai < 2; ++ai) {
;                 f32x4 bs[4][2][2];
; #pragma unroll
;                 for (int m = 0; m < 4; ++m)
; #pragma unroll
;                     for (int bj = 0; bj < 2; ++bj)
; #pragma unroll
;                         for (int n = 0; n < 2; ++n) bs[m][bj][n] = *(const f32x4*)(bb + off0 + (unsigned)((ai * HALF + m * 16) * 1024 + bj * HALF + n * 16) * 4u);
; #pragma unroll
;                 for (int m = 0; m < 4; ++m)
; #pragma unroll
;                     for (int bj = 0; bj < 2; ++bj)
; #pragma unroll
;                         for (int n = 0; n < 2; ++n) *(f32x4*)(ob + off0 + (unsigned)((ai * HALF + m * 16) * 1024 + bj * HALF + n * 16) * 4u) = bs[m][bj][n] * DN_ALPHA + acc[ai][bj][m][n];
;                 asm volatile("" : "+v"(off0) :: "memory"); }
	v_pk_fma_f32 v[106:107], v[164:165], s[88:89], v[106:107] op_sel_hi:[1,0,1]
	v_pk_fma_f32 v[104:105], v[170:171], s[88:89], v[104:105] op_sel_hi:[1,0,1]
	v_pk_fma_f32 v[102:103], v[168:169], s[88:89], v[102:103] op_sel_hi:[1,0,1]
	v_pk_fma_f32 v[94:95], v[192:193], s[88:89], v[94:95] op_sel_hi:[1,0,1]
	v_pk_fma_f32 v[92:93], v[190:191], s[88:89], v[92:93] op_sel_hi:[1,0,1]
	v_pk_fma_f32 v[90:91], v[204:205], s[88:89], v[90:91] op_sel_hi:[1,0,1]
	v_pk_fma_f32 v[88:89], v[202:203], s[88:89], v[88:89] op_sel_hi:[1,0,1]
	v_pk_fma_f32 v[86:87], v[208:209], s[88:89], v[86:87] op_sel_hi:[1,0,1]
	v_pk_fma_f32 v[84:85], v[206:207], s[88:89], v[84:85] op_sel_hi:[1,0,1]
	v_pk_fma_f32 v[78:79], v[236:237], s[88:89], v[78:79] op_sel_hi:[1,0,1]
	v_pk_fma_f32 v[76:77], v[234:235], s[88:89], v[76:77] op_sel_hi:[1,0,1]
	v_addc_co_u32_e32 v81, vcc, 0, v143, vcc
	v_pk_fma_f32 v[74:75], v[140:141], s[88:89], v[74:75] op_sel_hi:[1,0,1]
	v_pk_fma_f32 v[72:73], v[138:139], s[88:89], v[72:73] op_sel_hi:[1,0,1]
	v_pk_fma_f32 v[70:71], v[136:137], s[88:89], v[70:71] op_sel_hi:[1,0,1]
	v_pk_fma_f32 v[68:69], v[134:135], s[88:89], v[68:69] op_sel_hi:[1,0,1]
	v_pk_fma_f32 v[66:67], v[132:133], s[88:89], v[66:67] op_sel_hi:[1,0,1]
	v_pk_fma_f32 v[64:65], v[130:131], s[88:89], v[64:65] op_sel_hi:[1,0,1]
	global_store_dwordx4 v96, v[126:129], s[66:67] sc1
	global_store_dwordx4 v96, v[122:125], s[66:67] offset:64 sc1
	global_store_dwordx4 v96, v[118:121], s[66:67] offset:512 sc1
	global_store_dwordx4 v[114:115], v[110:113], off sc1
	global_store_dwordx4 v[114:115], v[106:109], off offset:64 sc1
	global_store_dwordx4 v[114:115], v[102:105], off offset:512 sc1
	global_store_dwordx4 v[98:99], v[92:95], off sc1
	global_store_dwordx4 v[98:99], v[88:91], off offset:64 sc1
	global_store_dwordx4 v[98:99], v[84:87], off offset:512 sc1
	global_store_dwordx4 v[80:81], v[76:79], off sc1
	global_store_dwordx4 v[80:81], v[72:75], off offset:64 sc1
	global_store_dwordx4 v[80:81], v[68:71], off offset:512 sc1
	global_store_dwordx4 v[80:81], v[64:67], off offset:576 sc1
	s_mov_b32 s24, 0x80000
	v_lshl_add_u64 v[92:93], s[66:67], 0, v[96:97]
	v_lshl_add_u64 v[64:65], s[68:69], 0, v[96:97]
	v_add_co_u32_e32 v66, vcc, s24, v64
	s_mov_b32 s68, 0xa0000
	s_nop 0
	v_addc_co_u32_e32 v67, vcc, 0, v65, vcc
	global_load_dwordx4 v[98:101], v[66:67], off
	global_load_dwordx4 v[102:105], v[66:67], off offset:64
	global_load_dwordx4 v[106:109], v[66:67], off offset:512
	global_load_dwordx4 v[110:113], v[66:67], off offset:576
	v_add_co_u32_e32 v66, vcc, s25, v64
	s_mov_b32 s69, 0xb0000
	s_nop 0
	v_addc_co_u32_e32 v67, vcc, 0, v65, vcc
	global_load_dwordx4 v[114:117], v[66:67], off
	global_load_dwordx4 v[118:121], v[66:67], off offset:64
	global_load_dwordx4 v[122:125], v[66:67], off offset:512
	global_load_dwordx4 v[126:129], v[66:67], off offset:576
	v_add_co_u32_e32 v66, vcc, s68, v64
	s_waitcnt vmcnt(7)
	v_pk_fma_f32 v[62:63], v[100:101], s[88:89], v[62:63] op_sel_hi:[1,0,1]
	v_addc_co_u32_e32 v67, vcc, 0, v65, vcc
	global_load_dwordx4 v[130:133], v[66:67], off
	global_load_dwordx4 v[88:91], v[66:67], off offset:64
	global_load_dwordx4 v[84:87], v[66:67], off offset:512
	global_load_dwordx4 v[80:83], v[66:67], off offset:576
	v_add_co_u32_e32 v64, vcc, s69, v64
	s_waitcnt vmcnt(8)
	v_pk_fma_f32 v[50:51], v[112:113], s[88:89], v[50:51] op_sel_hi:[1,0,1]
	v_addc_co_u32_e32 v65, vcc, 0, v65, vcc
	global_load_dwordx4 v[76:79], v[64:65], off
	global_load_dwordx4 v[72:75], v[64:65], off offset:64
	global_load_dwordx4 v[68:71], v[64:65], off offset:512
	s_nop 0
	global_load_dwordx4 v[64:67], v[64:65], off offset:576
	v_add_co_u32_e32 v94, vcc, s24, v92
	v_pk_fma_f32 v[48:49], v[110:111], s[88:89], v[48:49] op_sel_hi:[1,0,1]
	s_nop 0
	v_addc_co_u32_e32 v95, vcc, 0, v93, vcc
	global_store_dwordx4 v[94:95], v[48:51], off offset:576 sc1
	s_waitcnt vmcnt(9)
;     __device__ __forceinline__ void operator()(const f32x4 (&acc)[2][2][4][2], const Unit& u, int wr, int wc, int fr, int fq) const {
;     ...
;         if (stats == nullptr) {
; #pragma unroll
;             for (int ai = 0; ai < 2; ++ai) {
;                 f32x4 bs[4][2][2];
; #pragma unroll
;                 for (int m = 0; m < 4; ++m)
; #pragma unroll
;                     for (int bj = 0; bj < 2; ++bj)
; #pragma unroll
;                         for (int n = 0; n < 2; ++n) bs[m][bj][n] = *(const f32x4*)(bb + off0 + (unsigned)((ai * HALF + m * 16) * 1024 + bj * HALF + n * 16) * 4u);
; #pragma unroll
;                 for (int m = 0; m < 4; ++m)
; #pragma unroll
;                     for (int bj = 0; bj < 2; ++bj)
; #pragma unroll
;                         for (int n = 0; n < 2; ++n) *(f32x4*)(ob + off0 + (unsigned)((ai * HALF + m * 16) * 1024 + bj * HALF + n * 16) * 4u) = bs[m][bj][n] * DN_ALPHA + acc[ai][bj][m][n];
;                 asm volatile("" : "+v"(off0) :: "memory"); }
	v_pk_fma_f32 v[30:31], v[128:129], s[88:89], v[30:31] op_sel_hi:[1,0,1]
	v_pk_fma_f32 v[28:29], v[126:127], s[88:89], v[28:29] op_sel_hi:[1,0,1]
	v_add_co_u32_e32 v48, vcc, s25, v92
	v_pk_fma_f32 v[60:61], v[98:99], s[88:89], v[60:61] op_sel_hi:[1,0,1]
	s_nop 0
	v_addc_co_u32_e32 v49, vcc, 0, v93, vcc
	global_store_dwordx4 v[48:49], v[28:31], off offset:576 sc1
	v_pk_fma_f32 v[58:59], v[104:105], s[88:89], v[58:59] op_sel_hi:[1,0,1]
	v_pk_fma_f32 v[56:57], v[102:103], s[88:89], v[56:57] op_sel_hi:[1,0,1]
	v_pk_fma_f32 v[54:55], v[108:109], s[88:89], v[54:55] op_sel_hi:[1,0,1]
	v_pk_fma_f32 v[52:53], v[106:107], s[88:89], v[52:53] op_sel_hi:[1,0,1]
	v_pk_fma_f32 v[46:47], v[116:117], s[88:89], v[46:47] op_sel_hi:[1,0,1]
	v_pk_fma_f32 v[44:45], v[114:115], s[88:89], v[44:45] op_sel_hi:[1,0,1]
	v_pk_fma_f32 v[42:43], v[120:121], s[88:89], v[42:43] op_sel_hi:[1,0,1]
	v_pk_fma_f32 v[40:41], v[118:119], s[88:89], v[40:41] op_sel_hi:[1,0,1]
	v_pk_fma_f32 v[38:39], v[124:125], s[88:89], v[38:39] op_sel_hi:[1,0,1]
	v_pk_fma_f32 v[36:37], v[122:123], s[88:89], v[36:37] op_sel_hi:[1,0,1]
	global_store_dwordx4 v[94:95], v[60:63], off sc1
	global_store_dwordx4 v[94:95], v[56:59], off offset:64 sc1
	global_store_dwordx4 v[94:95], v[52:55], off offset:512 sc1
	global_store_dwordx4 v[48:49], v[44:47], off sc1
	global_store_dwordx4 v[48:49], v[40:43], off offset:64 sc1
	global_store_dwordx4 v[48:49], v[36:39], off offset:512 sc1
	s_waitcnt vmcnt(15)
	v_pk_fma_f32 v[28:29], v[130:131], s[88:89], v[32:33] op_sel_hi:[1,0,1]
	v_add_co_u32_e32 v32, vcc, s68, v92
	s_waitcnt vmcnt(12)
	v_pk_fma_f32 v[18:19], v[82:83], s[88:89], v[18:19] op_sel_hi:[1,0,1]
	v_addc_co_u32_e32 v33, vcc, 0, v93, vcc
	v_pk_fma_f32 v[16:17], v[80:81], s[88:89], v[16:17] op_sel_hi:[1,0,1]
	global_store_dwordx4 v[32:33], v[16:19], off offset:576 sc1
	v_pk_fma_f32 v[30:31], v[132:133], s[88:89], v[34:35] op_sel_hi:[1,0,1]
	v_pk_fma_f32 v[26:27], v[90:91], s[88:89], v[26:27] op_sel_hi:[1,0,1]
	v_add_co_u32_e32 v16, vcc, s69, v92
	v_pk_fma_f32 v[24:25], v[88:89], s[88:89], v[24:25] op_sel_hi:[1,0,1]
	v_pk_fma_f32 v[22:23], v[86:87], s[88:89], v[22:23] op_sel_hi:[1,0,1]
	v_pk_fma_f32 v[20:21], v[84:85], s[88:89], v[20:21] op_sel_hi:[1,0,1]
	s_waitcnt vmcnt(12)
	v_pk_fma_f32 v[14:15], v[78:79], s[88:89], v[14:15] op_sel_hi:[1,0,1]
	v_pk_fma_f32 v[12:13], v[76:77], s[88:89], v[12:13] op_sel_hi:[1,0,1]
	v_addc_co_u32_e32 v17, vcc, 0, v93, vcc
	s_waitcnt vmcnt(11)
	v_pk_fma_f32 v[10:11], v[74:75], s[88:89], v[10:11] op_sel_hi:[1,0,1]
	v_pk_fma_f32 v[8:9], v[72:73], s[88:89], v[8:9] op_sel_hi:[1,0,1]
	s_waitcnt vmcnt(10)
	v_pk_fma_f32 v[6:7], v[70:71], s[88:89], v[6:7] op_sel_hi:[1,0,1]
	v_pk_fma_f32 v[4:5], v[68:69], s[88:89], v[4:5] op_sel_hi:[1,0,1]
	s_waitcnt vmcnt(9)
	v_pk_fma_f32 v[2:3], v[66:67], s[88:89], v[2:3] op_sel_hi:[1,0,1]
	v_pk_fma_f32 v[0:1], v[64:65], s[88:89], v[0:1] op_sel_hi:[1,0,1]
	global_store_dwordx4 v[32:33], v[28:31], off sc1
	global_store_dwordx4 v[32:33], v[24:27], off offset:64 sc1
	global_store_dwordx4 v[32:33], v[20:23], off offset:512 sc1
	global_store_dwordx4 v[16:17], v[12:15], off sc1
	global_store_dwordx4 v[16:17], v[8:11], off offset:64 sc1
	global_store_dwordx4 v[16:17], v[4:7], off offset:512 sc1
	global_store_dwordx4 v[16:17], v[0:3], off offset:576 sc1

; __device__ __forceinline__ unsigned pk_bf16(float lo, float hi) { return pg8::cvt_pk_bf16(lo, hi); }
; #define LDS_FENCE() asm volatile("s_waitcnt lgkmcnt(0)" ::: "memory")
; __device__ __forceinline__ void transpose_item(const float* Wsrc, int ldw, bf16_t* WT, int ldt, int kb, int nb, float* scr, int lane) {
;     const int k0 = 64 * kb, n0 = 32 * nb;
; #pragma unroll
;     for (int i = 0; i < 8; ++i) { const int kk = 8 * i + (lane >> 3), n4 = 4 * (lane & 7);
;         const f32x4 v = *(const f32x4*)(Wsrc + (size_t)(k0 + kk) * ldw + n0 + n4);
;         scr[kk * 33 + n4] = v[0]; scr[kk * 33 + n4 + 1] = v[1]; scr[kk * 33 + n4 + 2] = v[2]; scr[kk * 33 + n4 + 3] = v[3]; }
;     LDS_FENCE();
;     const int c = lane & 7;
; #pragma unroll
;     for (int j = 0; j < 4; ++j) { const int n = (lane >> 3) + 8 * j; const float* s = scr + (8 * c) * 33 + n;
;         u32x4 o; o.x = pk_bf16(s[0 * 33], s[1 * 33]); o.y = pk_bf16(s[2 * 33], s[3 * 33]); o.z = pk_bf16(s[4 * 33], s[5 * 33]); o.w = pk_bf16(s[6 * 33], s[7 * 33]);
;         *(u32x4*)(WT + (size_t)(n0 + n) * ldt + k0 + 8 * c) = o; }
;     LDS_FENCE();
; }
; __device__ __forceinline__ void phase_rows(const Ctx& c, int l) {
;     ...
;             transpose_item(c.inp(IN_WGLU) + (size_t)l * 256 * 256, 256, Wglu_t, 256, r / 8, r % 8, scr, lane);
.LBB0_459:
	s_cmpk_gt_i32 s23, 0xbff
	s_mov_b64 s[52:53], -1
	s_cbranch_scc0 .LBB0_477
	s_cmpk_gt_u32 s23, 0xc7f
	s_cbranch_scc0 .LBB0_474
	s_cmpk_gt_u32 s23, 0xd7f
	s_cbranch_scc0 .LBB0_471
	s_cmpk_gt_u32 s23, 0xdff
	s_cbranch_scc0 .LBB0_468
	s_cmpk_gt_u32 s23, 0xfff
	s_cbranch_scc0 .LBB0_465
	s_load_dwordx2 s[52:53], s[50:51], 0x68
	v_lshlrev_b32_e32 v96, 2, v4
	s_waitcnt lgkmcnt(0)
	s_add_u32 s31, s52, s38
	s_addc_u32 s36, s53, s39
	s_and_b32 s6, s17, 0x7fffffc0
	s_add_i32 s34, s6, 0xffff8000
	s_and_b32 s6, s13, 0xe0
	s_lshl_b32 s47, s6, 2
	s_add_u32 s52, s31, s47
	s_addc_u32 s53, s36, 0
	v_lshl_add_u64 v[18:19], s[52:53], 0, v[96:97]
	v_or_b32_e32 v96, s34, v20
	v_lshlrev_b64 v[0:1], 10, v[96:97]
	v_lshl_add_u64 v[0:1], v[18:19], 0, v[0:1]
	global_load_dwordx4 v[0:3], v[0:1], off
	v_or_b32_e32 v96, s34, v22
	v_or_b32_e32 v37, s6, v20
	s_mov_b64 s[52:53], 0
	s_waitcnt vmcnt(0)
	ds_write2_b32 v21, v0, v1 offset1:1
	ds_write2_b32 v21, v2, v3 offset0:2 offset1:3
	v_lshlrev_b64 v[0:1], 10, v[96:97]
	v_lshl_add_u64 v[0:1], v[18:19], 0, v[0:1]
	global_load_dwordx4 v[0:3], v[0:1], off
	v_or_b32_e32 v96, s34, v24
	s_waitcnt vmcnt(0)
	ds_write2_b32 v23, v0, v1 offset1:1
	ds_write2_b32 v23, v2, v3 offset0:2 offset1:3
	v_lshlrev_b64 v[0:1], 10, v[96:97]
	v_lshl_add_u64 v[0:1], v[18:19], 0, v[0:1]
	global_load_dwordx4 v[0:3], v[0:1], off
	v_or_b32_e32 v96, s34, v26
	s_waitcnt vmcnt(0)
	ds_write2_b32 v25, v0, v1 offset1:1
	ds_write2_b32 v25, v2, v3 offset0:2 offset1:3
	v_lshlrev_b64 v[0:1], 10, v[96:97]
	v_lshl_add_u64 v[0:1], v[18:19], 0, v[0:1]
	global_load_dwordx4 v[0:3], v[0:1], off
	v_or_b32_e32 v96, s34, v28
	s_waitcnt vmcnt(0)
	ds_write2_b32 v27, v0, v1 offset1:1
	ds_write2_b32 v27, v2, v3 offset0:2 offset1:3
	v_lshlrev_b64 v[0:1], 10, v[96:97]
	v_lshl_add_u64 v[0:1], v[18:19], 0, v[0:1]
	global_load_dwordx4 v[0:3], v[0:1], off
	v_or_b32_e32 v96, s34, v30
	s_waitcnt vmcnt(0)
	ds_write2_b32 v29, v0, v1 offset1:1
	ds_write2_b32 v29, v2, v3 offset0:2 offset1:3
	v_lshlrev_b64 v[0:1], 10, v[96:97]
	v_lshl_add_u64 v[0:1], v[18:19], 0, v[0:1]
	global_load_dwordx4 v[0:3], v[0:1], off
	v_or_b32_e32 v96, s34, v32
	s_waitcnt vmcnt(0)
	ds_write2_b32 v31, v0, v1 offset1:1
	ds_write2_b32 v31, v2, v3 offset0:2 offset1:3
	v_lshlrev_b64 v[0:1], 10, v[96:97]
	v_lshl_add_u64 v[0:1], v[18:19], 0, v[0:1]
	global_load_dwordx4 v[0:3], v[0:1], off
	v_or_b32_e32 v96, s34, v34
	s_waitcnt vmcnt(0)
	ds_write2_b32 v33, v0, v1 offset1:1
	ds_write2_b32 v33, v2, v3 offset0:2 offset1:3
	v_lshlrev_b64 v[0:1], 10, v[96:97]
	v_lshl_add_u64 v[0:1], v[18:19], 0, v[0:1]
	global_load_dwordx4 v[0:3], v[0:1], off
	v_lshl_add_u64 v[18:19], s[34:35], 1, v[6:7]
	v_lshlrev_b32_e32 v96, 9, v37
	v_or_b32_e32 v37, s6, v22
	v_lshl_add_u64 v[54:55], v[18:19], 0, v[96:97]
	v_lshlrev_b32_e32 v96, 9, v37
	v_or_b32_e32 v37, s6, v24
	s_waitcnt vmcnt(0)
	ds_write2_b32 v35, v0, v1 offset1:1
	ds_write2_b32 v35, v2, v3 offset0:2 offset1:3
	s_waitcnt lgkmcnt(0)
	ds_read2_b32 v[38:39], v36 offset0:33 offset1:41
	ds_read2_b32 v[40:41], v36 offset1:8
	ds_read2_b32 v[42:43], v36 offset0:66 offset1:74
	ds_read2_b32 v[44:45], v36 offset0:99 offset1:107
	ds_read2_b32 v[46:47], v36 offset0:132 offset1:140
	ds_read2_b32 v[48:49], v36 offset0:165 offset1:173
	ds_read2_b32 v[50:51], v36 offset0:198 offset1:206
	ds_read2_b32 v[52:53], v36 offset0:231 offset1:239
	s_waitcnt lgkmcnt(6)
	v_cvt_pk_bf16_f32 v0, v40, v38
	s_waitcnt lgkmcnt(4)
	v_cvt_pk_bf16_f32 v1, v42, v44
	s_waitcnt lgkmcnt(2)
	v_cvt_pk_bf16_f32 v2, v46, v48
	s_waitcnt lgkmcnt(0)
	v_cvt_pk_bf16_f32 v3, v50, v52
	global_store_dwordx4 v[54:55], v[0:3], off sc1
	s_nop 1
	v_cvt_pk_bf16_f32 v0, v41, v39
	v_cvt_pk_bf16_f32 v1, v43, v45
	v_cvt_pk_bf16_f32 v2, v47, v49
	v_cvt_pk_bf16_f32 v3, v51, v53
	v_lshl_add_u64 v[38:39], v[18:19], 0, v[96:97]
	global_store_dwordx4 v[38:39], v[0:3], off sc1
	ds_read2_b32 v[38:39], v36 offset0:49 offset1:57
	ds_read2_b32 v[40:41], v36 offset0:16 offset1:24
	ds_read2_b32 v[42:43], v36 offset0:82 offset1:90
	ds_read2_b32 v[44:45], v36 offset0:115 offset1:123
	ds_read2_b32 v[46:47], v36 offset0:148 offset1:156
	ds_read2_b32 v[48:49], v36 offset0:181 offset1:189
	ds_read2_b32 v[50:51], v36 offset0:214 offset1:222
	ds_read2_b32 v[52:53], v36 offset0:247 offset1:255
	v_lshlrev_b32_e32 v96, 9, v37
	v_or_b32_e32 v37, s6, v26
	s_waitcnt lgkmcnt(6)
	v_cvt_pk_bf16_f32 v0, v40, v38
	s_waitcnt lgkmcnt(4)
	v_cvt_pk_bf16_f32 v1, v42, v44
	s_waitcnt lgkmcnt(2)
	v_cvt_pk_bf16_f32 v2, v46, v48
	s_waitcnt lgkmcnt(0)
	v_cvt_pk_bf16_f32 v3, v50, v52
	v_lshl_add_u64 v[54:55], v[18:19], 0, v[96:97]
	v_lshlrev_b32_e32 v96, 9, v37
	global_store_dwordx4 v[54:55], v[0:3], off sc1
	v_lshl_add_u64 v[18:19], v[18:19], 0, v[96:97]
	s_nop 0
	v_cvt_pk_bf16_f32 v0, v41, v39
	v_cvt_pk_bf16_f32 v1, v43, v45
	v_cvt_pk_bf16_f32 v2, v47, v49
	v_cvt_pk_bf16_f32 v3, v51, v53
	global_store_dwordx4 v[18:19], v[0:3], off sc1
	s_waitcnt lgkmcnt(0)
; __device__ __forceinline__ unsigned pk_bf16(float lo, float hi) { return pg8::cvt_pk_bf16(lo, hi); }
; #define LDS_FENCE() asm volatile("s_waitcnt lgkmcnt(0)" ::: "memory")
; __device__ __forceinline__ void transpose_item(const float* Wsrc, int ldw, bf16_t* WT, int ldt, int kb, int nb, float* scr, int lane) {
;     const int k0 = 64 * kb, n0 = 32 * nb;
; #pragma unroll
;     for (int i = 0; i < 8; ++i) { const int kk = 8 * i + (lane >> 3), n4 = 4 * (lane & 7);
;         const f32x4 v = *(const f32x4*)(Wsrc + (size_t)(k0 + kk) * ldw + n0 + n4);
;         scr[kk * 33 + n4] = v[0]; scr[kk * 33 + n4 + 1] = v[1]; scr[kk * 33 + n4 + 2] = v[2]; scr[kk * 33 + n4 + 3] = v[3]; }
;     LDS_FENCE();
;     const int c = lane & 7;
; #pragma unroll
;     for (int j = 0; j < 4; ++j) { const int n = (lane >> 3) + 8 * j; const float* s = scr + (8 * c) * 33 + n;
;         u32x4 o; o.x = pk_bf16(s[0 * 33], s[1 * 33]); o.y = pk_bf16(s[2 * 33], s[3 * 33]); o.z = pk_bf16(s[4 * 33], s[5 * 33]); o.w = pk_bf16(s[6 * 33], s[7 * 33]);
;         *(u32x4*)(WT + (size_t)(n0 + n) * ldt + k0 + 8 * c) = o; }
;     LDS_FENCE();
; }
; __device__ __forceinline__ void phase_rows(const Ctx& c, int l) {
;     ...
;             if (r < I_O) { transpose_item(c.inp(IN_WOUT) + (size_t)l * 1024 * 1024, 1024, Wout_t, 1024, r / 32, r % 32, scr, lane); continue; } r -= I_O;
.LBB0_465:
	s_andn2_b64 vcc, exec, s[52:53]
	s_cbranch_vccnz .LBB0_467
	s_load_dwordx2 s[52:53], s[50:51], 0x90
	v_lshlrev_b32_e32 v96, 2, v4
	s_waitcnt lgkmcnt(0)
	s_add_u32 s31, s52, s40
	s_addc_u32 s36, s53, s41
	s_and_b32 s6, s21, 0x1fc0
	s_add_i32 s34, s6, 0xffffe400
	s_and_b32 s6, s13, 0x3e0
	s_lshl_b32 s47, s6, 2
	s_add_u32 s52, s31, s47
	s_addc_u32 s53, s36, 0
	v_lshl_add_u64 v[18:19], s[52:53], 0, v[96:97]
	v_or_b32_e32 v96, s34, v20
	v_lshlrev_b64 v[0:1], 12, v[96:97]
	v_lshl_add_u64 v[0:1], v[18:19], 0, v[0:1]
	global_load_dwordx4 v[0:3], v[0:1], off
	v_or_b32_e32 v96, s34, v22
	v_or_b32_e32 v37, s6, v20
	s_waitcnt vmcnt(0)
	ds_write2_b32 v21, v0, v1 offset1:1
	ds_write2_b32 v21, v2, v3 offset0:2 offset1:3
	v_lshlrev_b64 v[0:1], 12, v[96:97]
	v_lshl_add_u64 v[0:1], v[18:19], 0, v[0:1]
	global_load_dwordx4 v[0:3], v[0:1], off
	v_or_b32_e32 v96, s34, v24
	s_waitcnt vmcnt(0)
	ds_write2_b32 v23, v0, v1 offset1:1
	ds_write2_b32 v23, v2, v3 offset0:2 offset1:3
	v_lshlrev_b64 v[0:1], 12, v[96:97]
	v_lshl_add_u64 v[0:1], v[18:19], 0, v[0:1]
	global_load_dwordx4 v[0:3], v[0:1], off
	v_or_b32_e32 v96, s34, v26
	s_waitcnt vmcnt(0)
	ds_write2_b32 v25, v0, v1 offset1:1
	ds_write2_b32 v25, v2, v3 offset0:2 offset1:3
	v_lshlrev_b64 v[0:1], 12, v[96:97]
	v_lshl_add_u64 v[0:1], v[18:19], 0, v[0:1]
	global_load_dwordx4 v[0:3], v[0:1], off
	v_or_b32_e32 v96, s34, v28
	s_waitcnt vmcnt(0)
	ds_write2_b32 v27, v0, v1 offset1:1
	ds_write2_b32 v27, v2, v3 offset0:2 offset1:3
	v_lshlrev_b64 v[0:1], 12, v[96:97]
	v_lshl_add_u64 v[0:1], v[18:19], 0, v[0:1]
	global_load_dwordx4 v[0:3], v[0:1], off
	v_or_b32_e32 v96, s34, v30
	s_waitcnt vmcnt(0)
	ds_write2_b32 v29, v0, v1 offset1:1
	ds_write2_b32 v29, v2, v3 offset0:2 offset1:3
	v_lshlrev_b64 v[0:1], 12, v[96:97]
	v_lshl_add_u64 v[0:1], v[18:19], 0, v[0:1]
	global_load_dwordx4 v[0:3], v[0:1], off
	v_or_b32_e32 v96, s34, v32
	s_waitcnt vmcnt(0)
	ds_write2_b32 v31, v0, v1 offset1:1
	ds_write2_b32 v31, v2, v3 offset0:2 offset1:3
	v_lshlrev_b64 v[0:1], 12, v[96:97]
	v_lshl_add_u64 v[0:1], v[18:19], 0, v[0:1]
	global_load_dwordx4 v[0:3], v[0:1], off
	v_or_b32_e32 v96, s34, v34
	s_waitcnt vmcnt(0)
	ds_write2_b32 v33, v0, v1 offset1:1
	ds_write2_b32 v33, v2, v3 offset0:2 offset1:3
	v_lshlrev_b64 v[0:1], 12, v[96:97]
	v_lshl_add_u64 v[0:1], v[18:19], 0, v[0:1]
	global_load_dwordx4 v[0:3], v[0:1], off
	v_lshl_add_u64 v[18:19], s[34:35], 1, v[8:9]
	v_lshlrev_b32_e32 v96, 11, v37
	v_or_b32_e32 v37, s6, v22
	v_lshl_add_u64 v[54:55], v[18:19], 0, v[96:97]
	v_lshlrev_b32_e32 v96, 11, v37
	v_or_b32_e32 v37, s6, v24
	s_waitcnt vmcnt(0)
	ds_write2_b32 v35, v0, v1 offset1:1
	ds_write2_b32 v35, v2, v3 offset0:2 offset1:3
	s_waitcnt lgkmcnt(0)
	ds_read2_b32 v[38:39], v36 offset0:33 offset1:41
	ds_read2_b32 v[40:41], v36 offset1:8
	ds_read2_b32 v[42:43], v36 offset0:66 offset1:74
	ds_read2_b32 v[44:45], v36 offset0:99 offset1:107
	ds_read2_b32 v[46:47], v36 offset0:132 offset1:140
	ds_read2_b32 v[48:49], v36 offset0:165 offset1:173
	ds_read2_b32 v[50:51], v36 offset0:198 offset1:206
	ds_read2_b32 v[52:53], v36 offset0:231 offset1:239
	s_waitcnt lgkmcnt(6)
	v_cvt_pk_bf16_f32 v0, v40, v38
	s_waitcnt lgkmcnt(4)
	v_cvt_pk_bf16_f32 v1, v42, v44
	s_waitcnt lgkmcnt(2)
	v_cvt_pk_bf16_f32 v2, v46, v48
	s_waitcnt lgkmcnt(0)
	v_cvt_pk_bf16_f32 v3, v50, v52
	global_store_dwordx4 v[54:55], v[0:3], off sc1
	s_nop 1
	v_cvt_pk_bf16_f32 v0, v41, v39
	v_cvt_pk_bf16_f32 v1, v43, v45
	v_cvt_pk_bf16_f32 v2, v47, v49
	v_cvt_pk_bf16_f32 v3, v51, v53
	v_lshl_add_u64 v[38:39], v[18:19], 0, v[96:97]
	global_store_dwordx4 v[38:39], v[0:3], off sc1
	ds_read2_b32 v[38:39], v36 offset0:49 offset1:57
	ds_read2_b32 v[40:41], v36 offset0:16 offset1:24
	ds_read2_b32 v[42:43], v36 offset0:82 offset1:90
	ds_read2_b32 v[44:45], v36 offset0:115 offset1:123
	ds_read2_b32 v[46:47], v36 offset0:148 offset1:156
	ds_read2_b32 v[48:49], v36 offset0:181 offset1:189
	ds_read2_b32 v[50:51], v36 offset0:214 offset1:222
	ds_read2_b32 v[52:53], v36 offset0:247 offset1:255
	v_lshlrev_b32_e32 v96, 11, v37
	v_or_b32_e32 v37, s6, v26
	s_waitcnt lgkmcnt(6)
	v_cvt_pk_bf16_f32 v0, v40, v38
	s_waitcnt lgkmcnt(4)
	v_cvt_pk_bf16_f32 v1, v42, v44
	s_waitcnt lgkmcnt(2)
	v_cvt_pk_bf16_f32 v2, v46, v48
	s_waitcnt lgkmcnt(0)
	v_cvt_pk_bf16_f32 v3, v50, v52
	v_lshl_add_u64 v[54:55], v[18:19], 0, v[96:97]
	v_lshlrev_b32_e32 v96, 11, v37
	global_store_dwordx4 v[54:55], v[0:3], off sc1
	v_lshl_add_u64 v[18:19], v[18:19], 0, v[96:97]
	s_nop 0
	v_cvt_pk_bf16_f32 v0, v41, v39
	v_cvt_pk_bf16_f32 v1, v43, v45
	v_cvt_pk_bf16_f32 v2, v47, v49
	v_cvt_pk_bf16_f32 v3, v51, v53
	global_store_dwordx4 v[18:19], v[0:3], off sc1
	s_waitcnt lgkmcnt(0)

; __device__ __forceinline__ unsigned pk_bf16(float lo, float hi) { return pg8::cvt_pk_bf16(lo, hi); }
; #define LDS_FENCE() asm volatile("s_waitcnt lgkmcnt(0)" ::: "memory")
; __device__ __forceinline__ void transpose_item(const float* Wsrc, int ldw, bf16_t* WT, int ldt, int kb, int nb, float* scr, int lane) {
;     const int k0 = 64 * kb, n0 = 32 * nb;
; #pragma unroll
;     for (int i = 0; i < 8; ++i) { const int kk = 8 * i + (lane >> 3), n4 = 4 * (lane & 7);
;         const f32x4 v = *(const f32x4*)(Wsrc + (size_t)(k0 + kk) * ldw + n0 + n4);
;         scr[kk * 33 + n4] = v[0]; scr[kk * 33 + n4 + 1] = v[1]; scr[kk * 33 + n4 + 2] = v[2]; scr[kk * 33 + n4 + 3] = v[3]; }
;     LDS_FENCE();
;     const int c = lane & 7;
; #pragma unroll
;     for (int j = 0; j < 4; ++j) { const int n = (lane >> 3) + 8 * j; const float* s = scr + (8 * c) * 33 + n;
;         u32x4 o; o.x = pk_bf16(s[0 * 33], s[1 * 33]); o.y = pk_bf16(s[2 * 33], s[3 * 33]); o.z = pk_bf16(s[4 * 33], s[5 * 33]); o.w = pk_bf16(s[6 * 33], s[7 * 33]);
;         *(u32x4*)(WT + (size_t)(n0 + n) * ldt + k0 + 8 * c) = o; }
;     LDS_FENCE();
; }
; __device__ __forceinline__ void phase_rows(const Ctx& c, int l) {
;     ...
;             if (r < I_C) { transpose_item(c.inp(IN_WUPC) + (size_t)l * 256 * 1024, 1024, Wup_t + 768, 1024, r / 32, r % 32, scr, lane); continue; } r -= I_C;
.LBB0_468:
	s_andn2_b64 vcc, exec, s[52:53]
	s_cbranch_vccnz .LBB0_470
	s_load_dwordx2 s[52:53], s[50:51], 0x88
	v_lshlrev_b32_e32 v96, 2, v4
	s_waitcnt lgkmcnt(0)
	s_add_u32 s31, s52, s42
	s_addc_u32 s36, s53, s43
	s_and_b32 s6, s21, 0x1fc0
	s_add_i32 s34, s6, 0xffffe500
	s_and_b32 s6, s13, 0x3e0
	s_lshl_b32 s47, s6, 2
	s_add_u32 s52, s31, s47
	s_addc_u32 s53, s36, 0
	v_lshl_add_u64 v[18:19], s[52:53], 0, v[96:97]
	v_or_b32_e32 v96, s34, v20
	v_lshlrev_b64 v[0:1], 12, v[96:97]
	v_lshl_add_u64 v[0:1], v[18:19], 0, v[0:1]
	global_load_dwordx4 v[0:3], v[0:1], off
	v_or_b32_e32 v96, s34, v22
	v_or_b32_e32 v37, s6, v20
	s_waitcnt vmcnt(0)
	ds_write2_b32 v21, v0, v1 offset1:1
	ds_write2_b32 v21, v2, v3 offset0:2 offset1:3
	v_lshlrev_b64 v[0:1], 12, v[96:97]
	v_lshl_add_u64 v[0:1], v[18:19], 0, v[0:1]
	global_load_dwordx4 v[0:3], v[0:1], off
	v_or_b32_e32 v96, s34, v24
	s_waitcnt vmcnt(0)
	ds_write2_b32 v23, v0, v1 offset1:1
	ds_write2_b32 v23, v2, v3 offset0:2 offset1:3
	v_lshlrev_b64 v[0:1], 12, v[96:97]
	v_lshl_add_u64 v[0:1], v[18:19], 0, v[0:1]
	global_load_dwordx4 v[0:3], v[0:1], off
	v_or_b32_e32 v96, s34, v26
	s_waitcnt vmcnt(0)
	ds_write2_b32 v25, v0, v1 offset1:1
	ds_write2_b32 v25, v2, v3 offset0:2 offset1:3
	v_lshlrev_b64 v[0:1], 12, v[96:97]
	v_lshl_add_u64 v[0:1], v[18:19], 0, v[0:1]
	global_load_dwordx4 v[0:3], v[0:1], off
	v_or_b32_e32 v96, s34, v28
	s_waitcnt vmcnt(0)
	ds_write2_b32 v27, v0, v1 offset1:1
	ds_write2_b32 v27, v2, v3 offset0:2 offset1:3
	v_lshlrev_b64 v[0:1], 12, v[96:97]
	v_lshl_add_u64 v[0:1], v[18:19], 0, v[0:1]
	global_load_dwordx4 v[0:3], v[0:1], off
	v_or_b32_e32 v96, s34, v30
	s_waitcnt vmcnt(0)
	ds_write2_b32 v29, v0, v1 offset1:1
	ds_write2_b32 v29, v2, v3 offset0:2 offset1:3
	v_lshlrev_b64 v[0:1], 12, v[96:97]
	v_lshl_add_u64 v[0:1], v[18:19], 0, v[0:1]
	global_load_dwordx4 v[0:3], v[0:1], off
	v_or_b32_e32 v96, s34, v32
	s_waitcnt vmcnt(0)
	ds_write2_b32 v31, v0, v1 offset1:1
	ds_write2_b32 v31, v2, v3 offset0:2 offset1:3
	v_lshlrev_b64 v[0:1], 12, v[96:97]
	v_lshl_add_u64 v[0:1], v[18:19], 0, v[0:1]
	global_load_dwordx4 v[0:3], v[0:1], off
	v_or_b32_e32 v96, s34, v34
	s_waitcnt vmcnt(0)
	ds_write2_b32 v33, v0, v1 offset1:1
	ds_write2_b32 v33, v2, v3 offset0:2 offset1:3
	v_lshlrev_b64 v[0:1], 12, v[96:97]
	v_lshl_add_u64 v[0:1], v[18:19], 0, v[0:1]
	global_load_dwordx4 v[0:3], v[0:1], off
	v_lshl_add_u64 v[18:19], s[34:35], 1, v[10:11]
	v_lshlrev_b32_e32 v96, 11, v37
	v_or_b32_e32 v37, s6, v22
	v_lshl_add_u64 v[54:55], v[18:19], 0, v[96:97]
	v_lshlrev_b32_e32 v96, 11, v37
	v_or_b32_e32 v37, s6, v24
	s_waitcnt vmcnt(0)
	ds_write2_b32 v35, v0, v1 offset1:1
	ds_write2_b32 v35, v2, v3 offset0:2 offset1:3
	s_waitcnt lgkmcnt(0)
	ds_read2_b32 v[38:39], v36 offset0:33 offset1:41
	ds_read2_b32 v[40:41], v36 offset1:8
	ds_read2_b32 v[42:43], v36 offset0:66 offset1:74
	ds_read2_b32 v[44:45], v36 offset0:99 offset1:107
	ds_read2_b32 v[46:47], v36 offset0:132 offset1:140
	ds_read2_b32 v[48:49], v36 offset0:165 offset1:173
	ds_read2_b32 v[50:51], v36 offset0:198 offset1:206
	ds_read2_b32 v[52:53], v36 offset0:231 offset1:239
	s_waitcnt lgkmcnt(6)
	v_cvt_pk_bf16_f32 v0, v40, v38
	s_waitcnt lgkmcnt(4)
	v_cvt_pk_bf16_f32 v1, v42, v44
	s_waitcnt lgkmcnt(2)
	v_cvt_pk_bf16_f32 v2, v46, v48
	s_waitcnt lgkmcnt(0)
	v_cvt_pk_bf16_f32 v3, v50, v52
	global_store_dwordx4 v[54:55], v[0:3], off sc1
	s_nop 1
	v_cvt_pk_bf16_f32 v0, v41, v39
	v_cvt_pk_bf16_f32 v1, v43, v45
	v_cvt_pk_bf16_f32 v2, v47, v49
	v_cvt_pk_bf16_f32 v3, v51, v53
	v_lshl_add_u64 v[38:39], v[18:19], 0, v[96:97]
	global_store_dwordx4 v[38:39], v[0:3], off sc1
	ds_read2_b32 v[38:39], v36 offset0:49 offset1:57
	ds_read2_b32 v[40:41], v36 offset0:16 offset1:24
	ds_read2_b32 v[42:43], v36 offset0:82 offset1:90
	ds_read2_b32 v[44:45], v36 offset0:115 offset1:123
	ds_read2_b32 v[46:47], v36 offset0:148 offset1:156
	ds_read2_b32 v[48:49], v36 offset0:181 offset1:189
	ds_read2_b32 v[50:51], v36 offset0:214 offset1:222
	ds_read2_b32 v[52:53], v36 offset0:247 offset1:255
	v_lshlrev_b32_e32 v96, 11, v37
	v_or_b32_e32 v37, s6, v26
	s_waitcnt lgkmcnt(6)
	v_cvt_pk_bf16_f32 v0, v40, v38
	s_waitcnt lgkmcnt(4)
	v_cvt_pk_bf16_f32 v1, v42, v44
	s_waitcnt lgkmcnt(2)
	v_cvt_pk_bf16_f32 v2, v46, v48
	s_waitcnt lgkmcnt(0)
	v_cvt_pk_bf16_f32 v3, v50, v52
	v_lshl_add_u64 v[54:55], v[18:19], 0, v[96:97]
	v_lshlrev_b32_e32 v96, 11, v37
	global_store_dwordx4 v[54:55], v[0:3], off sc1
	v_lshl_add_u64 v[18:19], v[18:19], 0, v[96:97]
	s_nop 0
	v_cvt_pk_bf16_f32 v0, v41, v39
	v_cvt_pk_bf16_f32 v1, v43, v45
	v_cvt_pk_bf16_f32 v2, v47, v49
	v_cvt_pk_bf16_f32 v3, v51, v53
	global_store_dwordx4 v[18:19], v[0:3], off sc1
	s_waitcnt lgkmcnt(0)

; __device__ __forceinline__ unsigned pk_bf16(float lo, float hi) { return pg8::cvt_pk_bf16(lo, hi); }
; #define LDS_FENCE() asm volatile("s_waitcnt lgkmcnt(0)" ::: "memory")
; __device__ __forceinline__ void transpose_item(const float* Wsrc, int ldw, bf16_t* WT, int ldt, int kb, int nb, float* scr, int lane) {
;     const int k0 = 64 * kb, n0 = 32 * nb;
; #pragma unroll
;     for (int i = 0; i < 8; ++i) { const int kk = 8 * i + (lane >> 3), n4 = 4 * (lane & 7);
;         const f32x4 v = *(const f32x4*)(Wsrc + (size_t)(k0 + kk) * ldw + n0 + n4);
;         scr[kk * 33 + n4] = v[0]; scr[kk * 33 + n4 + 1] = v[1]; scr[kk * 33 + n4 + 2] = v[2]; scr[kk * 33 + n4 + 3] = v[3]; }
;     LDS_FENCE();
;     const int c = lane & 7;
; #pragma unroll
;     for (int j = 0; j < 4; ++j) { const int n = (lane >> 3) + 8 * j; const float* s = scr + (8 * c) * 33 + n;
;         u32x4 o; o.x = pk_bf16(s[0 * 33], s[1 * 33]); o.y = pk_bf16(s[2 * 33], s[3 * 33]); o.z = pk_bf16(s[4 * 33], s[5 * 33]); o.w = pk_bf16(s[6 * 33], s[7 * 33]);
;         *(u32x4*)(WT + (size_t)(n0 + n) * ldt + k0 + 8 * c) = o; }
;     LDS_FENCE();
; }
; __device__ __forceinline__ void phase_rows(const Ctx& c, int l) {
;     ...
;             if (r < I_B) { transpose_item(c.inp(IN_WUPB) + (size_t)l * 512 * 1024, 1024, Wup_t + 256, 1024, r / 32, r % 32, scr, lane); continue; } r -= I_B;
.LBB0_471:
	s_andn2_b64 vcc, exec, s[52:53]
	s_cbranch_vccnz .LBB0_473
	s_load_dwordx2 s[52:53], s[50:51], 0x80
	v_lshlrev_b32_e32 v96, 2, v4
	s_waitcnt lgkmcnt(0)
	s_add_u32 s31, s52, s48
	s_addc_u32 s36, s53, s49
	s_and_b32 s6, s21, 0x1fc0
	s_add_i32 s34, s6, 0xffffe700
	s_and_b32 s6, s13, 0x3e0
	s_lshl_b32 s47, s6, 2
	s_add_u32 s52, s31, s47
	s_addc_u32 s53, s36, 0
	v_lshl_add_u64 v[18:19], s[52:53], 0, v[96:97]
	v_or_b32_e32 v96, s34, v20
	v_lshlrev_b64 v[0:1], 12, v[96:97]
	v_lshl_add_u64 v[0:1], v[18:19], 0, v[0:1]
	global_load_dwordx4 v[0:3], v[0:1], off
	v_or_b32_e32 v96, s34, v22
	v_or_b32_e32 v37, s6, v20
	s_waitcnt vmcnt(0)
	ds_write2_b32 v21, v0, v1 offset1:1
	ds_write2_b32 v21, v2, v3 offset0:2 offset1:3
	v_lshlrev_b64 v[0:1], 12, v[96:97]
	v_lshl_add_u64 v[0:1], v[18:19], 0, v[0:1]
	global_load_dwordx4 v[0:3], v[0:1], off
	v_or_b32_e32 v96, s34, v24
	s_waitcnt vmcnt(0)
	ds_write2_b32 v23, v0, v1 offset1:1
	ds_write2_b32 v23, v2, v3 offset0:2 offset1:3
	v_lshlrev_b64 v[0:1], 12, v[96:97]
	v_lshl_add_u64 v[0:1], v[18:19], 0, v[0:1]
	global_load_dwordx4 v[0:3], v[0:1], off
	v_or_b32_e32 v96, s34, v26
	s_waitcnt vmcnt(0)
	ds_write2_b32 v25, v0, v1 offset1:1
	ds_write2_b32 v25, v2, v3 offset0:2 offset1:3
	v_lshlrev_b64 v[0:1], 12, v[96:97]
	v_lshl_add_u64 v[0:1], v[18:19], 0, v[0:1]
	global_load_dwordx4 v[0:3], v[0:1], off
	v_or_b32_e32 v96, s34, v28
	s_waitcnt vmcnt(0)
	ds_write2_b32 v27, v0, v1 offset1:1
	ds_write2_b32 v27, v2, v3 offset0:2 offset1:3
	v_lshlrev_b64 v[0:1], 12, v[96:97]
	v_lshl_add_u64 v[0:1], v[18:19], 0, v[0:1]
	global_load_dwordx4 v[0:3], v[0:1], off
	v_or_b32_e32 v96, s34, v30
	s_waitcnt vmcnt(0)
	ds_write2_b32 v29, v0, v1 offset1:1
	ds_write2_b32 v29, v2, v3 offset0:2 offset1:3
	v_lshlrev_b64 v[0:1], 12, v[96:97]
	v_lshl_add_u64 v[0:1], v[18:19], 0, v[0:1]
	global_load_dwordx4 v[0:3], v[0:1], off
	v_or_b32_e32 v96, s34, v32
	s_waitcnt vmcnt(0)
	ds_write2_b32 v31, v0, v1 offset1:1
	ds_write2_b32 v31, v2, v3 offset0:2 offset1:3
	v_lshlrev_b64 v[0:1], 12, v[96:97]
	v_lshl_add_u64 v[0:1], v[18:19], 0, v[0:1]
	global_load_dwordx4 v[0:3], v[0:1], off
	v_or_b32_e32 v96, s34, v34
	s_waitcnt vmcnt(0)
	ds_write2_b32 v33, v0, v1 offset1:1
	ds_write2_b32 v33, v2, v3 offset0:2 offset1:3
	v_lshlrev_b64 v[0:1], 12, v[96:97]
	v_lshl_add_u64 v[0:1], v[18:19], 0, v[0:1]
	global_load_dwordx4 v[0:3], v[0:1], off
	v_lshl_add_u64 v[18:19], s[34:35], 1, v[12:13]
	v_lshlrev_b32_e32 v96, 11, v37
	v_or_b32_e32 v37, s6, v22
	v_lshl_add_u64 v[54:55], v[18:19], 0, v[96:97]
	v_lshlrev_b32_e32 v96, 11, v37
	v_or_b32_e32 v37, s6, v24
	s_waitcnt vmcnt(0)
	ds_write2_b32 v35, v0, v1 offset1:1
	ds_write2_b32 v35, v2, v3 offset0:2 offset1:3
	s_waitcnt lgkmcnt(0)
	ds_read2_b32 v[38:39], v36 offset0:33 offset1:41
	ds_read2_b32 v[40:41], v36 offset1:8
	ds_read2_b32 v[42:43], v36 offset0:66 offset1:74
	ds_read2_b32 v[44:45], v36 offset0:99 offset1:107
	ds_read2_b32 v[46:47], v36 offset0:132 offset1:140
	ds_read2_b32 v[48:49], v36 offset0:165 offset1:173
	ds_read2_b32 v[50:51], v36 offset0:198 offset1:206
	ds_read2_b32 v[52:53], v36 offset0:231 offset1:239
	s_waitcnt lgkmcnt(6)
	v_cvt_pk_bf16_f32 v0, v40, v38
	s_waitcnt lgkmcnt(4)
	v_cvt_pk_bf16_f32 v1, v42, v44
	s_waitcnt lgkmcnt(2)
	v_cvt_pk_bf16_f32 v2, v46, v48
	s_waitcnt lgkmcnt(0)
	v_cvt_pk_bf16_f32 v3, v50, v52
	global_store_dwordx4 v[54:55], v[0:3], off sc1
	s_nop 1
	v_cvt_pk_bf16_f32 v0, v41, v39
	v_cvt_pk_bf16_f32 v1, v43, v45
	v_cvt_pk_bf16_f32 v2, v47, v49
	v_cvt_pk_bf16_f32 v3, v51, v53
	v_lshl_add_u64 v[38:39], v[18:19], 0, v[96:97]
	global_store_dwordx4 v[38:39], v[0:3], off sc1
	ds_read2_b32 v[38:39], v36 offset0:49 offset1:57
	ds_read2_b32 v[40:41], v36 offset0:16 offset1:24
	ds_read2_b32 v[42:43], v36 offset0:82 offset1:90
	ds_read2_b32 v[44:45], v36 offset0:115 offset1:123
	ds_read2_b32 v[46:47], v36 offset0:148 offset1:156
	ds_read2_b32 v[48:49], v36 offset0:181 offset1:189
	ds_read2_b32 v[50:51], v36 offset0:214 offset1:222
	ds_read2_b32 v[52:53], v36 offset0:247 offset1:255
	v_lshlrev_b32_e32 v96, 11, v37
	v_or_b32_e32 v37, s6, v26
	s_waitcnt lgkmcnt(6)
	v_cvt_pk_bf16_f32 v0, v40, v38
	s_waitcnt lgkmcnt(4)
	v_cvt_pk_bf16_f32 v1, v42, v44
	s_waitcnt lgkmcnt(2)
	v_cvt_pk_bf16_f32 v2, v46, v48
	s_waitcnt lgkmcnt(0)
	v_cvt_pk_bf16_f32 v3, v50, v52
	v_lshl_add_u64 v[54:55], v[18:19], 0, v[96:97]
	v_lshlrev_b32_e32 v96, 11, v37
	global_store_dwordx4 v[54:55], v[0:3], off sc1
	v_lshl_add_u64 v[18:19], v[18:19], 0, v[96:97]
	s_nop 0
	v_cvt_pk_bf16_f32 v0, v41, v39
	v_cvt_pk_bf16_f32 v1, v43, v45
	v_cvt_pk_bf16_f32 v2, v47, v49
	v_cvt_pk_bf16_f32 v3, v51, v53
	global_store_dwordx4 v[18:19], v[0:3], off sc1
	s_waitcnt lgkmcnt(0)

; __device__ __forceinline__ unsigned pk_bf16(float lo, float hi) { return pg8::cvt_pk_bf16(lo, hi); }
; #define LDS_FENCE() asm volatile("s_waitcnt lgkmcnt(0)" ::: "memory")
; __device__ __forceinline__ void transpose_item(const float* Wsrc, int ldw, bf16_t* WT, int ldt, int kb, int nb, float* scr, int lane) {
;     const int k0 = 64 * kb, n0 = 32 * nb;
; #pragma unroll
;     for (int i = 0; i < 8; ++i) { const int kk = 8 * i + (lane >> 3), n4 = 4 * (lane & 7);
;         const f32x4 v = *(const f32x4*)(Wsrc + (size_t)(k0 + kk) * ldw + n0 + n4);
;         scr[kk * 33 + n4] = v[0]; scr[kk * 33 + n4 + 1] = v[1]; scr[kk * 33 + n4 + 2] = v[2]; scr[kk * 33 + n4 + 3] = v[3]; }
;     LDS_FENCE();
;     const int c = lane & 7;
; #pragma unroll
;     for (int j = 0; j < 4; ++j) { const int n = (lane >> 3) + 8 * j; const float* s = scr + (8 * c) * 33 + n;
;         u32x4 o; o.x = pk_bf16(s[0 * 33], s[1 * 33]); o.y = pk_bf16(s[2 * 33], s[3 * 33]); o.z = pk_bf16(s[4 * 33], s[5 * 33]); o.w = pk_bf16(s[6 * 33], s[7 * 33]);
;         *(u32x4*)(WT + (size_t)(n0 + n) * ldt + k0 + 8 * c) = o; }
;     LDS_FENCE();
; }
; __device__ __forceinline__ void phase_rows(const Ctx& c, int l) {
;     ...
;             if (r < I_A) { transpose_item(c.inp(IN_WUPA) + (size_t)l * 256 * 1024, 1024, Wup_t, 1024, r / 32, r % 32, scr, lane); continue; } r -= I_A;
.LBB0_474:
	s_andn2_b64 vcc, exec, s[52:53]
	s_cbranch_vccnz .LBB0_476
	s_load_dwordx2 s[52:53], s[50:51], 0x78
	v_lshlrev_b32_e32 v96, 2, v4
	s_waitcnt lgkmcnt(0)
	s_add_u32 s31, s52, s42
	s_addc_u32 s36, s53, s43
	s_and_b32 s6, s21, 0x1fc0
	s_add_i32 s34, s6, 0xffffe800
	s_and_b32 s6, s13, 0x3e0
	s_lshl_b32 s47, s6, 2
	s_add_u32 s52, s31, s47
	s_addc_u32 s53, s36, 0
	v_lshl_add_u64 v[18:19], s[52:53], 0, v[96:97]
	v_or_b32_e32 v96, s34, v20
	v_lshlrev_b64 v[0:1], 12, v[96:97]
	v_lshl_add_u64 v[0:1], v[18:19], 0, v[0:1]
	global_load_dwordx4 v[0:3], v[0:1], off
	v_or_b32_e32 v96, s34, v22
	v_or_b32_e32 v37, s6, v20
	s_waitcnt vmcnt(0)
	ds_write2_b32 v21, v0, v1 offset1:1
	ds_write2_b32 v21, v2, v3 offset0:2 offset1:3
	v_lshlrev_b64 v[0:1], 12, v[96:97]
	v_lshl_add_u64 v[0:1], v[18:19], 0, v[0:1]
	global_load_dwordx4 v[0:3], v[0:1], off
	v_or_b32_e32 v96, s34, v24
	s_waitcnt vmcnt(0)
	ds_write2_b32 v23, v0, v1 offset1:1
	ds_write2_b32 v23, v2, v3 offset0:2 offset1:3
	v_lshlrev_b64 v[0:1], 12, v[96:97]
	v_lshl_add_u64 v[0:1], v[18:19], 0, v[0:1]
	global_load_dwordx4 v[0:3], v[0:1], off
	v_or_b32_e32 v96, s34, v26
	s_waitcnt vmcnt(0)
	ds_write2_b32 v25, v0, v1 offset1:1
	ds_write2_b32 v25, v2, v3 offset0:2 offset1:3
	v_lshlrev_b64 v[0:1], 12, v[96:97]
	v_lshl_add_u64 v[0:1], v[18:19], 0, v[0:1]
	global_load_dwordx4 v[0:3], v[0:1], off
	v_or_b32_e32 v96, s34, v28
	s_waitcnt vmcnt(0)
	ds_write2_b32 v27, v0, v1 offset1:1
	ds_write2_b32 v27, v2, v3 offset0:2 offset1:3
	v_lshlrev_b64 v[0:1], 12, v[96:97]
	v_lshl_add_u64 v[0:1], v[18:19], 0, v[0:1]
	global_load_dwordx4 v[0:3], v[0:1], off
	v_or_b32_e32 v96, s34, v30
	s_waitcnt vmcnt(0)
	ds_write2_b32 v29, v0, v1 offset1:1
	ds_write2_b32 v29, v2, v3 offset0:2 offset1:3
	v_lshlrev_b64 v[0:1], 12, v[96:97]
	v_lshl_add_u64 v[0:1], v[18:19], 0, v[0:1]
	global_load_dwordx4 v[0:3], v[0:1], off
	v_or_b32_e32 v96, s34, v32
	s_waitcnt vmcnt(0)
	ds_write2_b32 v31, v0, v1 offset1:1
	ds_write2_b32 v31, v2, v3 offset0:2 offset1:3
	v_lshlrev_b64 v[0:1], 12, v[96:97]
	v_lshl_add_u64 v[0:1], v[18:19], 0, v[0:1]
	global_load_dwordx4 v[0:3], v[0:1], off
	v_or_b32_e32 v96, s34, v34
	s_waitcnt vmcnt(0)
	ds_write2_b32 v33, v0, v1 offset1:1
	ds_write2_b32 v33, v2, v3 offset0:2 offset1:3
	v_lshlrev_b64 v[0:1], 12, v[96:97]
	v_lshl_add_u64 v[0:1], v[18:19], 0, v[0:1]
	global_load_dwordx4 v[0:3], v[0:1], off
	v_lshl_add_u64 v[18:19], s[34:35], 1, v[14:15]
	v_lshlrev_b32_e32 v96, 11, v37
	v_or_b32_e32 v37, s6, v22
	v_lshl_add_u64 v[54:55], v[18:19], 0, v[96:97]
	v_lshlrev_b32_e32 v96, 11, v37
	v_or_b32_e32 v37, s6, v24
	s_waitcnt vmcnt(0)
	ds_write2_b32 v35, v0, v1 offset1:1
	ds_write2_b32 v35, v2, v3 offset0:2 offset1:3
	s_waitcnt lgkmcnt(0)
	ds_read2_b32 v[38:39], v36 offset0:33 offset1:41
	ds_read2_b32 v[40:41], v36 offset1:8
	ds_read2_b32 v[42:43], v36 offset0:66 offset1:74
	ds_read2_b32 v[44:45], v36 offset0:99 offset1:107
	ds_read2_b32 v[46:47], v36 offset0:132 offset1:140
	ds_read2_b32 v[48:49], v36 offset0:165 offset1:173
	ds_read2_b32 v[50:51], v36 offset0:198 offset1:206
	ds_read2_b32 v[52:53], v36 offset0:231 offset1:239
	s_waitcnt lgkmcnt(6)
	v_cvt_pk_bf16_f32 v0, v40, v38
	s_waitcnt lgkmcnt(4)
	v_cvt_pk_bf16_f32 v1, v42, v44
	s_waitcnt lgkmcnt(2)
	v_cvt_pk_bf16_f32 v2, v46, v48
	s_waitcnt lgkmcnt(0)
	v_cvt_pk_bf16_f32 v3, v50, v52
	global_store_dwordx4 v[54:55], v[0:3], off sc1
	s_nop 1
	v_cvt_pk_bf16_f32 v0, v41, v39
	v_cvt_pk_bf16_f32 v1, v43, v45
	v_cvt_pk_bf16_f32 v2, v47, v49
	v_cvt_pk_bf16_f32 v3, v51, v53
	v_lshl_add_u64 v[38:39], v[18:19], 0, v[96:97]
	global_store_dwordx4 v[38:39], v[0:3], off sc1
	ds_read2_b32 v[38:39], v36 offset0:49 offset1:57
	ds_read2_b32 v[40:41], v36 offset0:16 offset1:24
	ds_read2_b32 v[42:43], v36 offset0:82 offset1:90
	ds_read2_b32 v[44:45], v36 offset0:115 offset1:123
	ds_read2_b32 v[46:47], v36 offset0:148 offset1:156
	ds_read2_b32 v[48:49], v36 offset0:181 offset1:189
	ds_read2_b32 v[50:51], v36 offset0:214 offset1:222
	ds_read2_b32 v[52:53], v36 offset0:247 offset1:255
	v_lshlrev_b32_e32 v96, 11, v37
	v_or_b32_e32 v37, s6, v26
	s_waitcnt lgkmcnt(6)
	v_cvt_pk_bf16_f32 v0, v40, v38
	s_waitcnt lgkmcnt(4)
	v_cvt_pk_bf16_f32 v1, v42, v44
	s_waitcnt lgkmcnt(2)
	v_cvt_pk_bf16_f32 v2, v46, v48
	s_waitcnt lgkmcnt(0)
	v_cvt_pk_bf16_f32 v3, v50, v52
	v_lshl_add_u64 v[54:55], v[18:19], 0, v[96:97]
	v_lshlrev_b32_e32 v96, 11, v37
	global_store_dwordx4 v[54:55], v[0:3], off sc1
	v_lshl_add_u64 v[18:19], v[18:19], 0, v[96:97]
	s_nop 0
	v_cvt_pk_bf16_f32 v0, v41, v39
	v_cvt_pk_bf16_f32 v1, v43, v45
	v_cvt_pk_bf16_f32 v2, v47, v49
	v_cvt_pk_bf16_f32 v3, v51, v53
	global_store_dwordx4 v[18:19], v[0:3], off sc1
	s_waitcnt lgkmcnt(0)

; __device__ __forceinline__ unsigned pk_bf16(float lo, float hi) { return pg8::cvt_pk_bf16(lo, hi); }
; #define LDS_FENCE() asm volatile("s_waitcnt lgkmcnt(0)" ::: "memory")
; __device__ __forceinline__ void transpose_item(const float* Wsrc, int ldw, bf16_t* WT, int ldt, int kb, int nb, float* scr, int lane) {
;     const int k0 = 64 * kb, n0 = 32 * nb;
; #pragma unroll
;     for (int i = 0; i < 8; ++i) { const int kk = 8 * i + (lane >> 3), n4 = 4 * (lane & 7);
;         const f32x4 v = *(const f32x4*)(Wsrc + (size_t)(k0 + kk) * ldw + n0 + n4);
;         scr[kk * 33 + n4] = v[0]; scr[kk * 33 + n4 + 1] = v[1]; scr[kk * 33 + n4 + 2] = v[2]; scr[kk * 33 + n4 + 3] = v[3]; }
;     LDS_FENCE();
;     const int c = lane & 7;
; #pragma unroll
;     for (int j = 0; j < 4; ++j) { const int n = (lane >> 3) + 8 * j; const float* s = scr + (8 * c) * 33 + n;
;         u32x4 o; o.x = pk_bf16(s[0 * 33], s[1 * 33]); o.y = pk_bf16(s[2 * 33], s[3 * 33]); o.z = pk_bf16(s[4 * 33], s[5 * 33]); o.w = pk_bf16(s[6 * 33], s[7 * 33]);
;         *(u32x4*)(WT + (size_t)(n0 + n) * ldt + k0 + 8 * c) = o; }
;     LDS_FENCE();
; }
; __device__ __forceinline__ void phase_rows(const Ctx& c, int l) {
;     ...
;             if (r < I_IN) { const int kb = r / 192, nb = r % 192; const float* src = c.inp(IN_WIN) + (size_t)l * 1024 * DIN + (nb >= 64 ? 8 : 0);
;                 transpose_item(src, DIN, Win_t, 1024, kb, nb, scr, lane); continue; } r -= I_IN;
.LBB0_477:
	s_andn2_b64 vcc, exec, s[52:53]
	s_cbranch_vccnz .LBB0_458
	s_mul_hi_i32 s6, s23, 0x2aaaaaab
	s_load_dwordx2 s[52:53], s[50:51], 0x8
	s_lshr_b32 s31, s6, 31
	s_ashr_i32 s6, s6, 5
	s_add_i32 s6, s6, s31
	s_mul_i32 s31, s6, 0xffffff40
	s_add_i32 s31, s23, s31
	s_waitcnt lgkmcnt(0)
	s_add_u32 s34, s52, s12
	s_addc_u32 s36, s53, s0
	s_cmp_gt_i32 s31, 63
	s_cselect_b32 s31, 32, 0
	s_add_u32 s31, s34, s31
	s_addc_u32 s34, s36, 0
	s_lshl_b32 s54, s6, 6
	s_mulk_i32 s6, 0xe800
	s_add_i32 s52, s13, s6
	s_ashr_i32 s53, s52, 31
	s_lshl_b64 s[60:61], s[52:53], 2
	s_add_u32 s60, s31, s60
	s_addc_u32 s61, s34, s61
	v_lshlrev_b32_e32 v96, 2, v4
	v_lshl_add_u64 v[18:19], s[60:61], 0, v[96:97]
	v_or_b32_e32 v0, s54, v20
	s_movk_i32 s6, 0x6020
	v_mad_i64_i32 v[0:1], s[60:61], v0, s6, v[18:19]
	global_load_dwordx4 v[0:3], v[0:1], off
	s_ashr_i32 s55, s54, 31
	s_waitcnt vmcnt(0)
	ds_write2_b32 v21, v0, v1 offset1:1
	ds_write2_b32 v21, v2, v3 offset0:2 offset1:3
	v_or_b32_e32 v0, s54, v22
	v_mad_i64_i32 v[0:1], s[60:61], v0, s6, v[18:19]
	global_load_dwordx4 v[0:3], v[0:1], off
	s_waitcnt vmcnt(0)
	ds_write2_b32 v23, v0, v1 offset1:1
	ds_write2_b32 v23, v2, v3 offset0:2 offset1:3
	v_or_b32_e32 v0, s54, v24
	v_mad_i64_i32 v[0:1], s[60:61], v0, s6, v[18:19]
	global_load_dwordx4 v[0:3], v[0:1], off
	s_waitcnt vmcnt(0)
	ds_write2_b32 v25, v0, v1 offset1:1
	ds_write2_b32 v25, v2, v3 offset0:2 offset1:3
	v_or_b32_e32 v0, s54, v26
	v_mad_i64_i32 v[0:1], s[60:61], v0, s6, v[18:19]
	global_load_dwordx4 v[0:3], v[0:1], off
	s_waitcnt vmcnt(0)
	ds_write2_b32 v27, v0, v1 offset1:1
	ds_write2_b32 v27, v2, v3 offset0:2 offset1:3
	v_or_b32_e32 v0, s54, v28
	v_mad_i64_i32 v[0:1], s[60:61], v0, s6, v[18:19]
	global_load_dwordx4 v[0:3], v[0:1], off
	s_waitcnt vmcnt(0)
	ds_write2_b32 v29, v0, v1 offset1:1
	ds_write2_b32 v29, v2, v3 offset0:2 offset1:3
	v_or_b32_e32 v0, s54, v30
	v_mad_i64_i32 v[0:1], s[60:61], v0, s6, v[18:19]
	global_load_dwordx4 v[0:3], v[0:1], off
	s_waitcnt vmcnt(0)
	ds_write2_b32 v31, v0, v1 offset1:1
	ds_write2_b32 v31, v2, v3 offset0:2 offset1:3
	v_or_b32_e32 v0, s54, v32
	v_mad_i64_i32 v[0:1], s[60:61], v0, s6, v[18:19]
	global_load_dwordx4 v[0:3], v[0:1], off
	s_waitcnt vmcnt(0)
	ds_write2_b32 v33, v0, v1 offset1:1
	ds_write2_b32 v33, v2, v3 offset0:2 offset1:3
	v_or_b32_e32 v0, s54, v34
	v_mad_i64_i32 v[0:1], s[60:61], v0, s6, v[18:19]
	global_load_dwordx4 v[0:3], v[0:1], off
	s_waitcnt vmcnt(0)
	ds_write2_b32 v35, v0, v1 offset1:1
	ds_write2_b32 v35, v2, v3 offset0:2 offset1:3
	s_waitcnt lgkmcnt(0)
	ds_read2_b32 v[18:19], v36 offset0:33 offset1:41
	ds_read2_b32 v[42:43], v36 offset1:8
	ds_read2_b32 v[44:45], v36 offset0:66 offset1:74
	ds_read2_b32 v[46:47], v36 offset0:99 offset1:107
	ds_read2_b32 v[48:49], v36 offset0:132 offset1:140
	ds_read2_b32 v[50:51], v36 offset0:165 offset1:173
	ds_read2_b32 v[52:53], v36 offset0:198 offset1:206
	ds_read2_b32 v[54:55], v36 offset0:231 offset1:239
	v_add_u32_e32 v2, s52, v20
	v_ashrrev_i32_e32 v3, 31, v2
	v_lshl_add_u64 v[0:1], s[54:55], 1, v[16:17]
	v_lshlrev_b64 v[56:57], 11, v[2:3]
	s_waitcnt lgkmcnt(6)
	v_cvt_pk_bf16_f32 v38, v42, v18
	s_waitcnt lgkmcnt(4)
	v_cvt_pk_bf16_f32 v39, v44, v46
	s_waitcnt lgkmcnt(2)
	v_cvt_pk_bf16_f32 v40, v48, v50
	s_waitcnt lgkmcnt(0)
	v_cvt_pk_bf16_f32 v41, v52, v54
	v_lshl_add_u64 v[56:57], v[0:1], 0, v[56:57]
	v_add_u32_e32 v18, 8, v2
	global_store_dwordx4 v[56:57], v[38:41], off sc1
	v_add_u32_e32 v56, 16, v2
	v_ashrrev_i32_e32 v57, 31, v56
	v_cvt_pk_bf16_f32 v38, v43, v19
	v_ashrrev_i32_e32 v19, 31, v18
	v_lshlrev_b64 v[18:19], 11, v[18:19]
	v_cvt_pk_bf16_f32 v39, v45, v47
	v_cvt_pk_bf16_f32 v40, v49, v51
	v_cvt_pk_bf16_f32 v41, v53, v55
	v_lshl_add_u64 v[18:19], v[0:1], 0, v[18:19]
	global_store_dwordx4 v[18:19], v[38:41], off sc1
	ds_read2_b32 v[18:19], v36 offset0:49 offset1:57
	ds_read2_b32 v[42:43], v36 offset0:16 offset1:24
	ds_read2_b32 v[44:45], v36 offset0:82 offset1:90
	ds_read2_b32 v[46:47], v36 offset0:115 offset1:123
	ds_read2_b32 v[48:49], v36 offset0:148 offset1:156
	ds_read2_b32 v[50:51], v36 offset0:181 offset1:189
	ds_read2_b32 v[52:53], v36 offset0:214 offset1:222
	ds_read2_b32 v[54:55], v36 offset0:247 offset1:255
	v_add_u32_e32 v2, 24, v2
	v_lshlrev_b64 v[56:57], 11, v[56:57]
	v_ashrrev_i32_e32 v3, 31, v2
	s_waitcnt lgkmcnt(6)
	v_cvt_pk_bf16_f32 v38, v42, v18
	s_waitcnt lgkmcnt(4)
	v_cvt_pk_bf16_f32 v39, v44, v46
	s_waitcnt lgkmcnt(2)
	v_cvt_pk_bf16_f32 v40, v48, v50
	s_waitcnt lgkmcnt(0)
	v_cvt_pk_bf16_f32 v41, v52, v54
	v_lshl_add_u64 v[56:57], v[0:1], 0, v[56:57]
	v_lshlrev_b64 v[2:3], 11, v[2:3]
	global_store_dwordx4 v[56:57], v[38:41], off sc1
	v_lshl_add_u64 v[0:1], v[0:1], 0, v[2:3]
	s_nop 0
	v_cvt_pk_bf16_f32 v38, v43, v19
	v_cvt_pk_bf16_f32 v39, v45, v47
	v_cvt_pk_bf16_f32 v40, v49, v51
	v_cvt_pk_bf16_f32 v41, v53, v55
	global_store_dwordx4 v[0:1], v[38:41], off sc1
	s_waitcnt lgkmcnt(0)
	s_branch .LBB0_458

; __device__ __forceinline__ void phase_rows(const Ctx& c, int l) {
;     ...
;         if (l > 0) {
;             float s = 0.f;
; #pragma unroll
;             for (int j = 0; j < 4; ++j) s += (v[q][j].x + v[q][j].y) + (v[q][j].z + v[q][j].w);
;             const float mean = wave_sum(s) * (1.f / DM); float s2 = 0.f;
; #pragma unroll
;             for (int j = 0; j < 4; ++j) { v[q][j] = v[q][j] - mean; s2 += (v[q][j].x * v[q][j].x + v[q][j].y * v[q][j].y) + (v[q][j].z * v[q][j].z + v[q][j].w * v[q][j].w); }
;             const float rstd = 1.f / sqrtf(wave_sum(s2) * (1.f / DM) + LN_EPS);
;             const f32x4* gp = (const f32x4*)(c.inp(IN_LNG) + (size_t)(l - 1) * DM) + lane; const f32x4* bp = (const f32x4*)(c.inp(IN_LNB) + (size_t)(l - 1) * DM) + lane;
;             f32x4* orow = (f32x4*)(c.out + (size_t)m * DM) + lane;
; #pragma unroll
;             for (int j = 0; j < 4; ++j) { v[q][j] = v[q][j] * rstd * gp[64 * j] + bp[64 * j]; if (l == NLAYER) orow[64 * j] = v[q][j]; }
.LBB0_487:
	s_add_i32 s54, s46, s26
	s_ashr_i32 s47, s46, 31
	s_min_i32 s16, s54, 0x7fff
	s_lshl_b64 s[60:61], s[46:47], 12
	s_ashr_i32 s17, s16, 31
	s_waitcnt vmcnt(0)
	v_lshl_add_u64 v[138:139], v[174:175], 0, s[60:61]
	s_lshl_b64 s[16:17], s[16:17], 12
	global_load_dwordx4 v[166:169], v[138:139], off
	global_load_dwordx4 v[162:165], v[138:139], off offset:1024
	global_load_dwordx4 v[158:161], v[138:139], off offset:2048
	global_load_dwordx4 v[154:157], v[138:139], off offset:3072
	v_lshl_add_u64 v[138:139], v[174:175], 0, s[16:17]
	global_load_dwordx4 v[150:153], v[138:139], off
	global_load_dwordx4 v[146:149], v[138:139], off offset:1024
	global_load_dwordx4 v[142:145], v[138:139], off offset:2048
	s_nop 0
	global_load_dwordx4 v[138:141], v[138:139], off offset:3072
	v_cndmask_b32_e64 v96, 0, 1, s[48:49]
	v_cmp_ne_u32_e64 s[42:43], 1, v96
	s_andn2_b64 vcc, exec, s[48:49]
	s_cbranch_vccnz .LBB0_500
	s_waitcnt vmcnt(0)
	v_mov_b32_e32 v170, v167
	v_mov_b32_e32 v171, v168
	v_mov_b32_e32 v172, v166
	v_mov_b32_e32 v173, v169
	v_pk_add_f32 v[170:171], v[170:171], v[172:173]
	v_mov_b32_e32 v172, v163
	v_mov_b32_e32 v173, v164
	v_mov_b32_e32 v180, v162
	v_mov_b32_e32 v181, v165
	v_pk_add_f32 v[172:173], v[172:173], v[180:181]
	v_add_f32_e32 v96, v170, v171
	v_pk_add_f32 v[172:173], v[172:173], v[172:173] op_sel:[0,1] op_sel_hi:[1,0]
	v_add_f32_e32 v170, 0, v96
	v_add_f32_e32 v180, v158, v159
	v_add_f32_e32 v182, v160, v161
	v_mov_b32_e32 v171, v154
	v_mov_b32_e32 v173, v155
	v_mov_b32_e32 v181, v156
	v_mov_b32_e32 v183, v157
	v_pk_add_f32 v[170:171], v[170:171], v[172:173]
	v_pk_add_f32 v[172:173], v[180:181], v[182:183]
	s_load_dwordx4 s[64:67], s[12:13], 0x98
	v_pk_add_f32 v[170:171], v[170:171], v[172:173]
	v_lshl_add_u64 v[184:185], v[178:179], 0, s[60:61]
	v_add_f32_e32 v96, v170, v171
	s_nop 1
	v_add_f32_dpp v96, v96, v96 quad_perm:[1,0,3,2] row_mask:0xf bank_mask:0xf bound_ctrl:1
	s_nop 1
	v_add_f32_dpp v96, v96, v96 quad_perm:[2,3,0,1] row_mask:0xf bank_mask:0xf bound_ctrl:1
	s_nop 1
	v_add_f32_dpp v96, v96, v96 row_half_mirror row_mask:0xf bank_mask:0xf bound_ctrl:1
	s_nop 1
	v_add_f32_dpp v96, v96, v96 row_mirror row_mask:0xf bank_mask:0xf bound_ctrl:1
	s_nop 0
	v_readlane_b32 s0, v96, 16
	v_readlane_b32 s6, v96, 48
	v_readlane_b32 s16, v96, 0
	v_readlane_b32 s17, v96, 32
	v_mov_b32_e32 v170, s0
	v_mov_b32_e32 v171, s6
	v_pk_add_f32 v[170:171], s[16:17], v[170:171]
	s_nop 0
	v_add_f32_e32 v96, v170, v171
	v_fmamk_f32 v167, v96, 0xba800000, v167
	v_fmamk_f32 v166, v96, 0xba800000, v166
	v_fmamk_f32 v169, v96, 0xba800000, v169
	v_fmac_f32_e32 v168, 0xba800000, v96
	v_pk_mul_f32 v[170:171], v[168:169], v[168:169]
	v_pk_mul_f32 v[172:173], v[166:167], v[166:167]
	v_fmamk_f32 v183, v96, 0xba800000, v165
	v_pk_mov_b32 v[180:181], v[172:173], v[170:171] op_sel:[1,0]
	v_mov_b32_e32 v173, v171
	v_fmamk_f32 v182, v96, 0xba800000, v164
	v_fmamk_f32 v163, v96, 0xba800000, v163
	v_fmac_f32_e32 v162, 0xba800000, v96
	v_pk_add_f32 v[170:171], v[180:181], v[172:173]
	v_pk_mul_f32 v[164:165], v[182:183], v[182:183]
	v_pk_mul_f32 v[172:173], v[162:163], v[162:163]
	v_fmac_f32_e32 v158, 0xba800000, v96
	v_pk_mov_b32 v[180:181], v[172:173], v[164:165] op_sel:[1,0]
	v_mov_b32_e32 v173, v165
	v_pk_add_f32 v[164:165], v[180:181], v[172:173]
	v_fmamk_f32 v160, v96, 0xba800000, v160
	v_pk_add_f32 v[164:165], v[164:165], v[164:165] op_sel_hi:[0,1]
	v_fmamk_f32 v159, v96, 0xba800000, v159
	v_mul_f32_e32 v164, v158, v158
	v_fmamk_f32 v161, v96, 0xba800000, v161
	v_pk_fma_f32 v[172:173], v[158:159], v[158:159], v[164:165] op_sel_hi:[1,1,0]
	v_mul_f32_e32 v164, v160, v160
	v_pk_add_f32 v[170:171], v[170:171], v[170:171] op_sel_hi:[0,1]
	v_pk_fma_f32 v[180:181], v[160:161], v[160:161], v[164:165] op_sel_hi:[1,1,0]
	v_fmamk_f32 v157, v96, 0xba800000, v157
	v_fmamk_f32 v156, v96, 0xba800000, v156
	v_fmamk_f32 v155, v96, 0xba800000, v155
	v_fmac_f32_e32 v154, 0xba800000, v96
	v_mul_f32_e32 v172, v154, v154
	v_mul_f32_e32 v180, v155, v155
	v_mul_f32_e32 v170, v156, v156
	v_mul_f32_e32 v164, v157, v157
	v_pk_add_f32 v[172:173], v[172:173], v[180:181]
	v_pk_add_f32 v[164:165], v[170:171], v[164:165]
	s_nop 0
	v_pk_add_f32 v[164:165], v[172:173], v[164:165]
	s_nop 0
	v_add_f32_e32 v164, v164, v165
	s_nop 1
	v_add_f32_dpp v164, v164, v164 quad_perm:[1,0,3,2] row_mask:0xf bank_mask:0xf bound_ctrl:1
	s_nop 1
	v_add_f32_dpp v164, v164, v164 quad_perm:[2,3,0,1] row_mask:0xf bank_mask:0xf bound_ctrl:1
	s_nop 1
	v_add_f32_dpp v164, v164, v164 row_half_mirror row_mask:0xf bank_mask:0xf bound_ctrl:1
	s_nop 1
	v_add_f32_dpp v164, v164, v164 row_mirror row_mask:0xf bank_mask:0xf bound_ctrl:1
	s_nop 0
	v_readlane_b32 s0, v164, 16
	v_readlane_b32 s6, v164, 48
	v_readlane_b32 s16, v164, 0
	v_readlane_b32 s17, v164, 32
	v_mov_b32_e32 v164, s0
	v_mov_b32_e32 v165, s6
	v_pk_add_f32 v[164:165], s[16:17], v[164:165]
	s_nop 0
	v_add_f32_e32 v164, v164, v165
	v_fmamk_f32 v164, v164, 0x3a800000, v219
	v_cmp_gt_f32_e32 vcc, s87, v164
	v_mul_f32_e32 v165, 0x4f800000, v164
	s_nop 0
	v_cndmask_b32_e32 v164, v164, v165, vcc
	v_sqrt_f32_e32 v165, v164
	s_nop 0
	v_add_u32_e32 v170, -1, v165
	v_fma_f32 v171, -v170, v165, v164
	v_cmp_ge_f32_e64 s[40:41], 0, v171
	v_add_u32_e32 v171, 1, v165
	s_nop 0
	v_cndmask_b32_e64 v170, v165, v170, s[40:41]
	v_fma_f32 v165, -v171, v165, v164
	v_cmp_lt_f32_e64 s[40:41], 0, v165
	s_nop 1
	v_cndmask_b32_e64 v165, v170, v171, s[40:41]
	v_mul_f32_e32 v170, 0x37800000, v165
	v_cndmask_b32_e32 v165, v165, v170, vcc
	v_cmp_class_f32_e32 vcc, v164, v213
	s_nop 1
	v_cndmask_b32_e32 v164, v165, v164, vcc
	v_div_scale_f32 v165, s[16:17], v164, v164, 1.0
	v_rcp_f32_e32 v170, v165
	s_lshl_b64 s[16:17], s[22:23], 2
	s_waitcnt lgkmcnt(0)
	s_add_u32 s20, s64, s16
	s_addc_u32 s21, s65, s17
	v_fma_f32 v171, -v165, v170, 1.0
	v_fmac_f32_e32 v170, v171, v170
	v_div_scale_f32 v171, vcc, 1.0, v164, 1.0
	v_mul_f32_e32 v172, v171, v170
	v_fma_f32 v173, -v165, v172, v171
	v_fmac_f32_e32 v172, v173, v170
	v_fma_f32 v165, -v165, v172, v171
	v_div_fmas_f32 v165, v165, v170, v172
	v_div_fixup_f32 v180, v165, v164, 1.0
	v_lshlrev_b64 v[164:165], 4, v[200:201]
	s_add_u32 s16, s66, s16
	v_lshl_add_u64 v[186:187], s[20:21], 0, v[164:165]
	s_addc_u32 s17, s67, s17
	v_lshl_add_u64 v[188:189], s[16:17], 0, v[164:165]
	v_pk_mul_f32 v[190:191], v[166:167], v[180:181] op_sel_hi:[1,0]
	global_load_dwordx4 v[164:167], v[186:187], off
	global_load_dwordx4 v[170:173], v[188:189], off
	v_pk_mul_f32 v[168:169], v[168:169], v[180:181] op_sel_hi:[1,0]
	s_andn2_b64 vcc, exec, s[50:51]
	s_waitcnt vmcnt(0)
	v_pk_fma_f32 v[168:169], v[166:167], v[168:169], v[172:173]
	v_pk_fma_f32 v[166:167], v[164:165], v[190:191], v[170:171]
	v_cndmask_b32_e64 v164, 0, 1, s[50:51]
	v_cmp_ne_u32_e64 s[40:41], 1, v164
	s_cbranch_vccnz .LBB0_490
	global_store_dwordx4 v[184:185], v[166:169], off sc1
; __device__ __forceinline__ void phase_rows(const Ctx& c, int l) {
;     ...
;             for (int j = 0; j < 4; ++j) { v[q][j] = v[q][j] * rstd * gp[64 * j] + bp[64 * j]; if (l == NLAYER) orow[64 * j] = v[q][j]; }
;             if (l < NLAYER && lane == 0) *(float2*)((float*)(c.ws + WS_STATS) + (size_t)m * 2) = make_float2(mean, rstd);
.LBB0_490:
	global_load_dwordx4 v[190:193], v[186:187], off offset:1024
	global_load_dwordx4 v[202:205], v[188:189], off offset:1024
	v_mov_b32_e32 v181, v180
	v_mov_b32_e32 v170, v180
	v_mov_b32_e32 v171, v180
	v_pk_mul_f32 v[164:165], v[182:183], v[170:171]
	v_pk_mul_f32 v[162:163], v[162:163], v[180:181]
	s_and_b64 vcc, exec, s[40:41]
	s_waitcnt vmcnt(0)
	v_pk_fma_f32 v[164:165], v[164:165], v[192:193], v[204:205]
	v_pk_fma_f32 v[162:163], v[162:163], v[190:191], v[202:203]
	s_cbranch_vccnz .LBB0_492
	global_store_dwordx4 v[184:185], v[162:165], off offset:1024 sc1
.LBB0_492:
	v_pk_mul_f32 v[182:183], v[160:161], v[170:171]
	v_pk_mul_f32 v[190:191], v[158:159], v[180:181]
	global_load_dwordx4 v[158:161], v[186:187], off offset:2048
	global_load_dwordx4 v[170:173], v[188:189], off offset:2048
	s_and_b64 vcc, exec, s[40:41]
	s_waitcnt vmcnt(0)
	v_pk_fma_f32 v[160:161], v[182:183], v[160:161], v[172:173]
	v_pk_fma_f32 v[158:159], v[190:191], v[158:159], v[170:171]
	s_cbranch_vccnz .LBB0_494
	global_store_dwordx4 v[184:185], v[158:161], off offset:2048 sc1
.LBB0_494:
	v_mov_b32_e32 v170, v180
	v_mov_b32_e32 v171, v180
	v_pk_mul_f32 v[182:183], v[156:157], v[170:171]
	v_pk_mul_f32 v[190:191], v[154:155], v[180:181]
	global_load_dwordx4 v[154:157], v[186:187], off offset:3072
	global_load_dwordx4 v[170:173], v[188:189], off offset:3072
	s_and_b64 vcc, exec, s[40:41]
	s_waitcnt vmcnt(0)
	v_pk_fma_f32 v[156:157], v[182:183], v[156:157], v[172:173]
	v_pk_fma_f32 v[154:155], v[190:191], v[154:155], v[170:171]
	s_cbranch_vccnz .LBB0_496
	global_store_dwordx4 v[184:185], v[154:157], off offset:3072 sc1
.LBB0_496:
	s_and_saveexec_b64 s[40:41], s[52:53]
	s_cbranch_execz .LBB0_498
	s_lshl_b64 s[16:17], s[46:47], 3
	v_readlane_b32 s0, v253, 37
	s_add_u32 s16, s0, s16
	v_readlane_b32 s0, v253, 38
	v_mul_f32_e32 v170, 0x3a800000, v96
	s_addc_u32 s17, s0, s17
	v_mov_b32_e32 v171, v180
	global_store_dwordx2 v97, v[170:171], s[16:17] sc1

; __device__ __forceinline__ unsigned pk_bf16(float lo, float hi) { return pg8::cvt_pk_bf16(lo, hi); }
; __device__ __forceinline__ void phase_rows(const Ctx& c, int l) {
;     ...
;         if (l < NLAYER) {
;             u32x2* o8 = (u32x2*)(XB + (size_t)m * DM) + lane;
; #pragma unroll
;             for (int j = 0; j < 4; ++j) { u32x2 w; w.x = pk_bf16(v[q][j].x, v[q][j].y); w.y = pk_bf16(v[q][j].z, v[q][j].w); o8[64 * j] = w; }
;             f32x4 a0 = {0.f, 0.f, 0.f, 0.f}, a1 = {0.f, 0.f, 0.f, 0.f};
; #pragma unroll
;             for (int j = 0; j < 4; ++j)
; #pragma unroll
;                 for (int i = 0; i < 4; ++i) { const float xv = v[q][j][i]; a0 += wf[4 * j + i][0] * xv; a1 += wf[4 * j + i][1] * xv; }
.LBB0_501:
	s_lshl_b64 s[16:17], s[46:47], 11
	v_lshl_add_u64 v[170:171], v[176:177], 0, s[16:17]
	s_waitcnt vmcnt(0)
	v_cvt_pk_bf16_f32 v172, v166, v167
	v_cvt_pk_bf16_f32 v173, v168, v169
	global_store_dwordx2 v[170:171], v[172:173], off sc1
	v_cvt_pk_bf16_f32 v172, v162, v163
	v_cvt_pk_bf16_f32 v173, v164, v165
	global_store_dwordx2 v[170:171], v[172:173], off offset:512 sc1
	v_cvt_pk_bf16_f32 v172, v158, v159
	v_cvt_pk_bf16_f32 v173, v160, v161
	global_store_dwordx2 v[170:171], v[172:173], off offset:1024 sc1
	v_cvt_pk_bf16_f32 v172, v154, v155
	v_cvt_pk_bf16_f32 v173, v156, v157
	global_store_dwordx2 v[170:171], v[172:173], off offset:1536 sc1
	v_pk_fma_f32 v[170:171], v[0:1], v[166:167], 0 op_sel_hi:[1,0,0]
	v_pk_fma_f32 v[172:173], v[2:3], v[166:167], 0 op_sel_hi:[1,0,0]
	v_pk_fma_f32 v[180:181], v[4:5], v[166:167], 0 op_sel_hi:[1,0,0]
	v_pk_fma_f32 v[182:183], v[6:7], v[166:167], 0 op_sel_hi:[1,0,0]
	v_pk_fma_f32 v[170:171], v[12:13], v[166:167], v[170:171] op_sel:[0,1,0]
	v_pk_fma_f32 v[172:173], v[14:15], v[166:167], v[172:173] op_sel:[0,1,0]
	v_pk_fma_f32 v[182:183], v[10:11], v[166:167], v[182:183] op_sel:[0,1,0]
	v_pk_fma_f32 v[166:167], v[8:9], v[166:167], v[180:181] op_sel:[0,1,0]
	v_pk_fma_f32 v[170:171], v[20:21], v[168:169], v[170:171] op_sel_hi:[1,0,1]
	v_mov_b32_e32 v96, v169
	v_pk_fma_f32 v[172:173], v[22:23], v[168:169], v[172:173] op_sel_hi:[1,0,1]
	v_pk_fma_f32 v[166:167], v[16:17], v[168:169], v[166:167] op_sel_hi:[1,0,1]
	v_pk_fma_f32 v[180:181], v[18:19], v[168:169], v[182:183] op_sel_hi:[1,0,1]
	v_pk_fma_f32 v[170:171], v[28:29], v[96:97], v[170:171] op_sel_hi:[1,0,1]
	v_pk_fma_f32 v[168:169], v[30:31], v[96:97], v[172:173] op_sel_hi:[1,0,1]
	v_pk_fma_f32 v[172:173], v[26:27], v[96:97], v[180:181] op_sel_hi:[1,0,1]
	v_pk_fma_f32 v[166:167], v[24:25], v[96:97], v[166:167] op_sel_hi:[1,0,1]
	v_pk_fma_f32 v[170:171], v[36:37], v[162:163], v[170:171] op_sel_hi:[1,0,1]
	v_pk_fma_f32 v[168:169], v[38:39], v[162:163], v[168:169] op_sel_hi:[1,0,1]
	v_pk_fma_f32 v[166:167], v[32:33], v[162:163], v[166:167] op_sel_hi:[1,0,1]
	v_pk_fma_f32 v[172:173], v[34:35], v[162:163], v[172:173] op_sel_hi:[1,0,1]
	v_pk_fma_f32 v[170:171], v[44:45], v[162:163], v[170:171] op_sel:[0,1,0]
	v_pk_fma_f32 v[168:169], v[46:47], v[162:163], v[168:169] op_sel:[0,1,0]
	v_pk_fma_f32 v[172:173], v[42:43], v[162:163], v[172:173] op_sel:[0,1,0]
	v_pk_fma_f32 v[162:163], v[40:41], v[162:163], v[166:167] op_sel:[0,1,0]
	v_pk_fma_f32 v[166:167], v[52:53], v[164:165], v[170:171] op_sel_hi:[1,0,1]
	v_mov_b32_e32 v96, v165
	v_pk_fma_f32 v[168:169], v[54:55], v[164:165], v[168:169] op_sel_hi:[1,0,1]
	v_pk_fma_f32 v[162:163], v[48:49], v[164:165], v[162:163] op_sel_hi:[1,0,1]
	v_pk_fma_f32 v[170:171], v[50:51], v[164:165], v[172:173] op_sel_hi:[1,0,1]
	v_pk_fma_f32 v[166:167], v[60:61], v[96:97], v[166:167] op_sel_hi:[1,0,1]
	v_pk_fma_f32 v[164:165], v[62:63], v[96:97], v[168:169] op_sel_hi:[1,0,1]
	v_pk_fma_f32 v[168:169], v[58:59], v[96:97], v[170:171] op_sel_hi:[1,0,1]
	v_pk_fma_f32 v[162:163], v[56:57], v[96:97], v[162:163] op_sel_hi:[1,0,1]
	v_pk_fma_f32 v[166:167], v[68:69], v[158:159], v[166:167] op_sel_hi:[1,0,1]
	v_pk_fma_f32 v[164:165], v[70:71], v[158:159], v[164:165] op_sel_hi:[1,0,1]
	v_pk_fma_f32 v[162:163], v[64:65], v[158:159], v[162:163] op_sel_hi:[1,0,1]
	v_pk_fma_f32 v[168:169], v[66:67], v[158:159], v[168:169] op_sel_hi:[1,0,1]
	v_pk_fma_f32 v[166:167], v[76:77], v[158:159], v[166:167] op_sel:[0,1,0]
	v_pk_fma_f32 v[164:165], v[78:79], v[158:159], v[164:165] op_sel:[0,1,0]
	v_pk_fma_f32 v[168:169], v[74:75], v[158:159], v[168:169] op_sel:[0,1,0]
	v_pk_fma_f32 v[158:159], v[72:73], v[158:159], v[162:163] op_sel:[0,1,0]
	v_pk_fma_f32 v[162:163], v[92:93], v[160:161], v[166:167] op_sel_hi:[1,0,1]
	v_mov_b32_e32 v96, v161
	v_pk_fma_f32 v[164:165], v[94:95], v[160:161], v[164:165] op_sel_hi:[1,0,1]
	v_pk_fma_f32 v[158:159], v[88:89], v[160:161], v[158:159] op_sel_hi:[1,0,1]
	v_pk_fma_f32 v[166:167], v[90:91], v[160:161], v[168:169] op_sel_hi:[1,0,1]
	v_pk_fma_f32 v[162:163], v[102:103], v[96:97], v[162:163] op_sel_hi:[1,0,1]
	v_pk_fma_f32 v[160:161], v[104:105], v[96:97], v[164:165] op_sel_hi:[1,0,1]
	v_pk_fma_f32 v[164:165], v[100:101], v[96:97], v[166:167] op_sel_hi:[1,0,1]
	v_pk_fma_f32 v[158:159], v[98:99], v[96:97], v[158:159] op_sel_hi:[1,0,1]
	v_pk_fma_f32 v[162:163], v[110:111], v[154:155], v[162:163] op_sel_hi:[1,0,1]
	v_pk_fma_f32 v[160:161], v[112:113], v[154:155], v[160:161] op_sel_hi:[1,0,1]
	v_pk_fma_f32 v[158:159], v[106:107], v[154:155], v[158:159] op_sel_hi:[1,0,1]
	v_pk_fma_f32 v[164:165], v[108:109], v[154:155], v[164:165] op_sel_hi:[1,0,1]
	v_pk_fma_f32 v[162:163], v[118:119], v[154:155], v[162:163] op_sel:[0,1,0]
	v_pk_fma_f32 v[160:161], v[120:121], v[154:155], v[160:161] op_sel:[0,1,0]
	v_pk_fma_f32 v[164:165], v[116:117], v[154:155], v[164:165] op_sel:[0,1,0]
	v_pk_fma_f32 v[154:155], v[114:115], v[154:155], v[158:159] op_sel:[0,1,0]
	v_pk_fma_f32 v[158:159], v[126:127], v[156:157], v[162:163] op_sel_hi:[1,0,1]
	v_mov_b32_e32 v96, v157
	v_pk_fma_f32 v[160:161], v[128:129], v[156:157], v[160:161] op_sel_hi:[1,0,1]
	v_pk_fma_f32 v[154:155], v[122:123], v[156:157], v[154:155] op_sel_hi:[1,0,1]
	v_pk_fma_f32 v[162:163], v[124:125], v[156:157], v[164:165] op_sel_hi:[1,0,1]
	v_pk_fma_f32 v[158:159], v[134:135], v[96:97], v[158:159] op_sel_hi:[1,0,1]
	v_pk_fma_f32 v[156:157], v[136:137], v[96:97], v[160:161] op_sel_hi:[1,0,1]
	v_pk_fma_f32 v[160:161], v[132:133], v[96:97], v[162:163] op_sel_hi:[1,0,1]
; __device__ __forceinline__ void phase_rows(const Ctx& c, int l) {
;     ...
;             for (int h = 0; h < 4; ++h) { f[h] = wave_sum(a0[h]) + bfv[h]; f[4 + h] = wave_sum(a1[h]) + bfv[4 + h]; }
;             if (lane == 0) { *(f32x4*)(flog + (size_t)m * 8) = (f32x4){f[0], f[1], f[2], f[3]}; *(f32x4*)(flog + (size_t)m * 8 + 4) = (f32x4){f[4], f[5], f[6], f[7]}; }
	v_pk_fma_f32 v[154:155], v[130:131], v[96:97], v[154:155] op_sel_hi:[1,0,1]
	v_add_f32_dpp v96, v158, v158 quad_perm:[1,0,3,2] row_mask:0xf bank_mask:0xf bound_ctrl:1
	s_nop 1
	v_add_f32_dpp v96, v96, v96 quad_perm:[2,3,0,1] row_mask:0xf bank_mask:0xf bound_ctrl:1
	s_nop 1
	v_add_f32_dpp v96, v96, v96 row_half_mirror row_mask:0xf bank_mask:0xf bound_ctrl:1
	s_nop 1
	v_add_f32_dpp v96, v96, v96 row_mirror row_mask:0xf bank_mask:0xf bound_ctrl:1
	s_nop 0
	v_readlane_b32 s68, v96, 0
	v_readlane_b32 s21, v96, 16
	v_readlane_b32 s64, v96, 32
	v_readlane_b32 s17, v96, 48
	v_add_f32_dpp v96, v154, v154 quad_perm:[1,0,3,2] row_mask:0xf bank_mask:0xf bound_ctrl:1
	s_nop 1
	v_add_f32_dpp v96, v96, v96 quad_perm:[2,3,0,1] row_mask:0xf bank_mask:0xf bound_ctrl:1
	s_nop 1
	v_add_f32_dpp v96, v96, v96 row_half_mirror row_mask:0xf bank_mask:0xf bound_ctrl:1
	s_nop 1
	v_add_f32_dpp v96, v96, v96 row_mirror row_mask:0xf bank_mask:0xf bound_ctrl:1
	s_nop 0
	v_readlane_b32 s62, v96, 0
	v_readlane_b32 s6, v96, 16
	v_readlane_b32 s60, v96, 32
	v_readlane_b32 s0, v96, 48
	v_add_f32_dpp v96, v159, v159 quad_perm:[1,0,3,2] row_mask:0xf bank_mask:0xf bound_ctrl:1
	s_nop 1
	v_add_f32_dpp v96, v96, v96 quad_perm:[2,3,0,1] row_mask:0xf bank_mask:0xf bound_ctrl:1
	s_nop 1
	v_add_f32_dpp v96, v96, v96 row_half_mirror row_mask:0xf bank_mask:0xf bound_ctrl:1
	s_nop 1
	v_add_f32_dpp v96, v96, v96 row_mirror row_mask:0xf bank_mask:0xf bound_ctrl:1
	s_nop 0
	v_readlane_b32 s69, v96, 0
	v_readlane_b32 s55, v96, 16
	v_readlane_b32 s65, v96, 32
	v_readlane_b32 s34, v96, 48
	v_add_f32_dpp v96, v155, v155 quad_perm:[1,0,3,2] row_mask:0xf bank_mask:0xf bound_ctrl:1
	s_nop 1
	v_add_f32_dpp v96, v96, v96 quad_perm:[2,3,0,1] row_mask:0xf bank_mask:0xf bound_ctrl:1
	s_nop 1
	v_add_f32_dpp v96, v96, v96 row_half_mirror row_mask:0xf bank_mask:0xf bound_ctrl:1
	s_nop 1
	v_add_f32_dpp v96, v96, v96 row_mirror row_mask:0xf bank_mask:0xf bound_ctrl:1
	s_nop 0
	v_readlane_b32 s63, v96, 0
	v_readlane_b32 s20, v96, 16
	v_readlane_b32 s61, v96, 32
	v_readlane_b32 s16, v96, 48
	v_add_f32_dpp v96, v156, v156 quad_perm:[1,0,3,2] row_mask:0xf bank_mask:0xf bound_ctrl:1
	s_nop 1
	v_add_f32_dpp v96, v96, v96 quad_perm:[2,3,0,1] row_mask:0xf bank_mask:0xf bound_ctrl:1
	s_nop 1
	v_add_f32_dpp v96, v96, v96 row_half_mirror row_mask:0xf bank_mask:0xf bound_ctrl:1
	s_nop 1
	v_add_f32_dpp v96, v96, v96 row_mirror row_mask:0xf bank_mask:0xf bound_ctrl:1
	s_nop 0
	v_readlane_b32 s92, v96, 0
	v_readlane_b32 s87, v96, 16
	v_readlane_b32 s74, v96, 32
	v_readlane_b32 s81, v96, 48
	v_add_f32_dpp v96, v160, v160 quad_perm:[1,0,3,2] row_mask:0xf bank_mask:0xf bound_ctrl:1
	s_nop 1
	v_add_f32_dpp v96, v96, v96 quad_perm:[2,3,0,1] row_mask:0xf bank_mask:0xf bound_ctrl:1
	s_nop 1
	v_add_f32_dpp v96, v96, v96 row_half_mirror row_mask:0xf bank_mask:0xf bound_ctrl:1
	s_nop 1
	v_add_f32_dpp v96, v96, v96 row_mirror row_mask:0xf bank_mask:0xf bound_ctrl:1
	s_nop 0
	v_readlane_b32 s72, v96, 0
	v_readlane_b32 s36, v96, 16
	v_readlane_b32 s70, v96, 32
	v_readlane_b32 s31, v96, 48
	v_add_f32_dpp v96, v157, v157 quad_perm:[1,0,3,2] row_mask:0xf bank_mask:0xf bound_ctrl:1
	s_nop 1
	v_add_f32_dpp v96, v96, v96 quad_perm:[2,3,0,1] row_mask:0xf bank_mask:0xf bound_ctrl:1
	s_nop 1
	v_add_f32_dpp v96, v96, v96 row_half_mirror row_mask:0xf bank_mask:0xf bound_ctrl:1
	s_nop 1
	v_add_f32_dpp v96, v96, v96 row_mirror row_mask:0xf bank_mask:0xf bound_ctrl:1
	s_nop 0
	v_readlane_b32 s93, v96, 0
	v_readlane_b32 vcc_lo, v96, 16
	v_readlane_b32 s75, v96, 32
	v_readlane_b32 s94, v96, 48
	v_add_f32_dpp v96, v161, v161 quad_perm:[1,0,3,2] row_mask:0xf bank_mask:0xf bound_ctrl:1
	s_nop 1
	v_add_f32_dpp v96, v96, v96 quad_perm:[2,3,0,1] row_mask:0xf bank_mask:0xf bound_ctrl:1
	s_nop 1
	v_add_f32_dpp v96, v96, v96 row_half_mirror row_mask:0xf bank_mask:0xf bound_ctrl:1
	s_nop 1
	v_add_f32_dpp v96, v96, v96 row_mirror row_mask:0xf bank_mask:0xf bound_ctrl:1
	s_nop 0
	v_readlane_b32 s73, v96, 0
	v_readlane_b32 s86, v96, 16
	v_readlane_b32 s71, v96, 32
	v_readlane_b32 s80, v96, 48
	s_and_saveexec_b64 s[66:67], s[38:39]
	s_cbranch_execz .LBB0_503
	v_mov_b32_e32 v154, s87
	v_mov_b32_e32 v155, vcc_lo
	v_mov_b32_e32 v156, s21
	v_mov_b32_e32 v157, s55
	v_mov_b32_e32 v158, s81
	v_mov_b32_e32 v159, s94
	v_mov_b32_e32 v160, s17
	v_mov_b32_e32 v161, s34
	v_pk_add_f32 v[154:155], s[92:93], v[154:155]
	v_pk_add_f32 v[156:157], s[68:69], v[156:157]
	v_pk_add_f32 v[158:159], s[74:75], v[158:159]
	v_pk_add_f32 v[160:161], s[64:65], v[160:161]
	v_pk_add_f32 v[154:155], v[154:155], v[158:159]
	v_pk_add_f32 v[160:161], v[156:157], v[160:161]
	v_pk_add_f32 v[156:157], v[86:87], v[154:155]
	v_pk_add_f32 v[154:155], v[84:85], v[160:161]
	v_mov_b32_e32 v158, s36
	v_mov_b32_e32 v159, s86
	v_mov_b32_e32 v160, s6
	v_mov_b32_e32 v161, s20
	v_mov_b32_e32 v162, s31
	v_mov_b32_e32 v163, s80
	v_mov_b32_e32 v164, s0
	v_mov_b32_e32 v165, s16
	s_lshl_b64 s[16:17], s[46:47], 5
	v_readlane_b32 s0, v253, 25
	v_pk_add_f32 v[158:159], s[72:73], v[158:159]
	v_pk_add_f32 v[160:161], s[62:63], v[160:161]
	v_pk_add_f32 v[162:163], s[70:71], v[162:163]
	v_pk_add_f32 v[164:165], s[60:61], v[164:165]
	s_add_u32 s16, s0, s16
	v_readlane_b32 s0, v253, 26
	v_pk_add_f32 v[164:165], v[160:161], v[164:165]
	v_pk_add_f32 v[158:159], v[158:159], v[162:163]
	s_addc_u32 s17, s0, s17
	v_pk_add_f32 v[160:161], v[82:83], v[158:159]
	v_pk_add_f32 v[158:159], v[80:81], v[164:165]
	global_store_dwordx4 v97, v[154:157], s[16:17] sc1
	global_store_dwordx4 v97, v[158:161], s[16:17] offset:16 sc1

; __device__ __forceinline__ void phase_rows(const Ctx& c, int l) {
;     ...
;         if (l > 0) {
;             float s = 0.f;
; #pragma unroll
;             for (int j = 0; j < 4; ++j) s += (v[q][j].x + v[q][j].y) + (v[q][j].z + v[q][j].w);
;             const float mean = wave_sum(s) * (1.f / DM); float s2 = 0.f;
; #pragma unroll
;             for (int j = 0; j < 4; ++j) { v[q][j] = v[q][j] - mean; s2 += (v[q][j].x * v[q][j].x + v[q][j].y * v[q][j].y) + (v[q][j].z * v[q][j].z + v[q][j].w * v[q][j].w); }
;             const float rstd = 1.f / sqrtf(wave_sum(s2) * (1.f / DM) + LN_EPS);
;             const f32x4* gp = (const f32x4*)(c.inp(IN_LNG) + (size_t)(l - 1) * DM) + lane; const f32x4* bp = (const f32x4*)(c.inp(IN_LNB) + (size_t)(l - 1) * DM) + lane;
;             f32x4* orow = (f32x4*)(c.out + (size_t)m * DM) + lane;
; #pragma unroll
;             for (int j = 0; j < 4; ++j) { v[q][j] = v[q][j] * rstd * gp[64 * j] + bp[64 * j]; if (l == NLAYER) orow[64 * j] = v[q][j]; }
.LBB0_504:
	s_and_b64 vcc, exec, s[42:43]
	s_cbranch_vccnz .LBB0_516
	s_waitcnt vmcnt(0)
	v_mov_b32_e32 v154, v151
	v_mov_b32_e32 v155, v152
	v_mov_b32_e32 v156, v150
	v_mov_b32_e32 v157, v153
	v_pk_add_f32 v[154:155], v[154:155], v[156:157]
	v_mov_b32_e32 v156, v147
	v_mov_b32_e32 v157, v148
	v_mov_b32_e32 v158, v146
	v_mov_b32_e32 v159, v149
	v_pk_add_f32 v[156:157], v[156:157], v[158:159]
	v_add_f32_e32 v96, v154, v155
	v_pk_add_f32 v[156:157], v[156:157], v[156:157] op_sel:[0,1] op_sel_hi:[1,0]
	v_add_f32_e32 v154, 0, v96
	v_add_f32_e32 v158, v142, v143
	v_add_f32_e32 v160, v144, v145
	v_mov_b32_e32 v155, v138
	v_mov_b32_e32 v157, v139
	v_mov_b32_e32 v159, v140
	v_mov_b32_e32 v161, v141
	v_pk_add_f32 v[154:155], v[154:155], v[156:157]
	v_pk_add_f32 v[156:157], v[158:159], v[160:161]
	s_load_dwordx4 s[60:63], s[12:13], 0x98
	v_pk_add_f32 v[154:155], v[154:155], v[156:157]
	s_nop 0
	v_add_f32_e32 v96, v154, v155
	s_nop 1
	v_add_f32_dpp v96, v96, v96 quad_perm:[1,0,3,2] row_mask:0xf bank_mask:0xf bound_ctrl:1
	s_nop 1
	v_add_f32_dpp v96, v96, v96 quad_perm:[2,3,0,1] row_mask:0xf bank_mask:0xf bound_ctrl:1
	s_nop 1
	v_add_f32_dpp v96, v96, v96 row_half_mirror row_mask:0xf bank_mask:0xf bound_ctrl:1
	s_nop 1
	v_add_f32_dpp v96, v96, v96 row_mirror row_mask:0xf bank_mask:0xf bound_ctrl:1
	s_nop 0
	v_readlane_b32 s0, v96, 16
	v_readlane_b32 s6, v96, 48
	v_readlane_b32 s16, v96, 0
	v_readlane_b32 s17, v96, 32
	v_mov_b32_e32 v154, s0
	v_mov_b32_e32 v155, s6
	v_pk_add_f32 v[154:155], s[16:17], v[154:155]
	s_nop 0
	v_add_f32_e32 v96, v154, v155
	v_fmamk_f32 v151, v96, 0xba800000, v151
	v_fmamk_f32 v150, v96, 0xba800000, v150
	v_fmamk_f32 v153, v96, 0xba800000, v153
	v_fmac_f32_e32 v152, 0xba800000, v96
	v_pk_mul_f32 v[154:155], v[152:153], v[152:153]
	v_pk_mul_f32 v[156:157], v[150:151], v[150:151]
	v_fmamk_f32 v161, v96, 0xba800000, v149
	v_pk_mov_b32 v[158:159], v[156:157], v[154:155] op_sel:[1,0]
	v_mov_b32_e32 v157, v155
	v_fmamk_f32 v160, v96, 0xba800000, v148
	v_fmamk_f32 v147, v96, 0xba800000, v147
	v_fmac_f32_e32 v146, 0xba800000, v96
	v_pk_add_f32 v[154:155], v[158:159], v[156:157]
	v_pk_mul_f32 v[148:149], v[160:161], v[160:161]
	v_pk_mul_f32 v[156:157], v[146:147], v[146:147]
	v_fmac_f32_e32 v142, 0xba800000, v96
	v_pk_mov_b32 v[158:159], v[156:157], v[148:149] op_sel:[1,0]
	v_mov_b32_e32 v157, v149
	v_pk_add_f32 v[148:149], v[158:159], v[156:157]
	v_fmamk_f32 v144, v96, 0xba800000, v144
	v_pk_add_f32 v[148:149], v[148:149], v[148:149] op_sel_hi:[0,1]
	v_fmamk_f32 v143, v96, 0xba800000, v143
	v_mul_f32_e32 v148, v142, v142
	v_fmamk_f32 v145, v96, 0xba800000, v145
	v_pk_fma_f32 v[156:157], v[142:143], v[142:143], v[148:149] op_sel_hi:[1,1,0]
	v_mul_f32_e32 v148, v144, v144
	v_pk_add_f32 v[154:155], v[154:155], v[154:155] op_sel_hi:[0,1]
	v_pk_fma_f32 v[158:159], v[144:145], v[144:145], v[148:149] op_sel_hi:[1,1,0]
	v_fmamk_f32 v141, v96, 0xba800000, v141
	v_fmamk_f32 v140, v96, 0xba800000, v140
	v_fmamk_f32 v139, v96, 0xba800000, v139
	v_fmac_f32_e32 v138, 0xba800000, v96
	v_mul_f32_e32 v156, v138, v138
	v_mul_f32_e32 v158, v139, v139
	v_mul_f32_e32 v154, v140, v140
	v_mul_f32_e32 v148, v141, v141
	v_pk_add_f32 v[156:157], v[156:157], v[158:159]
	v_pk_add_f32 v[148:149], v[154:155], v[148:149]
	s_nop 0
	v_pk_add_f32 v[148:149], v[156:157], v[148:149]
	s_nop 0
	v_add_f32_e32 v148, v148, v149
	s_nop 1
	v_add_f32_dpp v148, v148, v148 quad_perm:[1,0,3,2] row_mask:0xf bank_mask:0xf bound_ctrl:1
	s_nop 1
	v_add_f32_dpp v148, v148, v148 quad_perm:[2,3,0,1] row_mask:0xf bank_mask:0xf bound_ctrl:1
	s_nop 1
	v_add_f32_dpp v148, v148, v148 row_half_mirror row_mask:0xf bank_mask:0xf bound_ctrl:1
	s_nop 1
	v_add_f32_dpp v148, v148, v148 row_mirror row_mask:0xf bank_mask:0xf bound_ctrl:1
	s_nop 0
	v_readlane_b32 s0, v148, 16
	v_readlane_b32 s6, v148, 48
	v_readlane_b32 s16, v148, 0
	v_readlane_b32 s17, v148, 32
	v_mov_b32_e32 v148, s0
	v_mov_b32_e32 v149, s6
	v_pk_add_f32 v[148:149], s[16:17], v[148:149]
	s_nop 0
	v_add_f32_e32 v148, v148, v149
	v_fmamk_f32 v148, v148, 0x3a800000, v219
	v_cmp_gt_f32_e32 vcc, s87, v148
	v_mul_f32_e32 v149, 0x4f800000, v148
	s_nop 0
	v_cndmask_b32_e32 v148, v148, v149, vcc
	v_sqrt_f32_e32 v149, v148
	s_nop 0
	v_add_u32_e32 v154, -1, v149
	v_fma_f32 v155, -v154, v149, v148
	v_cmp_ge_f32_e64 s[42:43], 0, v155
	v_add_u32_e32 v155, 1, v149
	s_nop 0
	v_cndmask_b32_e64 v154, v149, v154, s[42:43]
	v_fma_f32 v149, -v155, v149, v148
	v_cmp_lt_f32_e64 s[42:43], 0, v149
	s_nop 1
	v_cndmask_b32_e64 v149, v154, v155, s[42:43]
	v_mul_f32_e32 v154, 0x37800000, v149
	v_cndmask_b32_e32 v149, v149, v154, vcc
	v_cmp_class_f32_e32 vcc, v148, v213
	s_nop 1
	v_cndmask_b32_e32 v148, v149, v148, vcc
	v_div_scale_f32 v149, s[16:17], v148, v148, 1.0
	v_rcp_f32_e32 v154, v149
	s_lshl_b64 s[16:17], s[22:23], 2
	s_waitcnt lgkmcnt(0)
	s_add_u32 s20, s60, s16
	s_addc_u32 s21, s61, s17
	v_fma_f32 v155, -v149, v154, 1.0
	v_fmac_f32_e32 v154, v155, v154
	v_div_scale_f32 v155, vcc, 1.0, v148, 1.0
	v_mul_f32_e32 v156, v155, v154
	v_fma_f32 v157, -v149, v156, v155
	v_fmac_f32_e32 v156, v157, v154
	v_fma_f32 v149, -v149, v156, v155
	v_div_fmas_f32 v149, v149, v154, v156
	v_div_fixup_f32 v158, v149, v148, 1.0
	v_lshlrev_b64 v[148:149], 4, v[200:201]
	s_add_u32 s16, s62, s16
	v_lshl_add_u64 v[164:165], s[20:21], 0, v[148:149]
	s_addc_u32 s17, s63, s17
	v_lshl_add_u64 v[166:167], s[16:17], 0, v[148:149]
	v_pk_mul_f32 v[168:169], v[150:151], v[158:159] op_sel_hi:[1,0]
	global_load_dwordx4 v[148:151], v[164:165], off
	global_load_dwordx4 v[154:157], v[166:167], off
	s_ashr_i32 s55, s54, 31
	v_pk_mul_f32 v[152:153], v[152:153], v[158:159] op_sel_hi:[1,0]
	s_lshl_b64 s[16:17], s[54:55], 12
	v_lshl_add_u64 v[162:163], v[178:179], 0, s[16:17]
	s_andn2_b64 vcc, exec, s[50:51]
	s_waitcnt vmcnt(0)
	v_pk_fma_f32 v[152:153], v[150:151], v[152:153], v[156:157]
	v_pk_fma_f32 v[150:151], v[148:149], v[168:169], v[154:155]
	v_cndmask_b32_e64 v148, 0, 1, s[50:51]
	v_cmp_ne_u32_e64 s[42:43], 1, v148
	s_cbranch_vccnz .LBB0_507
	global_store_dwordx4 v[162:163], v[150:153], off sc1
; __device__ __forceinline__ void phase_rows(const Ctx& c, int l) {
;     ...
;             f32x4* orow = (f32x4*)(c.out + (size_t)m * DM) + lane;
; #pragma unroll
;             for (int j = 0; j < 4; ++j) { v[q][j] = v[q][j] * rstd * gp[64 * j] + bp[64 * j]; if (l == NLAYER) orow[64 * j] = v[q][j]; }
;             if (l < NLAYER && lane == 0) *(float2*)((float*)(c.ws + WS_STATS) + (size_t)m * 2) = make_float2(mean, rstd);
.LBB0_507:
	global_load_dwordx4 v[168:171], v[164:165], off offset:1024
	global_load_dwordx4 v[180:183], v[166:167], off offset:1024
	v_mov_b32_e32 v159, v158
	v_mov_b32_e32 v154, v158
	v_mov_b32_e32 v155, v158
	v_pk_mul_f32 v[148:149], v[160:161], v[154:155]
	v_pk_mul_f32 v[146:147], v[146:147], v[158:159]
	s_and_b64 vcc, exec, s[42:43]
	s_waitcnt vmcnt(0)
	v_pk_fma_f32 v[148:149], v[148:149], v[170:171], v[182:183]
	v_pk_fma_f32 v[146:147], v[146:147], v[168:169], v[180:181]
	s_cbranch_vccnz .LBB0_509
	global_store_dwordx4 v[162:163], v[146:149], off offset:1024 sc1
.LBB0_509:
	v_pk_mul_f32 v[160:161], v[144:145], v[154:155]
	v_pk_mul_f32 v[168:169], v[142:143], v[158:159]
	global_load_dwordx4 v[142:145], v[164:165], off offset:2048
	global_load_dwordx4 v[154:157], v[166:167], off offset:2048
	s_and_b64 vcc, exec, s[42:43]
	s_waitcnt vmcnt(0)
	v_pk_fma_f32 v[144:145], v[160:161], v[144:145], v[156:157]
	v_pk_fma_f32 v[142:143], v[168:169], v[142:143], v[154:155]
	s_cbranch_vccnz .LBB0_511
	global_store_dwordx4 v[162:163], v[142:145], off offset:2048 sc1
.LBB0_511:
	v_mov_b32_e32 v154, v158
	v_mov_b32_e32 v155, v158
	v_pk_mul_f32 v[160:161], v[140:141], v[154:155]
	v_pk_mul_f32 v[168:169], v[138:139], v[158:159]
	global_load_dwordx4 v[138:141], v[164:165], off offset:3072
	global_load_dwordx4 v[154:157], v[166:167], off offset:3072
	s_and_b64 vcc, exec, s[42:43]
	s_waitcnt vmcnt(0)
	v_pk_fma_f32 v[140:141], v[160:161], v[140:141], v[156:157]
	v_pk_fma_f32 v[138:139], v[168:169], v[138:139], v[154:155]
	s_cbranch_vccnz .LBB0_513
	global_store_dwordx4 v[162:163], v[138:141], off offset:3072 sc1
.LBB0_513:
	s_and_saveexec_b64 s[42:43], s[52:53]
	s_cbranch_execz .LBB0_515
	s_lshl_b64 s[16:17], s[54:55], 3
	v_readlane_b32 s0, v253, 37
	s_add_u32 s16, s0, s16
	v_readlane_b32 s0, v253, 38
	v_mul_f32_e32 v154, 0x3a800000, v96
	s_addc_u32 s17, s0, s17
	v_mov_b32_e32 v155, v158
	global_store_dwordx2 v97, v[154:155], s[16:17] sc1

; __device__ __forceinline__ unsigned pk_bf16(float lo, float hi) { return pg8::cvt_pk_bf16(lo, hi); }
; __device__ __forceinline__ void phase_rows(const Ctx& c, int l) {
;     ...
;         if (l < NLAYER) {
;             u32x2* o8 = (u32x2*)(XB + (size_t)m * DM) + lane;
; #pragma unroll
;             for (int j = 0; j < 4; ++j) { u32x2 w; w.x = pk_bf16(v[q][j].x, v[q][j].y); w.y = pk_bf16(v[q][j].z, v[q][j].w); o8[64 * j] = w; }
;             f32x4 a0 = {0.f, 0.f, 0.f, 0.f}, a1 = {0.f, 0.f, 0.f, 0.f};
; #pragma unroll
;             for (int j = 0; j < 4; ++j)
; #pragma unroll
;                 for (int i = 0; i < 4; ++i) { const float xv = v[q][j][i]; a0 += wf[4 * j + i][0] * xv; a1 += wf[4 * j + i][1] * xv; }
.LBB0_516:
	s_and_b64 vcc, exec, s[40:41]
	s_cbranch_vccnz .LBB0_486
	s_ashr_i32 s55, s54, 31
	s_lshl_b64 s[16:17], s[54:55], 11
	s_waitcnt vmcnt(0)
	v_lshl_add_u64 v[154:155], v[176:177], 0, s[16:17]
	v_cvt_pk_bf16_f32 v156, v150, v151
	v_cvt_pk_bf16_f32 v157, v152, v153
	global_store_dwordx2 v[154:155], v[156:157], off sc1
	v_cvt_pk_bf16_f32 v156, v146, v147
	v_cvt_pk_bf16_f32 v157, v148, v149
	global_store_dwordx2 v[154:155], v[156:157], off offset:512 sc1
	v_cvt_pk_bf16_f32 v156, v142, v143
	v_cvt_pk_bf16_f32 v157, v144, v145
	global_store_dwordx2 v[154:155], v[156:157], off offset:1024 sc1
	v_cvt_pk_bf16_f32 v156, v138, v139
	v_cvt_pk_bf16_f32 v157, v140, v141
	global_store_dwordx2 v[154:155], v[156:157], off offset:1536 sc1
	v_pk_fma_f32 v[154:155], v[0:1], v[150:151], 0 op_sel_hi:[1,0,0]
	v_pk_fma_f32 v[156:157], v[2:3], v[150:151], 0 op_sel_hi:[1,0,0]
	v_pk_fma_f32 v[158:159], v[4:5], v[150:151], 0 op_sel_hi:[1,0,0]
	v_pk_fma_f32 v[160:161], v[6:7], v[150:151], 0 op_sel_hi:[1,0,0]
	v_pk_fma_f32 v[154:155], v[12:13], v[150:151], v[154:155] op_sel:[0,1,0]
	v_pk_fma_f32 v[156:157], v[14:15], v[150:151], v[156:157] op_sel:[0,1,0]
	v_pk_fma_f32 v[160:161], v[10:11], v[150:151], v[160:161] op_sel:[0,1,0]
	v_pk_fma_f32 v[150:151], v[8:9], v[150:151], v[158:159] op_sel:[0,1,0]
	v_pk_fma_f32 v[154:155], v[20:21], v[152:153], v[154:155] op_sel_hi:[1,0,1]
	v_mov_b32_e32 v96, v153
	v_pk_fma_f32 v[156:157], v[22:23], v[152:153], v[156:157] op_sel_hi:[1,0,1]
	v_pk_fma_f32 v[150:151], v[16:17], v[152:153], v[150:151] op_sel_hi:[1,0,1]
	v_pk_fma_f32 v[158:159], v[18:19], v[152:153], v[160:161] op_sel_hi:[1,0,1]
	v_pk_fma_f32 v[154:155], v[28:29], v[96:97], v[154:155] op_sel_hi:[1,0,1]
	v_pk_fma_f32 v[152:153], v[30:31], v[96:97], v[156:157] op_sel_hi:[1,0,1]
	v_pk_fma_f32 v[156:157], v[26:27], v[96:97], v[158:159] op_sel_hi:[1,0,1]
	v_pk_fma_f32 v[150:151], v[24:25], v[96:97], v[150:151] op_sel_hi:[1,0,1]
	v_pk_fma_f32 v[154:155], v[36:37], v[146:147], v[154:155] op_sel_hi:[1,0,1]
	v_pk_fma_f32 v[152:153], v[38:39], v[146:147], v[152:153] op_sel_hi:[1,0,1]
	v_pk_fma_f32 v[150:151], v[32:33], v[146:147], v[150:151] op_sel_hi:[1,0,1]
	v_pk_fma_f32 v[156:157], v[34:35], v[146:147], v[156:157] op_sel_hi:[1,0,1]
	v_pk_fma_f32 v[154:155], v[44:45], v[146:147], v[154:155] op_sel:[0,1,0]
	v_pk_fma_f32 v[152:153], v[46:47], v[146:147], v[152:153] op_sel:[0,1,0]
	v_pk_fma_f32 v[156:157], v[42:43], v[146:147], v[156:157] op_sel:[0,1,0]
	v_pk_fma_f32 v[146:147], v[40:41], v[146:147], v[150:151] op_sel:[0,1,0]
	v_pk_fma_f32 v[150:151], v[52:53], v[148:149], v[154:155] op_sel_hi:[1,0,1]
	v_mov_b32_e32 v96, v149
	v_pk_fma_f32 v[152:153], v[54:55], v[148:149], v[152:153] op_sel_hi:[1,0,1]
	v_pk_fma_f32 v[146:147], v[48:49], v[148:149], v[146:147] op_sel_hi:[1,0,1]
	v_pk_fma_f32 v[154:155], v[50:51], v[148:149], v[156:157] op_sel_hi:[1,0,1]
	v_pk_fma_f32 v[150:151], v[60:61], v[96:97], v[150:151] op_sel_hi:[1,0,1]
	v_pk_fma_f32 v[148:149], v[62:63], v[96:97], v[152:153] op_sel_hi:[1,0,1]
	v_pk_fma_f32 v[152:153], v[58:59], v[96:97], v[154:155] op_sel_hi:[1,0,1]
	v_pk_fma_f32 v[146:147], v[56:57], v[96:97], v[146:147] op_sel_hi:[1,0,1]
	v_pk_fma_f32 v[150:151], v[68:69], v[142:143], v[150:151] op_sel_hi:[1,0,1]
	v_pk_fma_f32 v[148:149], v[70:71], v[142:143], v[148:149] op_sel_hi:[1,0,1]
	v_pk_fma_f32 v[146:147], v[64:65], v[142:143], v[146:147] op_sel_hi:[1,0,1]
	v_pk_fma_f32 v[152:153], v[66:67], v[142:143], v[152:153] op_sel_hi:[1,0,1]
	v_pk_fma_f32 v[150:151], v[76:77], v[142:143], v[150:151] op_sel:[0,1,0]
	v_pk_fma_f32 v[148:149], v[78:79], v[142:143], v[148:149] op_sel:[0,1,0]
	v_pk_fma_f32 v[152:153], v[74:75], v[142:143], v[152:153] op_sel:[0,1,0]
	v_pk_fma_f32 v[142:143], v[72:73], v[142:143], v[146:147] op_sel:[0,1,0]
	v_pk_fma_f32 v[146:147], v[92:93], v[144:145], v[150:151] op_sel_hi:[1,0,1]
	v_mov_b32_e32 v96, v145
	v_pk_fma_f32 v[148:149], v[94:95], v[144:145], v[148:149] op_sel_hi:[1,0,1]
	v_pk_fma_f32 v[142:143], v[88:89], v[144:145], v[142:143] op_sel_hi:[1,0,1]
	v_pk_fma_f32 v[150:151], v[90:91], v[144:145], v[152:153] op_sel_hi:[1,0,1]
	v_pk_fma_f32 v[146:147], v[102:103], v[96:97], v[146:147] op_sel_hi:[1,0,1]
	v_pk_fma_f32 v[144:145], v[104:105], v[96:97], v[148:149] op_sel_hi:[1,0,1]
	v_pk_fma_f32 v[148:149], v[100:101], v[96:97], v[150:151] op_sel_hi:[1,0,1]
	v_pk_fma_f32 v[142:143], v[98:99], v[96:97], v[142:143] op_sel_hi:[1,0,1]
	v_pk_fma_f32 v[146:147], v[110:111], v[138:139], v[146:147] op_sel_hi:[1,0,1]
	v_pk_fma_f32 v[144:145], v[112:113], v[138:139], v[144:145] op_sel_hi:[1,0,1]
	v_pk_fma_f32 v[142:143], v[106:107], v[138:139], v[142:143] op_sel_hi:[1,0,1]
	v_pk_fma_f32 v[148:149], v[108:109], v[138:139], v[148:149] op_sel_hi:[1,0,1]
	v_pk_fma_f32 v[146:147], v[118:119], v[138:139], v[146:147] op_sel:[0,1,0]
	v_pk_fma_f32 v[144:145], v[120:121], v[138:139], v[144:145] op_sel:[0,1,0]
	v_pk_fma_f32 v[148:149], v[116:117], v[138:139], v[148:149] op_sel:[0,1,0]
	v_pk_fma_f32 v[138:139], v[114:115], v[138:139], v[142:143] op_sel:[0,1,0]
	v_pk_fma_f32 v[142:143], v[126:127], v[140:141], v[146:147] op_sel_hi:[1,0,1]
	v_mov_b32_e32 v96, v141
	v_pk_fma_f32 v[144:145], v[128:129], v[140:141], v[144:145] op_sel_hi:[1,0,1]
	v_pk_fma_f32 v[138:139], v[122:123], v[140:141], v[138:139] op_sel_hi:[1,0,1]
	v_pk_fma_f32 v[146:147], v[124:125], v[140:141], v[148:149] op_sel_hi:[1,0,1]
	v_pk_fma_f32 v[142:143], v[134:135], v[96:97], v[142:143] op_sel_hi:[1,0,1]
	v_pk_fma_f32 v[140:141], v[136:137], v[96:97], v[144:145] op_sel_hi:[1,0,1]
	v_pk_fma_f32 v[144:145], v[132:133], v[96:97], v[146:147] op_sel_hi:[1,0,1]
; __device__ __forceinline__ float wave_sum(float v) {
;     v += __int_as_float(__builtin_amdgcn_update_dpp(0, __float_as_int(v), 0xB1, 0xf, 0xf, true));
;     v += __int_as_float(__builtin_amdgcn_update_dpp(0, __float_as_int(v), 0x4E, 0xf, 0xf, true));
;     v += __int_as_float(__builtin_amdgcn_update_dpp(0, __float_as_int(v), 0x141, 0xf, 0xf, true));
;     v += __int_as_float(__builtin_amdgcn_update_dpp(0, __float_as_int(v), 0x140, 0xf, 0xf, true));
;     const int iv = __float_as_int(v);
;     const float r0 = __int_as_float(__builtin_amdgcn_readlane(iv, 0)), r1 = __int_as_float(__builtin_amdgcn_readlane(iv, 16)), r2 = __int_as_float(__builtin_amdgcn_readlane(iv, 32)), r3 = __int_as_float(__builtin_amdgcn_readlane(iv, 48));
;     return (r0 + r1) + (r2 + r3);
; __device__ __forceinline__ void phase_rows(const Ctx& c, int l) {
;     ...
;             float f[8];
; #pragma unroll
;             for (int h = 0; h < 4; ++h) { f[h] = wave_sum(a0[h]) + bfv[h]; f[4 + h] = wave_sum(a1[h]) + bfv[4 + h]; }
;             if (lane == 0) { *(f32x4*)(flog + (size_t)m * 8) = (f32x4){f[0], f[1], f[2], f[3]}; *(f32x4*)(flog + (size_t)m * 8 + 4) = (f32x4){f[4], f[5], f[6], f[7]}; }
	v_pk_fma_f32 v[138:139], v[130:131], v[96:97], v[138:139] op_sel_hi:[1,0,1]
	v_add_f32_dpp v96, v142, v142 quad_perm:[1,0,3,2] row_mask:0xf bank_mask:0xf bound_ctrl:1
	s_nop 1
	v_add_f32_dpp v96, v96, v96 quad_perm:[2,3,0,1] row_mask:0xf bank_mask:0xf bound_ctrl:1
	s_nop 1
	v_add_f32_dpp v96, v96, v96 row_half_mirror row_mask:0xf bank_mask:0xf bound_ctrl:1
	s_nop 1
	v_add_f32_dpp v96, v96, v96 row_mirror row_mask:0xf bank_mask:0xf bound_ctrl:1
	s_nop 0
	v_readlane_b32 s62, v96, 0
	v_readlane_b32 s21, v96, 16
	v_readlane_b32 s46, v96, 32
	v_readlane_b32 s17, v96, 48
	v_add_f32_dpp v96, v138, v138 quad_perm:[1,0,3,2] row_mask:0xf bank_mask:0xf bound_ctrl:1
	s_nop 1
	v_add_f32_dpp v96, v96, v96 quad_perm:[2,3,0,1] row_mask:0xf bank_mask:0xf bound_ctrl:1
	s_nop 1
	v_add_f32_dpp v96, v96, v96 row_half_mirror row_mask:0xf bank_mask:0xf bound_ctrl:1
	s_nop 1
	v_add_f32_dpp v96, v96, v96 row_mirror row_mask:0xf bank_mask:0xf bound_ctrl:1
	s_nop 0
	v_readlane_b32 s42, v96, 0
	v_readlane_b32 s6, v96, 16
	v_readlane_b32 s40, v96, 32
	v_readlane_b32 s0, v96, 48
	v_add_f32_dpp v96, v143, v143 quad_perm:[1,0,3,2] row_mask:0xf bank_mask:0xf bound_ctrl:1
	s_nop 1
	v_add_f32_dpp v96, v96, v96 quad_perm:[2,3,0,1] row_mask:0xf bank_mask:0xf bound_ctrl:1
	s_nop 1
	v_add_f32_dpp v96, v96, v96 row_half_mirror row_mask:0xf bank_mask:0xf bound_ctrl:1
	s_nop 1
	v_add_f32_dpp v96, v96, v96 row_mirror row_mask:0xf bank_mask:0xf bound_ctrl:1
	s_nop 0
	v_readlane_b32 s63, v96, 0
	v_readlane_b32 s72, v96, 16
	v_readlane_b32 s47, v96, 32
	v_readlane_b32 s34, v96, 48
	v_add_f32_dpp v96, v139, v139 quad_perm:[1,0,3,2] row_mask:0xf bank_mask:0xf bound_ctrl:1
	s_nop 1
	v_add_f32_dpp v96, v96, v96 quad_perm:[2,3,0,1] row_mask:0xf bank_mask:0xf bound_ctrl:1
	s_nop 1
	v_add_f32_dpp v96, v96, v96 row_half_mirror row_mask:0xf bank_mask:0xf bound_ctrl:1
	s_nop 1
	v_add_f32_dpp v96, v96, v96 row_mirror row_mask:0xf bank_mask:0xf bound_ctrl:1
	s_nop 0
	v_readlane_b32 s43, v96, 0
	v_readlane_b32 s20, v96, 16
	v_readlane_b32 s41, v96, 32
	v_readlane_b32 s16, v96, 48
	v_add_f32_dpp v96, v140, v140 quad_perm:[1,0,3,2] row_mask:0xf bank_mask:0xf bound_ctrl:1
	s_nop 1
	v_add_f32_dpp v96, v96, v96 quad_perm:[2,3,0,1] row_mask:0xf bank_mask:0xf bound_ctrl:1
	s_nop 1
	v_add_f32_dpp v96, v96, v96 row_half_mirror row_mask:0xf bank_mask:0xf bound_ctrl:1
	s_nop 1
	v_add_f32_dpp v96, v96, v96 row_mirror row_mask:0xf bank_mask:0xf bound_ctrl:1
	s_nop 0
	v_readlane_b32 s70, v96, 0
	v_readlane_b32 s80, v96, 16
	v_readlane_b32 s68, v96, 32
	v_readlane_b32 s74, v96, 48
	v_add_f32_dpp v96, v144, v144 quad_perm:[1,0,3,2] row_mask:0xf bank_mask:0xf bound_ctrl:1
	s_nop 1
	v_add_f32_dpp v96, v96, v96 quad_perm:[2,3,0,1] row_mask:0xf bank_mask:0xf bound_ctrl:1
	s_nop 1
	v_add_f32_dpp v96, v96, v96 row_half_mirror row_mask:0xf bank_mask:0xf bound_ctrl:1
	s_nop 1
	v_add_f32_dpp v96, v96, v96 row_mirror row_mask:0xf bank_mask:0xf bound_ctrl:1
	s_nop 0
	v_readlane_b32 s66, v96, 0
	v_readlane_b32 s36, v96, 16
	v_readlane_b32 s64, v96, 32
	v_readlane_b32 s31, v96, 48
	v_add_f32_dpp v96, v141, v141 quad_perm:[1,0,3,2] row_mask:0xf bank_mask:0xf bound_ctrl:1
	s_nop 1
	v_add_f32_dpp v96, v96, v96 quad_perm:[2,3,0,1] row_mask:0xf bank_mask:0xf bound_ctrl:1
	s_nop 1
	v_add_f32_dpp v96, v96, v96 row_half_mirror row_mask:0xf bank_mask:0xf bound_ctrl:1
	s_nop 1
	v_add_f32_dpp v96, v96, v96 row_mirror row_mask:0xf bank_mask:0xf bound_ctrl:1
	s_nop 0
	v_readlane_b32 s71, v96, 0
	v_readlane_b32 s86, v96, 16
	v_readlane_b32 s69, v96, 32
	v_readlane_b32 s81, v96, 48
	v_add_f32_dpp v96, v145, v145 quad_perm:[1,0,3,2] row_mask:0xf bank_mask:0xf bound_ctrl:1
	s_nop 1
	v_add_f32_dpp v96, v96, v96 quad_perm:[2,3,0,1] row_mask:0xf bank_mask:0xf bound_ctrl:1
	s_nop 1
	v_add_f32_dpp v96, v96, v96 row_half_mirror row_mask:0xf bank_mask:0xf bound_ctrl:1
	s_nop 1
	v_add_f32_dpp v96, v96, v96 row_mirror row_mask:0xf bank_mask:0xf bound_ctrl:1
	s_nop 0
	v_readlane_b32 s67, v96, 0
	v_readlane_b32 s75, v96, 16
	v_readlane_b32 s65, v96, 32
	v_readlane_b32 s73, v96, 48
	s_and_saveexec_b64 s[60:61], s[38:39]
	s_cbranch_execz .LBB0_485
	v_mov_b32_e32 v138, s80
	v_mov_b32_e32 v139, s86
	v_mov_b32_e32 v140, s21
	v_mov_b32_e32 v141, s72
	v_mov_b32_e32 v142, s74
	v_mov_b32_e32 v143, s81
	v_mov_b32_e32 v144, s17
	v_mov_b32_e32 v145, s34
	v_pk_add_f32 v[138:139], s[70:71], v[138:139]
	v_pk_add_f32 v[140:141], s[62:63], v[140:141]
	v_pk_add_f32 v[142:143], s[68:69], v[142:143]
	v_pk_add_f32 v[144:145], s[46:47], v[144:145]
	v_pk_add_f32 v[138:139], v[138:139], v[142:143]
	v_pk_add_f32 v[144:145], v[140:141], v[144:145]
	v_pk_add_f32 v[140:141], v[86:87], v[138:139]
	v_pk_add_f32 v[138:139], v[84:85], v[144:145]
	v_mov_b32_e32 v142, s36
	v_mov_b32_e32 v143, s75
	v_mov_b32_e32 v144, s6
	v_mov_b32_e32 v145, s20
	v_mov_b32_e32 v146, s31
	v_mov_b32_e32 v147, s73
	v_mov_b32_e32 v148, s0
	v_mov_b32_e32 v149, s16
	s_lshl_b64 s[16:17], s[54:55], 5
	v_readlane_b32 s0, v253, 25
	v_pk_add_f32 v[142:143], s[66:67], v[142:143]
	v_pk_add_f32 v[144:145], s[42:43], v[144:145]
	v_pk_add_f32 v[146:147], s[64:65], v[146:147]
	v_pk_add_f32 v[148:149], s[40:41], v[148:149]
	s_add_u32 s16, s0, s16
	v_readlane_b32 s0, v253, 26
	v_pk_add_f32 v[148:149], v[144:145], v[148:149]
	v_pk_add_f32 v[142:143], v[142:143], v[146:147]
	s_addc_u32 s17, s0, s17
	v_pk_add_f32 v[144:145], v[82:83], v[142:143]
	v_pk_add_f32 v[142:143], v[80:81], v[148:149]
	global_store_dwordx4 v97, v[138:141], s[16:17] sc1
	global_store_dwordx4 v97, v[142:145], s[16:17] offset:16 sc1
	s_branch .LBB0_485
